# all 12 GEMM main loops: LDS-DMA staging + v_mfma_f32_16x16x32_bf16 (same bf16/f32-acc numerics) with LDS accumulator-layout conversion before the unchanged epilogues; scan-loop nop squeeze
# speedup vs baseline: 1.0834x; 1.0648x over previous
.LBB0_281:
	s_mul_hi_i32 s4, s36, 0x38e38e39
	s_lshr_b32 s8, s4, 31
	s_ashr_i32 s4, s4, 4
	s_add_i32 s4, s4, s8
	s_mul_i32 s8, s4, 0x48
	s_sub_i32 s8, s36, s8
	s_lshl_b32 s8, s8, 7
	v_add_u32_e32 v0, s8, v120
	v_ashrrev_i32_e32 v1, 31, v0
	v_lshlrev_b64 v[32:33], 12, v[0:1]
	v_lshl_add_u64 v[34:35], v[98:99], 0, v[32:33]
	v_add_co_u32_e32 v40, vcc, s87, v34
	s_lshl_b32 s9, s4, 7
	s_nop 0
	v_addc_co_u32_e32 v41, vcc, 0, v35, vcc
	v_add_co_u32_e32 v42, vcc, s66, v34
	v_add_u32_e32 v0, s9, v120
	s_nop 0
	v_addc_co_u32_e32 v43, vcc, 0, v35, vcc
	v_ashrrev_i32_e32 v1, 31, v0
	v_add_co_u32_e32 v44, vcc, s20, v34
	v_lshlrev_b64 v[36:37], 12, v[0:1]
	s_nop 0
	v_addc_co_u32_e32 v45, vcc, 0, v35, vcc
	v_lshl_add_u64 v[38:39], v[100:101], 0, v[36:37]
	v_readfirstlane_b32 s100, v112
	s_nop 3
	s_add_u32 m0, s100, 0x0
	s_nop 0
	global_load_lds_dwordx4 v[34:35], off
	s_add_u32 m0, s100, 0x1000
	s_nop 0
	global_load_lds_dwordx4 v[40:41], off
	s_add_u32 m0, s100, 0x2000
	s_nop 0
	global_load_lds_dwordx4 v[42:43], off
	s_add_u32 m0, s100, 0x3000
	s_nop 0
	global_load_lds_dwordx4 v[44:45], off
	s_add_u32 m0, s100, 0x4000
	s_nop 0
	global_load_lds_dwordx4 v[38:39], off
	v_add_co_u32_e32 v46, vcc, s87, v38
	v_lshl_add_u64 v[104:105], v[102:103], 0, v[36:37]
	s_nop 0
	v_addc_co_u32_e32 v47, vcc, 0, v39, vcc
	v_add_co_u32_e32 v48, vcc, s66, v38
	s_add_u32 m0, s100, 0x5000
	s_nop 0
	global_load_lds_dwordx4 v[46:47], off
	s_nop 0
	v_addc_co_u32_e32 v49, vcc, 0, v39, vcc
	v_add_co_u32_e32 v50, vcc, s20, v38
	s_add_u32 m0, s100, 0x6000
	s_nop 0
	global_load_lds_dwordx4 v[48:49], off
	s_nop 0
	v_addc_co_u32_e32 v51, vcc, 0, v39, vcc
	s_add_u32 m0, s100, 0x7000
	s_nop 0
	global_load_lds_dwordx4 v[50:51], off
	v_lshl_add_u64 v[106:107], v[102:103], 0, v[32:33]
	s_mov_b64 s[34:35], 0
	v_mov_b32_e32 v0, 0
	v_mov_b32_e32 v1, v0
	v_mov_b32_e32 v2, v0
	v_mov_b32_e32 v3, v0
	v_mov_b32_e32 v4, v0
	v_mov_b32_e32 v5, v0
	v_mov_b32_e32 v6, v0
	v_mov_b32_e32 v7, v0
	v_mov_b32_e32 v8, v0
	v_mov_b32_e32 v9, v0
	v_mov_b32_e32 v10, v0
	v_mov_b32_e32 v11, v0
	v_mov_b32_e32 v12, v0
	v_mov_b32_e32 v13, v0
	v_mov_b32_e32 v14, v0
	v_mov_b32_e32 v15, v0
	v_mov_b32_e32 v16, v0
	v_mov_b32_e32 v17, v0
	v_mov_b32_e32 v18, v0
	v_mov_b32_e32 v19, v0
	v_mov_b32_e32 v20, v0
	v_mov_b32_e32 v21, v0
	v_mov_b32_e32 v22, v0
	v_mov_b32_e32 v23, v0
	v_mov_b32_e32 v24, v0
	v_mov_b32_e32 v25, v0
	v_mov_b32_e32 v26, v0
	v_mov_b32_e32 v27, v0
	v_mov_b32_e32 v28, v0
	v_mov_b32_e32 v29, v0
	v_mov_b32_e32 v30, v0
	v_mov_b32_e32 v31, v0
	v_mov_b32_e32 v32, v0
	v_mov_b32_e32 v33, v0
	v_mov_b32_e32 v34, v0
	v_mov_b32_e32 v35, v0
	v_mov_b32_e32 v36, v0
	v_mov_b32_e32 v37, v0
	v_mov_b32_e32 v38, v0
	v_mov_b32_e32 v39, v0
	v_mov_b32_e32 v40, v0
	v_mov_b32_e32 v41, v0
	v_mov_b32_e32 v42, v0
	v_mov_b32_e32 v43, v0
	v_mov_b32_e32 v44, v0
	v_mov_b32_e32 v45, v0
	v_mov_b32_e32 v46, v0
	v_mov_b32_e32 v47, v0
	v_mov_b32_e32 v48, v0
	v_mov_b32_e32 v49, v0
	v_mov_b32_e32 v50, v0
	v_mov_b32_e32 v51, v0
	v_mov_b32_e32 v52, v0
	v_mov_b32_e32 v53, v0
	v_mov_b32_e32 v54, v0
	v_mov_b32_e32 v55, v0
	v_mov_b32_e32 v56, v0
	v_mov_b32_e32 v57, v0
	v_mov_b32_e32 v58, v0
	v_mov_b32_e32 v59, v0
	v_mov_b32_e32 v60, v0
	v_mov_b32_e32 v61, v0
	v_mov_b32_e32 v62, v0
	v_mov_b32_e32 v63, v0
	v_and_b32_e32 v130, 15, v143
	v_lshrrev_b32_e32 v131, 1, v130
	v_bfe_u32 v123, v143, 4, 2
	v_xor_b32_e32 v131, v131, v123
	v_lshlrev_b32_e32 v131, 4, v131
	v_lshl_add_u32 v131, v130, 7, v131
	v_lshrrev_b32_e32 v130, 6, v143
	v_lshrrev_b32_e32 v121, 1, v130
	v_and_b32_e32 v130, 1, v130
	v_lshl_add_u32 v121, v121, 13, v131
	v_lshl_add_u32 v122, v130, 13, v131
	v_add_u32_e32 v122, 0x4000, v122
	v_xor_b32_e32 v123, 64, v121
	v_xor_b32_e32 v124, 64, v122
	s_waitcnt vmcnt(0) lgkmcnt(0)
	s_barrier
.LBB0_282:
	v_lshl_add_u64 v[72:73], v[106:107], 0, s[34:35]
	v_add_co_u32_e32 v134, vcc, s21, v72
	v_lshl_add_u64 v[88:89], v[104:105], 0, s[34:35]
	s_nop 0
	v_addc_co_u32_e32 v135, vcc, 0, v73, vcc
	v_add_co_u32_e32 v152, vcc, s74, v72
	s_mov_b32 s4, 0x38380000
	s_nop 0
	v_addc_co_u32_e32 v153, vcc, 0, v73, vcc
	v_add_co_u32_e32 v154, vcc, s75, v72
	v_addc_co_u32_e32 v155, vcc, 0, v73, vcc
	v_add_co_u32_e32 v156, vcc, s14, v72
	s_nop 1
	v_addc_co_u32_e32 v157, vcc, 0, v73, vcc
	v_add_co_u32_e32 v178, vcc, s4, v88
	s_mov_b32 s4, 0x383a0000
	s_nop 0
	v_addc_co_u32_e32 v179, vcc, 0, v89, vcc
	v_add_co_u32_e32 v180, vcc, s4, v88
	s_mov_b32 s4, 0x383c0000
	s_nop 0
	v_addc_co_u32_e32 v181, vcc, 0, v89, vcc
	v_add_co_u32_e32 v182, vcc, s4, v88
	s_mov_b32 s4, 0x383e0000
	s_nop 0
	v_addc_co_u32_e32 v183, vcc, 0, v89, vcc
	v_add_co_u32_e32 v184, vcc, s4, v88
	v_addc_co_u32_e32 v185, vcc, 0, v89, vcc
	v_lshl_add_u64 v[134:135], 8, 4, v[134:135]
	v_lshl_add_u64 v[152:153], 8, 4, v[152:153]
	v_lshl_add_u64 v[154:155], 8, 4, v[154:155]
	v_lshl_add_u64 v[156:157], 8, 4, v[156:157]
	v_lshl_add_u64 v[178:179], 8, 4, v[178:179]
	v_lshl_add_u64 v[180:181], 8, 4, v[180:181]
	v_lshl_add_u64 v[182:183], 8, 4, v[182:183]
	v_lshl_add_u64 v[184:185], 8, 4, v[184:185]
	s_add_u32 m0, s100, 0x8000
	s_nop 0
	global_load_lds_dwordx4 v[134:135], off
	s_add_u32 m0, s100, 0x9000
	s_nop 0
	global_load_lds_dwordx4 v[152:153], off
	s_add_u32 m0, s100, 0xa000
	s_nop 0
	global_load_lds_dwordx4 v[154:155], off
	s_add_u32 m0, s100, 0xb000
	s_nop 0
	global_load_lds_dwordx4 v[156:157], off
	s_add_u32 m0, s100, 0xc000
	s_nop 0
	global_load_lds_dwordx4 v[178:179], off
	s_add_u32 m0, s100, 0xd000
	s_nop 0
	global_load_lds_dwordx4 v[180:181], off
	s_add_u32 m0, s100, 0xe000
	s_nop 0
	global_load_lds_dwordx4 v[182:183], off
	s_add_u32 m0, s100, 0xf000
	s_nop 0
	global_load_lds_dwordx4 v[184:185], off
	ds_read_b128 a[0:3], v121
	ds_read_b128 v[80:83], v122
	ds_read_b128 a[4:7], v121 offset:2048
	ds_read_b128 a[8:11], v121 offset:4096
	ds_read_b128 a[12:15], v121 offset:6144
	ds_read_b128 v[92:95], v122 offset:2048
	ds_read_b128 v[88:91], v122 offset:4096
	ds_read_b128 v[84:87], v122 offset:6144
	ds_read_b128 a[16:19], v123
	ds_read_b128 a[20:23], v123 offset:2048
	ds_read_b128 a[24:27], v123 offset:4096
	ds_read_b128 a[28:31], v123 offset:6144
	s_setprio 1
	s_waitcnt lgkmcnt(10)
	v_mfma_f32_16x16x32_bf16 v[0:3], a[0:3], v[80:83], v[0:3]
	s_waitcnt lgkmcnt(9)
	v_mfma_f32_16x16x32_bf16 v[16:19], a[4:7], v[80:83], v[16:19]
	s_waitcnt lgkmcnt(8)
	v_mfma_f32_16x16x32_bf16 v[32:35], a[8:11], v[80:83], v[32:35]
	s_waitcnt lgkmcnt(7)
	v_mfma_f32_16x16x32_bf16 v[48:51], a[12:15], v[80:83], v[48:51]
	ds_read_b128 v[80:83], v124
	s_waitcnt lgkmcnt(7)
	v_mfma_f32_16x16x32_bf16 v[4:7], a[0:3], v[92:95], v[4:7]
	v_mfma_f32_16x16x32_bf16 v[20:23], a[4:7], v[92:95], v[20:23]
	v_mfma_f32_16x16x32_bf16 v[36:39], a[8:11], v[92:95], v[36:39]
	v_mfma_f32_16x16x32_bf16 v[52:55], a[12:15], v[92:95], v[52:55]
	ds_read_b128 v[92:95], v124 offset:2048
	s_waitcnt lgkmcnt(7)
	v_mfma_f32_16x16x32_bf16 v[8:11], a[0:3], v[88:91], v[8:11]
	v_mfma_f32_16x16x32_bf16 v[24:27], a[4:7], v[88:91], v[24:27]
	v_mfma_f32_16x16x32_bf16 v[40:43], a[8:11], v[88:91], v[40:43]
	v_mfma_f32_16x16x32_bf16 v[56:59], a[12:15], v[88:91], v[56:59]
	ds_read_b128 v[88:91], v124 offset:4096
	s_waitcnt lgkmcnt(7)
	v_mfma_f32_16x16x32_bf16 v[12:15], a[0:3], v[84:87], v[12:15]
	v_mfma_f32_16x16x32_bf16 v[28:31], a[4:7], v[84:87], v[28:31]
	v_mfma_f32_16x16x32_bf16 v[44:47], a[8:11], v[84:87], v[44:47]
	v_mfma_f32_16x16x32_bf16 v[60:63], a[12:15], v[84:87], v[60:63]
	ds_read_b128 v[84:87], v124 offset:6144
	s_waitcnt lgkmcnt(3)
	v_mfma_f32_16x16x32_bf16 v[0:3], a[16:19], v[80:83], v[0:3]
	v_mfma_f32_16x16x32_bf16 v[16:19], a[20:23], v[80:83], v[16:19]
	v_mfma_f32_16x16x32_bf16 v[32:35], a[24:27], v[80:83], v[32:35]
	v_mfma_f32_16x16x32_bf16 v[48:51], a[28:31], v[80:83], v[48:51]
	s_waitcnt lgkmcnt(2)
	v_mfma_f32_16x16x32_bf16 v[4:7], a[16:19], v[92:95], v[4:7]
	v_mfma_f32_16x16x32_bf16 v[20:23], a[20:23], v[92:95], v[20:23]
	v_mfma_f32_16x16x32_bf16 v[36:39], a[24:27], v[92:95], v[36:39]
	v_mfma_f32_16x16x32_bf16 v[52:55], a[28:31], v[92:95], v[52:55]
	s_waitcnt lgkmcnt(1)
	v_mfma_f32_16x16x32_bf16 v[8:11], a[16:19], v[88:91], v[8:11]
	v_mfma_f32_16x16x32_bf16 v[24:27], a[20:23], v[88:91], v[24:27]
	v_mfma_f32_16x16x32_bf16 v[40:43], a[24:27], v[88:91], v[40:43]
	v_mfma_f32_16x16x32_bf16 v[56:59], a[28:31], v[88:91], v[56:59]
	s_waitcnt lgkmcnt(0)
	v_mfma_f32_16x16x32_bf16 v[12:15], a[16:19], v[84:87], v[12:15]
	v_mfma_f32_16x16x32_bf16 v[28:31], a[20:23], v[84:87], v[28:31]
	v_mfma_f32_16x16x32_bf16 v[44:47], a[24:27], v[84:87], v[44:47]
	v_mfma_f32_16x16x32_bf16 v[60:63], a[28:31], v[84:87], v[60:63]
	s_setprio 0
	s_waitcnt vmcnt(0) lgkmcnt(0)
	s_barrier
	v_lshl_add_u64 v[64:65], 8, 4, v[134:135]
	v_lshl_add_u64 v[66:67], 8, 4, v[152:153]
	v_lshl_add_u64 v[68:69], 8, 4, v[154:155]
	v_lshl_add_u64 v[70:71], 8, 4, v[156:157]
	v_lshl_add_u64 v[76:77], 8, 4, v[178:179]
	v_lshl_add_u64 v[78:79], 8, 4, v[180:181]
	v_lshl_add_u64 v[72:73], 8, 4, v[182:183]
	v_lshl_add_u64 v[74:75], 8, 4, v[184:185]
	s_add_u32 m0, s100, 0x0
	s_nop 0
	global_load_lds_dwordx4 v[64:65], off
	s_add_u32 m0, s100, 0x1000
	s_nop 0
	global_load_lds_dwordx4 v[66:67], off
	s_add_u32 m0, s100, 0x2000
	s_nop 0
	global_load_lds_dwordx4 v[68:69], off
	s_add_u32 m0, s100, 0x3000
	s_nop 0
	global_load_lds_dwordx4 v[70:71], off
	s_add_u32 m0, s100, 0x4000
	s_nop 0
	global_load_lds_dwordx4 v[76:77], off
	s_add_u32 m0, s100, 0x5000
	s_nop 0
	global_load_lds_dwordx4 v[78:79], off
	s_add_u32 m0, s100, 0x6000
	s_nop 0
	global_load_lds_dwordx4 v[72:73], off
	s_add_u32 m0, s100, 0x7000
	s_nop 0
	global_load_lds_dwordx4 v[74:75], off
	ds_read_b128 a[0:3], v121 offset:32768
	ds_read_b128 v[80:83], v122 offset:32768
	ds_read_b128 a[4:7], v121 offset:34816
	ds_read_b128 a[8:11], v121 offset:36864
	ds_read_b128 a[12:15], v121 offset:38912
	ds_read_b128 v[92:95], v122 offset:34816
	ds_read_b128 v[88:91], v122 offset:36864
	ds_read_b128 v[84:87], v122 offset:38912
	ds_read_b128 a[16:19], v123 offset:32768
	ds_read_b128 a[20:23], v123 offset:34816
	ds_read_b128 a[24:27], v123 offset:36864
	ds_read_b128 a[28:31], v123 offset:38912
	s_setprio 1
	s_waitcnt lgkmcnt(10)
	v_mfma_f32_16x16x32_bf16 v[0:3], a[0:3], v[80:83], v[0:3]
	s_waitcnt lgkmcnt(9)
	v_mfma_f32_16x16x32_bf16 v[16:19], a[4:7], v[80:83], v[16:19]
	s_waitcnt lgkmcnt(8)
	v_mfma_f32_16x16x32_bf16 v[32:35], a[8:11], v[80:83], v[32:35]
	s_waitcnt lgkmcnt(7)
	v_mfma_f32_16x16x32_bf16 v[48:51], a[12:15], v[80:83], v[48:51]
	ds_read_b128 v[80:83], v124 offset:32768
	s_waitcnt lgkmcnt(7)
	v_mfma_f32_16x16x32_bf16 v[4:7], a[0:3], v[92:95], v[4:7]
	v_mfma_f32_16x16x32_bf16 v[20:23], a[4:7], v[92:95], v[20:23]
	v_mfma_f32_16x16x32_bf16 v[36:39], a[8:11], v[92:95], v[36:39]
	v_mfma_f32_16x16x32_bf16 v[52:55], a[12:15], v[92:95], v[52:55]
	ds_read_b128 v[92:95], v124 offset:34816
	s_waitcnt lgkmcnt(7)
	v_mfma_f32_16x16x32_bf16 v[8:11], a[0:3], v[88:91], v[8:11]
	v_mfma_f32_16x16x32_bf16 v[24:27], a[4:7], v[88:91], v[24:27]
	v_mfma_f32_16x16x32_bf16 v[40:43], a[8:11], v[88:91], v[40:43]
	v_mfma_f32_16x16x32_bf16 v[56:59], a[12:15], v[88:91], v[56:59]
	ds_read_b128 v[88:91], v124 offset:36864
	s_waitcnt lgkmcnt(7)
	v_mfma_f32_16x16x32_bf16 v[12:15], a[0:3], v[84:87], v[12:15]
	v_mfma_f32_16x16x32_bf16 v[28:31], a[4:7], v[84:87], v[28:31]
	v_mfma_f32_16x16x32_bf16 v[44:47], a[8:11], v[84:87], v[44:47]
	v_mfma_f32_16x16x32_bf16 v[60:63], a[12:15], v[84:87], v[60:63]
	ds_read_b128 v[84:87], v124 offset:38912
	s_waitcnt lgkmcnt(3)
	v_mfma_f32_16x16x32_bf16 v[0:3], a[16:19], v[80:83], v[0:3]
	v_mfma_f32_16x16x32_bf16 v[16:19], a[20:23], v[80:83], v[16:19]
	v_mfma_f32_16x16x32_bf16 v[32:35], a[24:27], v[80:83], v[32:35]
	v_mfma_f32_16x16x32_bf16 v[48:51], a[28:31], v[80:83], v[48:51]
	s_waitcnt lgkmcnt(2)
	v_mfma_f32_16x16x32_bf16 v[4:7], a[16:19], v[92:95], v[4:7]
	v_mfma_f32_16x16x32_bf16 v[20:23], a[20:23], v[92:95], v[20:23]
	v_mfma_f32_16x16x32_bf16 v[36:39], a[24:27], v[92:95], v[36:39]
	v_mfma_f32_16x16x32_bf16 v[52:55], a[28:31], v[92:95], v[52:55]
	s_waitcnt lgkmcnt(1)
	v_mfma_f32_16x16x32_bf16 v[8:11], a[16:19], v[88:91], v[8:11]
	v_mfma_f32_16x16x32_bf16 v[24:27], a[20:23], v[88:91], v[24:27]
	v_mfma_f32_16x16x32_bf16 v[40:43], a[24:27], v[88:91], v[40:43]
	v_mfma_f32_16x16x32_bf16 v[56:59], a[28:31], v[88:91], v[56:59]
	s_waitcnt lgkmcnt(0)
	v_mfma_f32_16x16x32_bf16 v[12:15], a[16:19], v[84:87], v[12:15]
	v_mfma_f32_16x16x32_bf16 v[28:31], a[20:23], v[84:87], v[28:31]
	v_mfma_f32_16x16x32_bf16 v[44:47], a[24:27], v[84:87], v[44:47]
	v_mfma_f32_16x16x32_bf16 v[60:63], a[28:31], v[84:87], v[60:63]
	s_setprio 0
	s_waitcnt vmcnt(0) lgkmcnt(0)
	s_barrier
	s_add_u32 s34, s34, 0x100
	s_addc_u32 s35, s35, 0
	s_cmpk_eq_i32 s34, 0xf00
	s_cbranch_scc0 .LBB0_282
	v_lshl_add_u64 v[64:65], 8, 4, v[64:65]
	v_lshl_add_u64 v[66:67], 8, 4, v[66:67]
	v_lshl_add_u64 v[68:69], 8, 4, v[68:69]
	v_lshl_add_u64 v[70:71], 8, 4, v[70:71]
	v_lshl_add_u64 v[76:77], 8, 4, v[76:77]
	v_lshl_add_u64 v[78:79], 8, 4, v[78:79]
	v_lshl_add_u64 v[72:73], 8, 4, v[72:73]
	v_lshl_add_u64 v[74:75], 8, 4, v[74:75]
	s_add_u32 m0, s100, 0x8000
	s_nop 0
	global_load_lds_dwordx4 v[64:65], off
	s_add_u32 m0, s100, 0x9000
	s_nop 0
	global_load_lds_dwordx4 v[66:67], off
	s_add_u32 m0, s100, 0xa000
	s_nop 0
	global_load_lds_dwordx4 v[68:69], off
	s_add_u32 m0, s100, 0xb000
	s_nop 0
	global_load_lds_dwordx4 v[70:71], off
	s_add_u32 m0, s100, 0xc000
	s_nop 0
	global_load_lds_dwordx4 v[76:77], off
	s_add_u32 m0, s100, 0xd000
	s_nop 0
	global_load_lds_dwordx4 v[78:79], off
	s_add_u32 m0, s100, 0xe000
	s_nop 0
	global_load_lds_dwordx4 v[72:73], off
	s_add_u32 m0, s100, 0xf000
	s_nop 0
	global_load_lds_dwordx4 v[74:75], off
	ds_read_b128 a[0:3], v121
	ds_read_b128 v[80:83], v122
	ds_read_b128 a[4:7], v121 offset:2048
	ds_read_b128 a[8:11], v121 offset:4096
	ds_read_b128 a[12:15], v121 offset:6144
	ds_read_b128 v[92:95], v122 offset:2048
	ds_read_b128 v[88:91], v122 offset:4096
	ds_read_b128 v[84:87], v122 offset:6144
	ds_read_b128 a[16:19], v123
	ds_read_b128 a[20:23], v123 offset:2048
	ds_read_b128 a[24:27], v123 offset:4096
	ds_read_b128 a[28:31], v123 offset:6144
	s_setprio 1
	s_waitcnt lgkmcnt(10)
	v_mfma_f32_16x16x32_bf16 v[0:3], a[0:3], v[80:83], v[0:3]
	s_waitcnt lgkmcnt(9)
	v_mfma_f32_16x16x32_bf16 v[16:19], a[4:7], v[80:83], v[16:19]
	s_waitcnt lgkmcnt(8)
	v_mfma_f32_16x16x32_bf16 v[32:35], a[8:11], v[80:83], v[32:35]
	s_waitcnt lgkmcnt(7)
	v_mfma_f32_16x16x32_bf16 v[48:51], a[12:15], v[80:83], v[48:51]
	ds_read_b128 v[80:83], v124
	s_waitcnt lgkmcnt(7)
	v_mfma_f32_16x16x32_bf16 v[4:7], a[0:3], v[92:95], v[4:7]
	v_mfma_f32_16x16x32_bf16 v[20:23], a[4:7], v[92:95], v[20:23]
	v_mfma_f32_16x16x32_bf16 v[36:39], a[8:11], v[92:95], v[36:39]
	v_mfma_f32_16x16x32_bf16 v[52:55], a[12:15], v[92:95], v[52:55]
	ds_read_b128 v[92:95], v124 offset:2048
	s_waitcnt lgkmcnt(7)
	v_mfma_f32_16x16x32_bf16 v[8:11], a[0:3], v[88:91], v[8:11]
	v_mfma_f32_16x16x32_bf16 v[24:27], a[4:7], v[88:91], v[24:27]
	v_mfma_f32_16x16x32_bf16 v[40:43], a[8:11], v[88:91], v[40:43]
	v_mfma_f32_16x16x32_bf16 v[56:59], a[12:15], v[88:91], v[56:59]
	ds_read_b128 v[88:91], v124 offset:4096
	s_waitcnt lgkmcnt(7)
	v_mfma_f32_16x16x32_bf16 v[12:15], a[0:3], v[84:87], v[12:15]
	v_mfma_f32_16x16x32_bf16 v[28:31], a[4:7], v[84:87], v[28:31]
	v_mfma_f32_16x16x32_bf16 v[44:47], a[8:11], v[84:87], v[44:47]
	v_mfma_f32_16x16x32_bf16 v[60:63], a[12:15], v[84:87], v[60:63]
	ds_read_b128 v[84:87], v124 offset:6144
	s_waitcnt lgkmcnt(3)
	v_mfma_f32_16x16x32_bf16 v[0:3], a[16:19], v[80:83], v[0:3]
	v_mfma_f32_16x16x32_bf16 v[16:19], a[20:23], v[80:83], v[16:19]
	v_mfma_f32_16x16x32_bf16 v[32:35], a[24:27], v[80:83], v[32:35]
	v_mfma_f32_16x16x32_bf16 v[48:51], a[28:31], v[80:83], v[48:51]
	s_waitcnt lgkmcnt(2)
	v_mfma_f32_16x16x32_bf16 v[4:7], a[16:19], v[92:95], v[4:7]
	v_mfma_f32_16x16x32_bf16 v[20:23], a[20:23], v[92:95], v[20:23]
	v_mfma_f32_16x16x32_bf16 v[36:39], a[24:27], v[92:95], v[36:39]
	v_mfma_f32_16x16x32_bf16 v[52:55], a[28:31], v[92:95], v[52:55]
	s_waitcnt lgkmcnt(1)
	v_mfma_f32_16x16x32_bf16 v[8:11], a[16:19], v[88:91], v[8:11]
	v_mfma_f32_16x16x32_bf16 v[24:27], a[20:23], v[88:91], v[24:27]
	v_mfma_f32_16x16x32_bf16 v[40:43], a[24:27], v[88:91], v[40:43]
	v_mfma_f32_16x16x32_bf16 v[56:59], a[28:31], v[88:91], v[56:59]
	s_waitcnt lgkmcnt(0)
	v_mfma_f32_16x16x32_bf16 v[12:15], a[16:19], v[84:87], v[12:15]
	v_mfma_f32_16x16x32_bf16 v[28:31], a[20:23], v[84:87], v[28:31]
	v_mfma_f32_16x16x32_bf16 v[44:47], a[24:27], v[84:87], v[44:47]
	v_mfma_f32_16x16x32_bf16 v[60:63], a[28:31], v[84:87], v[60:63]
	s_setprio 0
	s_waitcnt vmcnt(0) lgkmcnt(0)
	s_barrier
	ds_read_b128 a[0:3], v121 offset:32768
	ds_read_b128 v[80:83], v122 offset:32768
	ds_read_b128 a[4:7], v121 offset:34816
	ds_read_b128 a[8:11], v121 offset:36864
	ds_read_b128 a[12:15], v121 offset:38912
	ds_read_b128 v[92:95], v122 offset:34816
	ds_read_b128 v[88:91], v122 offset:36864
	ds_read_b128 v[84:87], v122 offset:38912
	ds_read_b128 a[16:19], v123 offset:32768
	ds_read_b128 a[20:23], v123 offset:34816
	ds_read_b128 a[24:27], v123 offset:36864
	ds_read_b128 a[28:31], v123 offset:38912
	s_setprio 1
	s_waitcnt lgkmcnt(10)
	v_mfma_f32_16x16x32_bf16 v[0:3], a[0:3], v[80:83], v[0:3]
	s_waitcnt lgkmcnt(9)
	v_mfma_f32_16x16x32_bf16 v[16:19], a[4:7], v[80:83], v[16:19]
	s_waitcnt lgkmcnt(8)
	v_mfma_f32_16x16x32_bf16 v[32:35], a[8:11], v[80:83], v[32:35]
	s_waitcnt lgkmcnt(7)
	v_mfma_f32_16x16x32_bf16 v[48:51], a[12:15], v[80:83], v[48:51]
	ds_read_b128 v[80:83], v124 offset:32768
	s_waitcnt lgkmcnt(7)
	v_mfma_f32_16x16x32_bf16 v[4:7], a[0:3], v[92:95], v[4:7]
	v_mfma_f32_16x16x32_bf16 v[20:23], a[4:7], v[92:95], v[20:23]
	v_mfma_f32_16x16x32_bf16 v[36:39], a[8:11], v[92:95], v[36:39]
	v_mfma_f32_16x16x32_bf16 v[52:55], a[12:15], v[92:95], v[52:55]
	ds_read_b128 v[92:95], v124 offset:34816
	s_waitcnt lgkmcnt(7)
	v_mfma_f32_16x16x32_bf16 v[8:11], a[0:3], v[88:91], v[8:11]
	v_mfma_f32_16x16x32_bf16 v[24:27], a[4:7], v[88:91], v[24:27]
	v_mfma_f32_16x16x32_bf16 v[40:43], a[8:11], v[88:91], v[40:43]
	v_mfma_f32_16x16x32_bf16 v[56:59], a[12:15], v[88:91], v[56:59]
	ds_read_b128 v[88:91], v124 offset:36864
	s_waitcnt lgkmcnt(7)
	v_mfma_f32_16x16x32_bf16 v[12:15], a[0:3], v[84:87], v[12:15]
	v_mfma_f32_16x16x32_bf16 v[28:31], a[4:7], v[84:87], v[28:31]
	v_mfma_f32_16x16x32_bf16 v[44:47], a[8:11], v[84:87], v[44:47]
	v_mfma_f32_16x16x32_bf16 v[60:63], a[12:15], v[84:87], v[60:63]
	ds_read_b128 v[84:87], v124 offset:38912
	s_waitcnt lgkmcnt(3)
	v_mfma_f32_16x16x32_bf16 v[0:3], a[16:19], v[80:83], v[0:3]
	v_mfma_f32_16x16x32_bf16 v[16:19], a[20:23], v[80:83], v[16:19]
	v_mfma_f32_16x16x32_bf16 v[32:35], a[24:27], v[80:83], v[32:35]
	v_mfma_f32_16x16x32_bf16 v[48:51], a[28:31], v[80:83], v[48:51]
	s_waitcnt lgkmcnt(2)
	v_mfma_f32_16x16x32_bf16 v[4:7], a[16:19], v[92:95], v[4:7]
	v_mfma_f32_16x16x32_bf16 v[20:23], a[20:23], v[92:95], v[20:23]
	v_mfma_f32_16x16x32_bf16 v[36:39], a[24:27], v[92:95], v[36:39]
	v_mfma_f32_16x16x32_bf16 v[52:55], a[28:31], v[92:95], v[52:55]
	s_waitcnt lgkmcnt(1)
	v_mfma_f32_16x16x32_bf16 v[8:11], a[16:19], v[88:91], v[8:11]
	v_mfma_f32_16x16x32_bf16 v[24:27], a[20:23], v[88:91], v[24:27]
	v_mfma_f32_16x16x32_bf16 v[40:43], a[24:27], v[88:91], v[40:43]
	v_mfma_f32_16x16x32_bf16 v[56:59], a[28:31], v[88:91], v[56:59]
	s_waitcnt lgkmcnt(0)
	v_mfma_f32_16x16x32_bf16 v[12:15], a[16:19], v[84:87], v[12:15]
	v_mfma_f32_16x16x32_bf16 v[28:31], a[20:23], v[84:87], v[28:31]
	v_mfma_f32_16x16x32_bf16 v[44:47], a[24:27], v[84:87], v[44:47]
	v_mfma_f32_16x16x32_bf16 v[60:63], a[28:31], v[84:87], v[60:63]
	s_setprio 0
	v_readfirstlane_b32 s15, v111
	v_readfirstlane_b32 s4, v110
	s_lshl_b32 s15, s15, 6
	s_waitcnt lgkmcnt(0)
	s_barrier
	s_add_i32 s15, s15, s9
	s_lshl_b32 s23, s4, 6
	s_add_i32 s23, s23, s8
	v_or_b32_e32 v67, s15, v109
	s_movk_i32 s4, 0x800
	s_ashr_i32 s22, s23, 11
	v_cmp_gt_i32_e32 vcc, s4, v67
	v_add_u32_e32 v65, 0x1000, v67
	v_add_u32_e32 v64, v67, v97
	v_lshl_or_b32 v66, s23, 11, v97
	s_barrier
	v_and_b32_e32 v130, 15, v143
	v_bfe_u32 v131, v143, 4, 2
	v_xor_b32_e32 v131, v131, v130
	v_lshlrev_b32_e32 v131, 4, v131
	v_lshl_add_u32 v131, v130, 8, v131
	v_lshrrev_b32_e32 v130, 6, v143
	v_lshl_add_u32 v131, v130, 14, v131
	ds_write_b128 v131, v[0:3]
	ds_write_b128 v131, v[4:7] offset:4096
	ds_write_b128 v131, v[8:11] offset:8192
	ds_write_b128 v131, v[12:15] offset:12288
	v_xor_b32_e32 v124, 64, v131
	ds_write_b128 v124, v[16:19]
	ds_write_b128 v124, v[20:23] offset:4096
	ds_write_b128 v124, v[24:27] offset:8192
	ds_write_b128 v124, v[28:31] offset:12288
	v_xor_b32_e32 v124, 128, v131
	ds_write_b128 v124, v[32:35]
	ds_write_b128 v124, v[36:39] offset:4096
	ds_write_b128 v124, v[40:43] offset:8192
	ds_write_b128 v124, v[44:47] offset:12288
	v_xor_b32_e32 v124, 192, v131
	ds_write_b128 v124, v[48:51]
	ds_write_b128 v124, v[52:55] offset:4096
	ds_write_b128 v124, v[56:59] offset:8192
	ds_write_b128 v124, v[60:63] offset:12288
	v_and_b32_e32 v121, 31, v143
	v_bfe_u32 v123, v143, 5, 1
	v_and_b32_e32 v131, 15, v121
	v_xor_b32_e32 v123, v123, v131
	v_lshlrev_b32_e32 v123, 4, v123
	v_lshl_add_u32 v123, v121, 8, v123
	v_lshl_add_u32 v123, v130, 14, v123
	ds_read_b128 v[48:51], v123
	ds_read_b128 v[32:35], v123 offset:8192
	v_xor_b32_e32 v122, 32, v123
	ds_read_b128 v[52:55], v122
	ds_read_b128 v[36:39], v122 offset:8192
	v_xor_b32_e32 v122, 64, v123
	ds_read_b128 v[56:59], v122
	ds_read_b128 v[40:43], v122 offset:8192
	v_xor_b32_e32 v122, 96, v123
	ds_read_b128 v[60:63], v122
	ds_read_b128 v[44:47], v122 offset:8192
	v_xor_b32_e32 v122, 128, v123
	ds_read_b128 v[16:19], v122
	ds_read_b128 v[0:3], v122 offset:8192
	v_xor_b32_e32 v122, 160, v123
	ds_read_b128 v[20:23], v122
	ds_read_b128 v[4:7], v122 offset:8192
	v_xor_b32_e32 v122, 192, v123
	ds_read_b128 v[24:27], v122
	ds_read_b128 v[8:11], v122 offset:8192
	v_xor_b32_e32 v122, 224, v123
	ds_read_b128 v[28:31], v122
	ds_read_b128 v[12:15], v122 offset:8192
	s_waitcnt lgkmcnt(0)
	s_barrier
	s_and_saveexec_b64 s[8:9], vcc
	s_cbranch_execz .LBB0_285
	s_add_i32 s4, s23, 0xffffe000
	s_lshr_b32 s4, s4, 3
	s_or_b32 s4, s4, 4
	s_cmpk_lt_i32 s23, 0x2000
	s_cselect_b32 s4, s22, s4
	s_mulk_i32 s4, 0x3000
	v_add_u32_e32 v68, s4, v65
	v_mov_b32_e32 v69, v140
	v_lshl_add_u64 v[68:69], v[68:69], 2, s[26:27]
	global_load_dword v72, v[68:69], off
	v_add_u32_e32 v68, v66, v67
	v_mov_b32_e32 v69, v140
	v_lshl_add_u64 v[70:71], v[68:69], 2, s[0:1]
	global_load_dword v69, v[70:71], off
	s_waitcnt vmcnt(0)
	v_fmac_f32_e32 v69, v48, v72
	global_store_dword v[70:71], v69, off
	v_add_u32_e32 v70, 0x800, v68
	v_mov_b32_e32 v71, v140
	v_lshl_add_u64 v[70:71], v[70:71], 2, s[0:1]
	global_load_dword v48, v[70:71], off
	s_waitcnt vmcnt(0)
	v_fmac_f32_e32 v48, v49, v72
	global_store_dword v[70:71], v48, off
	v_add_u32_e32 v48, 0x1000, v68
	v_mov_b32_e32 v49, v140
	v_lshl_add_u64 v[48:49], v[48:49], 2, s[0:1]
	global_load_dword v69, v[48:49], off
	s_waitcnt vmcnt(0)
	v_fmac_f32_e32 v69, v50, v72
	global_store_dword v[48:49], v69, off
	v_add_u32_e32 v48, 0x1800, v68
	v_mov_b32_e32 v49, v140
	v_lshl_add_u64 v[48:49], v[48:49], 2, s[0:1]
	global_load_dword v50, v[48:49], off
	s_waitcnt vmcnt(0)
	v_fmac_f32_e32 v50, v51, v72
	global_store_dword v[48:49], v50, off
	s_add_i32 s15, s23, 0xffffe008
	s_lshr_b32 s15, s15, 3
	s_or_b32 s4, s23, 8
	s_or_b32 s15, s15, 4
	s_cmpk_lt_i32 s4, 0x2000
	s_cselect_b32 s15, s22, s15
	s_mulk_i32 s15, 0x3000
	v_add_u32_e32 v48, s15, v65
	v_mov_b32_e32 v49, v140
	v_lshl_add_u64 v[48:49], v[48:49], 2, s[26:27]
	global_load_dword v68, v[48:49], off
	v_lshl_add_u32 v48, s4, 11, v64
	v_mov_b32_e32 v49, v140
	v_lshl_add_u64 v[50:51], v[48:49], 2, s[0:1]
	global_load_dword v49, v[50:51], off
	s_waitcnt vmcnt(0)
	v_fmac_f32_e32 v49, v52, v68
	global_store_dword v[50:51], v49, off
	v_add_u32_e32 v50, 0x800, v48
	v_mov_b32_e32 v51, v140
	v_lshl_add_u64 v[50:51], v[50:51], 2, s[0:1]
	global_load_dword v49, v[50:51], off
	s_waitcnt vmcnt(0)
	v_fmac_f32_e32 v49, v53, v68
	global_store_dword v[50:51], v49, off
	v_add_u32_e32 v50, 0x1000, v48
	v_mov_b32_e32 v51, v140
	v_lshl_add_u64 v[50:51], v[50:51], 2, s[0:1]
	global_load_dword v49, v[50:51], off
	v_add_u32_e32 v48, 0x1800, v48
	s_waitcnt vmcnt(0)
	v_fmac_f32_e32 v49, v54, v68
	global_store_dword v[50:51], v49, off
	v_mov_b32_e32 v49, v140
	v_lshl_add_u64 v[48:49], v[48:49], 2, s[0:1]
	global_load_dword v50, v[48:49], off
	s_waitcnt vmcnt(0)
	v_fmac_f32_e32 v50, v55, v68
	global_store_dword v[48:49], v50, off
	s_add_i32 s15, s23, 0xffffe010
	s_lshr_b32 s15, s15, 3
	s_or_b32 s4, s23, 16
	s_or_b32 s15, s15, 4
	s_cmpk_lt_i32 s4, 0x2000
	s_cselect_b32 s15, s22, s15
	s_mulk_i32 s15, 0x3000
	v_add_u32_e32 v48, s15, v65
	v_mov_b32_e32 v49, v140
	v_lshl_add_u64 v[48:49], v[48:49], 2, s[26:27]
	global_load_dword v52, v[48:49], off
	v_lshl_add_u32 v48, s4, 11, v64
	v_mov_b32_e32 v49, v140
	v_lshl_add_u64 v[50:51], v[48:49], 2, s[0:1]
	global_load_dword v49, v[50:51], off
	s_waitcnt vmcnt(0)
	v_fmac_f32_e32 v49, v56, v52
	global_store_dword v[50:51], v49, off
	v_add_u32_e32 v50, 0x800, v48
	v_mov_b32_e32 v51, v140
	v_lshl_add_u64 v[50:51], v[50:51], 2, s[0:1]
	global_load_dword v49, v[50:51], off
	s_waitcnt vmcnt(0)
	v_fmac_f32_e32 v49, v57, v52
	global_store_dword v[50:51], v49, off
	v_add_u32_e32 v50, 0x1000, v48
	v_mov_b32_e32 v51, v140
	v_lshl_add_u64 v[50:51], v[50:51], 2, s[0:1]
	global_load_dword v49, v[50:51], off
	v_add_u32_e32 v48, 0x1800, v48
	s_waitcnt vmcnt(0)
	v_fmac_f32_e32 v49, v58, v52
	global_store_dword v[50:51], v49, off
	v_mov_b32_e32 v49, v140
	v_lshl_add_u64 v[48:49], v[48:49], 2, s[0:1]
	global_load_dword v50, v[48:49], off
	s_waitcnt vmcnt(0)
	v_fmac_f32_e32 v50, v59, v52
	global_store_dword v[48:49], v50, off
	s_add_i32 s15, s23, 0xffffe018
	s_lshr_b32 s15, s15, 3
	s_or_b32 s4, s23, 24
	s_or_b32 s15, s15, 4
	s_cmpk_lt_i32 s4, 0x2000
	s_cselect_b32 s15, s22, s15
	s_mulk_i32 s15, 0x3000
	v_add_u32_e32 v48, s15, v65
	v_mov_b32_e32 v49, v140
	v_lshl_add_u64 v[48:49], v[48:49], 2, s[26:27]
	global_load_dword v52, v[48:49], off
	v_lshl_add_u32 v48, s4, 11, v64
	v_mov_b32_e32 v49, v140
	v_lshl_add_u64 v[50:51], v[48:49], 2, s[0:1]
	global_load_dword v49, v[50:51], off
	s_waitcnt vmcnt(0)
	v_fmac_f32_e32 v49, v60, v52
	global_store_dword v[50:51], v49, off
	v_add_u32_e32 v50, 0x800, v48
	v_mov_b32_e32 v51, v140
	v_lshl_add_u64 v[50:51], v[50:51], 2, s[0:1]
	global_load_dword v49, v[50:51], off
	s_waitcnt vmcnt(0)
	v_fmac_f32_e32 v49, v61, v52
	global_store_dword v[50:51], v49, off
	v_add_u32_e32 v50, 0x1000, v48
	v_mov_b32_e32 v51, v140
	v_lshl_add_u64 v[50:51], v[50:51], 2, s[0:1]
	global_load_dword v49, v[50:51], off
	v_add_u32_e32 v48, 0x1800, v48
	s_waitcnt vmcnt(0)
	v_fmac_f32_e32 v49, v62, v52
	global_store_dword v[50:51], v49, off
	v_mov_b32_e32 v49, v140
	v_lshl_add_u64 v[48:49], v[48:49], 2, s[0:1]
	global_load_dword v50, v[48:49], off
	s_waitcnt vmcnt(0)
	v_fmac_f32_e32 v50, v63, v52
	global_store_dword v[48:49], v50, off

.LBB0_582:
	s_mul_hi_i32 s4, s22, 0x38e38e39
	s_lshr_b32 s8, s4, 31
	s_ashr_i32 s4, s4, 4
	s_add_i32 s4, s4, s8
	s_mul_i32 s8, s4, 0x48
	s_sub_i32 s8, s22, s8
	v_lshl_add_u32 v0, s8, 7, v109
	v_ashrrev_i32_e32 v1, 31, v0
	v_lshlrev_b64 v[32:33], 12, v[0:1]
	v_lshl_add_u64 v[34:35], v[96:97], 0, v[32:33]
	v_add_co_u32_e32 v40, vcc, s87, v34
	s_lshl_b32 s9, s4, 7
	s_nop 0
	v_addc_co_u32_e32 v41, vcc, 0, v35, vcc
	v_add_co_u32_e32 v42, vcc, s66, v34
	v_add_u32_e32 v0, s9, v109
	s_nop 0
	v_addc_co_u32_e32 v43, vcc, 0, v35, vcc
	v_ashrrev_i32_e32 v1, 31, v0
	v_add_co_u32_e32 v44, vcc, s20, v34
	v_lshlrev_b64 v[36:37], 12, v[0:1]
	s_nop 0
	v_addc_co_u32_e32 v45, vcc, 0, v35, vcc
	v_lshl_add_u64 v[38:39], v[98:99], 0, v[36:37]
	v_readfirstlane_b32 s100, v110
	s_nop 3
	s_add_u32 m0, s100, 0x0
	s_nop 0
	global_load_lds_dwordx4 v[34:35], off
	s_add_u32 m0, s100, 0x1000
	s_nop 0
	global_load_lds_dwordx4 v[40:41], off
	s_add_u32 m0, s100, 0x2000
	s_nop 0
	global_load_lds_dwordx4 v[42:43], off
	s_add_u32 m0, s100, 0x3000
	s_nop 0
	global_load_lds_dwordx4 v[44:45], off
	s_add_u32 m0, s100, 0x4000
	s_nop 0
	global_load_lds_dwordx4 v[38:39], off
	v_add_co_u32_e32 v46, vcc, s87, v38
	v_lshl_add_u64 v[102:103], v[100:101], 0, v[36:37]
	s_nop 0
	v_addc_co_u32_e32 v47, vcc, 0, v39, vcc
	s_waitcnt vmcnt(16)
	v_add_co_u32_e32 v48, vcc, s66, v38
	s_add_u32 m0, s100, 0x5000
	s_nop 0
	global_load_lds_dwordx4 v[46:47], off
	s_nop 0
	v_addc_co_u32_e32 v49, vcc, 0, v39, vcc
	v_add_co_u32_e32 v50, vcc, s20, v38
	s_add_u32 m0, s100, 0x6000
	s_nop 0
	global_load_lds_dwordx4 v[48:49], off
	s_nop 0
	v_addc_co_u32_e32 v51, vcc, 0, v39, vcc
	s_add_u32 m0, s100, 0x7000
	s_nop 0
	global_load_lds_dwordx4 v[50:51], off
	v_lshl_add_u64 v[104:105], v[100:101], 0, v[32:33]
	s_mov_b64 s[28:29], 0
	v_mov_b32_e32 v0, 0
	v_mov_b32_e32 v1, v0
	v_mov_b32_e32 v2, v0
	v_mov_b32_e32 v3, v0
	v_mov_b32_e32 v4, v0
	v_mov_b32_e32 v5, v0
	v_mov_b32_e32 v6, v0
	v_mov_b32_e32 v7, v0
	v_mov_b32_e32 v8, v0
	v_mov_b32_e32 v9, v0
	v_mov_b32_e32 v10, v0
	v_mov_b32_e32 v11, v0
	v_mov_b32_e32 v12, v0
	v_mov_b32_e32 v13, v0
	v_mov_b32_e32 v14, v0
	v_mov_b32_e32 v15, v0
	v_mov_b32_e32 v16, v0
	v_mov_b32_e32 v17, v0
	v_mov_b32_e32 v18, v0
	v_mov_b32_e32 v19, v0
	v_mov_b32_e32 v20, v0
	v_mov_b32_e32 v21, v0
	v_mov_b32_e32 v22, v0
	v_mov_b32_e32 v23, v0
	v_mov_b32_e32 v24, v0
	v_mov_b32_e32 v25, v0
	v_mov_b32_e32 v26, v0
	v_mov_b32_e32 v27, v0
	v_mov_b32_e32 v28, v0
	v_mov_b32_e32 v29, v0
	v_mov_b32_e32 v30, v0
	v_mov_b32_e32 v31, v0
	v_mov_b32_e32 v32, v0
	v_mov_b32_e32 v33, v0
	v_mov_b32_e32 v34, v0
	v_mov_b32_e32 v35, v0
	v_mov_b32_e32 v36, v0
	v_mov_b32_e32 v37, v0
	v_mov_b32_e32 v38, v0
	v_mov_b32_e32 v39, v0
	v_mov_b32_e32 v40, v0
	v_mov_b32_e32 v41, v0
	v_mov_b32_e32 v42, v0
	v_mov_b32_e32 v43, v0
	v_mov_b32_e32 v44, v0
	v_mov_b32_e32 v45, v0
	v_mov_b32_e32 v46, v0
	v_mov_b32_e32 v47, v0
	v_mov_b32_e32 v48, v0
	v_mov_b32_e32 v49, v0
	v_mov_b32_e32 v50, v0
	v_mov_b32_e32 v51, v0
	v_mov_b32_e32 v52, v0
	v_mov_b32_e32 v53, v0
	v_mov_b32_e32 v54, v0
	v_mov_b32_e32 v55, v0
	v_mov_b32_e32 v56, v0
	v_mov_b32_e32 v57, v0
	v_mov_b32_e32 v58, v0
	v_mov_b32_e32 v59, v0
	v_mov_b32_e32 v60, v0
	v_mov_b32_e32 v61, v0
	v_mov_b32_e32 v62, v0
	v_mov_b32_e32 v63, v0
	v_and_b32_e32 v124, 15, v143
	v_lshrrev_b32_e32 v125, 1, v124
	v_bfe_u32 v117, v143, 4, 2
	v_xor_b32_e32 v125, v125, v117
	v_lshlrev_b32_e32 v125, 4, v125
	v_lshl_add_u32 v125, v124, 7, v125
	v_lshrrev_b32_e32 v124, 6, v143
	v_lshrrev_b32_e32 v115, 1, v124
	v_and_b32_e32 v124, 1, v124
	v_lshl_add_u32 v115, v115, 13, v125
	v_lshl_add_u32 v116, v124, 13, v125
	v_add_u32_e32 v116, 0x4000, v116
	v_xor_b32_e32 v117, 64, v115
	v_xor_b32_e32 v118, 64, v116
	s_waitcnt vmcnt(0) lgkmcnt(0)
	s_barrier
.LBB0_583:
	v_lshl_add_u64 v[72:73], v[104:105], 0, s[28:29]
	s_mov_b32 s4, 0x15ab8000
	v_add_co_u32_e32 v144, vcc, s4, v72
	s_mov_b32 s4, 0x15ad8000
	s_nop 0
	v_addc_co_u32_e32 v145, vcc, 0, v73, vcc
	v_add_co_u32_e32 v146, vcc, s4, v72
	s_mov_b32 s4, 0x15af8000
	s_nop 0
	v_addc_co_u32_e32 v147, vcc, 0, v73, vcc
	v_add_co_u32_e32 v148, vcc, s4, v72
	s_mov_b32 s4, 0x15b18000
	s_nop 0
	v_addc_co_u32_e32 v149, vcc, 0, v73, vcc
	v_add_co_u32_e32 v150, vcc, s4, v72
	v_lshl_add_u64 v[88:89], v[102:103], 0, s[28:29]
	s_nop 0
	v_addc_co_u32_e32 v151, vcc, 0, v73, vcc
	s_mov_b32 s4, 0x36b80000
	v_add_co_u32_e32 v152, vcc, s4, v88
	s_mov_b32 s4, 0x36ba0000
	s_nop 0
	v_addc_co_u32_e32 v153, vcc, 0, v89, vcc
	v_add_co_u32_e32 v154, vcc, s4, v88
	s_mov_b32 s4, 0x36bc0000
	s_nop 0
	v_addc_co_u32_e32 v155, vcc, 0, v89, vcc
	v_add_co_u32_e32 v156, vcc, s4, v88
	s_mov_b32 s4, 0x36be0000
	s_nop 0
	v_addc_co_u32_e32 v157, vcc, 0, v89, vcc
	v_add_co_u32_e32 v178, vcc, s4, v88
	v_addc_co_u32_e32 v179, vcc, 0, v89, vcc
	v_lshl_add_u64 v[144:145], 8, 4, v[144:145]
	v_lshl_add_u64 v[146:147], 8, 4, v[146:147]
	v_lshl_add_u64 v[148:149], 8, 4, v[148:149]
	v_lshl_add_u64 v[150:151], 8, 4, v[150:151]
	v_lshl_add_u64 v[152:153], 8, 4, v[152:153]
	v_lshl_add_u64 v[154:155], 8, 4, v[154:155]
	v_lshl_add_u64 v[156:157], 8, 4, v[156:157]
	v_lshl_add_u64 v[178:179], 8, 4, v[178:179]
	s_add_u32 m0, s100, 0x8000
	s_nop 0
	global_load_lds_dwordx4 v[144:145], off
	s_add_u32 m0, s100, 0x9000
	s_nop 0
	global_load_lds_dwordx4 v[146:147], off
	s_add_u32 m0, s100, 0xa000
	s_nop 0
	global_load_lds_dwordx4 v[148:149], off
	s_add_u32 m0, s100, 0xb000
	s_nop 0
	global_load_lds_dwordx4 v[150:151], off
	s_add_u32 m0, s100, 0xc000
	s_nop 0
	global_load_lds_dwordx4 v[152:153], off
	s_add_u32 m0, s100, 0xd000
	s_nop 0
	global_load_lds_dwordx4 v[154:155], off
	s_add_u32 m0, s100, 0xe000
	s_nop 0
	global_load_lds_dwordx4 v[156:157], off
	s_add_u32 m0, s100, 0xf000
	s_nop 0
	global_load_lds_dwordx4 v[178:179], off
	ds_read_b128 a[0:3], v115
	ds_read_b128 v[80:83], v116
	ds_read_b128 a[4:7], v115 offset:2048
	ds_read_b128 a[8:11], v115 offset:4096
	ds_read_b128 a[12:15], v115 offset:6144
	ds_read_b128 v[92:95], v116 offset:2048
	ds_read_b128 v[88:91], v116 offset:4096
	ds_read_b128 v[84:87], v116 offset:6144
	ds_read_b128 a[16:19], v117
	ds_read_b128 a[20:23], v117 offset:2048
	ds_read_b128 a[24:27], v117 offset:4096
	ds_read_b128 a[28:31], v117 offset:6144
	s_setprio 1
	s_waitcnt lgkmcnt(10)
	v_mfma_f32_16x16x32_bf16 v[0:3], a[0:3], v[80:83], v[0:3]
	s_waitcnt lgkmcnt(9)
	v_mfma_f32_16x16x32_bf16 v[16:19], a[4:7], v[80:83], v[16:19]
	s_waitcnt lgkmcnt(8)
	v_mfma_f32_16x16x32_bf16 v[32:35], a[8:11], v[80:83], v[32:35]
	s_waitcnt lgkmcnt(7)
	v_mfma_f32_16x16x32_bf16 v[48:51], a[12:15], v[80:83], v[48:51]
	ds_read_b128 v[80:83], v118
	s_waitcnt lgkmcnt(7)
	v_mfma_f32_16x16x32_bf16 v[4:7], a[0:3], v[92:95], v[4:7]
	v_mfma_f32_16x16x32_bf16 v[20:23], a[4:7], v[92:95], v[20:23]
	v_mfma_f32_16x16x32_bf16 v[36:39], a[8:11], v[92:95], v[36:39]
	v_mfma_f32_16x16x32_bf16 v[52:55], a[12:15], v[92:95], v[52:55]
	ds_read_b128 v[92:95], v118 offset:2048
	s_waitcnt lgkmcnt(7)
	v_mfma_f32_16x16x32_bf16 v[8:11], a[0:3], v[88:91], v[8:11]
	v_mfma_f32_16x16x32_bf16 v[24:27], a[4:7], v[88:91], v[24:27]
	v_mfma_f32_16x16x32_bf16 v[40:43], a[8:11], v[88:91], v[40:43]
	v_mfma_f32_16x16x32_bf16 v[56:59], a[12:15], v[88:91], v[56:59]
	ds_read_b128 v[88:91], v118 offset:4096
	s_waitcnt lgkmcnt(7)
	v_mfma_f32_16x16x32_bf16 v[12:15], a[0:3], v[84:87], v[12:15]
	v_mfma_f32_16x16x32_bf16 v[28:31], a[4:7], v[84:87], v[28:31]
	v_mfma_f32_16x16x32_bf16 v[44:47], a[8:11], v[84:87], v[44:47]
	v_mfma_f32_16x16x32_bf16 v[60:63], a[12:15], v[84:87], v[60:63]
	ds_read_b128 v[84:87], v118 offset:6144
	s_waitcnt lgkmcnt(3)
	v_mfma_f32_16x16x32_bf16 v[0:3], a[16:19], v[80:83], v[0:3]
	v_mfma_f32_16x16x32_bf16 v[16:19], a[20:23], v[80:83], v[16:19]
	v_mfma_f32_16x16x32_bf16 v[32:35], a[24:27], v[80:83], v[32:35]
	v_mfma_f32_16x16x32_bf16 v[48:51], a[28:31], v[80:83], v[48:51]
	s_waitcnt lgkmcnt(2)
	v_mfma_f32_16x16x32_bf16 v[4:7], a[16:19], v[92:95], v[4:7]
	v_mfma_f32_16x16x32_bf16 v[20:23], a[20:23], v[92:95], v[20:23]
	v_mfma_f32_16x16x32_bf16 v[36:39], a[24:27], v[92:95], v[36:39]
	v_mfma_f32_16x16x32_bf16 v[52:55], a[28:31], v[92:95], v[52:55]
	s_waitcnt lgkmcnt(1)
	v_mfma_f32_16x16x32_bf16 v[8:11], a[16:19], v[88:91], v[8:11]
	v_mfma_f32_16x16x32_bf16 v[24:27], a[20:23], v[88:91], v[24:27]
	v_mfma_f32_16x16x32_bf16 v[40:43], a[24:27], v[88:91], v[40:43]
	v_mfma_f32_16x16x32_bf16 v[56:59], a[28:31], v[88:91], v[56:59]
	s_waitcnt lgkmcnt(0)
	v_mfma_f32_16x16x32_bf16 v[12:15], a[16:19], v[84:87], v[12:15]
	v_mfma_f32_16x16x32_bf16 v[28:31], a[20:23], v[84:87], v[28:31]
	v_mfma_f32_16x16x32_bf16 v[44:47], a[24:27], v[84:87], v[44:47]
	v_mfma_f32_16x16x32_bf16 v[60:63], a[28:31], v[84:87], v[60:63]
	s_setprio 0
	s_waitcnt vmcnt(0) lgkmcnt(0)
	s_barrier
	v_lshl_add_u64 v[64:65], 8, 4, v[144:145]
	v_lshl_add_u64 v[66:67], 8, 4, v[146:147]
	v_lshl_add_u64 v[68:69], 8, 4, v[148:149]
	v_lshl_add_u64 v[70:71], 8, 4, v[150:151]
	v_lshl_add_u64 v[76:77], 8, 4, v[152:153]
	v_lshl_add_u64 v[78:79], 8, 4, v[154:155]
	v_lshl_add_u64 v[72:73], 8, 4, v[156:157]
	v_lshl_add_u64 v[74:75], 8, 4, v[178:179]
	s_add_u32 m0, s100, 0x0
	s_nop 0
	global_load_lds_dwordx4 v[64:65], off
	s_add_u32 m0, s100, 0x1000
	s_nop 0
	global_load_lds_dwordx4 v[66:67], off
	s_add_u32 m0, s100, 0x2000
	s_nop 0
	global_load_lds_dwordx4 v[68:69], off
	s_add_u32 m0, s100, 0x3000
	s_nop 0
	global_load_lds_dwordx4 v[70:71], off
	s_add_u32 m0, s100, 0x4000
	s_nop 0
	global_load_lds_dwordx4 v[76:77], off
	s_add_u32 m0, s100, 0x5000
	s_nop 0
	global_load_lds_dwordx4 v[78:79], off
	s_add_u32 m0, s100, 0x6000
	s_nop 0
	global_load_lds_dwordx4 v[72:73], off
	s_add_u32 m0, s100, 0x7000
	s_nop 0
	global_load_lds_dwordx4 v[74:75], off
	ds_read_b128 a[0:3], v115 offset:32768
	ds_read_b128 v[80:83], v116 offset:32768
	ds_read_b128 a[4:7], v115 offset:34816
	ds_read_b128 a[8:11], v115 offset:36864
	ds_read_b128 a[12:15], v115 offset:38912
	ds_read_b128 v[92:95], v116 offset:34816
	ds_read_b128 v[88:91], v116 offset:36864
	ds_read_b128 v[84:87], v116 offset:38912
	ds_read_b128 a[16:19], v117 offset:32768
	ds_read_b128 a[20:23], v117 offset:34816
	ds_read_b128 a[24:27], v117 offset:36864
	ds_read_b128 a[28:31], v117 offset:38912
	s_setprio 1
	s_waitcnt lgkmcnt(10)
	v_mfma_f32_16x16x32_bf16 v[0:3], a[0:3], v[80:83], v[0:3]
	s_waitcnt lgkmcnt(9)
	v_mfma_f32_16x16x32_bf16 v[16:19], a[4:7], v[80:83], v[16:19]
	s_waitcnt lgkmcnt(8)
	v_mfma_f32_16x16x32_bf16 v[32:35], a[8:11], v[80:83], v[32:35]
	s_waitcnt lgkmcnt(7)
	v_mfma_f32_16x16x32_bf16 v[48:51], a[12:15], v[80:83], v[48:51]
	ds_read_b128 v[80:83], v118 offset:32768
	s_waitcnt lgkmcnt(7)
	v_mfma_f32_16x16x32_bf16 v[4:7], a[0:3], v[92:95], v[4:7]
	v_mfma_f32_16x16x32_bf16 v[20:23], a[4:7], v[92:95], v[20:23]
	v_mfma_f32_16x16x32_bf16 v[36:39], a[8:11], v[92:95], v[36:39]
	v_mfma_f32_16x16x32_bf16 v[52:55], a[12:15], v[92:95], v[52:55]
	ds_read_b128 v[92:95], v118 offset:34816
	s_waitcnt lgkmcnt(7)
	v_mfma_f32_16x16x32_bf16 v[8:11], a[0:3], v[88:91], v[8:11]
	v_mfma_f32_16x16x32_bf16 v[24:27], a[4:7], v[88:91], v[24:27]
	v_mfma_f32_16x16x32_bf16 v[40:43], a[8:11], v[88:91], v[40:43]
	v_mfma_f32_16x16x32_bf16 v[56:59], a[12:15], v[88:91], v[56:59]
	ds_read_b128 v[88:91], v118 offset:36864
	s_waitcnt lgkmcnt(7)
	v_mfma_f32_16x16x32_bf16 v[12:15], a[0:3], v[84:87], v[12:15]
	v_mfma_f32_16x16x32_bf16 v[28:31], a[4:7], v[84:87], v[28:31]
	v_mfma_f32_16x16x32_bf16 v[44:47], a[8:11], v[84:87], v[44:47]
	v_mfma_f32_16x16x32_bf16 v[60:63], a[12:15], v[84:87], v[60:63]
	ds_read_b128 v[84:87], v118 offset:38912
	s_waitcnt lgkmcnt(3)
	v_mfma_f32_16x16x32_bf16 v[0:3], a[16:19], v[80:83], v[0:3]
	v_mfma_f32_16x16x32_bf16 v[16:19], a[20:23], v[80:83], v[16:19]
	v_mfma_f32_16x16x32_bf16 v[32:35], a[24:27], v[80:83], v[32:35]
	v_mfma_f32_16x16x32_bf16 v[48:51], a[28:31], v[80:83], v[48:51]
	s_waitcnt lgkmcnt(2)
	v_mfma_f32_16x16x32_bf16 v[4:7], a[16:19], v[92:95], v[4:7]
	v_mfma_f32_16x16x32_bf16 v[20:23], a[20:23], v[92:95], v[20:23]
	v_mfma_f32_16x16x32_bf16 v[36:39], a[24:27], v[92:95], v[36:39]
	v_mfma_f32_16x16x32_bf16 v[52:55], a[28:31], v[92:95], v[52:55]
	s_waitcnt lgkmcnt(1)
	v_mfma_f32_16x16x32_bf16 v[8:11], a[16:19], v[88:91], v[8:11]
	v_mfma_f32_16x16x32_bf16 v[24:27], a[20:23], v[88:91], v[24:27]
	v_mfma_f32_16x16x32_bf16 v[40:43], a[24:27], v[88:91], v[40:43]
	v_mfma_f32_16x16x32_bf16 v[56:59], a[28:31], v[88:91], v[56:59]
	s_waitcnt lgkmcnt(0)
	v_mfma_f32_16x16x32_bf16 v[12:15], a[16:19], v[84:87], v[12:15]
	v_mfma_f32_16x16x32_bf16 v[28:31], a[20:23], v[84:87], v[28:31]
	v_mfma_f32_16x16x32_bf16 v[44:47], a[24:27], v[84:87], v[44:47]
	v_mfma_f32_16x16x32_bf16 v[60:63], a[28:31], v[84:87], v[60:63]
	s_setprio 0
	s_waitcnt vmcnt(0) lgkmcnt(0)
	s_barrier
	s_add_u32 s28, s28, 0x100
	s_addc_u32 s29, s29, 0
	s_cmpk_eq_i32 s28, 0xf00
	s_cbranch_scc0 .LBB0_583
	v_lshl_add_u64 v[64:65], 8, 4, v[64:65]
	v_lshl_add_u64 v[66:67], 8, 4, v[66:67]
	v_lshl_add_u64 v[68:69], 8, 4, v[68:69]
	v_lshl_add_u64 v[70:71], 8, 4, v[70:71]
	v_lshl_add_u64 v[76:77], 8, 4, v[76:77]
	v_lshl_add_u64 v[78:79], 8, 4, v[78:79]
	v_lshl_add_u64 v[72:73], 8, 4, v[72:73]
	v_lshl_add_u64 v[74:75], 8, 4, v[74:75]
	s_add_u32 m0, s100, 0x8000
	s_nop 0
	global_load_lds_dwordx4 v[64:65], off
	s_add_u32 m0, s100, 0x9000
	s_nop 0
	global_load_lds_dwordx4 v[66:67], off
	s_add_u32 m0, s100, 0xa000
	s_nop 0
	global_load_lds_dwordx4 v[68:69], off
	s_add_u32 m0, s100, 0xb000
	s_nop 0
	global_load_lds_dwordx4 v[70:71], off
	s_add_u32 m0, s100, 0xc000
	s_nop 0
	global_load_lds_dwordx4 v[76:77], off
	s_add_u32 m0, s100, 0xd000
	s_nop 0
	global_load_lds_dwordx4 v[78:79], off
	s_add_u32 m0, s100, 0xe000
	s_nop 0
	global_load_lds_dwordx4 v[72:73], off
	s_add_u32 m0, s100, 0xf000
	s_nop 0
	global_load_lds_dwordx4 v[74:75], off
	ds_read_b128 a[0:3], v115
	ds_read_b128 v[80:83], v116
	ds_read_b128 a[4:7], v115 offset:2048
	ds_read_b128 a[8:11], v115 offset:4096
	ds_read_b128 a[12:15], v115 offset:6144
	ds_read_b128 v[92:95], v116 offset:2048
	ds_read_b128 v[88:91], v116 offset:4096
	ds_read_b128 v[84:87], v116 offset:6144
	ds_read_b128 a[16:19], v117
	ds_read_b128 a[20:23], v117 offset:2048
	ds_read_b128 a[24:27], v117 offset:4096
	ds_read_b128 a[28:31], v117 offset:6144
	s_setprio 1
	s_waitcnt lgkmcnt(10)
	v_mfma_f32_16x16x32_bf16 v[0:3], a[0:3], v[80:83], v[0:3]
	s_waitcnt lgkmcnt(9)
	v_mfma_f32_16x16x32_bf16 v[16:19], a[4:7], v[80:83], v[16:19]
	s_waitcnt lgkmcnt(8)
	v_mfma_f32_16x16x32_bf16 v[32:35], a[8:11], v[80:83], v[32:35]
	s_waitcnt lgkmcnt(7)
	v_mfma_f32_16x16x32_bf16 v[48:51], a[12:15], v[80:83], v[48:51]
	ds_read_b128 v[80:83], v118
	s_waitcnt lgkmcnt(7)
	v_mfma_f32_16x16x32_bf16 v[4:7], a[0:3], v[92:95], v[4:7]
	v_mfma_f32_16x16x32_bf16 v[20:23], a[4:7], v[92:95], v[20:23]
	v_mfma_f32_16x16x32_bf16 v[36:39], a[8:11], v[92:95], v[36:39]
	v_mfma_f32_16x16x32_bf16 v[52:55], a[12:15], v[92:95], v[52:55]
	ds_read_b128 v[92:95], v118 offset:2048
	s_waitcnt lgkmcnt(7)
	v_mfma_f32_16x16x32_bf16 v[8:11], a[0:3], v[88:91], v[8:11]
	v_mfma_f32_16x16x32_bf16 v[24:27], a[4:7], v[88:91], v[24:27]
	v_mfma_f32_16x16x32_bf16 v[40:43], a[8:11], v[88:91], v[40:43]
	v_mfma_f32_16x16x32_bf16 v[56:59], a[12:15], v[88:91], v[56:59]
	ds_read_b128 v[88:91], v118 offset:4096
	s_waitcnt lgkmcnt(7)
	v_mfma_f32_16x16x32_bf16 v[12:15], a[0:3], v[84:87], v[12:15]
	v_mfma_f32_16x16x32_bf16 v[28:31], a[4:7], v[84:87], v[28:31]
	v_mfma_f32_16x16x32_bf16 v[44:47], a[8:11], v[84:87], v[44:47]
	v_mfma_f32_16x16x32_bf16 v[60:63], a[12:15], v[84:87], v[60:63]
	ds_read_b128 v[84:87], v118 offset:6144
	s_waitcnt lgkmcnt(3)
	v_mfma_f32_16x16x32_bf16 v[0:3], a[16:19], v[80:83], v[0:3]
	v_mfma_f32_16x16x32_bf16 v[16:19], a[20:23], v[80:83], v[16:19]
	v_mfma_f32_16x16x32_bf16 v[32:35], a[24:27], v[80:83], v[32:35]
	v_mfma_f32_16x16x32_bf16 v[48:51], a[28:31], v[80:83], v[48:51]
	s_waitcnt lgkmcnt(2)
	v_mfma_f32_16x16x32_bf16 v[4:7], a[16:19], v[92:95], v[4:7]
	v_mfma_f32_16x16x32_bf16 v[20:23], a[20:23], v[92:95], v[20:23]
	v_mfma_f32_16x16x32_bf16 v[36:39], a[24:27], v[92:95], v[36:39]
	v_mfma_f32_16x16x32_bf16 v[52:55], a[28:31], v[92:95], v[52:55]
	s_waitcnt lgkmcnt(1)
	v_mfma_f32_16x16x32_bf16 v[8:11], a[16:19], v[88:91], v[8:11]
	v_mfma_f32_16x16x32_bf16 v[24:27], a[20:23], v[88:91], v[24:27]
	v_mfma_f32_16x16x32_bf16 v[40:43], a[24:27], v[88:91], v[40:43]
	v_mfma_f32_16x16x32_bf16 v[56:59], a[28:31], v[88:91], v[56:59]
	s_waitcnt lgkmcnt(0)
	v_mfma_f32_16x16x32_bf16 v[12:15], a[16:19], v[84:87], v[12:15]
	v_mfma_f32_16x16x32_bf16 v[28:31], a[20:23], v[84:87], v[28:31]
	v_mfma_f32_16x16x32_bf16 v[44:47], a[24:27], v[84:87], v[44:47]
	v_mfma_f32_16x16x32_bf16 v[60:63], a[28:31], v[84:87], v[60:63]
	s_setprio 0
	s_waitcnt vmcnt(0) lgkmcnt(0)
	s_barrier
	ds_read_b128 a[0:3], v115 offset:32768
	ds_read_b128 v[80:83], v116 offset:32768
	ds_read_b128 a[4:7], v115 offset:34816
	ds_read_b128 a[8:11], v115 offset:36864
	ds_read_b128 a[12:15], v115 offset:38912
	ds_read_b128 v[92:95], v116 offset:34816
	ds_read_b128 v[88:91], v116 offset:36864
	ds_read_b128 v[84:87], v116 offset:38912
	ds_read_b128 a[16:19], v117 offset:32768
	ds_read_b128 a[20:23], v117 offset:34816
	ds_read_b128 a[24:27], v117 offset:36864
	ds_read_b128 a[28:31], v117 offset:38912
	s_setprio 1
	s_waitcnt lgkmcnt(10)
	v_mfma_f32_16x16x32_bf16 v[0:3], a[0:3], v[80:83], v[0:3]
	s_waitcnt lgkmcnt(9)
	v_mfma_f32_16x16x32_bf16 v[16:19], a[4:7], v[80:83], v[16:19]
	s_waitcnt lgkmcnt(8)
	v_mfma_f32_16x16x32_bf16 v[32:35], a[8:11], v[80:83], v[32:35]
	s_waitcnt lgkmcnt(7)
	v_mfma_f32_16x16x32_bf16 v[48:51], a[12:15], v[80:83], v[48:51]
	ds_read_b128 v[80:83], v118 offset:32768
	s_waitcnt lgkmcnt(7)
	v_mfma_f32_16x16x32_bf16 v[4:7], a[0:3], v[92:95], v[4:7]
	v_mfma_f32_16x16x32_bf16 v[20:23], a[4:7], v[92:95], v[20:23]
	v_mfma_f32_16x16x32_bf16 v[36:39], a[8:11], v[92:95], v[36:39]
	v_mfma_f32_16x16x32_bf16 v[52:55], a[12:15], v[92:95], v[52:55]
	ds_read_b128 v[92:95], v118 offset:34816
	s_waitcnt lgkmcnt(7)
	v_mfma_f32_16x16x32_bf16 v[8:11], a[0:3], v[88:91], v[8:11]
	v_mfma_f32_16x16x32_bf16 v[24:27], a[4:7], v[88:91], v[24:27]
	v_mfma_f32_16x16x32_bf16 v[40:43], a[8:11], v[88:91], v[40:43]
	v_mfma_f32_16x16x32_bf16 v[56:59], a[12:15], v[88:91], v[56:59]
	ds_read_b128 v[88:91], v118 offset:36864
	s_waitcnt lgkmcnt(7)
	v_mfma_f32_16x16x32_bf16 v[12:15], a[0:3], v[84:87], v[12:15]
	v_mfma_f32_16x16x32_bf16 v[28:31], a[4:7], v[84:87], v[28:31]
	v_mfma_f32_16x16x32_bf16 v[44:47], a[8:11], v[84:87], v[44:47]
	v_mfma_f32_16x16x32_bf16 v[60:63], a[12:15], v[84:87], v[60:63]
	ds_read_b128 v[84:87], v118 offset:38912
	s_waitcnt lgkmcnt(3)
	v_mfma_f32_16x16x32_bf16 v[0:3], a[16:19], v[80:83], v[0:3]
	v_mfma_f32_16x16x32_bf16 v[16:19], a[20:23], v[80:83], v[16:19]
	v_mfma_f32_16x16x32_bf16 v[32:35], a[24:27], v[80:83], v[32:35]
	v_mfma_f32_16x16x32_bf16 v[48:51], a[28:31], v[80:83], v[48:51]
	s_waitcnt lgkmcnt(2)
	v_mfma_f32_16x16x32_bf16 v[4:7], a[16:19], v[92:95], v[4:7]
	v_mfma_f32_16x16x32_bf16 v[20:23], a[20:23], v[92:95], v[20:23]
	v_mfma_f32_16x16x32_bf16 v[36:39], a[24:27], v[92:95], v[36:39]
	v_mfma_f32_16x16x32_bf16 v[52:55], a[28:31], v[92:95], v[52:55]
	s_waitcnt lgkmcnt(1)
	v_mfma_f32_16x16x32_bf16 v[8:11], a[16:19], v[88:91], v[8:11]
	v_mfma_f32_16x16x32_bf16 v[24:27], a[20:23], v[88:91], v[24:27]
	v_mfma_f32_16x16x32_bf16 v[40:43], a[24:27], v[88:91], v[40:43]
	v_mfma_f32_16x16x32_bf16 v[56:59], a[28:31], v[88:91], v[56:59]
	s_waitcnt lgkmcnt(0)
	v_mfma_f32_16x16x32_bf16 v[12:15], a[16:19], v[84:87], v[12:15]
	v_mfma_f32_16x16x32_bf16 v[28:31], a[20:23], v[84:87], v[28:31]
	v_mfma_f32_16x16x32_bf16 v[44:47], a[24:27], v[84:87], v[44:47]
	v_mfma_f32_16x16x32_bf16 v[60:63], a[28:31], v[84:87], v[60:63]
	s_setprio 0
	v_readfirstlane_b32 s15, v107
	v_readfirstlane_b32 s4, v106
	s_lshl_b32 s15, s15, 6
	s_waitcnt lgkmcnt(0)
	s_barrier
	s_add_i32 s9, s15, s9
	s_lshl_b32 s15, s4, 17
	s_lshl_b32 s4, s8, 18
	s_add_i32 s15, s15, s4
	v_or_b32_e32 v64, s9, v108
	s_movk_i32 s4, 0x800
	v_cmp_gt_i32_e32 vcc, s4, v64
	s_barrier
	v_and_b32_e32 v124, 15, v143
	v_bfe_u32 v125, v143, 4, 2
	v_xor_b32_e32 v125, v125, v124
	v_lshlrev_b32_e32 v125, 4, v125
	v_lshl_add_u32 v125, v124, 8, v125
	v_lshrrev_b32_e32 v124, 6, v143
	v_lshl_add_u32 v125, v124, 14, v125
	ds_write_b128 v125, v[0:3]
	ds_write_b128 v125, v[4:7] offset:4096
	ds_write_b128 v125, v[8:11] offset:8192
	ds_write_b128 v125, v[12:15] offset:12288
	v_xor_b32_e32 v118, 64, v125
	ds_write_b128 v118, v[16:19]
	ds_write_b128 v118, v[20:23] offset:4096
	ds_write_b128 v118, v[24:27] offset:8192
	ds_write_b128 v118, v[28:31] offset:12288
	v_xor_b32_e32 v118, 128, v125
	ds_write_b128 v118, v[32:35]
	ds_write_b128 v118, v[36:39] offset:4096
	ds_write_b128 v118, v[40:43] offset:8192
	ds_write_b128 v118, v[44:47] offset:12288
	v_xor_b32_e32 v118, 192, v125
	ds_write_b128 v118, v[48:51]
	ds_write_b128 v118, v[52:55] offset:4096
	ds_write_b128 v118, v[56:59] offset:8192
	ds_write_b128 v118, v[60:63] offset:12288
	v_and_b32_e32 v115, 31, v143
	v_bfe_u32 v117, v143, 5, 1
	v_and_b32_e32 v125, 15, v115
	v_xor_b32_e32 v117, v117, v125
	v_lshlrev_b32_e32 v117, 4, v117
	v_lshl_add_u32 v117, v115, 8, v117
	v_lshl_add_u32 v117, v124, 14, v117
	ds_read_b128 v[48:51], v117
	ds_read_b128 v[32:35], v117 offset:8192
	v_xor_b32_e32 v116, 32, v117
	ds_read_b128 v[52:55], v116
	ds_read_b128 v[36:39], v116 offset:8192
	v_xor_b32_e32 v116, 64, v117
	ds_read_b128 v[56:59], v116
	ds_read_b128 v[40:43], v116 offset:8192
	v_xor_b32_e32 v116, 96, v117
	ds_read_b128 v[60:63], v116
	ds_read_b128 v[44:47], v116 offset:8192
	v_xor_b32_e32 v116, 128, v117
	ds_read_b128 v[16:19], v116
	ds_read_b128 v[0:3], v116 offset:8192
	v_xor_b32_e32 v116, 160, v117
	ds_read_b128 v[20:23], v116
	ds_read_b128 v[4:7], v116 offset:8192
	v_xor_b32_e32 v116, 192, v117
	ds_read_b128 v[24:27], v116
	ds_read_b128 v[8:11], v116 offset:8192
	v_xor_b32_e32 v116, 224, v117
	ds_read_b128 v[28:31], v116
	ds_read_b128 v[12:15], v116 offset:8192
	s_waitcnt lgkmcnt(0)
	s_barrier
	s_and_saveexec_b64 s[8:9], vcc
	s_cbranch_execz .LBB0_586
	v_add_u32_e32 v65, s15, v64
	v_add_u32_e32 v66, v65, v111
	v_mov_b32_e32 v67, v140
	v_lshl_add_u64 v[68:69], v[66:67], 2, s[26:27]
	global_store_dword v[68:69], v48, off
	v_add_u32_e32 v68, 0x800, v66
	v_mov_b32_e32 v69, v140
	v_lshl_add_u64 v[68:69], v[68:69], 2, s[26:27]
	global_store_dword v[68:69], v49, off
	v_add_u32_e32 v48, 0x1000, v66
	v_mov_b32_e32 v49, v140
	v_lshl_add_u64 v[48:49], v[48:49], 2, s[26:27]
	global_store_dword v[48:49], v50, off
	v_add_u32_e32 v48, 0x1800, v66
	v_mov_b32_e32 v49, v140
	v_lshl_add_u64 v[48:49], v[48:49], 2, s[26:27]
	global_store_dword v[48:49], v51, off
	v_add_u32_e32 v48, v65, v112
	v_mov_b32_e32 v49, v140
	v_lshl_add_u64 v[50:51], v[48:49], 2, s[26:27]
	global_store_dword v[50:51], v52, off
	v_add_u32_e32 v50, 0x800, v48
	v_mov_b32_e32 v51, v140
	v_lshl_add_u64 v[50:51], v[50:51], 2, s[26:27]
	global_store_dword v[50:51], v53, off
	v_add_u32_e32 v50, 0x1000, v48
	v_mov_b32_e32 v51, v140
	v_add_u32_e32 v48, 0x1800, v48
	v_lshl_add_u64 v[50:51], v[50:51], 2, s[26:27]
	v_lshl_add_u64 v[48:49], v[48:49], 2, s[26:27]
	global_store_dword v[50:51], v54, off
	global_store_dword v[48:49], v55, off
	v_add_u32_e32 v48, v65, v113
	v_mov_b32_e32 v49, v140
	v_lshl_add_u64 v[50:51], v[48:49], 2, s[26:27]
	global_store_dword v[50:51], v56, off
	v_add_u32_e32 v50, 0x800, v48
	v_mov_b32_e32 v51, v140
	v_lshl_add_u64 v[50:51], v[50:51], 2, s[26:27]
	global_store_dword v[50:51], v57, off
	v_add_u32_e32 v50, 0x1000, v48
	v_mov_b32_e32 v51, v140
	v_add_u32_e32 v48, 0x1800, v48
	v_lshl_add_u64 v[50:51], v[50:51], 2, s[26:27]
	v_lshl_add_u64 v[48:49], v[48:49], 2, s[26:27]
	global_store_dword v[50:51], v58, off
	global_store_dword v[48:49], v59, off
	v_add_u32_e32 v48, v65, v114
	v_mov_b32_e32 v49, v140
	v_lshl_add_u64 v[50:51], v[48:49], 2, s[26:27]
	global_store_dword v[50:51], v60, off
	v_add_u32_e32 v50, 0x800, v48
	v_mov_b32_e32 v51, v140
	v_lshl_add_u64 v[50:51], v[50:51], 2, s[26:27]
	global_store_dword v[50:51], v61, off
	v_add_u32_e32 v50, 0x1000, v48
	v_mov_b32_e32 v51, v140
	v_add_u32_e32 v48, 0x1800, v48
	v_lshl_add_u64 v[50:51], v[50:51], 2, s[26:27]
	v_lshl_add_u64 v[48:49], v[48:49], 2, s[26:27]
	global_store_dword v[50:51], v62, off
	global_store_dword v[48:49], v63, off

.LBB0_596:
	v_lshl_add_u64 v[72:73], v[104:105], 0, s[28:29]
	s_mov_b32 s4, 0x1a2b8000
	v_add_co_u32_e32 v144, vcc, s4, v72
	s_mov_b32 s4, 0x1a2d8000
	s_nop 0
	v_addc_co_u32_e32 v145, vcc, 0, v73, vcc
	v_add_co_u32_e32 v146, vcc, s4, v72
	s_mov_b32 s4, 0x1a2f8000
	s_nop 0
	v_addc_co_u32_e32 v147, vcc, 0, v73, vcc
	v_add_co_u32_e32 v148, vcc, s4, v72
	s_mov_b32 s4, 0x1a318000
	s_nop 0
	v_addc_co_u32_e32 v149, vcc, 0, v73, vcc
	v_add_co_u32_e32 v150, vcc, s4, v72
	v_lshl_add_u64 v[88:89], v[102:103], 0, s[28:29]
	s_nop 0
	v_addc_co_u32_e32 v151, vcc, 0, v73, vcc
	s_mov_b32 s4, 0x37380000
	v_add_co_u32_e32 v152, vcc, s4, v88
	s_mov_b32 s4, 0x373a0000
	s_nop 0
	v_addc_co_u32_e32 v153, vcc, 0, v89, vcc
	v_add_co_u32_e32 v154, vcc, s4, v88
	s_mov_b32 s4, 0x373c0000
	s_nop 0
	v_addc_co_u32_e32 v155, vcc, 0, v89, vcc
	v_add_co_u32_e32 v156, vcc, s4, v88
	s_mov_b32 s4, 0x373e0000
	s_nop 0
	v_addc_co_u32_e32 v157, vcc, 0, v89, vcc
	v_add_co_u32_e32 v178, vcc, s4, v88
	v_addc_co_u32_e32 v179, vcc, 0, v89, vcc
	v_lshl_add_u64 v[144:145], 8, 4, v[144:145]
	v_lshl_add_u64 v[146:147], 8, 4, v[146:147]
	v_lshl_add_u64 v[148:149], 8, 4, v[148:149]
	v_lshl_add_u64 v[150:151], 8, 4, v[150:151]
	v_lshl_add_u64 v[152:153], 8, 4, v[152:153]
	v_lshl_add_u64 v[154:155], 8, 4, v[154:155]
	v_lshl_add_u64 v[156:157], 8, 4, v[156:157]
	v_lshl_add_u64 v[178:179], 8, 4, v[178:179]
	s_add_u32 m0, s100, 0x8000
	s_nop 0
	global_load_lds_dwordx4 v[144:145], off
	s_add_u32 m0, s100, 0x9000
	s_nop 0
	global_load_lds_dwordx4 v[146:147], off
	s_add_u32 m0, s100, 0xa000
	s_nop 0
	global_load_lds_dwordx4 v[148:149], off
	s_add_u32 m0, s100, 0xb000
	s_nop 0
	global_load_lds_dwordx4 v[150:151], off
	s_add_u32 m0, s100, 0xc000
	s_nop 0
	global_load_lds_dwordx4 v[152:153], off
	s_add_u32 m0, s100, 0xd000
	s_nop 0
	global_load_lds_dwordx4 v[154:155], off
	s_add_u32 m0, s100, 0xe000
	s_nop 0
	global_load_lds_dwordx4 v[156:157], off
	s_add_u32 m0, s100, 0xf000
	s_nop 0
	global_load_lds_dwordx4 v[178:179], off
	ds_read_b128 a[0:3], v115
	ds_read_b128 v[80:83], v116
	ds_read_b128 a[4:7], v115 offset:2048
	ds_read_b128 a[8:11], v115 offset:4096
	ds_read_b128 a[12:15], v115 offset:6144
	ds_read_b128 v[92:95], v116 offset:2048
	ds_read_b128 v[88:91], v116 offset:4096
	ds_read_b128 v[84:87], v116 offset:6144
	ds_read_b128 a[16:19], v117
	ds_read_b128 a[20:23], v117 offset:2048
	ds_read_b128 a[24:27], v117 offset:4096
	ds_read_b128 a[28:31], v117 offset:6144
	s_setprio 1
	s_waitcnt lgkmcnt(10)
	v_mfma_f32_16x16x32_bf16 v[0:3], a[0:3], v[80:83], v[0:3]
	s_waitcnt lgkmcnt(9)
	v_mfma_f32_16x16x32_bf16 v[16:19], a[4:7], v[80:83], v[16:19]
	s_waitcnt lgkmcnt(8)
	v_mfma_f32_16x16x32_bf16 v[32:35], a[8:11], v[80:83], v[32:35]
	s_waitcnt lgkmcnt(7)
	v_mfma_f32_16x16x32_bf16 v[48:51], a[12:15], v[80:83], v[48:51]
	ds_read_b128 v[80:83], v118
	s_waitcnt lgkmcnt(7)
	v_mfma_f32_16x16x32_bf16 v[4:7], a[0:3], v[92:95], v[4:7]
	v_mfma_f32_16x16x32_bf16 v[20:23], a[4:7], v[92:95], v[20:23]
	v_mfma_f32_16x16x32_bf16 v[36:39], a[8:11], v[92:95], v[36:39]
	v_mfma_f32_16x16x32_bf16 v[52:55], a[12:15], v[92:95], v[52:55]
	ds_read_b128 v[92:95], v118 offset:2048
	s_waitcnt lgkmcnt(7)
	v_mfma_f32_16x16x32_bf16 v[8:11], a[0:3], v[88:91], v[8:11]
	v_mfma_f32_16x16x32_bf16 v[24:27], a[4:7], v[88:91], v[24:27]
	v_mfma_f32_16x16x32_bf16 v[40:43], a[8:11], v[88:91], v[40:43]
	v_mfma_f32_16x16x32_bf16 v[56:59], a[12:15], v[88:91], v[56:59]
	ds_read_b128 v[88:91], v118 offset:4096
	s_waitcnt lgkmcnt(7)
	v_mfma_f32_16x16x32_bf16 v[12:15], a[0:3], v[84:87], v[12:15]
	v_mfma_f32_16x16x32_bf16 v[28:31], a[4:7], v[84:87], v[28:31]
	v_mfma_f32_16x16x32_bf16 v[44:47], a[8:11], v[84:87], v[44:47]
	v_mfma_f32_16x16x32_bf16 v[60:63], a[12:15], v[84:87], v[60:63]
	ds_read_b128 v[84:87], v118 offset:6144
	s_waitcnt lgkmcnt(3)
	v_mfma_f32_16x16x32_bf16 v[0:3], a[16:19], v[80:83], v[0:3]
	v_mfma_f32_16x16x32_bf16 v[16:19], a[20:23], v[80:83], v[16:19]
	v_mfma_f32_16x16x32_bf16 v[32:35], a[24:27], v[80:83], v[32:35]
	v_mfma_f32_16x16x32_bf16 v[48:51], a[28:31], v[80:83], v[48:51]
	s_waitcnt lgkmcnt(2)
	v_mfma_f32_16x16x32_bf16 v[4:7], a[16:19], v[92:95], v[4:7]
	v_mfma_f32_16x16x32_bf16 v[20:23], a[20:23], v[92:95], v[20:23]
	v_mfma_f32_16x16x32_bf16 v[36:39], a[24:27], v[92:95], v[36:39]
	v_mfma_f32_16x16x32_bf16 v[52:55], a[28:31], v[92:95], v[52:55]
	s_waitcnt lgkmcnt(1)
	v_mfma_f32_16x16x32_bf16 v[8:11], a[16:19], v[88:91], v[8:11]
	v_mfma_f32_16x16x32_bf16 v[24:27], a[20:23], v[88:91], v[24:27]
	v_mfma_f32_16x16x32_bf16 v[40:43], a[24:27], v[88:91], v[40:43]
	v_mfma_f32_16x16x32_bf16 v[56:59], a[28:31], v[88:91], v[56:59]
	s_waitcnt lgkmcnt(0)
	v_mfma_f32_16x16x32_bf16 v[12:15], a[16:19], v[84:87], v[12:15]
	v_mfma_f32_16x16x32_bf16 v[28:31], a[20:23], v[84:87], v[28:31]
	v_mfma_f32_16x16x32_bf16 v[44:47], a[24:27], v[84:87], v[44:47]
	v_mfma_f32_16x16x32_bf16 v[60:63], a[28:31], v[84:87], v[60:63]
	s_setprio 0
	s_waitcnt vmcnt(0) lgkmcnt(0)
	s_barrier
	v_lshl_add_u64 v[64:65], 8, 4, v[144:145]
	v_lshl_add_u64 v[66:67], 8, 4, v[146:147]
	v_lshl_add_u64 v[68:69], 8, 4, v[148:149]
	v_lshl_add_u64 v[70:71], 8, 4, v[150:151]
	v_lshl_add_u64 v[76:77], 8, 4, v[152:153]
	v_lshl_add_u64 v[78:79], 8, 4, v[154:155]
	v_lshl_add_u64 v[72:73], 8, 4, v[156:157]
	v_lshl_add_u64 v[74:75], 8, 4, v[178:179]
	s_add_u32 m0, s100, 0x0
	s_nop 0
	global_load_lds_dwordx4 v[64:65], off
	s_add_u32 m0, s100, 0x1000
	s_nop 0
	global_load_lds_dwordx4 v[66:67], off
	s_add_u32 m0, s100, 0x2000
	s_nop 0
	global_load_lds_dwordx4 v[68:69], off
	s_add_u32 m0, s100, 0x3000
	s_nop 0
	global_load_lds_dwordx4 v[70:71], off
	s_add_u32 m0, s100, 0x4000
	s_nop 0
	global_load_lds_dwordx4 v[76:77], off
	s_add_u32 m0, s100, 0x5000
	s_nop 0
	global_load_lds_dwordx4 v[78:79], off
	s_add_u32 m0, s100, 0x6000
	s_nop 0
	global_load_lds_dwordx4 v[72:73], off
	s_add_u32 m0, s100, 0x7000
	s_nop 0
	global_load_lds_dwordx4 v[74:75], off
	ds_read_b128 a[0:3], v115 offset:32768
	ds_read_b128 v[80:83], v116 offset:32768
	ds_read_b128 a[4:7], v115 offset:34816
	ds_read_b128 a[8:11], v115 offset:36864
	ds_read_b128 a[12:15], v115 offset:38912
	ds_read_b128 v[92:95], v116 offset:34816
	ds_read_b128 v[88:91], v116 offset:36864
	ds_read_b128 v[84:87], v116 offset:38912
	ds_read_b128 a[16:19], v117 offset:32768
	ds_read_b128 a[20:23], v117 offset:34816
	ds_read_b128 a[24:27], v117 offset:36864
	ds_read_b128 a[28:31], v117 offset:38912
	s_setprio 1
	s_waitcnt lgkmcnt(10)
	v_mfma_f32_16x16x32_bf16 v[0:3], a[0:3], v[80:83], v[0:3]
	s_waitcnt lgkmcnt(9)
	v_mfma_f32_16x16x32_bf16 v[16:19], a[4:7], v[80:83], v[16:19]
	s_waitcnt lgkmcnt(8)
	v_mfma_f32_16x16x32_bf16 v[32:35], a[8:11], v[80:83], v[32:35]
	s_waitcnt lgkmcnt(7)
	v_mfma_f32_16x16x32_bf16 v[48:51], a[12:15], v[80:83], v[48:51]
	ds_read_b128 v[80:83], v118 offset:32768
	s_waitcnt lgkmcnt(7)
	v_mfma_f32_16x16x32_bf16 v[4:7], a[0:3], v[92:95], v[4:7]
	v_mfma_f32_16x16x32_bf16 v[20:23], a[4:7], v[92:95], v[20:23]
	v_mfma_f32_16x16x32_bf16 v[36:39], a[8:11], v[92:95], v[36:39]
	v_mfma_f32_16x16x32_bf16 v[52:55], a[12:15], v[92:95], v[52:55]
	ds_read_b128 v[92:95], v118 offset:34816
	s_waitcnt lgkmcnt(7)
	v_mfma_f32_16x16x32_bf16 v[8:11], a[0:3], v[88:91], v[8:11]
	v_mfma_f32_16x16x32_bf16 v[24:27], a[4:7], v[88:91], v[24:27]
	v_mfma_f32_16x16x32_bf16 v[40:43], a[8:11], v[88:91], v[40:43]
	v_mfma_f32_16x16x32_bf16 v[56:59], a[12:15], v[88:91], v[56:59]
	ds_read_b128 v[88:91], v118 offset:36864
	s_waitcnt lgkmcnt(7)
	v_mfma_f32_16x16x32_bf16 v[12:15], a[0:3], v[84:87], v[12:15]
	v_mfma_f32_16x16x32_bf16 v[28:31], a[4:7], v[84:87], v[28:31]
	v_mfma_f32_16x16x32_bf16 v[44:47], a[8:11], v[84:87], v[44:47]
	v_mfma_f32_16x16x32_bf16 v[60:63], a[12:15], v[84:87], v[60:63]
	ds_read_b128 v[84:87], v118 offset:38912
	s_waitcnt lgkmcnt(3)
	v_mfma_f32_16x16x32_bf16 v[0:3], a[16:19], v[80:83], v[0:3]
	v_mfma_f32_16x16x32_bf16 v[16:19], a[20:23], v[80:83], v[16:19]
	v_mfma_f32_16x16x32_bf16 v[32:35], a[24:27], v[80:83], v[32:35]
	v_mfma_f32_16x16x32_bf16 v[48:51], a[28:31], v[80:83], v[48:51]
	s_waitcnt lgkmcnt(2)
	v_mfma_f32_16x16x32_bf16 v[4:7], a[16:19], v[92:95], v[4:7]
	v_mfma_f32_16x16x32_bf16 v[20:23], a[20:23], v[92:95], v[20:23]
	v_mfma_f32_16x16x32_bf16 v[36:39], a[24:27], v[92:95], v[36:39]
	v_mfma_f32_16x16x32_bf16 v[52:55], a[28:31], v[92:95], v[52:55]
	s_waitcnt lgkmcnt(1)
	v_mfma_f32_16x16x32_bf16 v[8:11], a[16:19], v[88:91], v[8:11]
	v_mfma_f32_16x16x32_bf16 v[24:27], a[20:23], v[88:91], v[24:27]
	v_mfma_f32_16x16x32_bf16 v[40:43], a[24:27], v[88:91], v[40:43]
	v_mfma_f32_16x16x32_bf16 v[56:59], a[28:31], v[88:91], v[56:59]
	s_waitcnt lgkmcnt(0)
	v_mfma_f32_16x16x32_bf16 v[12:15], a[16:19], v[84:87], v[12:15]
	v_mfma_f32_16x16x32_bf16 v[28:31], a[20:23], v[84:87], v[28:31]
	v_mfma_f32_16x16x32_bf16 v[44:47], a[24:27], v[84:87], v[44:47]
	v_mfma_f32_16x16x32_bf16 v[60:63], a[28:31], v[84:87], v[60:63]
	s_setprio 0
	s_waitcnt vmcnt(0) lgkmcnt(0)
	s_barrier
	s_add_u32 s28, s28, 0x100
	s_addc_u32 s29, s29, 0
	s_cmpk_eq_i32 s28, 0xf00
	s_cbranch_scc0 .LBB0_596
	v_lshl_add_u64 v[64:65], 8, 4, v[64:65]
	v_lshl_add_u64 v[66:67], 8, 4, v[66:67]
	v_lshl_add_u64 v[68:69], 8, 4, v[68:69]
	v_lshl_add_u64 v[70:71], 8, 4, v[70:71]
	v_lshl_add_u64 v[76:77], 8, 4, v[76:77]
	v_lshl_add_u64 v[78:79], 8, 4, v[78:79]
	v_lshl_add_u64 v[72:73], 8, 4, v[72:73]
	v_lshl_add_u64 v[74:75], 8, 4, v[74:75]
	s_add_u32 m0, s100, 0x8000
	s_nop 0
	global_load_lds_dwordx4 v[64:65], off
	s_add_u32 m0, s100, 0x9000
	s_nop 0
	global_load_lds_dwordx4 v[66:67], off
	s_add_u32 m0, s100, 0xa000
	s_nop 0
	global_load_lds_dwordx4 v[68:69], off
	s_add_u32 m0, s100, 0xb000
	s_nop 0
	global_load_lds_dwordx4 v[70:71], off
	s_add_u32 m0, s100, 0xc000
	s_nop 0
	global_load_lds_dwordx4 v[76:77], off
	s_add_u32 m0, s100, 0xd000
	s_nop 0
	global_load_lds_dwordx4 v[78:79], off
	s_add_u32 m0, s100, 0xe000
	s_nop 0
	global_load_lds_dwordx4 v[72:73], off
	s_add_u32 m0, s100, 0xf000
	s_nop 0
	global_load_lds_dwordx4 v[74:75], off
	ds_read_b128 a[0:3], v115
	ds_read_b128 v[80:83], v116
	ds_read_b128 a[4:7], v115 offset:2048
	ds_read_b128 a[8:11], v115 offset:4096
	ds_read_b128 a[12:15], v115 offset:6144
	ds_read_b128 v[92:95], v116 offset:2048
	ds_read_b128 v[88:91], v116 offset:4096
	ds_read_b128 v[84:87], v116 offset:6144
	ds_read_b128 a[16:19], v117
	ds_read_b128 a[20:23], v117 offset:2048
	ds_read_b128 a[24:27], v117 offset:4096
	ds_read_b128 a[28:31], v117 offset:6144
	s_setprio 1
	s_waitcnt lgkmcnt(10)
	v_mfma_f32_16x16x32_bf16 v[0:3], a[0:3], v[80:83], v[0:3]
	s_waitcnt lgkmcnt(9)
	v_mfma_f32_16x16x32_bf16 v[16:19], a[4:7], v[80:83], v[16:19]
	s_waitcnt lgkmcnt(8)
	v_mfma_f32_16x16x32_bf16 v[32:35], a[8:11], v[80:83], v[32:35]
	s_waitcnt lgkmcnt(7)
	v_mfma_f32_16x16x32_bf16 v[48:51], a[12:15], v[80:83], v[48:51]
	ds_read_b128 v[80:83], v118
	s_waitcnt lgkmcnt(7)
	v_mfma_f32_16x16x32_bf16 v[4:7], a[0:3], v[92:95], v[4:7]
	v_mfma_f32_16x16x32_bf16 v[20:23], a[4:7], v[92:95], v[20:23]
	v_mfma_f32_16x16x32_bf16 v[36:39], a[8:11], v[92:95], v[36:39]
	v_mfma_f32_16x16x32_bf16 v[52:55], a[12:15], v[92:95], v[52:55]
	ds_read_b128 v[92:95], v118 offset:2048
	s_waitcnt lgkmcnt(7)
	v_mfma_f32_16x16x32_bf16 v[8:11], a[0:3], v[88:91], v[8:11]
	v_mfma_f32_16x16x32_bf16 v[24:27], a[4:7], v[88:91], v[24:27]
	v_mfma_f32_16x16x32_bf16 v[40:43], a[8:11], v[88:91], v[40:43]
	v_mfma_f32_16x16x32_bf16 v[56:59], a[12:15], v[88:91], v[56:59]
	ds_read_b128 v[88:91], v118 offset:4096
	s_waitcnt lgkmcnt(7)
	v_mfma_f32_16x16x32_bf16 v[12:15], a[0:3], v[84:87], v[12:15]
	v_mfma_f32_16x16x32_bf16 v[28:31], a[4:7], v[84:87], v[28:31]
	v_mfma_f32_16x16x32_bf16 v[44:47], a[8:11], v[84:87], v[44:47]
	v_mfma_f32_16x16x32_bf16 v[60:63], a[12:15], v[84:87], v[60:63]
	ds_read_b128 v[84:87], v118 offset:6144
	s_waitcnt lgkmcnt(3)
	v_mfma_f32_16x16x32_bf16 v[0:3], a[16:19], v[80:83], v[0:3]
	v_mfma_f32_16x16x32_bf16 v[16:19], a[20:23], v[80:83], v[16:19]
	v_mfma_f32_16x16x32_bf16 v[32:35], a[24:27], v[80:83], v[32:35]
	v_mfma_f32_16x16x32_bf16 v[48:51], a[28:31], v[80:83], v[48:51]
	s_waitcnt lgkmcnt(2)
	v_mfma_f32_16x16x32_bf16 v[4:7], a[16:19], v[92:95], v[4:7]
	v_mfma_f32_16x16x32_bf16 v[20:23], a[20:23], v[92:95], v[20:23]
	v_mfma_f32_16x16x32_bf16 v[36:39], a[24:27], v[92:95], v[36:39]
	v_mfma_f32_16x16x32_bf16 v[52:55], a[28:31], v[92:95], v[52:55]
	s_waitcnt lgkmcnt(1)
	v_mfma_f32_16x16x32_bf16 v[8:11], a[16:19], v[88:91], v[8:11]
	v_mfma_f32_16x16x32_bf16 v[24:27], a[20:23], v[88:91], v[24:27]
	v_mfma_f32_16x16x32_bf16 v[40:43], a[24:27], v[88:91], v[40:43]
	v_mfma_f32_16x16x32_bf16 v[56:59], a[28:31], v[88:91], v[56:59]
	s_waitcnt lgkmcnt(0)
	v_mfma_f32_16x16x32_bf16 v[12:15], a[16:19], v[84:87], v[12:15]
	v_mfma_f32_16x16x32_bf16 v[28:31], a[20:23], v[84:87], v[28:31]
	v_mfma_f32_16x16x32_bf16 v[44:47], a[24:27], v[84:87], v[44:47]
	v_mfma_f32_16x16x32_bf16 v[60:63], a[28:31], v[84:87], v[60:63]
	s_setprio 0
	s_waitcnt vmcnt(0) lgkmcnt(0)
	s_barrier
	ds_read_b128 a[0:3], v115 offset:32768
	ds_read_b128 v[80:83], v116 offset:32768
	ds_read_b128 a[4:7], v115 offset:34816
	ds_read_b128 a[8:11], v115 offset:36864
	ds_read_b128 a[12:15], v115 offset:38912
	ds_read_b128 v[92:95], v116 offset:34816
	ds_read_b128 v[88:91], v116 offset:36864
	ds_read_b128 v[84:87], v116 offset:38912
	ds_read_b128 a[16:19], v117 offset:32768
	ds_read_b128 a[20:23], v117 offset:34816
	ds_read_b128 a[24:27], v117 offset:36864
	ds_read_b128 a[28:31], v117 offset:38912
	s_setprio 1
	s_waitcnt lgkmcnt(10)
	v_mfma_f32_16x16x32_bf16 v[0:3], a[0:3], v[80:83], v[0:3]
	s_waitcnt lgkmcnt(9)
	v_mfma_f32_16x16x32_bf16 v[16:19], a[4:7], v[80:83], v[16:19]
	s_waitcnt lgkmcnt(8)
	v_mfma_f32_16x16x32_bf16 v[32:35], a[8:11], v[80:83], v[32:35]
	s_waitcnt lgkmcnt(7)
	v_mfma_f32_16x16x32_bf16 v[48:51], a[12:15], v[80:83], v[48:51]
	ds_read_b128 v[80:83], v118 offset:32768
	s_waitcnt lgkmcnt(7)
	v_mfma_f32_16x16x32_bf16 v[4:7], a[0:3], v[92:95], v[4:7]
	v_mfma_f32_16x16x32_bf16 v[20:23], a[4:7], v[92:95], v[20:23]
	v_mfma_f32_16x16x32_bf16 v[36:39], a[8:11], v[92:95], v[36:39]
	v_mfma_f32_16x16x32_bf16 v[52:55], a[12:15], v[92:95], v[52:55]
	ds_read_b128 v[92:95], v118 offset:34816
	s_waitcnt lgkmcnt(7)
	v_mfma_f32_16x16x32_bf16 v[8:11], a[0:3], v[88:91], v[8:11]
	v_mfma_f32_16x16x32_bf16 v[24:27], a[4:7], v[88:91], v[24:27]
	v_mfma_f32_16x16x32_bf16 v[40:43], a[8:11], v[88:91], v[40:43]
	v_mfma_f32_16x16x32_bf16 v[56:59], a[12:15], v[88:91], v[56:59]
	ds_read_b128 v[88:91], v118 offset:36864
	s_waitcnt lgkmcnt(7)
	v_mfma_f32_16x16x32_bf16 v[12:15], a[0:3], v[84:87], v[12:15]
	v_mfma_f32_16x16x32_bf16 v[28:31], a[4:7], v[84:87], v[28:31]
	v_mfma_f32_16x16x32_bf16 v[44:47], a[8:11], v[84:87], v[44:47]
	v_mfma_f32_16x16x32_bf16 v[60:63], a[12:15], v[84:87], v[60:63]
	ds_read_b128 v[84:87], v118 offset:38912
	s_waitcnt lgkmcnt(3)
	v_mfma_f32_16x16x32_bf16 v[0:3], a[16:19], v[80:83], v[0:3]
	v_mfma_f32_16x16x32_bf16 v[16:19], a[20:23], v[80:83], v[16:19]
	v_mfma_f32_16x16x32_bf16 v[32:35], a[24:27], v[80:83], v[32:35]
	v_mfma_f32_16x16x32_bf16 v[48:51], a[28:31], v[80:83], v[48:51]
	s_waitcnt lgkmcnt(2)
	v_mfma_f32_16x16x32_bf16 v[4:7], a[16:19], v[92:95], v[4:7]
	v_mfma_f32_16x16x32_bf16 v[20:23], a[20:23], v[92:95], v[20:23]
	v_mfma_f32_16x16x32_bf16 v[36:39], a[24:27], v[92:95], v[36:39]
	v_mfma_f32_16x16x32_bf16 v[52:55], a[28:31], v[92:95], v[52:55]
	s_waitcnt lgkmcnt(1)
	v_mfma_f32_16x16x32_bf16 v[8:11], a[16:19], v[88:91], v[8:11]
	v_mfma_f32_16x16x32_bf16 v[24:27], a[20:23], v[88:91], v[24:27]
	v_mfma_f32_16x16x32_bf16 v[40:43], a[24:27], v[88:91], v[40:43]
	v_mfma_f32_16x16x32_bf16 v[56:59], a[28:31], v[88:91], v[56:59]
	s_waitcnt lgkmcnt(0)
	v_mfma_f32_16x16x32_bf16 v[12:15], a[16:19], v[84:87], v[12:15]
	v_mfma_f32_16x16x32_bf16 v[28:31], a[20:23], v[84:87], v[28:31]
	v_mfma_f32_16x16x32_bf16 v[44:47], a[24:27], v[84:87], v[44:47]
	v_mfma_f32_16x16x32_bf16 v[60:63], a[28:31], v[84:87], v[60:63]
	s_setprio 0
	v_readfirstlane_b32 s15, v107
	v_readfirstlane_b32 s4, v106
	s_lshl_b32 s15, s15, 6
	s_waitcnt lgkmcnt(0)
	s_barrier
	s_add_i32 s9, s15, s9
	s_lshl_b32 s15, s4, 17
	s_lshl_b32 s4, s8, 18
	s_add_i32 s15, s15, s4
	v_or_b32_e32 v64, s9, v108
	s_movk_i32 s4, 0x800
	v_cmp_gt_i32_e32 vcc, s4, v64
	s_barrier
	v_and_b32_e32 v124, 15, v143
	v_bfe_u32 v125, v143, 4, 2
	v_xor_b32_e32 v125, v125, v124
	v_lshlrev_b32_e32 v125, 4, v125
	v_lshl_add_u32 v125, v124, 8, v125
	v_lshrrev_b32_e32 v124, 6, v143
	v_lshl_add_u32 v125, v124, 14, v125
	ds_write_b128 v125, v[0:3]
	ds_write_b128 v125, v[4:7] offset:4096
	ds_write_b128 v125, v[8:11] offset:8192
	ds_write_b128 v125, v[12:15] offset:12288
	v_xor_b32_e32 v118, 64, v125
	ds_write_b128 v118, v[16:19]
	ds_write_b128 v118, v[20:23] offset:4096
	ds_write_b128 v118, v[24:27] offset:8192
	ds_write_b128 v118, v[28:31] offset:12288
	v_xor_b32_e32 v118, 128, v125
	ds_write_b128 v118, v[32:35]
	ds_write_b128 v118, v[36:39] offset:4096
	ds_write_b128 v118, v[40:43] offset:8192
	ds_write_b128 v118, v[44:47] offset:12288
	v_xor_b32_e32 v118, 192, v125
	ds_write_b128 v118, v[48:51]
	ds_write_b128 v118, v[52:55] offset:4096
	ds_write_b128 v118, v[56:59] offset:8192
	ds_write_b128 v118, v[60:63] offset:12288
	v_and_b32_e32 v115, 31, v143
	v_bfe_u32 v117, v143, 5, 1
	v_and_b32_e32 v125, 15, v115
	v_xor_b32_e32 v117, v117, v125
	v_lshlrev_b32_e32 v117, 4, v117
	v_lshl_add_u32 v117, v115, 8, v117
	v_lshl_add_u32 v117, v124, 14, v117
	ds_read_b128 v[48:51], v117
	ds_read_b128 v[32:35], v117 offset:8192
	v_xor_b32_e32 v116, 32, v117
	ds_read_b128 v[52:55], v116
	ds_read_b128 v[36:39], v116 offset:8192
	v_xor_b32_e32 v116, 64, v117
	ds_read_b128 v[56:59], v116
	ds_read_b128 v[40:43], v116 offset:8192
	v_xor_b32_e32 v116, 96, v117
	ds_read_b128 v[60:63], v116
	ds_read_b128 v[44:47], v116 offset:8192
	v_xor_b32_e32 v116, 128, v117
	ds_read_b128 v[16:19], v116
	ds_read_b128 v[0:3], v116 offset:8192
	v_xor_b32_e32 v116, 160, v117
	ds_read_b128 v[20:23], v116
	ds_read_b128 v[4:7], v116 offset:8192
	v_xor_b32_e32 v116, 192, v117
	ds_read_b128 v[24:27], v116
	ds_read_b128 v[8:11], v116 offset:8192
	v_xor_b32_e32 v116, 224, v117
	ds_read_b128 v[28:31], v116
	ds_read_b128 v[12:15], v116 offset:8192
	s_waitcnt lgkmcnt(0)
	s_barrier
	s_and_saveexec_b64 s[8:9], vcc
	s_cbranch_execz .LBB0_599
	v_add_u32_e32 v65, s15, v64
	v_add_u32_e32 v66, v65, v111
	v_mov_b32_e32 v67, v140
	v_lshl_add_u64 v[68:69], v[66:67], 2, s[26:27]
	global_store_dword v[68:69], v48, off
	v_add_u32_e32 v68, 0x800, v66
	v_mov_b32_e32 v69, v140
	v_lshl_add_u64 v[68:69], v[68:69], 2, s[26:27]
	global_store_dword v[68:69], v49, off
	v_add_u32_e32 v48, 0x1000, v66
	v_mov_b32_e32 v49, v140
	v_lshl_add_u64 v[48:49], v[48:49], 2, s[26:27]
	global_store_dword v[48:49], v50, off
	v_add_u32_e32 v48, 0x1800, v66
	v_mov_b32_e32 v49, v140
	v_lshl_add_u64 v[48:49], v[48:49], 2, s[26:27]
	global_store_dword v[48:49], v51, off
	v_add_u32_e32 v48, v65, v112
	v_mov_b32_e32 v49, v140
	v_lshl_add_u64 v[50:51], v[48:49], 2, s[26:27]
	global_store_dword v[50:51], v52, off
	v_add_u32_e32 v50, 0x800, v48
	v_mov_b32_e32 v51, v140
	v_lshl_add_u64 v[50:51], v[50:51], 2, s[26:27]
	global_store_dword v[50:51], v53, off
	v_add_u32_e32 v50, 0x1000, v48
	v_mov_b32_e32 v51, v140
	v_add_u32_e32 v48, 0x1800, v48
	v_lshl_add_u64 v[50:51], v[50:51], 2, s[26:27]
	v_lshl_add_u64 v[48:49], v[48:49], 2, s[26:27]
	global_store_dword v[50:51], v54, off
	global_store_dword v[48:49], v55, off
	v_add_u32_e32 v48, v65, v113
	v_mov_b32_e32 v49, v140
	v_lshl_add_u64 v[50:51], v[48:49], 2, s[26:27]
	global_store_dword v[50:51], v56, off
	v_add_u32_e32 v50, 0x800, v48
	v_mov_b32_e32 v51, v140
	v_lshl_add_u64 v[50:51], v[50:51], 2, s[26:27]
	global_store_dword v[50:51], v57, off
	v_add_u32_e32 v50, 0x1000, v48
	v_mov_b32_e32 v51, v140
	v_add_u32_e32 v48, 0x1800, v48
	v_lshl_add_u64 v[50:51], v[50:51], 2, s[26:27]
	v_lshl_add_u64 v[48:49], v[48:49], 2, s[26:27]
	global_store_dword v[50:51], v58, off
	global_store_dword v[48:49], v59, off
	v_add_u32_e32 v48, v65, v114
	v_mov_b32_e32 v49, v140
	v_lshl_add_u64 v[50:51], v[48:49], 2, s[26:27]
	global_store_dword v[50:51], v60, off
	v_add_u32_e32 v50, 0x800, v48
	v_mov_b32_e32 v51, v140
	v_lshl_add_u64 v[50:51], v[50:51], 2, s[26:27]
	global_store_dword v[50:51], v61, off
	v_add_u32_e32 v50, 0x1000, v48
	v_mov_b32_e32 v51, v140
	v_add_u32_e32 v48, 0x1800, v48
	v_lshl_add_u64 v[50:51], v[50:51], 2, s[26:27]
	v_lshl_add_u64 v[48:49], v[48:49], 2, s[26:27]
	global_store_dword v[50:51], v62, off
	global_store_dword v[48:49], v63, off

.LBB0_609:
	v_lshl_add_u64 v[72:73], v[104:105], 0, s[28:29]
	s_mov_b32 s4, 0x1c6b8000
	v_add_co_u32_e32 v144, vcc, s4, v72
	s_mov_b32 s4, 0x1c6d8000
	s_nop 0
	v_addc_co_u32_e32 v145, vcc, 0, v73, vcc
	v_add_co_u32_e32 v146, vcc, s4, v72
	s_mov_b32 s4, 0x1c6f8000
	s_nop 0
	v_addc_co_u32_e32 v147, vcc, 0, v73, vcc
	v_add_co_u32_e32 v148, vcc, s4, v72
	s_mov_b32 s4, 0x1c718000
	s_nop 0
	v_addc_co_u32_e32 v149, vcc, 0, v73, vcc
	v_add_co_u32_e32 v150, vcc, s4, v72
	v_lshl_add_u64 v[88:89], v[102:103], 0, s[28:29]
	s_nop 0
	v_addc_co_u32_e32 v151, vcc, 0, v73, vcc
	s_mov_b32 s4, 0x37b80000
	v_add_co_u32_e32 v152, vcc, s4, v88
	s_mov_b32 s4, 0x37ba0000
	s_nop 0
	v_addc_co_u32_e32 v153, vcc, 0, v89, vcc
	v_add_co_u32_e32 v154, vcc, s4, v88
	s_mov_b32 s4, 0x37bc0000
	s_nop 0
	v_addc_co_u32_e32 v155, vcc, 0, v89, vcc
	v_add_co_u32_e32 v156, vcc, s4, v88
	s_mov_b32 s4, 0x37be0000
	s_nop 0
	v_addc_co_u32_e32 v157, vcc, 0, v89, vcc
	v_add_co_u32_e32 v178, vcc, s4, v88
	v_addc_co_u32_e32 v179, vcc, 0, v89, vcc
	v_lshl_add_u64 v[144:145], 8, 4, v[144:145]
	v_lshl_add_u64 v[146:147], 8, 4, v[146:147]
	v_lshl_add_u64 v[148:149], 8, 4, v[148:149]
	v_lshl_add_u64 v[150:151], 8, 4, v[150:151]
	v_lshl_add_u64 v[152:153], 8, 4, v[152:153]
	v_lshl_add_u64 v[154:155], 8, 4, v[154:155]
	v_lshl_add_u64 v[156:157], 8, 4, v[156:157]
	v_lshl_add_u64 v[178:179], 8, 4, v[178:179]
	s_add_u32 m0, s100, 0x8000
	s_nop 0
	global_load_lds_dwordx4 v[144:145], off
	s_add_u32 m0, s100, 0x9000
	s_nop 0
	global_load_lds_dwordx4 v[146:147], off
	s_add_u32 m0, s100, 0xa000
	s_nop 0
	global_load_lds_dwordx4 v[148:149], off
	s_add_u32 m0, s100, 0xb000
	s_nop 0
	global_load_lds_dwordx4 v[150:151], off
	s_add_u32 m0, s100, 0xc000
	s_nop 0
	global_load_lds_dwordx4 v[152:153], off
	s_add_u32 m0, s100, 0xd000
	s_nop 0
	global_load_lds_dwordx4 v[154:155], off
	s_add_u32 m0, s100, 0xe000
	s_nop 0
	global_load_lds_dwordx4 v[156:157], off
	s_add_u32 m0, s100, 0xf000
	s_nop 0
	global_load_lds_dwordx4 v[178:179], off
	ds_read_b128 a[0:3], v115
	ds_read_b128 v[80:83], v116
	ds_read_b128 a[4:7], v115 offset:2048
	ds_read_b128 a[8:11], v115 offset:4096
	ds_read_b128 a[12:15], v115 offset:6144
	ds_read_b128 v[92:95], v116 offset:2048
	ds_read_b128 v[88:91], v116 offset:4096
	ds_read_b128 v[84:87], v116 offset:6144
	ds_read_b128 a[16:19], v117
	ds_read_b128 a[20:23], v117 offset:2048
	ds_read_b128 a[24:27], v117 offset:4096
	ds_read_b128 a[28:31], v117 offset:6144
	s_setprio 1
	s_waitcnt lgkmcnt(10)
	v_mfma_f32_16x16x32_bf16 v[0:3], a[0:3], v[80:83], v[0:3]
	s_waitcnt lgkmcnt(9)
	v_mfma_f32_16x16x32_bf16 v[16:19], a[4:7], v[80:83], v[16:19]
	s_waitcnt lgkmcnt(8)
	v_mfma_f32_16x16x32_bf16 v[32:35], a[8:11], v[80:83], v[32:35]
	s_waitcnt lgkmcnt(7)
	v_mfma_f32_16x16x32_bf16 v[48:51], a[12:15], v[80:83], v[48:51]
	ds_read_b128 v[80:83], v118
	s_waitcnt lgkmcnt(7)
	v_mfma_f32_16x16x32_bf16 v[4:7], a[0:3], v[92:95], v[4:7]
	v_mfma_f32_16x16x32_bf16 v[20:23], a[4:7], v[92:95], v[20:23]
	v_mfma_f32_16x16x32_bf16 v[36:39], a[8:11], v[92:95], v[36:39]
	v_mfma_f32_16x16x32_bf16 v[52:55], a[12:15], v[92:95], v[52:55]
	ds_read_b128 v[92:95], v118 offset:2048
	s_waitcnt lgkmcnt(7)
	v_mfma_f32_16x16x32_bf16 v[8:11], a[0:3], v[88:91], v[8:11]
	v_mfma_f32_16x16x32_bf16 v[24:27], a[4:7], v[88:91], v[24:27]
	v_mfma_f32_16x16x32_bf16 v[40:43], a[8:11], v[88:91], v[40:43]
	v_mfma_f32_16x16x32_bf16 v[56:59], a[12:15], v[88:91], v[56:59]
	ds_read_b128 v[88:91], v118 offset:4096
	s_waitcnt lgkmcnt(7)
	v_mfma_f32_16x16x32_bf16 v[12:15], a[0:3], v[84:87], v[12:15]
	v_mfma_f32_16x16x32_bf16 v[28:31], a[4:7], v[84:87], v[28:31]
	v_mfma_f32_16x16x32_bf16 v[44:47], a[8:11], v[84:87], v[44:47]
	v_mfma_f32_16x16x32_bf16 v[60:63], a[12:15], v[84:87], v[60:63]
	ds_read_b128 v[84:87], v118 offset:6144
	s_waitcnt lgkmcnt(3)
	v_mfma_f32_16x16x32_bf16 v[0:3], a[16:19], v[80:83], v[0:3]
	v_mfma_f32_16x16x32_bf16 v[16:19], a[20:23], v[80:83], v[16:19]
	v_mfma_f32_16x16x32_bf16 v[32:35], a[24:27], v[80:83], v[32:35]
	v_mfma_f32_16x16x32_bf16 v[48:51], a[28:31], v[80:83], v[48:51]
	s_waitcnt lgkmcnt(2)
	v_mfma_f32_16x16x32_bf16 v[4:7], a[16:19], v[92:95], v[4:7]
	v_mfma_f32_16x16x32_bf16 v[20:23], a[20:23], v[92:95], v[20:23]
	v_mfma_f32_16x16x32_bf16 v[36:39], a[24:27], v[92:95], v[36:39]
	v_mfma_f32_16x16x32_bf16 v[52:55], a[28:31], v[92:95], v[52:55]
	s_waitcnt lgkmcnt(1)
	v_mfma_f32_16x16x32_bf16 v[8:11], a[16:19], v[88:91], v[8:11]
	v_mfma_f32_16x16x32_bf16 v[24:27], a[20:23], v[88:91], v[24:27]
	v_mfma_f32_16x16x32_bf16 v[40:43], a[24:27], v[88:91], v[40:43]
	v_mfma_f32_16x16x32_bf16 v[56:59], a[28:31], v[88:91], v[56:59]
	s_waitcnt lgkmcnt(0)
	v_mfma_f32_16x16x32_bf16 v[12:15], a[16:19], v[84:87], v[12:15]
	v_mfma_f32_16x16x32_bf16 v[28:31], a[20:23], v[84:87], v[28:31]
	v_mfma_f32_16x16x32_bf16 v[44:47], a[24:27], v[84:87], v[44:47]
	v_mfma_f32_16x16x32_bf16 v[60:63], a[28:31], v[84:87], v[60:63]
	s_setprio 0
	s_waitcnt vmcnt(0) lgkmcnt(0)
	s_barrier
	v_lshl_add_u64 v[64:65], 8, 4, v[144:145]
	v_lshl_add_u64 v[66:67], 8, 4, v[146:147]
	v_lshl_add_u64 v[68:69], 8, 4, v[148:149]
	v_lshl_add_u64 v[70:71], 8, 4, v[150:151]
	v_lshl_add_u64 v[76:77], 8, 4, v[152:153]
	v_lshl_add_u64 v[78:79], 8, 4, v[154:155]
	v_lshl_add_u64 v[72:73], 8, 4, v[156:157]
	v_lshl_add_u64 v[74:75], 8, 4, v[178:179]
	s_add_u32 m0, s100, 0x0
	s_nop 0
	global_load_lds_dwordx4 v[64:65], off
	s_add_u32 m0, s100, 0x1000
	s_nop 0
	global_load_lds_dwordx4 v[66:67], off
	s_add_u32 m0, s100, 0x2000
	s_nop 0
	global_load_lds_dwordx4 v[68:69], off
	s_add_u32 m0, s100, 0x3000
	s_nop 0
	global_load_lds_dwordx4 v[70:71], off
	s_add_u32 m0, s100, 0x4000
	s_nop 0
	global_load_lds_dwordx4 v[76:77], off
	s_add_u32 m0, s100, 0x5000
	s_nop 0
	global_load_lds_dwordx4 v[78:79], off
	s_add_u32 m0, s100, 0x6000
	s_nop 0
	global_load_lds_dwordx4 v[72:73], off
	s_add_u32 m0, s100, 0x7000
	s_nop 0
	global_load_lds_dwordx4 v[74:75], off
	ds_read_b128 a[0:3], v115 offset:32768
	ds_read_b128 v[80:83], v116 offset:32768
	ds_read_b128 a[4:7], v115 offset:34816
	ds_read_b128 a[8:11], v115 offset:36864
	ds_read_b128 a[12:15], v115 offset:38912
	ds_read_b128 v[92:95], v116 offset:34816
	ds_read_b128 v[88:91], v116 offset:36864
	ds_read_b128 v[84:87], v116 offset:38912
	ds_read_b128 a[16:19], v117 offset:32768
	ds_read_b128 a[20:23], v117 offset:34816
	ds_read_b128 a[24:27], v117 offset:36864
	ds_read_b128 a[28:31], v117 offset:38912
	s_setprio 1
	s_waitcnt lgkmcnt(10)
	v_mfma_f32_16x16x32_bf16 v[0:3], a[0:3], v[80:83], v[0:3]
	s_waitcnt lgkmcnt(9)
	v_mfma_f32_16x16x32_bf16 v[16:19], a[4:7], v[80:83], v[16:19]
	s_waitcnt lgkmcnt(8)
	v_mfma_f32_16x16x32_bf16 v[32:35], a[8:11], v[80:83], v[32:35]
	s_waitcnt lgkmcnt(7)
	v_mfma_f32_16x16x32_bf16 v[48:51], a[12:15], v[80:83], v[48:51]
	ds_read_b128 v[80:83], v118 offset:32768
	s_waitcnt lgkmcnt(7)
	v_mfma_f32_16x16x32_bf16 v[4:7], a[0:3], v[92:95], v[4:7]
	v_mfma_f32_16x16x32_bf16 v[20:23], a[4:7], v[92:95], v[20:23]
	v_mfma_f32_16x16x32_bf16 v[36:39], a[8:11], v[92:95], v[36:39]
	v_mfma_f32_16x16x32_bf16 v[52:55], a[12:15], v[92:95], v[52:55]
	ds_read_b128 v[92:95], v118 offset:34816
	s_waitcnt lgkmcnt(7)
	v_mfma_f32_16x16x32_bf16 v[8:11], a[0:3], v[88:91], v[8:11]
	v_mfma_f32_16x16x32_bf16 v[24:27], a[4:7], v[88:91], v[24:27]
	v_mfma_f32_16x16x32_bf16 v[40:43], a[8:11], v[88:91], v[40:43]
	v_mfma_f32_16x16x32_bf16 v[56:59], a[12:15], v[88:91], v[56:59]
	ds_read_b128 v[88:91], v118 offset:36864
	s_waitcnt lgkmcnt(7)
	v_mfma_f32_16x16x32_bf16 v[12:15], a[0:3], v[84:87], v[12:15]
	v_mfma_f32_16x16x32_bf16 v[28:31], a[4:7], v[84:87], v[28:31]
	v_mfma_f32_16x16x32_bf16 v[44:47], a[8:11], v[84:87], v[44:47]
	v_mfma_f32_16x16x32_bf16 v[60:63], a[12:15], v[84:87], v[60:63]
	ds_read_b128 v[84:87], v118 offset:38912
	s_waitcnt lgkmcnt(3)
	v_mfma_f32_16x16x32_bf16 v[0:3], a[16:19], v[80:83], v[0:3]
	v_mfma_f32_16x16x32_bf16 v[16:19], a[20:23], v[80:83], v[16:19]
	v_mfma_f32_16x16x32_bf16 v[32:35], a[24:27], v[80:83], v[32:35]
	v_mfma_f32_16x16x32_bf16 v[48:51], a[28:31], v[80:83], v[48:51]
	s_waitcnt lgkmcnt(2)
	v_mfma_f32_16x16x32_bf16 v[4:7], a[16:19], v[92:95], v[4:7]
	v_mfma_f32_16x16x32_bf16 v[20:23], a[20:23], v[92:95], v[20:23]
	v_mfma_f32_16x16x32_bf16 v[36:39], a[24:27], v[92:95], v[36:39]
	v_mfma_f32_16x16x32_bf16 v[52:55], a[28:31], v[92:95], v[52:55]
	s_waitcnt lgkmcnt(1)
	v_mfma_f32_16x16x32_bf16 v[8:11], a[16:19], v[88:91], v[8:11]
	v_mfma_f32_16x16x32_bf16 v[24:27], a[20:23], v[88:91], v[24:27]
	v_mfma_f32_16x16x32_bf16 v[40:43], a[24:27], v[88:91], v[40:43]
	v_mfma_f32_16x16x32_bf16 v[56:59], a[28:31], v[88:91], v[56:59]
	s_waitcnt lgkmcnt(0)
	v_mfma_f32_16x16x32_bf16 v[12:15], a[16:19], v[84:87], v[12:15]
	v_mfma_f32_16x16x32_bf16 v[28:31], a[20:23], v[84:87], v[28:31]
	v_mfma_f32_16x16x32_bf16 v[44:47], a[24:27], v[84:87], v[44:47]
	v_mfma_f32_16x16x32_bf16 v[60:63], a[28:31], v[84:87], v[60:63]
	s_setprio 0
	s_waitcnt vmcnt(0) lgkmcnt(0)
	s_barrier
	s_add_u32 s28, s28, 0x100
	s_addc_u32 s29, s29, 0
	s_cmpk_eq_i32 s28, 0xf00
	s_cbranch_scc0 .LBB0_609
	v_lshl_add_u64 v[64:65], 8, 4, v[64:65]
	v_lshl_add_u64 v[66:67], 8, 4, v[66:67]
	v_lshl_add_u64 v[68:69], 8, 4, v[68:69]
	v_lshl_add_u64 v[70:71], 8, 4, v[70:71]
	v_lshl_add_u64 v[76:77], 8, 4, v[76:77]
	v_lshl_add_u64 v[78:79], 8, 4, v[78:79]
	v_lshl_add_u64 v[72:73], 8, 4, v[72:73]
	v_lshl_add_u64 v[74:75], 8, 4, v[74:75]
	s_add_u32 m0, s100, 0x8000
	s_nop 0
	global_load_lds_dwordx4 v[64:65], off
	s_add_u32 m0, s100, 0x9000
	s_nop 0
	global_load_lds_dwordx4 v[66:67], off
	s_add_u32 m0, s100, 0xa000
	s_nop 0
	global_load_lds_dwordx4 v[68:69], off
	s_add_u32 m0, s100, 0xb000
	s_nop 0
	global_load_lds_dwordx4 v[70:71], off
	s_add_u32 m0, s100, 0xc000
	s_nop 0
	global_load_lds_dwordx4 v[76:77], off
	s_add_u32 m0, s100, 0xd000
	s_nop 0
	global_load_lds_dwordx4 v[78:79], off
	s_add_u32 m0, s100, 0xe000
	s_nop 0
	global_load_lds_dwordx4 v[72:73], off
	s_add_u32 m0, s100, 0xf000
	s_nop 0
	global_load_lds_dwordx4 v[74:75], off
	ds_read_b128 a[0:3], v115
	ds_read_b128 v[80:83], v116
	ds_read_b128 a[4:7], v115 offset:2048
	ds_read_b128 a[8:11], v115 offset:4096
	ds_read_b128 a[12:15], v115 offset:6144
	ds_read_b128 v[92:95], v116 offset:2048
	ds_read_b128 v[88:91], v116 offset:4096
	ds_read_b128 v[84:87], v116 offset:6144
	ds_read_b128 a[16:19], v117
	ds_read_b128 a[20:23], v117 offset:2048
	ds_read_b128 a[24:27], v117 offset:4096
	ds_read_b128 a[28:31], v117 offset:6144
	s_setprio 1
	s_waitcnt lgkmcnt(10)
	v_mfma_f32_16x16x32_bf16 v[0:3], a[0:3], v[80:83], v[0:3]
	s_waitcnt lgkmcnt(9)
	v_mfma_f32_16x16x32_bf16 v[16:19], a[4:7], v[80:83], v[16:19]
	s_waitcnt lgkmcnt(8)
	v_mfma_f32_16x16x32_bf16 v[32:35], a[8:11], v[80:83], v[32:35]
	s_waitcnt lgkmcnt(7)
	v_mfma_f32_16x16x32_bf16 v[48:51], a[12:15], v[80:83], v[48:51]
	ds_read_b128 v[80:83], v118
	s_waitcnt lgkmcnt(7)
	v_mfma_f32_16x16x32_bf16 v[4:7], a[0:3], v[92:95], v[4:7]
	v_mfma_f32_16x16x32_bf16 v[20:23], a[4:7], v[92:95], v[20:23]
	v_mfma_f32_16x16x32_bf16 v[36:39], a[8:11], v[92:95], v[36:39]
	v_mfma_f32_16x16x32_bf16 v[52:55], a[12:15], v[92:95], v[52:55]
	ds_read_b128 v[92:95], v118 offset:2048
	s_waitcnt lgkmcnt(7)
	v_mfma_f32_16x16x32_bf16 v[8:11], a[0:3], v[88:91], v[8:11]
	v_mfma_f32_16x16x32_bf16 v[24:27], a[4:7], v[88:91], v[24:27]
	v_mfma_f32_16x16x32_bf16 v[40:43], a[8:11], v[88:91], v[40:43]
	v_mfma_f32_16x16x32_bf16 v[56:59], a[12:15], v[88:91], v[56:59]
	ds_read_b128 v[88:91], v118 offset:4096
	s_waitcnt lgkmcnt(7)
	v_mfma_f32_16x16x32_bf16 v[12:15], a[0:3], v[84:87], v[12:15]
	v_mfma_f32_16x16x32_bf16 v[28:31], a[4:7], v[84:87], v[28:31]
	v_mfma_f32_16x16x32_bf16 v[44:47], a[8:11], v[84:87], v[44:47]
	v_mfma_f32_16x16x32_bf16 v[60:63], a[12:15], v[84:87], v[60:63]
	ds_read_b128 v[84:87], v118 offset:6144
	s_waitcnt lgkmcnt(3)
	v_mfma_f32_16x16x32_bf16 v[0:3], a[16:19], v[80:83], v[0:3]
	v_mfma_f32_16x16x32_bf16 v[16:19], a[20:23], v[80:83], v[16:19]
	v_mfma_f32_16x16x32_bf16 v[32:35], a[24:27], v[80:83], v[32:35]
	v_mfma_f32_16x16x32_bf16 v[48:51], a[28:31], v[80:83], v[48:51]
	s_waitcnt lgkmcnt(2)
	v_mfma_f32_16x16x32_bf16 v[4:7], a[16:19], v[92:95], v[4:7]
	v_mfma_f32_16x16x32_bf16 v[20:23], a[20:23], v[92:95], v[20:23]
	v_mfma_f32_16x16x32_bf16 v[36:39], a[24:27], v[92:95], v[36:39]
	v_mfma_f32_16x16x32_bf16 v[52:55], a[28:31], v[92:95], v[52:55]
	s_waitcnt lgkmcnt(1)
	v_mfma_f32_16x16x32_bf16 v[8:11], a[16:19], v[88:91], v[8:11]
	v_mfma_f32_16x16x32_bf16 v[24:27], a[20:23], v[88:91], v[24:27]
	v_mfma_f32_16x16x32_bf16 v[40:43], a[24:27], v[88:91], v[40:43]
	v_mfma_f32_16x16x32_bf16 v[56:59], a[28:31], v[88:91], v[56:59]
	s_waitcnt lgkmcnt(0)
	v_mfma_f32_16x16x32_bf16 v[12:15], a[16:19], v[84:87], v[12:15]
	v_mfma_f32_16x16x32_bf16 v[28:31], a[20:23], v[84:87], v[28:31]
	v_mfma_f32_16x16x32_bf16 v[44:47], a[24:27], v[84:87], v[44:47]
	v_mfma_f32_16x16x32_bf16 v[60:63], a[28:31], v[84:87], v[60:63]
	s_setprio 0
	s_waitcnt vmcnt(0) lgkmcnt(0)
	s_barrier
	ds_read_b128 a[0:3], v115 offset:32768
	ds_read_b128 v[80:83], v116 offset:32768
	ds_read_b128 a[4:7], v115 offset:34816
	ds_read_b128 a[8:11], v115 offset:36864
	ds_read_b128 a[12:15], v115 offset:38912
	ds_read_b128 v[92:95], v116 offset:34816
	ds_read_b128 v[88:91], v116 offset:36864
	ds_read_b128 v[84:87], v116 offset:38912
	ds_read_b128 a[16:19], v117 offset:32768
	ds_read_b128 a[20:23], v117 offset:34816
	ds_read_b128 a[24:27], v117 offset:36864
	ds_read_b128 a[28:31], v117 offset:38912
	s_setprio 1
	s_waitcnt lgkmcnt(10)
	v_mfma_f32_16x16x32_bf16 v[0:3], a[0:3], v[80:83], v[0:3]
	s_waitcnt lgkmcnt(9)
	v_mfma_f32_16x16x32_bf16 v[16:19], a[4:7], v[80:83], v[16:19]
	s_waitcnt lgkmcnt(8)
	v_mfma_f32_16x16x32_bf16 v[32:35], a[8:11], v[80:83], v[32:35]
	s_waitcnt lgkmcnt(7)
	v_mfma_f32_16x16x32_bf16 v[48:51], a[12:15], v[80:83], v[48:51]
	ds_read_b128 v[80:83], v118 offset:32768
	s_waitcnt lgkmcnt(7)
	v_mfma_f32_16x16x32_bf16 v[4:7], a[0:3], v[92:95], v[4:7]
	v_mfma_f32_16x16x32_bf16 v[20:23], a[4:7], v[92:95], v[20:23]
	v_mfma_f32_16x16x32_bf16 v[36:39], a[8:11], v[92:95], v[36:39]
	v_mfma_f32_16x16x32_bf16 v[52:55], a[12:15], v[92:95], v[52:55]
	ds_read_b128 v[92:95], v118 offset:34816
	s_waitcnt lgkmcnt(7)
	v_mfma_f32_16x16x32_bf16 v[8:11], a[0:3], v[88:91], v[8:11]
	v_mfma_f32_16x16x32_bf16 v[24:27], a[4:7], v[88:91], v[24:27]
	v_mfma_f32_16x16x32_bf16 v[40:43], a[8:11], v[88:91], v[40:43]
	v_mfma_f32_16x16x32_bf16 v[56:59], a[12:15], v[88:91], v[56:59]
	ds_read_b128 v[88:91], v118 offset:36864
	s_waitcnt lgkmcnt(7)
	v_mfma_f32_16x16x32_bf16 v[12:15], a[0:3], v[84:87], v[12:15]
	v_mfma_f32_16x16x32_bf16 v[28:31], a[4:7], v[84:87], v[28:31]
	v_mfma_f32_16x16x32_bf16 v[44:47], a[8:11], v[84:87], v[44:47]
	v_mfma_f32_16x16x32_bf16 v[60:63], a[12:15], v[84:87], v[60:63]
	ds_read_b128 v[84:87], v118 offset:38912
	s_waitcnt lgkmcnt(3)
	v_mfma_f32_16x16x32_bf16 v[0:3], a[16:19], v[80:83], v[0:3]
	v_mfma_f32_16x16x32_bf16 v[16:19], a[20:23], v[80:83], v[16:19]
	v_mfma_f32_16x16x32_bf16 v[32:35], a[24:27], v[80:83], v[32:35]
	v_mfma_f32_16x16x32_bf16 v[48:51], a[28:31], v[80:83], v[48:51]
	s_waitcnt lgkmcnt(2)
	v_mfma_f32_16x16x32_bf16 v[4:7], a[16:19], v[92:95], v[4:7]
	v_mfma_f32_16x16x32_bf16 v[20:23], a[20:23], v[92:95], v[20:23]
	v_mfma_f32_16x16x32_bf16 v[36:39], a[24:27], v[92:95], v[36:39]
	v_mfma_f32_16x16x32_bf16 v[52:55], a[28:31], v[92:95], v[52:55]
	s_waitcnt lgkmcnt(1)
	v_mfma_f32_16x16x32_bf16 v[8:11], a[16:19], v[88:91], v[8:11]
	v_mfma_f32_16x16x32_bf16 v[24:27], a[20:23], v[88:91], v[24:27]
	v_mfma_f32_16x16x32_bf16 v[40:43], a[24:27], v[88:91], v[40:43]
	v_mfma_f32_16x16x32_bf16 v[56:59], a[28:31], v[88:91], v[56:59]
	s_waitcnt lgkmcnt(0)
	v_mfma_f32_16x16x32_bf16 v[12:15], a[16:19], v[84:87], v[12:15]
	v_mfma_f32_16x16x32_bf16 v[28:31], a[20:23], v[84:87], v[28:31]
	v_mfma_f32_16x16x32_bf16 v[44:47], a[24:27], v[84:87], v[44:47]
	v_mfma_f32_16x16x32_bf16 v[60:63], a[28:31], v[84:87], v[60:63]
	s_setprio 0
	v_readfirstlane_b32 s15, v107
	v_readfirstlane_b32 s4, v106
	s_lshl_b32 s15, s15, 6
	s_waitcnt lgkmcnt(0)
	s_barrier
	s_add_i32 s9, s15, s9
	s_lshl_b32 s15, s4, 17
	s_lshl_b32 s4, s8, 18
	s_add_i32 s15, s15, s4
	v_or_b32_e32 v64, s9, v108
	s_movk_i32 s4, 0x800
	v_cmp_gt_i32_e32 vcc, s4, v64
	s_barrier
	v_and_b32_e32 v124, 15, v143
	v_bfe_u32 v125, v143, 4, 2
	v_xor_b32_e32 v125, v125, v124
	v_lshlrev_b32_e32 v125, 4, v125
	v_lshl_add_u32 v125, v124, 8, v125
	v_lshrrev_b32_e32 v124, 6, v143
	v_lshl_add_u32 v125, v124, 14, v125
	ds_write_b128 v125, v[0:3]
	ds_write_b128 v125, v[4:7] offset:4096
	ds_write_b128 v125, v[8:11] offset:8192
	ds_write_b128 v125, v[12:15] offset:12288
	v_xor_b32_e32 v118, 64, v125
	ds_write_b128 v118, v[16:19]
	ds_write_b128 v118, v[20:23] offset:4096
	ds_write_b128 v118, v[24:27] offset:8192
	ds_write_b128 v118, v[28:31] offset:12288
	v_xor_b32_e32 v118, 128, v125
	ds_write_b128 v118, v[32:35]
	ds_write_b128 v118, v[36:39] offset:4096
	ds_write_b128 v118, v[40:43] offset:8192
	ds_write_b128 v118, v[44:47] offset:12288
	v_xor_b32_e32 v118, 192, v125
	ds_write_b128 v118, v[48:51]
	ds_write_b128 v118, v[52:55] offset:4096
	ds_write_b128 v118, v[56:59] offset:8192
	ds_write_b128 v118, v[60:63] offset:12288
	v_and_b32_e32 v115, 31, v143
	v_bfe_u32 v117, v143, 5, 1
	v_and_b32_e32 v125, 15, v115
	v_xor_b32_e32 v117, v117, v125
	v_lshlrev_b32_e32 v117, 4, v117
	v_lshl_add_u32 v117, v115, 8, v117
	v_lshl_add_u32 v117, v124, 14, v117
	ds_read_b128 v[48:51], v117
	ds_read_b128 v[32:35], v117 offset:8192
	v_xor_b32_e32 v116, 32, v117
	ds_read_b128 v[52:55], v116
	ds_read_b128 v[36:39], v116 offset:8192
	v_xor_b32_e32 v116, 64, v117
	ds_read_b128 v[56:59], v116
	ds_read_b128 v[40:43], v116 offset:8192
	v_xor_b32_e32 v116, 96, v117
	ds_read_b128 v[60:63], v116
	ds_read_b128 v[44:47], v116 offset:8192
	v_xor_b32_e32 v116, 128, v117
	ds_read_b128 v[16:19], v116
	ds_read_b128 v[0:3], v116 offset:8192
	v_xor_b32_e32 v116, 160, v117
	ds_read_b128 v[20:23], v116
	ds_read_b128 v[4:7], v116 offset:8192
	v_xor_b32_e32 v116, 192, v117
	ds_read_b128 v[24:27], v116
	ds_read_b128 v[8:11], v116 offset:8192
	v_xor_b32_e32 v116, 224, v117
	ds_read_b128 v[28:31], v116
	ds_read_b128 v[12:15], v116 offset:8192
	s_waitcnt lgkmcnt(0)
	s_barrier
	s_and_saveexec_b64 s[8:9], vcc
	s_cbranch_execz .LBB0_612
	v_add_u32_e32 v65, s15, v64
	v_add_u32_e32 v66, v65, v111
	v_mov_b32_e32 v67, v140
	v_lshl_add_u64 v[68:69], v[66:67], 2, s[26:27]
	global_store_dword v[68:69], v48, off
	v_add_u32_e32 v68, 0x800, v66
	v_mov_b32_e32 v69, v140
	v_lshl_add_u64 v[68:69], v[68:69], 2, s[26:27]
	global_store_dword v[68:69], v49, off
	v_add_u32_e32 v48, 0x1000, v66
	v_mov_b32_e32 v49, v140
	v_lshl_add_u64 v[48:49], v[48:49], 2, s[26:27]
	global_store_dword v[48:49], v50, off
	v_add_u32_e32 v48, 0x1800, v66
	v_mov_b32_e32 v49, v140
	v_lshl_add_u64 v[48:49], v[48:49], 2, s[26:27]
	global_store_dword v[48:49], v51, off
	v_add_u32_e32 v48, v65, v112
	v_mov_b32_e32 v49, v140
	v_lshl_add_u64 v[50:51], v[48:49], 2, s[26:27]
	global_store_dword v[50:51], v52, off
	v_add_u32_e32 v50, 0x800, v48
	v_mov_b32_e32 v51, v140
	v_lshl_add_u64 v[50:51], v[50:51], 2, s[26:27]
	global_store_dword v[50:51], v53, off
	v_add_u32_e32 v50, 0x1000, v48
	v_mov_b32_e32 v51, v140
	v_add_u32_e32 v48, 0x1800, v48
	v_lshl_add_u64 v[50:51], v[50:51], 2, s[26:27]
	v_lshl_add_u64 v[48:49], v[48:49], 2, s[26:27]
	global_store_dword v[50:51], v54, off
	global_store_dword v[48:49], v55, off
	v_add_u32_e32 v48, v65, v113
	v_mov_b32_e32 v49, v140
	v_lshl_add_u64 v[50:51], v[48:49], 2, s[26:27]
	global_store_dword v[50:51], v56, off
	v_add_u32_e32 v50, 0x800, v48
	v_mov_b32_e32 v51, v140
	v_lshl_add_u64 v[50:51], v[50:51], 2, s[26:27]
	global_store_dword v[50:51], v57, off
	v_add_u32_e32 v50, 0x1000, v48
	v_mov_b32_e32 v51, v140
	v_add_u32_e32 v48, 0x1800, v48
	v_lshl_add_u64 v[50:51], v[50:51], 2, s[26:27]
	v_lshl_add_u64 v[48:49], v[48:49], 2, s[26:27]
	global_store_dword v[50:51], v58, off
	global_store_dword v[48:49], v59, off
	v_add_u32_e32 v48, v65, v114
	v_mov_b32_e32 v49, v140
	v_lshl_add_u64 v[50:51], v[48:49], 2, s[26:27]
	global_store_dword v[50:51], v60, off
	v_add_u32_e32 v50, 0x800, v48
	v_mov_b32_e32 v51, v140
	v_lshl_add_u64 v[50:51], v[50:51], 2, s[26:27]
	global_store_dword v[50:51], v61, off
	v_add_u32_e32 v50, 0x1000, v48
	v_mov_b32_e32 v51, v140
	v_add_u32_e32 v48, 0x1800, v48
	v_lshl_add_u64 v[50:51], v[50:51], 2, s[26:27]
	v_lshl_add_u64 v[48:49], v[48:49], 2, s[26:27]
	global_store_dword v[50:51], v62, off
	global_store_dword v[48:49], v63, off

.LBB0_622:
	s_mul_hi_i32 s4, s30, 0x38e38e39
	s_lshr_b32 s8, s4, 31
	s_ashr_i32 s4, s4, 4
	s_add_i32 s4, s4, s8
	s_mul_i32 s8, s4, 0x48
	s_sub_i32 s8, s30, s8
	v_lshl_add_u32 v0, s8, 7, v109
	v_ashrrev_i32_e32 v1, 31, v0
	v_lshlrev_b64 v[32:33], 12, v[0:1]
	v_lshl_add_u64 v[34:35], v[96:97], 0, v[32:33]
	v_add_co_u32_e32 v40, vcc, s87, v34
	s_lshl_b32 s9, s4, 7
	s_nop 0
	v_addc_co_u32_e32 v41, vcc, 0, v35, vcc
	v_add_co_u32_e32 v42, vcc, s66, v34
	v_add_u32_e32 v0, s9, v109
	s_nop 0
	v_addc_co_u32_e32 v43, vcc, 0, v35, vcc
	v_ashrrev_i32_e32 v1, 31, v0
	v_add_co_u32_e32 v44, vcc, s20, v34
	v_lshlrev_b64 v[36:37], 12, v[0:1]
	s_nop 0
	v_addc_co_u32_e32 v45, vcc, 0, v35, vcc
	v_lshl_add_u64 v[38:39], v[98:99], 0, v[36:37]
	v_readfirstlane_b32 s100, v110
	s_nop 3
	s_add_u32 m0, s100, 0x0
	s_nop 0
	global_load_lds_dwordx4 v[34:35], off
	s_add_u32 m0, s100, 0x1000
	s_nop 0
	global_load_lds_dwordx4 v[40:41], off
	s_add_u32 m0, s100, 0x2000
	s_nop 0
	global_load_lds_dwordx4 v[42:43], off
	s_add_u32 m0, s100, 0x3000
	s_nop 0
	global_load_lds_dwordx4 v[44:45], off
	s_add_u32 m0, s100, 0x4000
	s_nop 0
	global_load_lds_dwordx4 v[38:39], off
	v_add_co_u32_e32 v46, vcc, s87, v38
	v_lshl_add_u64 v[102:103], v[100:101], 0, v[36:37]
	s_nop 0
	v_addc_co_u32_e32 v47, vcc, 0, v39, vcc
	s_waitcnt vmcnt(16)
	v_add_co_u32_e32 v48, vcc, s66, v38
	s_add_u32 m0, s100, 0x5000
	s_nop 0
	global_load_lds_dwordx4 v[46:47], off
	s_nop 0
	v_addc_co_u32_e32 v49, vcc, 0, v39, vcc
	v_add_co_u32_e32 v50, vcc, s20, v38
	s_add_u32 m0, s100, 0x6000
	s_nop 0
	global_load_lds_dwordx4 v[48:49], off
	s_nop 0
	v_addc_co_u32_e32 v51, vcc, 0, v39, vcc
	s_add_u32 m0, s100, 0x7000
	s_nop 0
	global_load_lds_dwordx4 v[50:51], off
	v_lshl_add_u64 v[104:105], v[100:101], 0, v[32:33]
	s_mov_b64 s[28:29], 0
	v_mov_b32_e32 v0, 0
	v_mov_b32_e32 v1, v0
	v_mov_b32_e32 v2, v0
	v_mov_b32_e32 v3, v0
	v_mov_b32_e32 v4, v0
	v_mov_b32_e32 v5, v0
	v_mov_b32_e32 v6, v0
	v_mov_b32_e32 v7, v0
	v_mov_b32_e32 v8, v0
	v_mov_b32_e32 v9, v0
	v_mov_b32_e32 v10, v0
	v_mov_b32_e32 v11, v0
	v_mov_b32_e32 v12, v0
	v_mov_b32_e32 v13, v0
	v_mov_b32_e32 v14, v0
	v_mov_b32_e32 v15, v0
	v_mov_b32_e32 v16, v0
	v_mov_b32_e32 v17, v0
	v_mov_b32_e32 v18, v0
	v_mov_b32_e32 v19, v0
	v_mov_b32_e32 v20, v0
	v_mov_b32_e32 v21, v0
	v_mov_b32_e32 v22, v0
	v_mov_b32_e32 v23, v0
	v_mov_b32_e32 v24, v0
	v_mov_b32_e32 v25, v0
	v_mov_b32_e32 v26, v0
	v_mov_b32_e32 v27, v0
	v_mov_b32_e32 v28, v0
	v_mov_b32_e32 v29, v0
	v_mov_b32_e32 v30, v0
	v_mov_b32_e32 v31, v0
	v_mov_b32_e32 v32, v0
	v_mov_b32_e32 v33, v0
	v_mov_b32_e32 v34, v0
	v_mov_b32_e32 v35, v0
	v_mov_b32_e32 v36, v0
	v_mov_b32_e32 v37, v0
	v_mov_b32_e32 v38, v0
	v_mov_b32_e32 v39, v0
	v_mov_b32_e32 v40, v0
	v_mov_b32_e32 v41, v0
	v_mov_b32_e32 v42, v0
	v_mov_b32_e32 v43, v0
	v_mov_b32_e32 v44, v0
	v_mov_b32_e32 v45, v0
	v_mov_b32_e32 v46, v0
	v_mov_b32_e32 v47, v0
	v_mov_b32_e32 v48, v0
	v_mov_b32_e32 v49, v0
	v_mov_b32_e32 v50, v0
	v_mov_b32_e32 v51, v0
	v_mov_b32_e32 v52, v0
	v_mov_b32_e32 v53, v0
	v_mov_b32_e32 v54, v0
	v_mov_b32_e32 v55, v0
	v_mov_b32_e32 v56, v0
	v_mov_b32_e32 v57, v0
	v_mov_b32_e32 v58, v0
	v_mov_b32_e32 v59, v0
	v_mov_b32_e32 v60, v0
	v_mov_b32_e32 v61, v0
	v_mov_b32_e32 v62, v0
	v_mov_b32_e32 v63, v0
	v_and_b32_e32 v120, 15, v143
	v_lshrrev_b32_e32 v121, 1, v120
	v_bfe_u32 v114, v143, 4, 2
	v_xor_b32_e32 v121, v121, v114
	v_lshlrev_b32_e32 v121, 4, v121
	v_lshl_add_u32 v121, v120, 7, v121
	v_lshrrev_b32_e32 v120, 6, v143
	v_lshrrev_b32_e32 v112, 1, v120
	v_and_b32_e32 v120, 1, v120
	v_lshl_add_u32 v112, v112, 13, v121
	v_lshl_add_u32 v113, v120, 13, v121
	v_add_u32_e32 v113, 0x4000, v113
	v_xor_b32_e32 v114, 64, v112
	v_xor_b32_e32 v115, 64, v113
	s_waitcnt vmcnt(0) lgkmcnt(0)
	s_barrier
.LBB0_623:
	v_lshl_add_u64 v[72:73], v[104:105], 0, s[28:29]
	s_mov_b32 s4, 0x17eb8000
	v_add_co_u32_e32 v132, vcc, s4, v72
	s_mov_b32 s4, 0x17ed8000
	s_nop 0
	v_addc_co_u32_e32 v133, vcc, 0, v73, vcc
	v_add_co_u32_e32 v134, vcc, s4, v72
	s_mov_b32 s4, 0x17ef8000
	s_nop 0
	v_addc_co_u32_e32 v135, vcc, 0, v73, vcc
	v_add_co_u32_e32 v144, vcc, s4, v72
	s_mov_b32 s4, 0x17f18000
	s_nop 0
	v_addc_co_u32_e32 v145, vcc, 0, v73, vcc
	v_add_co_u32_e32 v146, vcc, s4, v72
	v_lshl_add_u64 v[88:89], v[102:103], 0, s[28:29]
	s_nop 0
	v_addc_co_u32_e32 v147, vcc, 0, v73, vcc
	s_mov_b32 s4, 0x38b80000
	v_add_co_u32_e32 v148, vcc, s4, v88
	s_mov_b32 s4, 0x38ba0000
	s_nop 0
	v_addc_co_u32_e32 v149, vcc, 0, v89, vcc
	v_add_co_u32_e32 v150, vcc, s4, v88
	s_mov_b32 s4, 0x38bc0000
	s_nop 0
	v_addc_co_u32_e32 v151, vcc, 0, v89, vcc
	v_add_co_u32_e32 v152, vcc, s4, v88
	s_mov_b32 s4, 0x38be0000
	s_nop 0
	v_addc_co_u32_e32 v153, vcc, 0, v89, vcc
	v_add_co_u32_e32 v154, vcc, s4, v88
	v_addc_co_u32_e32 v155, vcc, 0, v89, vcc
	v_lshl_add_u64 v[132:133], 8, 4, v[132:133]
	v_lshl_add_u64 v[134:135], 8, 4, v[134:135]
	v_lshl_add_u64 v[144:145], 8, 4, v[144:145]
	v_lshl_add_u64 v[146:147], 8, 4, v[146:147]
	v_lshl_add_u64 v[148:149], 8, 4, v[148:149]
	v_lshl_add_u64 v[150:151], 8, 4, v[150:151]
	v_lshl_add_u64 v[152:153], 8, 4, v[152:153]
	v_lshl_add_u64 v[154:155], 8, 4, v[154:155]
	s_add_u32 m0, s100, 0x8000
	s_nop 0
	global_load_lds_dwordx4 v[132:133], off
	s_add_u32 m0, s100, 0x9000
	s_nop 0
	global_load_lds_dwordx4 v[134:135], off
	s_add_u32 m0, s100, 0xa000
	s_nop 0
	global_load_lds_dwordx4 v[144:145], off
	s_add_u32 m0, s100, 0xb000
	s_nop 0
	global_load_lds_dwordx4 v[146:147], off
	s_add_u32 m0, s100, 0xc000
	s_nop 0
	global_load_lds_dwordx4 v[148:149], off
	s_add_u32 m0, s100, 0xd000
	s_nop 0
	global_load_lds_dwordx4 v[150:151], off
	s_add_u32 m0, s100, 0xe000
	s_nop 0
	global_load_lds_dwordx4 v[152:153], off
	s_add_u32 m0, s100, 0xf000
	s_nop 0
	global_load_lds_dwordx4 v[154:155], off
	ds_read_b128 a[0:3], v112
	ds_read_b128 v[80:83], v113
	ds_read_b128 a[4:7], v112 offset:2048
	ds_read_b128 a[8:11], v112 offset:4096
	ds_read_b128 a[12:15], v112 offset:6144
	ds_read_b128 v[92:95], v113 offset:2048
	ds_read_b128 v[88:91], v113 offset:4096
	ds_read_b128 v[84:87], v113 offset:6144
	ds_read_b128 a[16:19], v114
	ds_read_b128 a[20:23], v114 offset:2048
	ds_read_b128 a[24:27], v114 offset:4096
	ds_read_b128 a[28:31], v114 offset:6144
	s_setprio 1
	s_waitcnt lgkmcnt(10)
	v_mfma_f32_16x16x32_bf16 v[0:3], a[0:3], v[80:83], v[0:3]
	s_waitcnt lgkmcnt(9)
	v_mfma_f32_16x16x32_bf16 v[16:19], a[4:7], v[80:83], v[16:19]
	s_waitcnt lgkmcnt(8)
	v_mfma_f32_16x16x32_bf16 v[32:35], a[8:11], v[80:83], v[32:35]
	s_waitcnt lgkmcnt(7)
	v_mfma_f32_16x16x32_bf16 v[48:51], a[12:15], v[80:83], v[48:51]
	ds_read_b128 v[80:83], v115
	s_waitcnt lgkmcnt(7)
	v_mfma_f32_16x16x32_bf16 v[4:7], a[0:3], v[92:95], v[4:7]
	v_mfma_f32_16x16x32_bf16 v[20:23], a[4:7], v[92:95], v[20:23]
	v_mfma_f32_16x16x32_bf16 v[36:39], a[8:11], v[92:95], v[36:39]
	v_mfma_f32_16x16x32_bf16 v[52:55], a[12:15], v[92:95], v[52:55]
	ds_read_b128 v[92:95], v115 offset:2048
	s_waitcnt lgkmcnt(7)
	v_mfma_f32_16x16x32_bf16 v[8:11], a[0:3], v[88:91], v[8:11]
	v_mfma_f32_16x16x32_bf16 v[24:27], a[4:7], v[88:91], v[24:27]
	v_mfma_f32_16x16x32_bf16 v[40:43], a[8:11], v[88:91], v[40:43]
	v_mfma_f32_16x16x32_bf16 v[56:59], a[12:15], v[88:91], v[56:59]
	ds_read_b128 v[88:91], v115 offset:4096
	s_waitcnt lgkmcnt(7)
	v_mfma_f32_16x16x32_bf16 v[12:15], a[0:3], v[84:87], v[12:15]
	v_mfma_f32_16x16x32_bf16 v[28:31], a[4:7], v[84:87], v[28:31]
	v_mfma_f32_16x16x32_bf16 v[44:47], a[8:11], v[84:87], v[44:47]
	v_mfma_f32_16x16x32_bf16 v[60:63], a[12:15], v[84:87], v[60:63]
	ds_read_b128 v[84:87], v115 offset:6144
	s_waitcnt lgkmcnt(3)
	v_mfma_f32_16x16x32_bf16 v[0:3], a[16:19], v[80:83], v[0:3]
	v_mfma_f32_16x16x32_bf16 v[16:19], a[20:23], v[80:83], v[16:19]
	v_mfma_f32_16x16x32_bf16 v[32:35], a[24:27], v[80:83], v[32:35]
	v_mfma_f32_16x16x32_bf16 v[48:51], a[28:31], v[80:83], v[48:51]
	s_waitcnt lgkmcnt(2)
	v_mfma_f32_16x16x32_bf16 v[4:7], a[16:19], v[92:95], v[4:7]
	v_mfma_f32_16x16x32_bf16 v[20:23], a[20:23], v[92:95], v[20:23]
	v_mfma_f32_16x16x32_bf16 v[36:39], a[24:27], v[92:95], v[36:39]
	v_mfma_f32_16x16x32_bf16 v[52:55], a[28:31], v[92:95], v[52:55]
	s_waitcnt lgkmcnt(1)
	v_mfma_f32_16x16x32_bf16 v[8:11], a[16:19], v[88:91], v[8:11]
	v_mfma_f32_16x16x32_bf16 v[24:27], a[20:23], v[88:91], v[24:27]
	v_mfma_f32_16x16x32_bf16 v[40:43], a[24:27], v[88:91], v[40:43]
	v_mfma_f32_16x16x32_bf16 v[56:59], a[28:31], v[88:91], v[56:59]
	s_waitcnt lgkmcnt(0)
	v_mfma_f32_16x16x32_bf16 v[12:15], a[16:19], v[84:87], v[12:15]
	v_mfma_f32_16x16x32_bf16 v[28:31], a[20:23], v[84:87], v[28:31]
	v_mfma_f32_16x16x32_bf16 v[44:47], a[24:27], v[84:87], v[44:47]
	v_mfma_f32_16x16x32_bf16 v[60:63], a[28:31], v[84:87], v[60:63]
	s_setprio 0
	s_waitcnt vmcnt(0) lgkmcnt(0)
	s_barrier
	v_lshl_add_u64 v[64:65], 8, 4, v[132:133]
	v_lshl_add_u64 v[66:67], 8, 4, v[134:135]
	v_lshl_add_u64 v[68:69], 8, 4, v[144:145]
	v_lshl_add_u64 v[70:71], 8, 4, v[146:147]
	v_lshl_add_u64 v[76:77], 8, 4, v[148:149]
	v_lshl_add_u64 v[78:79], 8, 4, v[150:151]
	v_lshl_add_u64 v[72:73], 8, 4, v[152:153]
	v_lshl_add_u64 v[74:75], 8, 4, v[154:155]
	s_add_u32 m0, s100, 0x0
	s_nop 0
	global_load_lds_dwordx4 v[64:65], off
	s_add_u32 m0, s100, 0x1000
	s_nop 0
	global_load_lds_dwordx4 v[66:67], off
	s_add_u32 m0, s100, 0x2000
	s_nop 0
	global_load_lds_dwordx4 v[68:69], off
	s_add_u32 m0, s100, 0x3000
	s_nop 0
	global_load_lds_dwordx4 v[70:71], off
	s_add_u32 m0, s100, 0x4000
	s_nop 0
	global_load_lds_dwordx4 v[76:77], off
	s_add_u32 m0, s100, 0x5000
	s_nop 0
	global_load_lds_dwordx4 v[78:79], off
	s_add_u32 m0, s100, 0x6000
	s_nop 0
	global_load_lds_dwordx4 v[72:73], off
	s_add_u32 m0, s100, 0x7000
	s_nop 0
	global_load_lds_dwordx4 v[74:75], off
	ds_read_b128 a[0:3], v112 offset:32768
	ds_read_b128 v[80:83], v113 offset:32768
	ds_read_b128 a[4:7], v112 offset:34816
	ds_read_b128 a[8:11], v112 offset:36864
	ds_read_b128 a[12:15], v112 offset:38912
	ds_read_b128 v[92:95], v113 offset:34816
	ds_read_b128 v[88:91], v113 offset:36864
	ds_read_b128 v[84:87], v113 offset:38912
	ds_read_b128 a[16:19], v114 offset:32768
	ds_read_b128 a[20:23], v114 offset:34816
	ds_read_b128 a[24:27], v114 offset:36864
	ds_read_b128 a[28:31], v114 offset:38912
	s_setprio 1
	s_waitcnt lgkmcnt(10)
	v_mfma_f32_16x16x32_bf16 v[0:3], a[0:3], v[80:83], v[0:3]
	s_waitcnt lgkmcnt(9)
	v_mfma_f32_16x16x32_bf16 v[16:19], a[4:7], v[80:83], v[16:19]
	s_waitcnt lgkmcnt(8)
	v_mfma_f32_16x16x32_bf16 v[32:35], a[8:11], v[80:83], v[32:35]
	s_waitcnt lgkmcnt(7)
	v_mfma_f32_16x16x32_bf16 v[48:51], a[12:15], v[80:83], v[48:51]
	ds_read_b128 v[80:83], v115 offset:32768
	s_waitcnt lgkmcnt(7)
	v_mfma_f32_16x16x32_bf16 v[4:7], a[0:3], v[92:95], v[4:7]
	v_mfma_f32_16x16x32_bf16 v[20:23], a[4:7], v[92:95], v[20:23]
	v_mfma_f32_16x16x32_bf16 v[36:39], a[8:11], v[92:95], v[36:39]
	v_mfma_f32_16x16x32_bf16 v[52:55], a[12:15], v[92:95], v[52:55]
	ds_read_b128 v[92:95], v115 offset:34816
	s_waitcnt lgkmcnt(7)
	v_mfma_f32_16x16x32_bf16 v[8:11], a[0:3], v[88:91], v[8:11]
	v_mfma_f32_16x16x32_bf16 v[24:27], a[4:7], v[88:91], v[24:27]
	v_mfma_f32_16x16x32_bf16 v[40:43], a[8:11], v[88:91], v[40:43]
	v_mfma_f32_16x16x32_bf16 v[56:59], a[12:15], v[88:91], v[56:59]
	ds_read_b128 v[88:91], v115 offset:36864
	s_waitcnt lgkmcnt(7)
	v_mfma_f32_16x16x32_bf16 v[12:15], a[0:3], v[84:87], v[12:15]
	v_mfma_f32_16x16x32_bf16 v[28:31], a[4:7], v[84:87], v[28:31]
	v_mfma_f32_16x16x32_bf16 v[44:47], a[8:11], v[84:87], v[44:47]
	v_mfma_f32_16x16x32_bf16 v[60:63], a[12:15], v[84:87], v[60:63]
	ds_read_b128 v[84:87], v115 offset:38912
	s_waitcnt lgkmcnt(3)
	v_mfma_f32_16x16x32_bf16 v[0:3], a[16:19], v[80:83], v[0:3]
	v_mfma_f32_16x16x32_bf16 v[16:19], a[20:23], v[80:83], v[16:19]
	v_mfma_f32_16x16x32_bf16 v[32:35], a[24:27], v[80:83], v[32:35]
	v_mfma_f32_16x16x32_bf16 v[48:51], a[28:31], v[80:83], v[48:51]
	s_waitcnt lgkmcnt(2)
	v_mfma_f32_16x16x32_bf16 v[4:7], a[16:19], v[92:95], v[4:7]
	v_mfma_f32_16x16x32_bf16 v[20:23], a[20:23], v[92:95], v[20:23]
	v_mfma_f32_16x16x32_bf16 v[36:39], a[24:27], v[92:95], v[36:39]
	v_mfma_f32_16x16x32_bf16 v[52:55], a[28:31], v[92:95], v[52:55]
	s_waitcnt lgkmcnt(1)
	v_mfma_f32_16x16x32_bf16 v[8:11], a[16:19], v[88:91], v[8:11]
	v_mfma_f32_16x16x32_bf16 v[24:27], a[20:23], v[88:91], v[24:27]
	v_mfma_f32_16x16x32_bf16 v[40:43], a[24:27], v[88:91], v[40:43]
	v_mfma_f32_16x16x32_bf16 v[56:59], a[28:31], v[88:91], v[56:59]
	s_waitcnt lgkmcnt(0)
	v_mfma_f32_16x16x32_bf16 v[12:15], a[16:19], v[84:87], v[12:15]
	v_mfma_f32_16x16x32_bf16 v[28:31], a[20:23], v[84:87], v[28:31]
	v_mfma_f32_16x16x32_bf16 v[44:47], a[24:27], v[84:87], v[44:47]
	v_mfma_f32_16x16x32_bf16 v[60:63], a[28:31], v[84:87], v[60:63]
	s_setprio 0
	s_waitcnt vmcnt(0) lgkmcnt(0)
	s_barrier
	s_add_u32 s28, s28, 0x100
	s_addc_u32 s29, s29, 0
	s_cmpk_eq_i32 s28, 0xf00
	s_cbranch_scc0 .LBB0_623
	v_lshl_add_u64 v[64:65], 8, 4, v[64:65]
	v_lshl_add_u64 v[66:67], 8, 4, v[66:67]
	v_lshl_add_u64 v[68:69], 8, 4, v[68:69]
	v_lshl_add_u64 v[70:71], 8, 4, v[70:71]
	v_lshl_add_u64 v[76:77], 8, 4, v[76:77]
	v_lshl_add_u64 v[78:79], 8, 4, v[78:79]
	v_lshl_add_u64 v[72:73], 8, 4, v[72:73]
	v_lshl_add_u64 v[74:75], 8, 4, v[74:75]
	s_add_u32 m0, s100, 0x8000
	s_nop 0
	global_load_lds_dwordx4 v[64:65], off
	s_add_u32 m0, s100, 0x9000
	s_nop 0
	global_load_lds_dwordx4 v[66:67], off
	s_add_u32 m0, s100, 0xa000
	s_nop 0
	global_load_lds_dwordx4 v[68:69], off
	s_add_u32 m0, s100, 0xb000
	s_nop 0
	global_load_lds_dwordx4 v[70:71], off
	s_add_u32 m0, s100, 0xc000
	s_nop 0
	global_load_lds_dwordx4 v[76:77], off
	s_add_u32 m0, s100, 0xd000
	s_nop 0
	global_load_lds_dwordx4 v[78:79], off
	s_add_u32 m0, s100, 0xe000
	s_nop 0
	global_load_lds_dwordx4 v[72:73], off
	s_add_u32 m0, s100, 0xf000
	s_nop 0
	global_load_lds_dwordx4 v[74:75], off
	ds_read_b128 a[0:3], v112
	ds_read_b128 v[80:83], v113
	ds_read_b128 a[4:7], v112 offset:2048
	ds_read_b128 a[8:11], v112 offset:4096
	ds_read_b128 a[12:15], v112 offset:6144
	ds_read_b128 v[92:95], v113 offset:2048
	ds_read_b128 v[88:91], v113 offset:4096
	ds_read_b128 v[84:87], v113 offset:6144
	ds_read_b128 a[16:19], v114
	ds_read_b128 a[20:23], v114 offset:2048
	ds_read_b128 a[24:27], v114 offset:4096
	ds_read_b128 a[28:31], v114 offset:6144
	s_setprio 1
	s_waitcnt lgkmcnt(10)
	v_mfma_f32_16x16x32_bf16 v[0:3], a[0:3], v[80:83], v[0:3]
	s_waitcnt lgkmcnt(9)
	v_mfma_f32_16x16x32_bf16 v[16:19], a[4:7], v[80:83], v[16:19]
	s_waitcnt lgkmcnt(8)
	v_mfma_f32_16x16x32_bf16 v[32:35], a[8:11], v[80:83], v[32:35]
	s_waitcnt lgkmcnt(7)
	v_mfma_f32_16x16x32_bf16 v[48:51], a[12:15], v[80:83], v[48:51]
	ds_read_b128 v[80:83], v115
	s_waitcnt lgkmcnt(7)
	v_mfma_f32_16x16x32_bf16 v[4:7], a[0:3], v[92:95], v[4:7]
	v_mfma_f32_16x16x32_bf16 v[20:23], a[4:7], v[92:95], v[20:23]
	v_mfma_f32_16x16x32_bf16 v[36:39], a[8:11], v[92:95], v[36:39]
	v_mfma_f32_16x16x32_bf16 v[52:55], a[12:15], v[92:95], v[52:55]
	ds_read_b128 v[92:95], v115 offset:2048
	s_waitcnt lgkmcnt(7)
	v_mfma_f32_16x16x32_bf16 v[8:11], a[0:3], v[88:91], v[8:11]
	v_mfma_f32_16x16x32_bf16 v[24:27], a[4:7], v[88:91], v[24:27]
	v_mfma_f32_16x16x32_bf16 v[40:43], a[8:11], v[88:91], v[40:43]
	v_mfma_f32_16x16x32_bf16 v[56:59], a[12:15], v[88:91], v[56:59]
	ds_read_b128 v[88:91], v115 offset:4096
	s_waitcnt lgkmcnt(7)
	v_mfma_f32_16x16x32_bf16 v[12:15], a[0:3], v[84:87], v[12:15]
	v_mfma_f32_16x16x32_bf16 v[28:31], a[4:7], v[84:87], v[28:31]
	v_mfma_f32_16x16x32_bf16 v[44:47], a[8:11], v[84:87], v[44:47]
	v_mfma_f32_16x16x32_bf16 v[60:63], a[12:15], v[84:87], v[60:63]
	ds_read_b128 v[84:87], v115 offset:6144
	s_waitcnt lgkmcnt(3)
	v_mfma_f32_16x16x32_bf16 v[0:3], a[16:19], v[80:83], v[0:3]
	v_mfma_f32_16x16x32_bf16 v[16:19], a[20:23], v[80:83], v[16:19]
	v_mfma_f32_16x16x32_bf16 v[32:35], a[24:27], v[80:83], v[32:35]
	v_mfma_f32_16x16x32_bf16 v[48:51], a[28:31], v[80:83], v[48:51]
	s_waitcnt lgkmcnt(2)
	v_mfma_f32_16x16x32_bf16 v[4:7], a[16:19], v[92:95], v[4:7]
	v_mfma_f32_16x16x32_bf16 v[20:23], a[20:23], v[92:95], v[20:23]
	v_mfma_f32_16x16x32_bf16 v[36:39], a[24:27], v[92:95], v[36:39]
	v_mfma_f32_16x16x32_bf16 v[52:55], a[28:31], v[92:95], v[52:55]
	s_waitcnt lgkmcnt(1)
	v_mfma_f32_16x16x32_bf16 v[8:11], a[16:19], v[88:91], v[8:11]
	v_mfma_f32_16x16x32_bf16 v[24:27], a[20:23], v[88:91], v[24:27]
	v_mfma_f32_16x16x32_bf16 v[40:43], a[24:27], v[88:91], v[40:43]
	v_mfma_f32_16x16x32_bf16 v[56:59], a[28:31], v[88:91], v[56:59]
	s_waitcnt lgkmcnt(0)
	v_mfma_f32_16x16x32_bf16 v[12:15], a[16:19], v[84:87], v[12:15]
	v_mfma_f32_16x16x32_bf16 v[28:31], a[20:23], v[84:87], v[28:31]
	v_mfma_f32_16x16x32_bf16 v[44:47], a[24:27], v[84:87], v[44:47]
	v_mfma_f32_16x16x32_bf16 v[60:63], a[28:31], v[84:87], v[60:63]
	s_setprio 0
	s_waitcnt vmcnt(0) lgkmcnt(0)
	s_barrier
	ds_read_b128 a[0:3], v112 offset:32768
	ds_read_b128 v[80:83], v113 offset:32768
	ds_read_b128 a[4:7], v112 offset:34816
	ds_read_b128 a[8:11], v112 offset:36864
	ds_read_b128 a[12:15], v112 offset:38912
	ds_read_b128 v[92:95], v113 offset:34816
	ds_read_b128 v[88:91], v113 offset:36864
	ds_read_b128 v[84:87], v113 offset:38912
	ds_read_b128 a[16:19], v114 offset:32768
	ds_read_b128 a[20:23], v114 offset:34816
	ds_read_b128 a[24:27], v114 offset:36864
	ds_read_b128 a[28:31], v114 offset:38912
	s_setprio 1
	s_waitcnt lgkmcnt(10)
	v_mfma_f32_16x16x32_bf16 v[0:3], a[0:3], v[80:83], v[0:3]
	s_waitcnt lgkmcnt(9)
	v_mfma_f32_16x16x32_bf16 v[16:19], a[4:7], v[80:83], v[16:19]
	s_waitcnt lgkmcnt(8)
	v_mfma_f32_16x16x32_bf16 v[32:35], a[8:11], v[80:83], v[32:35]
	s_waitcnt lgkmcnt(7)
	v_mfma_f32_16x16x32_bf16 v[48:51], a[12:15], v[80:83], v[48:51]
	ds_read_b128 v[80:83], v115 offset:32768
	s_waitcnt lgkmcnt(7)
	v_mfma_f32_16x16x32_bf16 v[4:7], a[0:3], v[92:95], v[4:7]
	v_mfma_f32_16x16x32_bf16 v[20:23], a[4:7], v[92:95], v[20:23]
	v_mfma_f32_16x16x32_bf16 v[36:39], a[8:11], v[92:95], v[36:39]
	v_mfma_f32_16x16x32_bf16 v[52:55], a[12:15], v[92:95], v[52:55]
	ds_read_b128 v[92:95], v115 offset:34816
	s_waitcnt lgkmcnt(7)
	v_mfma_f32_16x16x32_bf16 v[8:11], a[0:3], v[88:91], v[8:11]
	v_mfma_f32_16x16x32_bf16 v[24:27], a[4:7], v[88:91], v[24:27]
	v_mfma_f32_16x16x32_bf16 v[40:43], a[8:11], v[88:91], v[40:43]
	v_mfma_f32_16x16x32_bf16 v[56:59], a[12:15], v[88:91], v[56:59]
	ds_read_b128 v[88:91], v115 offset:36864
	s_waitcnt lgkmcnt(7)
	v_mfma_f32_16x16x32_bf16 v[12:15], a[0:3], v[84:87], v[12:15]
	v_mfma_f32_16x16x32_bf16 v[28:31], a[4:7], v[84:87], v[28:31]
	v_mfma_f32_16x16x32_bf16 v[44:47], a[8:11], v[84:87], v[44:47]
	v_mfma_f32_16x16x32_bf16 v[60:63], a[12:15], v[84:87], v[60:63]
	ds_read_b128 v[84:87], v115 offset:38912
	s_waitcnt lgkmcnt(3)
	v_mfma_f32_16x16x32_bf16 v[0:3], a[16:19], v[80:83], v[0:3]
	v_mfma_f32_16x16x32_bf16 v[16:19], a[20:23], v[80:83], v[16:19]
	v_mfma_f32_16x16x32_bf16 v[32:35], a[24:27], v[80:83], v[32:35]
	v_mfma_f32_16x16x32_bf16 v[48:51], a[28:31], v[80:83], v[48:51]
	s_waitcnt lgkmcnt(2)
	v_mfma_f32_16x16x32_bf16 v[4:7], a[16:19], v[92:95], v[4:7]
	v_mfma_f32_16x16x32_bf16 v[20:23], a[20:23], v[92:95], v[20:23]
	v_mfma_f32_16x16x32_bf16 v[36:39], a[24:27], v[92:95], v[36:39]
	v_mfma_f32_16x16x32_bf16 v[52:55], a[28:31], v[92:95], v[52:55]
	s_waitcnt lgkmcnt(1)
	v_mfma_f32_16x16x32_bf16 v[8:11], a[16:19], v[88:91], v[8:11]
	v_mfma_f32_16x16x32_bf16 v[24:27], a[20:23], v[88:91], v[24:27]
	v_mfma_f32_16x16x32_bf16 v[40:43], a[24:27], v[88:91], v[40:43]
	v_mfma_f32_16x16x32_bf16 v[56:59], a[28:31], v[88:91], v[56:59]
	s_waitcnt lgkmcnt(0)
	v_mfma_f32_16x16x32_bf16 v[12:15], a[16:19], v[84:87], v[12:15]
	v_mfma_f32_16x16x32_bf16 v[28:31], a[20:23], v[84:87], v[28:31]
	v_mfma_f32_16x16x32_bf16 v[44:47], a[24:27], v[84:87], v[44:47]
	v_mfma_f32_16x16x32_bf16 v[60:63], a[28:31], v[84:87], v[60:63]
	s_setprio 0
	v_readfirstlane_b32 s15, v107
	v_readfirstlane_b32 s4, v106
	s_lshl_b32 s15, s15, 6
	s_waitcnt lgkmcnt(0)
	s_barrier
	s_add_i32 s15, s15, s9
	s_lshl_b32 s31, s4, 13
	s_lshl_b32 s4, s8, 14
	s_add_i32 s31, s31, s4
	v_or_b32_e32 v64, s15, v108
	s_movk_i32 s4, 0x80
	v_cmp_gt_i32_e32 vcc, s4, v64
	s_barrier
	v_and_b32_e32 v120, 15, v143
	v_bfe_u32 v121, v143, 4, 2
	v_xor_b32_e32 v121, v121, v120
	v_lshlrev_b32_e32 v121, 4, v121
	v_lshl_add_u32 v121, v120, 8, v121
	v_lshrrev_b32_e32 v120, 6, v143
	v_lshl_add_u32 v121, v120, 14, v121
	ds_write_b128 v121, v[0:3]
	ds_write_b128 v121, v[4:7] offset:4096
	ds_write_b128 v121, v[8:11] offset:8192
	ds_write_b128 v121, v[12:15] offset:12288
	v_xor_b32_e32 v115, 64, v121
	ds_write_b128 v115, v[16:19]
	ds_write_b128 v115, v[20:23] offset:4096
	ds_write_b128 v115, v[24:27] offset:8192
	ds_write_b128 v115, v[28:31] offset:12288
	v_xor_b32_e32 v115, 128, v121
	ds_write_b128 v115, v[32:35]
	ds_write_b128 v115, v[36:39] offset:4096
	ds_write_b128 v115, v[40:43] offset:8192
	ds_write_b128 v115, v[44:47] offset:12288
	v_xor_b32_e32 v115, 192, v121
	ds_write_b128 v115, v[48:51]
	ds_write_b128 v115, v[52:55] offset:4096
	ds_write_b128 v115, v[56:59] offset:8192
	ds_write_b128 v115, v[60:63] offset:12288
	v_and_b32_e32 v112, 31, v143
	v_bfe_u32 v114, v143, 5, 1
	v_and_b32_e32 v121, 15, v112
	v_xor_b32_e32 v114, v114, v121
	v_lshlrev_b32_e32 v114, 4, v114
	v_lshl_add_u32 v114, v112, 8, v114
	v_lshl_add_u32 v114, v120, 14, v114
	ds_read_b128 v[48:51], v114
	ds_read_b128 v[32:35], v114 offset:8192
	v_xor_b32_e32 v113, 32, v114
	ds_read_b128 v[52:55], v113
	ds_read_b128 v[36:39], v113 offset:8192
	v_xor_b32_e32 v113, 64, v114
	ds_read_b128 v[56:59], v113
	ds_read_b128 v[40:43], v113 offset:8192
	v_xor_b32_e32 v113, 96, v114
	ds_read_b128 v[60:63], v113
	ds_read_b128 v[44:47], v113 offset:8192
	v_xor_b32_e32 v113, 128, v114
	ds_read_b128 v[16:19], v113
	ds_read_b128 v[0:3], v113 offset:8192
	v_xor_b32_e32 v113, 160, v114
	ds_read_b128 v[20:23], v113
	ds_read_b128 v[4:7], v113 offset:8192
	v_xor_b32_e32 v113, 192, v114
	ds_read_b128 v[24:27], v113
	ds_read_b128 v[8:11], v113 offset:8192
	v_xor_b32_e32 v113, 224, v114
	ds_read_b128 v[28:31], v113
	ds_read_b128 v[12:15], v113 offset:8192
	s_waitcnt lgkmcnt(0)
	s_barrier
	s_and_saveexec_b64 s[28:29], vcc
	s_cbranch_execz .LBB0_690
	v_cmp_nlt_f32_e64 s[8:9], |v48|, s56
	s_and_saveexec_b64 s[22:23], s[8:9]
	s_xor_b64 s[8:9], exec, s[22:23]
	s_cbranch_execz .LBB0_627
	v_add_f32_e64 v65, |v48|, |v48|
	v_mul_f32_e32 v66, 0x3fb8aa3b, v65
	v_rndne_f32_e32 v67, v66
	v_sub_f32_e32 v68, v66, v67
	v_fma_f32 v66, v65, s67, -v66
	v_fmac_f32_e32 v66, 0x32a5705f, v65
	v_add_f32_e32 v66, v68, v66
	v_cvt_i32_f32_e32 v67, v67
	v_exp_f32_e32 v66, v66
	v_cmp_ngt_f32_e64 s[38:39], s57, v65
	v_ldexp_f32 v66, v66, v67
	s_nop 0
	v_cndmask_b32_e64 v66, 0, v66, s[38:39]
	v_cmp_nlt_f32_e64 s[38:39], s58, v65
	s_nop 1
	v_cndmask_b32_e64 v65, v172, v66, s[38:39]
	v_add_f32_e32 v65, 1.0, v65
	v_rcp_f32_e32 v65, v65
	s_nop 0
	v_fma_f32 v65, v65, -2.0, 1.0

.LBB0_891:
	v_lshl_add_u64 v[72:73], v[104:105], 0, s[28:29]
	s_mov_b32 s4, 0x1eab8000
	v_add_co_u32_e32 v144, vcc, s4, v72
	s_mov_b32 s4, 0x1ead8000
	s_nop 0
	v_addc_co_u32_e32 v145, vcc, 0, v73, vcc
	v_add_co_u32_e32 v146, vcc, s4, v72
	s_mov_b32 s4, 0x1eaf8000
	s_nop 0
	v_addc_co_u32_e32 v147, vcc, 0, v73, vcc
	v_add_co_u32_e32 v148, vcc, s4, v72
	s_mov_b32 s4, 0x1eb18000
	s_nop 0
	v_addc_co_u32_e32 v149, vcc, 0, v73, vcc
	v_add_co_u32_e32 v150, vcc, s4, v72
	v_lshl_add_u64 v[88:89], v[102:103], 0, s[28:29]
	s_nop 0
	v_addc_co_u32_e32 v151, vcc, 0, v73, vcc
	s_mov_b32 s4, 0x38c00000
	v_add_co_u32_e32 v152, vcc, s4, v88
	s_mov_b32 s4, 0x38c20000
	s_nop 0
	v_addc_co_u32_e32 v153, vcc, 0, v89, vcc
	v_add_co_u32_e32 v154, vcc, s4, v88
	s_mov_b32 s4, 0x38c40000
	s_nop 0
	v_addc_co_u32_e32 v155, vcc, 0, v89, vcc
	v_add_co_u32_e32 v156, vcc, s4, v88
	s_mov_b32 s4, 0x38c60000
	s_nop 0
	v_addc_co_u32_e32 v157, vcc, 0, v89, vcc
	v_add_co_u32_e32 v178, vcc, s4, v88
	v_addc_co_u32_e32 v179, vcc, 0, v89, vcc
	v_lshl_add_u64 v[144:145], 8, 4, v[144:145]
	v_lshl_add_u64 v[146:147], 8, 4, v[146:147]
	v_lshl_add_u64 v[148:149], 8, 4, v[148:149]
	v_lshl_add_u64 v[150:151], 8, 4, v[150:151]
	v_lshl_add_u64 v[152:153], 8, 4, v[152:153]
	v_lshl_add_u64 v[154:155], 8, 4, v[154:155]
	v_lshl_add_u64 v[156:157], 8, 4, v[156:157]
	v_lshl_add_u64 v[178:179], 8, 4, v[178:179]
	s_add_u32 m0, s100, 0x8000
	s_nop 0
	global_load_lds_dwordx4 v[144:145], off
	s_add_u32 m0, s100, 0x9000
	s_nop 0
	global_load_lds_dwordx4 v[146:147], off
	s_add_u32 m0, s100, 0xa000
	s_nop 0
	global_load_lds_dwordx4 v[148:149], off
	s_add_u32 m0, s100, 0xb000
	s_nop 0
	global_load_lds_dwordx4 v[150:151], off
	s_add_u32 m0, s100, 0xc000
	s_nop 0
	global_load_lds_dwordx4 v[152:153], off
	s_add_u32 m0, s100, 0xd000
	s_nop 0
	global_load_lds_dwordx4 v[154:155], off
	s_add_u32 m0, s100, 0xe000
	s_nop 0
	global_load_lds_dwordx4 v[156:157], off
	s_add_u32 m0, s100, 0xf000
	s_nop 0
	global_load_lds_dwordx4 v[178:179], off
	ds_read_b128 a[0:3], v115
	ds_read_b128 v[80:83], v116
	ds_read_b128 a[4:7], v115 offset:2048
	ds_read_b128 a[8:11], v115 offset:4096
	ds_read_b128 a[12:15], v115 offset:6144
	ds_read_b128 v[92:95], v116 offset:2048
	ds_read_b128 v[88:91], v116 offset:4096
	ds_read_b128 v[84:87], v116 offset:6144
	ds_read_b128 a[16:19], v117
	ds_read_b128 a[20:23], v117 offset:2048
	ds_read_b128 a[24:27], v117 offset:4096
	ds_read_b128 a[28:31], v117 offset:6144
	s_setprio 1
	s_waitcnt lgkmcnt(10)
	v_mfma_f32_16x16x32_bf16 v[0:3], a[0:3], v[80:83], v[0:3]
	s_waitcnt lgkmcnt(9)
	v_mfma_f32_16x16x32_bf16 v[16:19], a[4:7], v[80:83], v[16:19]
	s_waitcnt lgkmcnt(8)
	v_mfma_f32_16x16x32_bf16 v[32:35], a[8:11], v[80:83], v[32:35]
	s_waitcnt lgkmcnt(7)
	v_mfma_f32_16x16x32_bf16 v[48:51], a[12:15], v[80:83], v[48:51]
	ds_read_b128 v[80:83], v118
	s_waitcnt lgkmcnt(7)
	v_mfma_f32_16x16x32_bf16 v[4:7], a[0:3], v[92:95], v[4:7]
	v_mfma_f32_16x16x32_bf16 v[20:23], a[4:7], v[92:95], v[20:23]
	v_mfma_f32_16x16x32_bf16 v[36:39], a[8:11], v[92:95], v[36:39]
	v_mfma_f32_16x16x32_bf16 v[52:55], a[12:15], v[92:95], v[52:55]
	ds_read_b128 v[92:95], v118 offset:2048
	s_waitcnt lgkmcnt(7)
	v_mfma_f32_16x16x32_bf16 v[8:11], a[0:3], v[88:91], v[8:11]
	v_mfma_f32_16x16x32_bf16 v[24:27], a[4:7], v[88:91], v[24:27]
	v_mfma_f32_16x16x32_bf16 v[40:43], a[8:11], v[88:91], v[40:43]
	v_mfma_f32_16x16x32_bf16 v[56:59], a[12:15], v[88:91], v[56:59]
	ds_read_b128 v[88:91], v118 offset:4096
	s_waitcnt lgkmcnt(7)
	v_mfma_f32_16x16x32_bf16 v[12:15], a[0:3], v[84:87], v[12:15]
	v_mfma_f32_16x16x32_bf16 v[28:31], a[4:7], v[84:87], v[28:31]
	v_mfma_f32_16x16x32_bf16 v[44:47], a[8:11], v[84:87], v[44:47]
	v_mfma_f32_16x16x32_bf16 v[60:63], a[12:15], v[84:87], v[60:63]
	ds_read_b128 v[84:87], v118 offset:6144
	s_waitcnt lgkmcnt(3)
	v_mfma_f32_16x16x32_bf16 v[0:3], a[16:19], v[80:83], v[0:3]
	v_mfma_f32_16x16x32_bf16 v[16:19], a[20:23], v[80:83], v[16:19]
	v_mfma_f32_16x16x32_bf16 v[32:35], a[24:27], v[80:83], v[32:35]
	v_mfma_f32_16x16x32_bf16 v[48:51], a[28:31], v[80:83], v[48:51]
	s_waitcnt lgkmcnt(2)
	v_mfma_f32_16x16x32_bf16 v[4:7], a[16:19], v[92:95], v[4:7]
	v_mfma_f32_16x16x32_bf16 v[20:23], a[20:23], v[92:95], v[20:23]
	v_mfma_f32_16x16x32_bf16 v[36:39], a[24:27], v[92:95], v[36:39]
	v_mfma_f32_16x16x32_bf16 v[52:55], a[28:31], v[92:95], v[52:55]
	s_waitcnt lgkmcnt(1)
	v_mfma_f32_16x16x32_bf16 v[8:11], a[16:19], v[88:91], v[8:11]
	v_mfma_f32_16x16x32_bf16 v[24:27], a[20:23], v[88:91], v[24:27]
	v_mfma_f32_16x16x32_bf16 v[40:43], a[24:27], v[88:91], v[40:43]
	v_mfma_f32_16x16x32_bf16 v[56:59], a[28:31], v[88:91], v[56:59]
	s_waitcnt lgkmcnt(0)
	v_mfma_f32_16x16x32_bf16 v[12:15], a[16:19], v[84:87], v[12:15]
	v_mfma_f32_16x16x32_bf16 v[28:31], a[20:23], v[84:87], v[28:31]
	v_mfma_f32_16x16x32_bf16 v[44:47], a[24:27], v[84:87], v[44:47]
	v_mfma_f32_16x16x32_bf16 v[60:63], a[28:31], v[84:87], v[60:63]
	s_setprio 0
	s_waitcnt vmcnt(0) lgkmcnt(0)
	s_barrier
	v_lshl_add_u64 v[64:65], 8, 4, v[144:145]
	v_lshl_add_u64 v[66:67], 8, 4, v[146:147]
	v_lshl_add_u64 v[68:69], 8, 4, v[148:149]
	v_lshl_add_u64 v[70:71], 8, 4, v[150:151]
	v_lshl_add_u64 v[76:77], 8, 4, v[152:153]
	v_lshl_add_u64 v[78:79], 8, 4, v[154:155]
	v_lshl_add_u64 v[72:73], 8, 4, v[156:157]
	v_lshl_add_u64 v[74:75], 8, 4, v[178:179]
	s_add_u32 m0, s100, 0x0
	s_nop 0
	global_load_lds_dwordx4 v[64:65], off
	s_add_u32 m0, s100, 0x1000
	s_nop 0
	global_load_lds_dwordx4 v[66:67], off
	s_add_u32 m0, s100, 0x2000
	s_nop 0
	global_load_lds_dwordx4 v[68:69], off
	s_add_u32 m0, s100, 0x3000
	s_nop 0
	global_load_lds_dwordx4 v[70:71], off
	s_add_u32 m0, s100, 0x4000
	s_nop 0
	global_load_lds_dwordx4 v[76:77], off
	s_add_u32 m0, s100, 0x5000
	s_nop 0
	global_load_lds_dwordx4 v[78:79], off
	s_add_u32 m0, s100, 0x6000
	s_nop 0
	global_load_lds_dwordx4 v[72:73], off
	s_add_u32 m0, s100, 0x7000
	s_nop 0
	global_load_lds_dwordx4 v[74:75], off
	ds_read_b128 a[0:3], v115 offset:32768
	ds_read_b128 v[80:83], v116 offset:32768
	ds_read_b128 a[4:7], v115 offset:34816
	ds_read_b128 a[8:11], v115 offset:36864
	ds_read_b128 a[12:15], v115 offset:38912
	ds_read_b128 v[92:95], v116 offset:34816
	ds_read_b128 v[88:91], v116 offset:36864
	ds_read_b128 v[84:87], v116 offset:38912
	ds_read_b128 a[16:19], v117 offset:32768
	ds_read_b128 a[20:23], v117 offset:34816
	ds_read_b128 a[24:27], v117 offset:36864
	ds_read_b128 a[28:31], v117 offset:38912
	s_setprio 1
	s_waitcnt lgkmcnt(10)
	v_mfma_f32_16x16x32_bf16 v[0:3], a[0:3], v[80:83], v[0:3]
	s_waitcnt lgkmcnt(9)
	v_mfma_f32_16x16x32_bf16 v[16:19], a[4:7], v[80:83], v[16:19]
	s_waitcnt lgkmcnt(8)
	v_mfma_f32_16x16x32_bf16 v[32:35], a[8:11], v[80:83], v[32:35]
	s_waitcnt lgkmcnt(7)
	v_mfma_f32_16x16x32_bf16 v[48:51], a[12:15], v[80:83], v[48:51]
	ds_read_b128 v[80:83], v118 offset:32768
	s_waitcnt lgkmcnt(7)
	v_mfma_f32_16x16x32_bf16 v[4:7], a[0:3], v[92:95], v[4:7]
	v_mfma_f32_16x16x32_bf16 v[20:23], a[4:7], v[92:95], v[20:23]
	v_mfma_f32_16x16x32_bf16 v[36:39], a[8:11], v[92:95], v[36:39]
	v_mfma_f32_16x16x32_bf16 v[52:55], a[12:15], v[92:95], v[52:55]
	ds_read_b128 v[92:95], v118 offset:34816
	s_waitcnt lgkmcnt(7)
	v_mfma_f32_16x16x32_bf16 v[8:11], a[0:3], v[88:91], v[8:11]
	v_mfma_f32_16x16x32_bf16 v[24:27], a[4:7], v[88:91], v[24:27]
	v_mfma_f32_16x16x32_bf16 v[40:43], a[8:11], v[88:91], v[40:43]
	v_mfma_f32_16x16x32_bf16 v[56:59], a[12:15], v[88:91], v[56:59]
	ds_read_b128 v[88:91], v118 offset:36864
	s_waitcnt lgkmcnt(7)
	v_mfma_f32_16x16x32_bf16 v[12:15], a[0:3], v[84:87], v[12:15]
	v_mfma_f32_16x16x32_bf16 v[28:31], a[4:7], v[84:87], v[28:31]
	v_mfma_f32_16x16x32_bf16 v[44:47], a[8:11], v[84:87], v[44:47]
	v_mfma_f32_16x16x32_bf16 v[60:63], a[12:15], v[84:87], v[60:63]
	ds_read_b128 v[84:87], v118 offset:38912
	s_waitcnt lgkmcnt(3)
	v_mfma_f32_16x16x32_bf16 v[0:3], a[16:19], v[80:83], v[0:3]
	v_mfma_f32_16x16x32_bf16 v[16:19], a[20:23], v[80:83], v[16:19]
	v_mfma_f32_16x16x32_bf16 v[32:35], a[24:27], v[80:83], v[32:35]
	v_mfma_f32_16x16x32_bf16 v[48:51], a[28:31], v[80:83], v[48:51]
	s_waitcnt lgkmcnt(2)
	v_mfma_f32_16x16x32_bf16 v[4:7], a[16:19], v[92:95], v[4:7]
	v_mfma_f32_16x16x32_bf16 v[20:23], a[20:23], v[92:95], v[20:23]
	v_mfma_f32_16x16x32_bf16 v[36:39], a[24:27], v[92:95], v[36:39]
	v_mfma_f32_16x16x32_bf16 v[52:55], a[28:31], v[92:95], v[52:55]
	s_waitcnt lgkmcnt(1)
	v_mfma_f32_16x16x32_bf16 v[8:11], a[16:19], v[88:91], v[8:11]
	v_mfma_f32_16x16x32_bf16 v[24:27], a[20:23], v[88:91], v[24:27]
	v_mfma_f32_16x16x32_bf16 v[40:43], a[24:27], v[88:91], v[40:43]
	v_mfma_f32_16x16x32_bf16 v[56:59], a[28:31], v[88:91], v[56:59]
	s_waitcnt lgkmcnt(0)
	v_mfma_f32_16x16x32_bf16 v[12:15], a[16:19], v[84:87], v[12:15]
	v_mfma_f32_16x16x32_bf16 v[28:31], a[20:23], v[84:87], v[28:31]
	v_mfma_f32_16x16x32_bf16 v[44:47], a[24:27], v[84:87], v[44:47]
	v_mfma_f32_16x16x32_bf16 v[60:63], a[28:31], v[84:87], v[60:63]
	s_setprio 0
	s_waitcnt vmcnt(0) lgkmcnt(0)
	s_barrier
	s_add_u32 s28, s28, 0x100
	s_addc_u32 s29, s29, 0
	s_cmpk_eq_i32 s28, 0xf00
	s_cbranch_scc0 .LBB0_891
	v_lshl_add_u64 v[64:65], 8, 4, v[64:65]
	v_lshl_add_u64 v[66:67], 8, 4, v[66:67]
	v_lshl_add_u64 v[68:69], 8, 4, v[68:69]
	v_lshl_add_u64 v[70:71], 8, 4, v[70:71]
	v_lshl_add_u64 v[76:77], 8, 4, v[76:77]
	v_lshl_add_u64 v[78:79], 8, 4, v[78:79]
	v_lshl_add_u64 v[72:73], 8, 4, v[72:73]
	v_lshl_add_u64 v[74:75], 8, 4, v[74:75]
	s_add_u32 m0, s100, 0x8000
	s_nop 0
	global_load_lds_dwordx4 v[64:65], off
	s_add_u32 m0, s100, 0x9000
	s_nop 0
	global_load_lds_dwordx4 v[66:67], off
	s_add_u32 m0, s100, 0xa000
	s_nop 0
	global_load_lds_dwordx4 v[68:69], off
	s_add_u32 m0, s100, 0xb000
	s_nop 0
	global_load_lds_dwordx4 v[70:71], off
	s_add_u32 m0, s100, 0xc000
	s_nop 0
	global_load_lds_dwordx4 v[76:77], off
	s_add_u32 m0, s100, 0xd000
	s_nop 0
	global_load_lds_dwordx4 v[78:79], off
	s_add_u32 m0, s100, 0xe000
	s_nop 0
	global_load_lds_dwordx4 v[72:73], off
	s_add_u32 m0, s100, 0xf000
	s_nop 0
	global_load_lds_dwordx4 v[74:75], off
	ds_read_b128 a[0:3], v115
	ds_read_b128 v[80:83], v116
	ds_read_b128 a[4:7], v115 offset:2048
	ds_read_b128 a[8:11], v115 offset:4096
	ds_read_b128 a[12:15], v115 offset:6144
	ds_read_b128 v[92:95], v116 offset:2048
	ds_read_b128 v[88:91], v116 offset:4096
	ds_read_b128 v[84:87], v116 offset:6144
	ds_read_b128 a[16:19], v117
	ds_read_b128 a[20:23], v117 offset:2048
	ds_read_b128 a[24:27], v117 offset:4096
	ds_read_b128 a[28:31], v117 offset:6144
	s_setprio 1
	s_waitcnt lgkmcnt(10)
	v_mfma_f32_16x16x32_bf16 v[0:3], a[0:3], v[80:83], v[0:3]
	s_waitcnt lgkmcnt(9)
	v_mfma_f32_16x16x32_bf16 v[16:19], a[4:7], v[80:83], v[16:19]
	s_waitcnt lgkmcnt(8)
	v_mfma_f32_16x16x32_bf16 v[32:35], a[8:11], v[80:83], v[32:35]
	s_waitcnt lgkmcnt(7)
	v_mfma_f32_16x16x32_bf16 v[48:51], a[12:15], v[80:83], v[48:51]
	ds_read_b128 v[80:83], v118
	s_waitcnt lgkmcnt(7)
	v_mfma_f32_16x16x32_bf16 v[4:7], a[0:3], v[92:95], v[4:7]
	v_mfma_f32_16x16x32_bf16 v[20:23], a[4:7], v[92:95], v[20:23]
	v_mfma_f32_16x16x32_bf16 v[36:39], a[8:11], v[92:95], v[36:39]
	v_mfma_f32_16x16x32_bf16 v[52:55], a[12:15], v[92:95], v[52:55]
	ds_read_b128 v[92:95], v118 offset:2048
	s_waitcnt lgkmcnt(7)
	v_mfma_f32_16x16x32_bf16 v[8:11], a[0:3], v[88:91], v[8:11]
	v_mfma_f32_16x16x32_bf16 v[24:27], a[4:7], v[88:91], v[24:27]
	v_mfma_f32_16x16x32_bf16 v[40:43], a[8:11], v[88:91], v[40:43]
	v_mfma_f32_16x16x32_bf16 v[56:59], a[12:15], v[88:91], v[56:59]
	ds_read_b128 v[88:91], v118 offset:4096
	s_waitcnt lgkmcnt(7)
	v_mfma_f32_16x16x32_bf16 v[12:15], a[0:3], v[84:87], v[12:15]
	v_mfma_f32_16x16x32_bf16 v[28:31], a[4:7], v[84:87], v[28:31]
	v_mfma_f32_16x16x32_bf16 v[44:47], a[8:11], v[84:87], v[44:47]
	v_mfma_f32_16x16x32_bf16 v[60:63], a[12:15], v[84:87], v[60:63]
	ds_read_b128 v[84:87], v118 offset:6144
	s_waitcnt lgkmcnt(3)
	v_mfma_f32_16x16x32_bf16 v[0:3], a[16:19], v[80:83], v[0:3]
	v_mfma_f32_16x16x32_bf16 v[16:19], a[20:23], v[80:83], v[16:19]
	v_mfma_f32_16x16x32_bf16 v[32:35], a[24:27], v[80:83], v[32:35]
	v_mfma_f32_16x16x32_bf16 v[48:51], a[28:31], v[80:83], v[48:51]
	s_waitcnt lgkmcnt(2)
	v_mfma_f32_16x16x32_bf16 v[4:7], a[16:19], v[92:95], v[4:7]
	v_mfma_f32_16x16x32_bf16 v[20:23], a[20:23], v[92:95], v[20:23]
	v_mfma_f32_16x16x32_bf16 v[36:39], a[24:27], v[92:95], v[36:39]
	v_mfma_f32_16x16x32_bf16 v[52:55], a[28:31], v[92:95], v[52:55]
	s_waitcnt lgkmcnt(1)
	v_mfma_f32_16x16x32_bf16 v[8:11], a[16:19], v[88:91], v[8:11]
	v_mfma_f32_16x16x32_bf16 v[24:27], a[20:23], v[88:91], v[24:27]
	v_mfma_f32_16x16x32_bf16 v[40:43], a[24:27], v[88:91], v[40:43]
	v_mfma_f32_16x16x32_bf16 v[56:59], a[28:31], v[88:91], v[56:59]
	s_waitcnt lgkmcnt(0)
	v_mfma_f32_16x16x32_bf16 v[12:15], a[16:19], v[84:87], v[12:15]
	v_mfma_f32_16x16x32_bf16 v[28:31], a[20:23], v[84:87], v[28:31]
	v_mfma_f32_16x16x32_bf16 v[44:47], a[24:27], v[84:87], v[44:47]
	v_mfma_f32_16x16x32_bf16 v[60:63], a[28:31], v[84:87], v[60:63]
	s_setprio 0
	s_waitcnt vmcnt(0) lgkmcnt(0)
	s_barrier
	ds_read_b128 a[0:3], v115 offset:32768
	ds_read_b128 v[80:83], v116 offset:32768
	ds_read_b128 a[4:7], v115 offset:34816
	ds_read_b128 a[8:11], v115 offset:36864
	ds_read_b128 a[12:15], v115 offset:38912
	ds_read_b128 v[92:95], v116 offset:34816
	ds_read_b128 v[88:91], v116 offset:36864
	ds_read_b128 v[84:87], v116 offset:38912
	ds_read_b128 a[16:19], v117 offset:32768
	ds_read_b128 a[20:23], v117 offset:34816
	ds_read_b128 a[24:27], v117 offset:36864
	ds_read_b128 a[28:31], v117 offset:38912
	s_setprio 1
	s_waitcnt lgkmcnt(10)
	v_mfma_f32_16x16x32_bf16 v[0:3], a[0:3], v[80:83], v[0:3]
	s_waitcnt lgkmcnt(9)
	v_mfma_f32_16x16x32_bf16 v[16:19], a[4:7], v[80:83], v[16:19]
	s_waitcnt lgkmcnt(8)
	v_mfma_f32_16x16x32_bf16 v[32:35], a[8:11], v[80:83], v[32:35]
	s_waitcnt lgkmcnt(7)
	v_mfma_f32_16x16x32_bf16 v[48:51], a[12:15], v[80:83], v[48:51]
	ds_read_b128 v[80:83], v118 offset:32768
	s_waitcnt lgkmcnt(7)
	v_mfma_f32_16x16x32_bf16 v[4:7], a[0:3], v[92:95], v[4:7]
	v_mfma_f32_16x16x32_bf16 v[20:23], a[4:7], v[92:95], v[20:23]
	v_mfma_f32_16x16x32_bf16 v[36:39], a[8:11], v[92:95], v[36:39]
	v_mfma_f32_16x16x32_bf16 v[52:55], a[12:15], v[92:95], v[52:55]
	ds_read_b128 v[92:95], v118 offset:34816
	s_waitcnt lgkmcnt(7)
	v_mfma_f32_16x16x32_bf16 v[8:11], a[0:3], v[88:91], v[8:11]
	v_mfma_f32_16x16x32_bf16 v[24:27], a[4:7], v[88:91], v[24:27]
	v_mfma_f32_16x16x32_bf16 v[40:43], a[8:11], v[88:91], v[40:43]
	v_mfma_f32_16x16x32_bf16 v[56:59], a[12:15], v[88:91], v[56:59]
	ds_read_b128 v[88:91], v118 offset:36864
	s_waitcnt lgkmcnt(7)
	v_mfma_f32_16x16x32_bf16 v[12:15], a[0:3], v[84:87], v[12:15]
	v_mfma_f32_16x16x32_bf16 v[28:31], a[4:7], v[84:87], v[28:31]
	v_mfma_f32_16x16x32_bf16 v[44:47], a[8:11], v[84:87], v[44:47]
	v_mfma_f32_16x16x32_bf16 v[60:63], a[12:15], v[84:87], v[60:63]
	ds_read_b128 v[84:87], v118 offset:38912
	s_waitcnt lgkmcnt(3)
	v_mfma_f32_16x16x32_bf16 v[0:3], a[16:19], v[80:83], v[0:3]
	v_mfma_f32_16x16x32_bf16 v[16:19], a[20:23], v[80:83], v[16:19]
	v_mfma_f32_16x16x32_bf16 v[32:35], a[24:27], v[80:83], v[32:35]
	v_mfma_f32_16x16x32_bf16 v[48:51], a[28:31], v[80:83], v[48:51]
	s_waitcnt lgkmcnt(2)
	v_mfma_f32_16x16x32_bf16 v[4:7], a[16:19], v[92:95], v[4:7]
	v_mfma_f32_16x16x32_bf16 v[20:23], a[20:23], v[92:95], v[20:23]
	v_mfma_f32_16x16x32_bf16 v[36:39], a[24:27], v[92:95], v[36:39]
	v_mfma_f32_16x16x32_bf16 v[52:55], a[28:31], v[92:95], v[52:55]
	s_waitcnt lgkmcnt(1)
	v_mfma_f32_16x16x32_bf16 v[8:11], a[16:19], v[88:91], v[8:11]
	v_mfma_f32_16x16x32_bf16 v[24:27], a[20:23], v[88:91], v[24:27]
	v_mfma_f32_16x16x32_bf16 v[40:43], a[24:27], v[88:91], v[40:43]
	v_mfma_f32_16x16x32_bf16 v[56:59], a[28:31], v[88:91], v[56:59]
	s_waitcnt lgkmcnt(0)
	v_mfma_f32_16x16x32_bf16 v[12:15], a[16:19], v[84:87], v[12:15]
	v_mfma_f32_16x16x32_bf16 v[28:31], a[20:23], v[84:87], v[28:31]
	v_mfma_f32_16x16x32_bf16 v[44:47], a[24:27], v[84:87], v[44:47]
	v_mfma_f32_16x16x32_bf16 v[60:63], a[28:31], v[84:87], v[60:63]
	s_setprio 0
	v_readfirstlane_b32 s15, v107
	v_readfirstlane_b32 s4, v106
	s_lshl_b32 s15, s15, 6
	s_waitcnt lgkmcnt(0)
	s_barrier
	s_add_i32 s9, s15, s9
	s_lshl_b32 s15, s4, 13
	s_lshl_b32 s4, s8, 14
	s_add_i32 s15, s15, s4
	v_or_b32_e32 v64, s9, v108
	s_movk_i32 s4, 0x80
	v_cmp_gt_i32_e32 vcc, s4, v64
	s_barrier
	v_and_b32_e32 v124, 15, v143
	v_bfe_u32 v125, v143, 4, 2
	v_xor_b32_e32 v125, v125, v124
	v_lshlrev_b32_e32 v125, 4, v125
	v_lshl_add_u32 v125, v124, 8, v125
	v_lshrrev_b32_e32 v124, 6, v143
	v_lshl_add_u32 v125, v124, 14, v125
	ds_write_b128 v125, v[0:3]
	ds_write_b128 v125, v[4:7] offset:4096
	ds_write_b128 v125, v[8:11] offset:8192
	ds_write_b128 v125, v[12:15] offset:12288
	v_xor_b32_e32 v118, 64, v125
	ds_write_b128 v118, v[16:19]
	ds_write_b128 v118, v[20:23] offset:4096
	ds_write_b128 v118, v[24:27] offset:8192
	ds_write_b128 v118, v[28:31] offset:12288
	v_xor_b32_e32 v118, 128, v125
	ds_write_b128 v118, v[32:35]
	ds_write_b128 v118, v[36:39] offset:4096
	ds_write_b128 v118, v[40:43] offset:8192
	ds_write_b128 v118, v[44:47] offset:12288
	v_xor_b32_e32 v118, 192, v125
	ds_write_b128 v118, v[48:51]
	ds_write_b128 v118, v[52:55] offset:4096
	ds_write_b128 v118, v[56:59] offset:8192
	ds_write_b128 v118, v[60:63] offset:12288
	v_and_b32_e32 v115, 31, v143
	v_bfe_u32 v117, v143, 5, 1
	v_and_b32_e32 v125, 15, v115
	v_xor_b32_e32 v117, v117, v125
	v_lshlrev_b32_e32 v117, 4, v117
	v_lshl_add_u32 v117, v115, 8, v117
	v_lshl_add_u32 v117, v124, 14, v117
	ds_read_b128 v[48:51], v117
	ds_read_b128 v[32:35], v117 offset:8192
	v_xor_b32_e32 v116, 32, v117
	ds_read_b128 v[52:55], v116
	ds_read_b128 v[36:39], v116 offset:8192
	v_xor_b32_e32 v116, 64, v117
	ds_read_b128 v[56:59], v116
	ds_read_b128 v[40:43], v116 offset:8192
	v_xor_b32_e32 v116, 96, v117
	ds_read_b128 v[60:63], v116
	ds_read_b128 v[44:47], v116 offset:8192
	v_xor_b32_e32 v116, 128, v117
	ds_read_b128 v[16:19], v116
	ds_read_b128 v[0:3], v116 offset:8192
	v_xor_b32_e32 v116, 160, v117
	ds_read_b128 v[20:23], v116
	ds_read_b128 v[4:7], v116 offset:8192
	v_xor_b32_e32 v116, 192, v117
	ds_read_b128 v[24:27], v116
	ds_read_b128 v[8:11], v116 offset:8192
	v_xor_b32_e32 v116, 224, v117
	ds_read_b128 v[28:31], v116
	ds_read_b128 v[12:15], v116 offset:8192
	s_waitcnt lgkmcnt(0)
	s_barrier
	s_and_saveexec_b64 s[8:9], vcc
	s_cbranch_execz .LBB0_894
	v_add_u32_e32 v65, s15, v64
	v_add_u32_e32 v66, v65, v111
	v_mov_b32_e32 v67, v140
	v_cvt_pk_bf16_f32 v48, v48, s0
	v_lshl_add_u64 v[68:69], v[66:67], 1, s[26:27]
	global_store_short v[68:69], v48, off
	v_cvt_pk_bf16_f32 v67, v49, s0
	v_add_u32_e32 v48, 0x80, v66
	v_mov_b32_e32 v49, v140
	v_lshl_add_u64 v[48:49], v[48:49], 1, s[26:27]
	global_store_short v[48:49], v67, off
	v_add_u32_e32 v48, 0x100, v66
	v_mov_b32_e32 v49, v140
	v_cvt_pk_bf16_f32 v50, v50, s0
	v_lshl_add_u64 v[48:49], v[48:49], 1, s[26:27]
	global_store_short v[48:49], v50, off
	v_add_u32_e32 v48, 0x180, v66
	v_mov_b32_e32 v49, v140
	v_cvt_pk_bf16_f32 v50, v51, s0
	v_lshl_add_u64 v[48:49], v[48:49], 1, s[26:27]
	global_store_short v[48:49], v50, off
	v_add_u32_e32 v48, v65, v112
	v_mov_b32_e32 v49, v140
	v_cvt_pk_bf16_f32 v52, v52, s0
	v_lshl_add_u64 v[50:51], v[48:49], 1, s[26:27]
	global_store_short v[50:51], v52, off
	v_add_u32_e32 v50, 0x80, v48
	v_mov_b32_e32 v51, v140
	v_cvt_pk_bf16_f32 v49, v53, s0
	v_lshl_add_u64 v[50:51], v[50:51], 1, s[26:27]
	global_store_short v[50:51], v49, off
	v_add_u32_e32 v50, 0x100, v48
	v_mov_b32_e32 v51, v140
	v_cvt_pk_bf16_f32 v49, v54, s0
	v_lshl_add_u64 v[50:51], v[50:51], 1, s[26:27]
	global_store_short v[50:51], v49, off
	v_add_u32_e32 v48, 0x180, v48
	v_mov_b32_e32 v49, v140
	v_cvt_pk_bf16_f32 v50, v55, s0
	v_lshl_add_u64 v[48:49], v[48:49], 1, s[26:27]
	global_store_short v[48:49], v50, off
	v_add_u32_e32 v48, v65, v113
	v_mov_b32_e32 v49, v140
	v_cvt_pk_bf16_f32 v52, v56, s0
	v_lshl_add_u64 v[50:51], v[48:49], 1, s[26:27]
	global_store_short v[50:51], v52, off
	v_add_u32_e32 v50, 0x80, v48
	v_mov_b32_e32 v51, v140
	v_cvt_pk_bf16_f32 v49, v57, s0
	v_lshl_add_u64 v[50:51], v[50:51], 1, s[26:27]
	global_store_short v[50:51], v49, off
	v_add_u32_e32 v50, 0x100, v48
	v_mov_b32_e32 v51, v140
	v_cvt_pk_bf16_f32 v49, v58, s0
	v_lshl_add_u64 v[50:51], v[50:51], 1, s[26:27]
	global_store_short v[50:51], v49, off
	v_add_u32_e32 v48, 0x180, v48
	v_mov_b32_e32 v49, v140
	v_cvt_pk_bf16_f32 v50, v59, s0
	v_lshl_add_u64 v[48:49], v[48:49], 1, s[26:27]
	global_store_short v[48:49], v50, off
	v_add_u32_e32 v48, v65, v114
	v_mov_b32_e32 v49, v140
	v_cvt_pk_bf16_f32 v52, v60, s0
	v_lshl_add_u64 v[50:51], v[48:49], 1, s[26:27]
	global_store_short v[50:51], v52, off
	v_add_u32_e32 v50, 0x80, v48
	v_mov_b32_e32 v51, v140
	v_cvt_pk_bf16_f32 v49, v61, s0
	v_lshl_add_u64 v[50:51], v[50:51], 1, s[26:27]
	global_store_short v[50:51], v49, off
	v_add_u32_e32 v50, 0x100, v48
	v_mov_b32_e32 v51, v140
	v_cvt_pk_bf16_f32 v49, v62, s0
	v_lshl_add_u64 v[50:51], v[50:51], 1, s[26:27]
	global_store_short v[50:51], v49, off
	v_add_u32_e32 v48, 0x180, v48
	v_mov_b32_e32 v49, v140
	v_cvt_pk_bf16_f32 v50, v63, s0
	v_lshl_add_u64 v[48:49], v[48:49], 1, s[26:27]
	global_store_short v[48:49], v50, off

.LBB0_903:
	s_mul_hi_i32 s0, s8, 0x38e38e39
	s_lshr_b32 s1, s0, 31
	s_ashr_i32 s0, s0, 4
	s_add_i32 s0, s0, s1
	s_mul_i32 s1, s0, 0x48
	s_sub_i32 s9, s8, s1
	v_lshl_add_u32 v0, s9, 7, v109
	v_ashrrev_i32_e32 v1, 31, v0
	v_lshlrev_b64 v[32:33], 12, v[0:1]
	v_lshl_add_u64 v[34:35], v[96:97], 0, v[32:33]
	v_add_co_u32_e32 v40, vcc, s87, v34
	s_lshl_b32 s15, s0, 7
	s_nop 0
	v_addc_co_u32_e32 v41, vcc, 0, v35, vcc
	v_add_co_u32_e32 v42, vcc, s66, v34
	v_add_u32_e32 v0, s15, v109
	s_nop 0
	v_addc_co_u32_e32 v43, vcc, 0, v35, vcc
	v_ashrrev_i32_e32 v1, 31, v0
	v_add_co_u32_e32 v44, vcc, s20, v34
	v_lshlrev_b64 v[36:37], 12, v[0:1]
	s_nop 0
	v_addc_co_u32_e32 v45, vcc, 0, v35, vcc
	v_lshl_add_u64 v[38:39], v[98:99], 0, v[36:37]
	v_readfirstlane_b32 s100, v110
	s_nop 3
	s_add_u32 m0, s100, 0x0
	s_nop 0
	global_load_lds_dwordx4 v[34:35], off
	s_add_u32 m0, s100, 0x1000
	s_nop 0
	global_load_lds_dwordx4 v[40:41], off
	s_add_u32 m0, s100, 0x2000
	s_nop 0
	global_load_lds_dwordx4 v[42:43], off
	s_add_u32 m0, s100, 0x3000
	s_nop 0
	global_load_lds_dwordx4 v[44:45], off
	s_add_u32 m0, s100, 0x4000
	s_nop 0
	global_load_lds_dwordx4 v[38:39], off
	v_add_co_u32_e32 v46, vcc, s87, v38
	v_lshl_add_u64 v[102:103], v[100:101], 0, v[36:37]
	s_nop 0
	v_addc_co_u32_e32 v47, vcc, 0, v39, vcc
	s_waitcnt vmcnt(16)
	v_add_co_u32_e32 v48, vcc, s66, v38
	s_add_u32 m0, s100, 0x5000
	s_nop 0
	global_load_lds_dwordx4 v[46:47], off
	s_nop 0
	v_addc_co_u32_e32 v49, vcc, 0, v39, vcc
	v_add_co_u32_e32 v50, vcc, s20, v38
	s_add_u32 m0, s100, 0x6000
	s_nop 0
	global_load_lds_dwordx4 v[48:49], off
	s_nop 0
	v_addc_co_u32_e32 v51, vcc, 0, v39, vcc
	s_add_u32 m0, s100, 0x7000
	s_nop 0
	global_load_lds_dwordx4 v[50:51], off
	v_lshl_add_u64 v[104:105], v[100:101], 0, v[32:33]
	s_mov_b64 s[0:1], 0
	v_mov_b32_e32 v0, 0
	v_mov_b32_e32 v1, v0
	v_mov_b32_e32 v2, v0
	v_mov_b32_e32 v3, v0
	v_mov_b32_e32 v4, v0
	v_mov_b32_e32 v5, v0
	v_mov_b32_e32 v6, v0
	v_mov_b32_e32 v7, v0
	v_mov_b32_e32 v8, v0
	v_mov_b32_e32 v9, v0
	v_mov_b32_e32 v10, v0
	v_mov_b32_e32 v11, v0
	v_mov_b32_e32 v12, v0
	v_mov_b32_e32 v13, v0
	v_mov_b32_e32 v14, v0
	v_mov_b32_e32 v15, v0
	v_mov_b32_e32 v16, v0
	v_mov_b32_e32 v17, v0
	v_mov_b32_e32 v18, v0
	v_mov_b32_e32 v19, v0
	v_mov_b32_e32 v20, v0
	v_mov_b32_e32 v21, v0
	v_mov_b32_e32 v22, v0
	v_mov_b32_e32 v23, v0
	v_mov_b32_e32 v24, v0
	v_mov_b32_e32 v25, v0
	v_mov_b32_e32 v26, v0
	v_mov_b32_e32 v27, v0
	v_mov_b32_e32 v28, v0
	v_mov_b32_e32 v29, v0
	v_mov_b32_e32 v30, v0
	v_mov_b32_e32 v31, v0
	v_mov_b32_e32 v32, v0
	v_mov_b32_e32 v33, v0
	v_mov_b32_e32 v34, v0
	v_mov_b32_e32 v35, v0
	v_mov_b32_e32 v36, v0
	v_mov_b32_e32 v37, v0
	v_mov_b32_e32 v38, v0
	v_mov_b32_e32 v39, v0
	v_mov_b32_e32 v40, v0
	v_mov_b32_e32 v41, v0
	v_mov_b32_e32 v42, v0
	v_mov_b32_e32 v43, v0
	v_mov_b32_e32 v44, v0
	v_mov_b32_e32 v45, v0
	v_mov_b32_e32 v46, v0
	v_mov_b32_e32 v47, v0
	v_mov_b32_e32 v48, v0
	v_mov_b32_e32 v49, v0
	v_mov_b32_e32 v50, v0
	v_mov_b32_e32 v51, v0
	v_mov_b32_e32 v52, v0
	v_mov_b32_e32 v53, v0
	v_mov_b32_e32 v54, v0
	v_mov_b32_e32 v55, v0
	v_mov_b32_e32 v56, v0
	v_mov_b32_e32 v57, v0
	v_mov_b32_e32 v58, v0
	v_mov_b32_e32 v59, v0
	v_mov_b32_e32 v60, v0
	v_mov_b32_e32 v61, v0
	v_mov_b32_e32 v62, v0
	v_mov_b32_e32 v63, v0
	v_and_b32_e32 v124, 15, v143
	v_lshrrev_b32_e32 v125, 1, v124
	v_bfe_u32 v117, v143, 4, 2
	v_xor_b32_e32 v125, v125, v117
	v_lshlrev_b32_e32 v125, 4, v125
	v_lshl_add_u32 v125, v124, 7, v125
	v_lshrrev_b32_e32 v124, 6, v143
	v_lshrrev_b32_e32 v115, 1, v124
	v_and_b32_e32 v124, 1, v124
	v_lshl_add_u32 v115, v115, 13, v125
	v_lshl_add_u32 v116, v124, 13, v125
	v_add_u32_e32 v116, 0x4000, v116
	v_xor_b32_e32 v117, 64, v115
	v_xor_b32_e32 v118, 64, v116
	s_waitcnt vmcnt(0) lgkmcnt(0)
	s_barrier
.LBB0_904:
	v_lshl_add_u64 v[72:73], v[104:105], 0, s[0:1]
	s_mov_b32 s4, 0x20eb8000
	v_add_co_u32_e32 v144, vcc, s4, v72
	s_mov_b32 s4, 0x20ed8000
	s_nop 0
	v_addc_co_u32_e32 v145, vcc, 0, v73, vcc
	v_add_co_u32_e32 v146, vcc, s4, v72
	s_mov_b32 s4, 0x20ef8000
	s_nop 0
	v_addc_co_u32_e32 v147, vcc, 0, v73, vcc
	v_add_co_u32_e32 v148, vcc, s4, v72
	s_mov_b32 s4, 0x20f18000
	s_nop 0
	v_addc_co_u32_e32 v149, vcc, 0, v73, vcc
	v_add_co_u32_e32 v150, vcc, s4, v72
	v_lshl_add_u64 v[88:89], v[102:103], 0, s[0:1]
	s_nop 0
	v_addc_co_u32_e32 v151, vcc, 0, v73, vcc
	s_mov_b32 s4, 0x38c80000
	v_add_co_u32_e32 v152, vcc, s4, v88
	s_mov_b32 s4, 0x38ca0000
	s_nop 0
	v_addc_co_u32_e32 v153, vcc, 0, v89, vcc
	v_add_co_u32_e32 v154, vcc, s4, v88
	s_mov_b32 s4, 0x38cc0000
	s_nop 0
	v_addc_co_u32_e32 v155, vcc, 0, v89, vcc
	v_add_co_u32_e32 v156, vcc, s4, v88
	s_mov_b32 s4, 0x38ce0000
	s_nop 0
	v_addc_co_u32_e32 v157, vcc, 0, v89, vcc
	v_add_co_u32_e32 v178, vcc, s4, v88
	v_addc_co_u32_e32 v179, vcc, 0, v89, vcc
	v_lshl_add_u64 v[144:145], 8, 4, v[144:145]
	v_lshl_add_u64 v[146:147], 8, 4, v[146:147]
	v_lshl_add_u64 v[148:149], 8, 4, v[148:149]
	v_lshl_add_u64 v[150:151], 8, 4, v[150:151]
	v_lshl_add_u64 v[152:153], 8, 4, v[152:153]
	v_lshl_add_u64 v[154:155], 8, 4, v[154:155]
	v_lshl_add_u64 v[156:157], 8, 4, v[156:157]
	v_lshl_add_u64 v[178:179], 8, 4, v[178:179]
	s_add_u32 m0, s100, 0x8000
	s_nop 0
	global_load_lds_dwordx4 v[144:145], off
	s_add_u32 m0, s100, 0x9000
	s_nop 0
	global_load_lds_dwordx4 v[146:147], off
	s_add_u32 m0, s100, 0xa000
	s_nop 0
	global_load_lds_dwordx4 v[148:149], off
	s_add_u32 m0, s100, 0xb000
	s_nop 0
	global_load_lds_dwordx4 v[150:151], off
	s_add_u32 m0, s100, 0xc000
	s_nop 0
	global_load_lds_dwordx4 v[152:153], off
	s_add_u32 m0, s100, 0xd000
	s_nop 0
	global_load_lds_dwordx4 v[154:155], off
	s_add_u32 m0, s100, 0xe000
	s_nop 0
	global_load_lds_dwordx4 v[156:157], off
	s_add_u32 m0, s100, 0xf000
	s_nop 0
	global_load_lds_dwordx4 v[178:179], off
	ds_read_b128 a[0:3], v115
	ds_read_b128 v[80:83], v116
	ds_read_b128 a[4:7], v115 offset:2048
	ds_read_b128 a[8:11], v115 offset:4096
	ds_read_b128 a[12:15], v115 offset:6144
	ds_read_b128 v[92:95], v116 offset:2048
	ds_read_b128 v[88:91], v116 offset:4096
	ds_read_b128 v[84:87], v116 offset:6144
	ds_read_b128 a[16:19], v117
	ds_read_b128 a[20:23], v117 offset:2048
	ds_read_b128 a[24:27], v117 offset:4096
	ds_read_b128 a[28:31], v117 offset:6144
	s_setprio 1
	s_waitcnt lgkmcnt(10)
	v_mfma_f32_16x16x32_bf16 v[0:3], a[0:3], v[80:83], v[0:3]
	s_waitcnt lgkmcnt(9)
	v_mfma_f32_16x16x32_bf16 v[16:19], a[4:7], v[80:83], v[16:19]
	s_waitcnt lgkmcnt(8)
	v_mfma_f32_16x16x32_bf16 v[32:35], a[8:11], v[80:83], v[32:35]
	s_waitcnt lgkmcnt(7)
	v_mfma_f32_16x16x32_bf16 v[48:51], a[12:15], v[80:83], v[48:51]
	ds_read_b128 v[80:83], v118
	s_waitcnt lgkmcnt(7)
	v_mfma_f32_16x16x32_bf16 v[4:7], a[0:3], v[92:95], v[4:7]
	v_mfma_f32_16x16x32_bf16 v[20:23], a[4:7], v[92:95], v[20:23]
	v_mfma_f32_16x16x32_bf16 v[36:39], a[8:11], v[92:95], v[36:39]
	v_mfma_f32_16x16x32_bf16 v[52:55], a[12:15], v[92:95], v[52:55]
	ds_read_b128 v[92:95], v118 offset:2048
	s_waitcnt lgkmcnt(7)
	v_mfma_f32_16x16x32_bf16 v[8:11], a[0:3], v[88:91], v[8:11]
	v_mfma_f32_16x16x32_bf16 v[24:27], a[4:7], v[88:91], v[24:27]
	v_mfma_f32_16x16x32_bf16 v[40:43], a[8:11], v[88:91], v[40:43]
	v_mfma_f32_16x16x32_bf16 v[56:59], a[12:15], v[88:91], v[56:59]
	ds_read_b128 v[88:91], v118 offset:4096
	s_waitcnt lgkmcnt(7)
	v_mfma_f32_16x16x32_bf16 v[12:15], a[0:3], v[84:87], v[12:15]
	v_mfma_f32_16x16x32_bf16 v[28:31], a[4:7], v[84:87], v[28:31]
	v_mfma_f32_16x16x32_bf16 v[44:47], a[8:11], v[84:87], v[44:47]
	v_mfma_f32_16x16x32_bf16 v[60:63], a[12:15], v[84:87], v[60:63]
	ds_read_b128 v[84:87], v118 offset:6144
	s_waitcnt lgkmcnt(3)
	v_mfma_f32_16x16x32_bf16 v[0:3], a[16:19], v[80:83], v[0:3]
	v_mfma_f32_16x16x32_bf16 v[16:19], a[20:23], v[80:83], v[16:19]
	v_mfma_f32_16x16x32_bf16 v[32:35], a[24:27], v[80:83], v[32:35]
	v_mfma_f32_16x16x32_bf16 v[48:51], a[28:31], v[80:83], v[48:51]
	s_waitcnt lgkmcnt(2)
	v_mfma_f32_16x16x32_bf16 v[4:7], a[16:19], v[92:95], v[4:7]
	v_mfma_f32_16x16x32_bf16 v[20:23], a[20:23], v[92:95], v[20:23]
	v_mfma_f32_16x16x32_bf16 v[36:39], a[24:27], v[92:95], v[36:39]
	v_mfma_f32_16x16x32_bf16 v[52:55], a[28:31], v[92:95], v[52:55]
	s_waitcnt lgkmcnt(1)
	v_mfma_f32_16x16x32_bf16 v[8:11], a[16:19], v[88:91], v[8:11]
	v_mfma_f32_16x16x32_bf16 v[24:27], a[20:23], v[88:91], v[24:27]
	v_mfma_f32_16x16x32_bf16 v[40:43], a[24:27], v[88:91], v[40:43]
	v_mfma_f32_16x16x32_bf16 v[56:59], a[28:31], v[88:91], v[56:59]
	s_waitcnt lgkmcnt(0)
	v_mfma_f32_16x16x32_bf16 v[12:15], a[16:19], v[84:87], v[12:15]
	v_mfma_f32_16x16x32_bf16 v[28:31], a[20:23], v[84:87], v[28:31]
	v_mfma_f32_16x16x32_bf16 v[44:47], a[24:27], v[84:87], v[44:47]
	v_mfma_f32_16x16x32_bf16 v[60:63], a[28:31], v[84:87], v[60:63]
	s_setprio 0
	s_waitcnt vmcnt(0) lgkmcnt(0)
	s_barrier
	v_lshl_add_u64 v[64:65], 8, 4, v[144:145]
	v_lshl_add_u64 v[66:67], 8, 4, v[146:147]
	v_lshl_add_u64 v[68:69], 8, 4, v[148:149]
	v_lshl_add_u64 v[70:71], 8, 4, v[150:151]
	v_lshl_add_u64 v[76:77], 8, 4, v[152:153]
	v_lshl_add_u64 v[78:79], 8, 4, v[154:155]
	v_lshl_add_u64 v[72:73], 8, 4, v[156:157]
	v_lshl_add_u64 v[74:75], 8, 4, v[178:179]
	s_add_u32 m0, s100, 0x0
	s_nop 0
	global_load_lds_dwordx4 v[64:65], off
	s_add_u32 m0, s100, 0x1000
	s_nop 0
	global_load_lds_dwordx4 v[66:67], off
	s_add_u32 m0, s100, 0x2000
	s_nop 0
	global_load_lds_dwordx4 v[68:69], off
	s_add_u32 m0, s100, 0x3000
	s_nop 0
	global_load_lds_dwordx4 v[70:71], off
	s_add_u32 m0, s100, 0x4000
	s_nop 0
	global_load_lds_dwordx4 v[76:77], off
	s_add_u32 m0, s100, 0x5000
	s_nop 0
	global_load_lds_dwordx4 v[78:79], off
	s_add_u32 m0, s100, 0x6000
	s_nop 0
	global_load_lds_dwordx4 v[72:73], off
	s_add_u32 m0, s100, 0x7000
	s_nop 0
	global_load_lds_dwordx4 v[74:75], off
	ds_read_b128 a[0:3], v115 offset:32768
	ds_read_b128 v[80:83], v116 offset:32768
	ds_read_b128 a[4:7], v115 offset:34816
	ds_read_b128 a[8:11], v115 offset:36864
	ds_read_b128 a[12:15], v115 offset:38912
	ds_read_b128 v[92:95], v116 offset:34816
	ds_read_b128 v[88:91], v116 offset:36864
	ds_read_b128 v[84:87], v116 offset:38912
	ds_read_b128 a[16:19], v117 offset:32768
	ds_read_b128 a[20:23], v117 offset:34816
	ds_read_b128 a[24:27], v117 offset:36864
	ds_read_b128 a[28:31], v117 offset:38912
	s_setprio 1
	s_waitcnt lgkmcnt(10)
	v_mfma_f32_16x16x32_bf16 v[0:3], a[0:3], v[80:83], v[0:3]
	s_waitcnt lgkmcnt(9)
	v_mfma_f32_16x16x32_bf16 v[16:19], a[4:7], v[80:83], v[16:19]
	s_waitcnt lgkmcnt(8)
	v_mfma_f32_16x16x32_bf16 v[32:35], a[8:11], v[80:83], v[32:35]
	s_waitcnt lgkmcnt(7)
	v_mfma_f32_16x16x32_bf16 v[48:51], a[12:15], v[80:83], v[48:51]
	ds_read_b128 v[80:83], v118 offset:32768
	s_waitcnt lgkmcnt(7)
	v_mfma_f32_16x16x32_bf16 v[4:7], a[0:3], v[92:95], v[4:7]
	v_mfma_f32_16x16x32_bf16 v[20:23], a[4:7], v[92:95], v[20:23]
	v_mfma_f32_16x16x32_bf16 v[36:39], a[8:11], v[92:95], v[36:39]
	v_mfma_f32_16x16x32_bf16 v[52:55], a[12:15], v[92:95], v[52:55]
	ds_read_b128 v[92:95], v118 offset:34816
	s_waitcnt lgkmcnt(7)
	v_mfma_f32_16x16x32_bf16 v[8:11], a[0:3], v[88:91], v[8:11]
	v_mfma_f32_16x16x32_bf16 v[24:27], a[4:7], v[88:91], v[24:27]
	v_mfma_f32_16x16x32_bf16 v[40:43], a[8:11], v[88:91], v[40:43]
	v_mfma_f32_16x16x32_bf16 v[56:59], a[12:15], v[88:91], v[56:59]
	ds_read_b128 v[88:91], v118 offset:36864
	s_waitcnt lgkmcnt(7)
	v_mfma_f32_16x16x32_bf16 v[12:15], a[0:3], v[84:87], v[12:15]
	v_mfma_f32_16x16x32_bf16 v[28:31], a[4:7], v[84:87], v[28:31]
	v_mfma_f32_16x16x32_bf16 v[44:47], a[8:11], v[84:87], v[44:47]
	v_mfma_f32_16x16x32_bf16 v[60:63], a[12:15], v[84:87], v[60:63]
	ds_read_b128 v[84:87], v118 offset:38912
	s_waitcnt lgkmcnt(3)
	v_mfma_f32_16x16x32_bf16 v[0:3], a[16:19], v[80:83], v[0:3]
	v_mfma_f32_16x16x32_bf16 v[16:19], a[20:23], v[80:83], v[16:19]
	v_mfma_f32_16x16x32_bf16 v[32:35], a[24:27], v[80:83], v[32:35]
	v_mfma_f32_16x16x32_bf16 v[48:51], a[28:31], v[80:83], v[48:51]
	s_waitcnt lgkmcnt(2)
	v_mfma_f32_16x16x32_bf16 v[4:7], a[16:19], v[92:95], v[4:7]
	v_mfma_f32_16x16x32_bf16 v[20:23], a[20:23], v[92:95], v[20:23]
	v_mfma_f32_16x16x32_bf16 v[36:39], a[24:27], v[92:95], v[36:39]
	v_mfma_f32_16x16x32_bf16 v[52:55], a[28:31], v[92:95], v[52:55]
	s_waitcnt lgkmcnt(1)
	v_mfma_f32_16x16x32_bf16 v[8:11], a[16:19], v[88:91], v[8:11]
	v_mfma_f32_16x16x32_bf16 v[24:27], a[20:23], v[88:91], v[24:27]
	v_mfma_f32_16x16x32_bf16 v[40:43], a[24:27], v[88:91], v[40:43]
	v_mfma_f32_16x16x32_bf16 v[56:59], a[28:31], v[88:91], v[56:59]
	s_waitcnt lgkmcnt(0)
	v_mfma_f32_16x16x32_bf16 v[12:15], a[16:19], v[84:87], v[12:15]
	v_mfma_f32_16x16x32_bf16 v[28:31], a[20:23], v[84:87], v[28:31]
	v_mfma_f32_16x16x32_bf16 v[44:47], a[24:27], v[84:87], v[44:47]
	v_mfma_f32_16x16x32_bf16 v[60:63], a[28:31], v[84:87], v[60:63]
	s_setprio 0
	s_waitcnt vmcnt(0) lgkmcnt(0)
	s_barrier
	s_add_u32 s0, s0, 0x100
	s_addc_u32 s1, s1, 0
	s_cmpk_eq_i32 s0, 0xf00
	s_cbranch_scc0 .LBB0_904
	v_lshl_add_u64 v[64:65], 8, 4, v[64:65]
	v_lshl_add_u64 v[66:67], 8, 4, v[66:67]
	v_lshl_add_u64 v[68:69], 8, 4, v[68:69]
	v_lshl_add_u64 v[70:71], 8, 4, v[70:71]
	v_lshl_add_u64 v[76:77], 8, 4, v[76:77]
	v_lshl_add_u64 v[78:79], 8, 4, v[78:79]
	v_lshl_add_u64 v[72:73], 8, 4, v[72:73]
	v_lshl_add_u64 v[74:75], 8, 4, v[74:75]
	s_add_u32 m0, s100, 0x8000
	s_nop 0
	global_load_lds_dwordx4 v[64:65], off
	s_add_u32 m0, s100, 0x9000
	s_nop 0
	global_load_lds_dwordx4 v[66:67], off
	s_add_u32 m0, s100, 0xa000
	s_nop 0
	global_load_lds_dwordx4 v[68:69], off
	s_add_u32 m0, s100, 0xb000
	s_nop 0
	global_load_lds_dwordx4 v[70:71], off
	s_add_u32 m0, s100, 0xc000
	s_nop 0
	global_load_lds_dwordx4 v[76:77], off
	s_add_u32 m0, s100, 0xd000
	s_nop 0
	global_load_lds_dwordx4 v[78:79], off
	s_add_u32 m0, s100, 0xe000
	s_nop 0
	global_load_lds_dwordx4 v[72:73], off
	s_add_u32 m0, s100, 0xf000
	s_nop 0
	global_load_lds_dwordx4 v[74:75], off
	ds_read_b128 a[0:3], v115
	ds_read_b128 v[80:83], v116
	ds_read_b128 a[4:7], v115 offset:2048
	ds_read_b128 a[8:11], v115 offset:4096
	ds_read_b128 a[12:15], v115 offset:6144
	ds_read_b128 v[92:95], v116 offset:2048
	ds_read_b128 v[88:91], v116 offset:4096
	ds_read_b128 v[84:87], v116 offset:6144
	ds_read_b128 a[16:19], v117
	ds_read_b128 a[20:23], v117 offset:2048
	ds_read_b128 a[24:27], v117 offset:4096
	ds_read_b128 a[28:31], v117 offset:6144
	s_setprio 1
	s_waitcnt lgkmcnt(10)
	v_mfma_f32_16x16x32_bf16 v[0:3], a[0:3], v[80:83], v[0:3]
	s_waitcnt lgkmcnt(9)
	v_mfma_f32_16x16x32_bf16 v[16:19], a[4:7], v[80:83], v[16:19]
	s_waitcnt lgkmcnt(8)
	v_mfma_f32_16x16x32_bf16 v[32:35], a[8:11], v[80:83], v[32:35]
	s_waitcnt lgkmcnt(7)
	v_mfma_f32_16x16x32_bf16 v[48:51], a[12:15], v[80:83], v[48:51]
	ds_read_b128 v[80:83], v118
	s_waitcnt lgkmcnt(7)
	v_mfma_f32_16x16x32_bf16 v[4:7], a[0:3], v[92:95], v[4:7]
	v_mfma_f32_16x16x32_bf16 v[20:23], a[4:7], v[92:95], v[20:23]
	v_mfma_f32_16x16x32_bf16 v[36:39], a[8:11], v[92:95], v[36:39]
	v_mfma_f32_16x16x32_bf16 v[52:55], a[12:15], v[92:95], v[52:55]
	ds_read_b128 v[92:95], v118 offset:2048
	s_waitcnt lgkmcnt(7)
	v_mfma_f32_16x16x32_bf16 v[8:11], a[0:3], v[88:91], v[8:11]
	v_mfma_f32_16x16x32_bf16 v[24:27], a[4:7], v[88:91], v[24:27]
	v_mfma_f32_16x16x32_bf16 v[40:43], a[8:11], v[88:91], v[40:43]
	v_mfma_f32_16x16x32_bf16 v[56:59], a[12:15], v[88:91], v[56:59]
	ds_read_b128 v[88:91], v118 offset:4096
	s_waitcnt lgkmcnt(7)
	v_mfma_f32_16x16x32_bf16 v[12:15], a[0:3], v[84:87], v[12:15]
	v_mfma_f32_16x16x32_bf16 v[28:31], a[4:7], v[84:87], v[28:31]
	v_mfma_f32_16x16x32_bf16 v[44:47], a[8:11], v[84:87], v[44:47]
	v_mfma_f32_16x16x32_bf16 v[60:63], a[12:15], v[84:87], v[60:63]
	ds_read_b128 v[84:87], v118 offset:6144
	s_waitcnt lgkmcnt(3)
	v_mfma_f32_16x16x32_bf16 v[0:3], a[16:19], v[80:83], v[0:3]
	v_mfma_f32_16x16x32_bf16 v[16:19], a[20:23], v[80:83], v[16:19]
	v_mfma_f32_16x16x32_bf16 v[32:35], a[24:27], v[80:83], v[32:35]
	v_mfma_f32_16x16x32_bf16 v[48:51], a[28:31], v[80:83], v[48:51]
	s_waitcnt lgkmcnt(2)
	v_mfma_f32_16x16x32_bf16 v[4:7], a[16:19], v[92:95], v[4:7]
	v_mfma_f32_16x16x32_bf16 v[20:23], a[20:23], v[92:95], v[20:23]
	v_mfma_f32_16x16x32_bf16 v[36:39], a[24:27], v[92:95], v[36:39]
	v_mfma_f32_16x16x32_bf16 v[52:55], a[28:31], v[92:95], v[52:55]
	s_waitcnt lgkmcnt(1)
	v_mfma_f32_16x16x32_bf16 v[8:11], a[16:19], v[88:91], v[8:11]
	v_mfma_f32_16x16x32_bf16 v[24:27], a[20:23], v[88:91], v[24:27]
	v_mfma_f32_16x16x32_bf16 v[40:43], a[24:27], v[88:91], v[40:43]
	v_mfma_f32_16x16x32_bf16 v[56:59], a[28:31], v[88:91], v[56:59]
	s_waitcnt lgkmcnt(0)
	v_mfma_f32_16x16x32_bf16 v[12:15], a[16:19], v[84:87], v[12:15]
	v_mfma_f32_16x16x32_bf16 v[28:31], a[20:23], v[84:87], v[28:31]
	v_mfma_f32_16x16x32_bf16 v[44:47], a[24:27], v[84:87], v[44:47]
	v_mfma_f32_16x16x32_bf16 v[60:63], a[28:31], v[84:87], v[60:63]
	s_setprio 0
	s_waitcnt vmcnt(0) lgkmcnt(0)
	s_barrier
	ds_read_b128 a[0:3], v115 offset:32768
	ds_read_b128 v[80:83], v116 offset:32768
	ds_read_b128 a[4:7], v115 offset:34816
	ds_read_b128 a[8:11], v115 offset:36864
	ds_read_b128 a[12:15], v115 offset:38912
	ds_read_b128 v[92:95], v116 offset:34816
	ds_read_b128 v[88:91], v116 offset:36864
	ds_read_b128 v[84:87], v116 offset:38912
	ds_read_b128 a[16:19], v117 offset:32768
	ds_read_b128 a[20:23], v117 offset:34816
	ds_read_b128 a[24:27], v117 offset:36864
	ds_read_b128 a[28:31], v117 offset:38912
	s_setprio 1
	s_waitcnt lgkmcnt(10)
	v_mfma_f32_16x16x32_bf16 v[0:3], a[0:3], v[80:83], v[0:3]
	s_waitcnt lgkmcnt(9)
	v_mfma_f32_16x16x32_bf16 v[16:19], a[4:7], v[80:83], v[16:19]
	s_waitcnt lgkmcnt(8)
	v_mfma_f32_16x16x32_bf16 v[32:35], a[8:11], v[80:83], v[32:35]
	s_waitcnt lgkmcnt(7)
	v_mfma_f32_16x16x32_bf16 v[48:51], a[12:15], v[80:83], v[48:51]
	ds_read_b128 v[80:83], v118 offset:32768
	s_waitcnt lgkmcnt(7)
	v_mfma_f32_16x16x32_bf16 v[4:7], a[0:3], v[92:95], v[4:7]
	v_mfma_f32_16x16x32_bf16 v[20:23], a[4:7], v[92:95], v[20:23]
	v_mfma_f32_16x16x32_bf16 v[36:39], a[8:11], v[92:95], v[36:39]
	v_mfma_f32_16x16x32_bf16 v[52:55], a[12:15], v[92:95], v[52:55]
	ds_read_b128 v[92:95], v118 offset:34816
	s_waitcnt lgkmcnt(7)
	v_mfma_f32_16x16x32_bf16 v[8:11], a[0:3], v[88:91], v[8:11]
	v_mfma_f32_16x16x32_bf16 v[24:27], a[4:7], v[88:91], v[24:27]
	v_mfma_f32_16x16x32_bf16 v[40:43], a[8:11], v[88:91], v[40:43]
	v_mfma_f32_16x16x32_bf16 v[56:59], a[12:15], v[88:91], v[56:59]
	ds_read_b128 v[88:91], v118 offset:36864
	s_waitcnt lgkmcnt(7)
	v_mfma_f32_16x16x32_bf16 v[12:15], a[0:3], v[84:87], v[12:15]
	v_mfma_f32_16x16x32_bf16 v[28:31], a[4:7], v[84:87], v[28:31]
	v_mfma_f32_16x16x32_bf16 v[44:47], a[8:11], v[84:87], v[44:47]
	v_mfma_f32_16x16x32_bf16 v[60:63], a[12:15], v[84:87], v[60:63]
	ds_read_b128 v[84:87], v118 offset:38912
	s_waitcnt lgkmcnt(3)
	v_mfma_f32_16x16x32_bf16 v[0:3], a[16:19], v[80:83], v[0:3]
	v_mfma_f32_16x16x32_bf16 v[16:19], a[20:23], v[80:83], v[16:19]
	v_mfma_f32_16x16x32_bf16 v[32:35], a[24:27], v[80:83], v[32:35]
	v_mfma_f32_16x16x32_bf16 v[48:51], a[28:31], v[80:83], v[48:51]
	s_waitcnt lgkmcnt(2)
	v_mfma_f32_16x16x32_bf16 v[4:7], a[16:19], v[92:95], v[4:7]
	v_mfma_f32_16x16x32_bf16 v[20:23], a[20:23], v[92:95], v[20:23]
	v_mfma_f32_16x16x32_bf16 v[36:39], a[24:27], v[92:95], v[36:39]
	v_mfma_f32_16x16x32_bf16 v[52:55], a[28:31], v[92:95], v[52:55]
	s_waitcnt lgkmcnt(1)
	v_mfma_f32_16x16x32_bf16 v[8:11], a[16:19], v[88:91], v[8:11]
	v_mfma_f32_16x16x32_bf16 v[24:27], a[20:23], v[88:91], v[24:27]
	v_mfma_f32_16x16x32_bf16 v[40:43], a[24:27], v[88:91], v[40:43]
	v_mfma_f32_16x16x32_bf16 v[56:59], a[28:31], v[88:91], v[56:59]
	s_waitcnt lgkmcnt(0)
	v_mfma_f32_16x16x32_bf16 v[12:15], a[16:19], v[84:87], v[12:15]
	v_mfma_f32_16x16x32_bf16 v[28:31], a[20:23], v[84:87], v[28:31]
	v_mfma_f32_16x16x32_bf16 v[44:47], a[24:27], v[84:87], v[44:47]
	v_mfma_f32_16x16x32_bf16 v[60:63], a[28:31], v[84:87], v[60:63]
	s_setprio 0
	v_readfirstlane_b32 s1, v107
	v_readfirstlane_b32 s0, v106
	s_lshl_b32 s1, s1, 6
	s_waitcnt lgkmcnt(0)
	s_barrier
	s_add_i32 s1, s1, s15
	s_lshl_b32 s0, s0, 14
	s_lshl_b32 s4, s9, 15
	s_add_i32 s9, s0, s4
	v_or_b32_e32 v64, s1, v108
	s_movk_i32 s0, 0x100
	v_cmp_gt_i32_e64 s[38:39], s0, v64
	s_barrier
	v_and_b32_e32 v124, 15, v143
	v_bfe_u32 v125, v143, 4, 2
	v_xor_b32_e32 v125, v125, v124
	v_lshlrev_b32_e32 v125, 4, v125
	v_lshl_add_u32 v125, v124, 8, v125
	v_lshrrev_b32_e32 v124, 6, v143
	v_lshl_add_u32 v125, v124, 14, v125
	ds_write_b128 v125, v[0:3]
	ds_write_b128 v125, v[4:7] offset:4096
	ds_write_b128 v125, v[8:11] offset:8192
	ds_write_b128 v125, v[12:15] offset:12288
	v_xor_b32_e32 v118, 64, v125
	ds_write_b128 v118, v[16:19]
	ds_write_b128 v118, v[20:23] offset:4096
	ds_write_b128 v118, v[24:27] offset:8192
	ds_write_b128 v118, v[28:31] offset:12288
	v_xor_b32_e32 v118, 128, v125
	ds_write_b128 v118, v[32:35]
	ds_write_b128 v118, v[36:39] offset:4096
	ds_write_b128 v118, v[40:43] offset:8192
	ds_write_b128 v118, v[44:47] offset:12288
	v_xor_b32_e32 v118, 192, v125
	ds_write_b128 v118, v[48:51]
	ds_write_b128 v118, v[52:55] offset:4096
	ds_write_b128 v118, v[56:59] offset:8192
	ds_write_b128 v118, v[60:63] offset:12288
	v_and_b32_e32 v115, 31, v143
	v_bfe_u32 v117, v143, 5, 1
	v_and_b32_e32 v125, 15, v115
	v_xor_b32_e32 v117, v117, v125
	v_lshlrev_b32_e32 v117, 4, v117
	v_lshl_add_u32 v117, v115, 8, v117
	v_lshl_add_u32 v117, v124, 14, v117
	ds_read_b128 v[48:51], v117
	ds_read_b128 v[32:35], v117 offset:8192
	v_xor_b32_e32 v116, 32, v117
	ds_read_b128 v[52:55], v116
	ds_read_b128 v[36:39], v116 offset:8192
	v_xor_b32_e32 v116, 64, v117
	ds_read_b128 v[56:59], v116
	ds_read_b128 v[40:43], v116 offset:8192
	v_xor_b32_e32 v116, 96, v117
	ds_read_b128 v[60:63], v116
	ds_read_b128 v[44:47], v116 offset:8192
	v_xor_b32_e32 v116, 128, v117
	ds_read_b128 v[16:19], v116
	ds_read_b128 v[0:3], v116 offset:8192
	v_xor_b32_e32 v116, 160, v117
	ds_read_b128 v[20:23], v116
	ds_read_b128 v[4:7], v116 offset:8192
	v_xor_b32_e32 v116, 192, v117
	ds_read_b128 v[24:27], v116
	ds_read_b128 v[8:11], v116 offset:8192
	v_xor_b32_e32 v116, 224, v117
	ds_read_b128 v[28:31], v116
	ds_read_b128 v[12:15], v116 offset:8192
	s_waitcnt lgkmcnt(0)
	s_barrier
	s_and_saveexec_b64 s[0:1], s[38:39]
	s_cbranch_execz .LBB0_907
	v_mul_f32_e32 v48, 0xbfb8aa3b, v48
	v_exp_f32_e32 v48, v48
	v_add_u32_e32 v65, s9, v64
	v_add_f32_e32 v48, 1.0, v48
	v_div_scale_f32 v66, s[22:23], v48, v48, 1.0
	v_rcp_f32_e32 v67, v66
	s_nop 0
	v_fma_f32 v68, -v66, v67, 1.0
	v_fmac_f32_e32 v67, v68, v67
	v_div_scale_f32 v68, vcc, 1.0, v48, 1.0
	v_mul_f32_e32 v69, v68, v67
	v_fma_f32 v70, -v66, v69, v68
	v_fmac_f32_e32 v69, v70, v67
	v_fma_f32 v66, -v66, v69, v68
	v_div_fmas_f32 v66, v66, v67, v69
	v_div_fixup_f32 v48, v66, v48, 1.0
	v_add_u32_e32 v66, v65, v111
	v_mov_b32_e32 v67, v140
	v_cvt_pk_bf16_f32 v48, v48, s0
	v_lshl_add_u64 v[68:69], v[66:67], 1, s[26:27]
	global_store_short v[68:69], v48, off
	v_mul_f32_e32 v48, 0xbfb8aa3b, v49
	v_exp_f32_e32 v48, v48
	s_nop 0
	v_add_f32_e32 v48, 1.0, v48
	v_div_scale_f32 v49, s[22:23], v48, v48, 1.0
	v_rcp_f32_e32 v67, v49
	s_nop 0
	v_fma_f32 v68, -v49, v67, 1.0
	v_fmac_f32_e32 v67, v68, v67
	v_div_scale_f32 v68, vcc, 1.0, v48, 1.0
	v_mul_f32_e32 v69, v68, v67
	v_fma_f32 v70, -v49, v69, v68
	v_fmac_f32_e32 v69, v70, v67
	v_fma_f32 v49, -v49, v69, v68
	v_div_fmas_f32 v49, v49, v67, v69
	v_div_fixup_f32 v48, v49, v48, 1.0
	v_cvt_pk_bf16_f32 v67, v48, s0
	v_add_u32_e32 v48, 0x100, v66
	v_mov_b32_e32 v49, v140
	v_lshl_add_u64 v[48:49], v[48:49], 1, s[26:27]
	global_store_short v[48:49], v67, off
	v_mul_f32_e32 v48, 0xbfb8aa3b, v50
	v_exp_f32_e32 v48, v48
	s_nop 0
	v_add_f32_e32 v48, 1.0, v48
	v_div_scale_f32 v49, s[22:23], v48, v48, 1.0
	v_rcp_f32_e32 v50, v49
	s_nop 0
	v_fma_f32 v67, -v49, v50, 1.0
	v_fmac_f32_e32 v50, v67, v50
	v_div_scale_f32 v67, vcc, 1.0, v48, 1.0
	v_mul_f32_e32 v68, v67, v50
	v_fma_f32 v69, -v49, v68, v67
	v_fmac_f32_e32 v68, v69, v50
	v_fma_f32 v49, -v49, v68, v67
	v_div_fmas_f32 v49, v49, v50, v68
	v_div_fixup_f32 v48, v49, v48, 1.0
	v_cvt_pk_bf16_f32 v50, v48, s0
	v_add_u32_e32 v48, 0x200, v66
	v_mov_b32_e32 v49, v140
	v_lshl_add_u64 v[48:49], v[48:49], 1, s[26:27]
	global_store_short v[48:49], v50, off
	v_mul_f32_e32 v48, 0xbfb8aa3b, v51
	v_exp_f32_e32 v48, v48
	s_nop 0
	v_add_f32_e32 v48, 1.0, v48
	v_div_scale_f32 v49, s[22:23], v48, v48, 1.0
	v_rcp_f32_e32 v50, v49
	s_nop 0
	v_fma_f32 v51, -v49, v50, 1.0
	v_fmac_f32_e32 v50, v51, v50
	v_div_scale_f32 v51, vcc, 1.0, v48, 1.0
	v_mul_f32_e32 v67, v51, v50
	v_fma_f32 v68, -v49, v67, v51
	v_fmac_f32_e32 v67, v68, v50
	v_fma_f32 v49, -v49, v67, v51
	v_div_fmas_f32 v49, v49, v50, v67
	v_div_fixup_f32 v48, v49, v48, 1.0
	v_cvt_pk_bf16_f32 v50, v48, s0
	v_add_u32_e32 v48, 0x300, v66
	v_mov_b32_e32 v49, v140
	v_lshl_add_u64 v[48:49], v[48:49], 1, s[26:27]
	global_store_short v[48:49], v50, off
	v_mul_f32_e32 v48, 0xbfb8aa3b, v52
	v_exp_f32_e32 v48, v48
	s_nop 0
	v_add_f32_e32 v48, 1.0, v48
	v_div_scale_f32 v49, s[22:23], v48, v48, 1.0
	v_rcp_f32_e32 v50, v49
	s_nop 0
	v_fma_f32 v51, -v49, v50, 1.0
	v_fmac_f32_e32 v50, v51, v50
	v_div_scale_f32 v51, vcc, 1.0, v48, 1.0
	v_mul_f32_e32 v52, v51, v50
	v_fma_f32 v66, -v49, v52, v51
	v_fmac_f32_e32 v52, v66, v50
	v_fma_f32 v49, -v49, v52, v51
	v_div_fmas_f32 v49, v49, v50, v52
	v_div_fixup_f32 v48, v49, v48, 1.0
	v_cvt_pk_bf16_f32 v52, v48, s0
	v_add_u32_e32 v48, v65, v112
	v_mov_b32_e32 v49, v140
	v_lshl_add_u64 v[50:51], v[48:49], 1, s[26:27]
	v_mul_f32_e32 v49, 0xbfb8aa3b, v53
	v_exp_f32_e32 v49, v49
	global_store_short v[50:51], v52, off
	v_add_f32_e32 v49, 1.0, v49
	v_div_scale_f32 v50, s[22:23], v49, v49, 1.0
	v_rcp_f32_e32 v51, v50
	s_nop 0
	v_fma_f32 v52, -v50, v51, 1.0
	v_fmac_f32_e32 v51, v52, v51
	v_div_scale_f32 v52, vcc, 1.0, v49, 1.0
	v_mul_f32_e32 v53, v52, v51
	v_fma_f32 v66, -v50, v53, v52
	v_fmac_f32_e32 v53, v66, v51
	v_fma_f32 v50, -v50, v53, v52
	v_div_fmas_f32 v50, v50, v51, v53
	v_div_fixup_f32 v49, v50, v49, 1.0
	v_add_u32_e32 v50, 0x100, v48
	v_mov_b32_e32 v51, v140
	v_cvt_pk_bf16_f32 v49, v49, s0
	v_lshl_add_u64 v[50:51], v[50:51], 1, s[26:27]
	global_store_short v[50:51], v49, off
	v_mul_f32_e32 v49, 0xbfb8aa3b, v54
	v_exp_f32_e32 v49, v49
	s_nop 0
	v_add_f32_e32 v49, 1.0, v49
	v_div_scale_f32 v50, s[22:23], v49, v49, 1.0
	v_rcp_f32_e32 v51, v50
	s_nop 0
	v_fma_f32 v52, -v50, v51, 1.0
	v_fmac_f32_e32 v51, v52, v51
	v_div_scale_f32 v52, vcc, 1.0, v49, 1.0
	v_mul_f32_e32 v53, v52, v51
	v_fma_f32 v54, -v50, v53, v52
	v_fmac_f32_e32 v53, v54, v51
	v_fma_f32 v50, -v50, v53, v52
	v_div_fmas_f32 v50, v50, v51, v53
	v_div_fixup_f32 v49, v50, v49, 1.0
	v_add_u32_e32 v50, 0x200, v48
	v_mov_b32_e32 v51, v140
	v_cvt_pk_bf16_f32 v49, v49, s0
	v_lshl_add_u64 v[50:51], v[50:51], 1, s[26:27]
	global_store_short v[50:51], v49, off
	v_mul_f32_e32 v49, 0xbfb8aa3b, v55
	v_exp_f32_e32 v49, v49
	v_add_u32_e32 v48, 0x300, v48
	v_add_f32_e32 v49, 1.0, v49
	v_div_scale_f32 v50, s[22:23], v49, v49, 1.0
	v_rcp_f32_e32 v51, v50
	s_nop 0
	v_fma_f32 v52, -v50, v51, 1.0
	v_fmac_f32_e32 v51, v52, v51
	v_div_scale_f32 v52, vcc, 1.0, v49, 1.0
	v_mul_f32_e32 v53, v52, v51
	v_fma_f32 v54, -v50, v53, v52
	v_fmac_f32_e32 v53, v54, v51
	v_fma_f32 v50, -v50, v53, v52
	v_div_fmas_f32 v50, v50, v51, v53
	v_div_fixup_f32 v49, v50, v49, 1.0
	v_cvt_pk_bf16_f32 v50, v49, s0
	v_mov_b32_e32 v49, v140
	v_lshl_add_u64 v[48:49], v[48:49], 1, s[26:27]
	global_store_short v[48:49], v50, off
	v_mul_f32_e32 v48, 0xbfb8aa3b, v56
	v_exp_f32_e32 v48, v48
	s_nop 0
	v_add_f32_e32 v48, 1.0, v48
	v_div_scale_f32 v49, s[22:23], v48, v48, 1.0
	v_rcp_f32_e32 v50, v49
	s_nop 0
	v_fma_f32 v51, -v49, v50, 1.0
	v_fmac_f32_e32 v50, v51, v50
	v_div_scale_f32 v51, vcc, 1.0, v48, 1.0
	v_mul_f32_e32 v52, v51, v50
	v_fma_f32 v53, -v49, v52, v51
	v_fmac_f32_e32 v52, v53, v50
	v_fma_f32 v49, -v49, v52, v51
	v_div_fmas_f32 v49, v49, v50, v52
	v_div_fixup_f32 v48, v49, v48, 1.0
	v_cvt_pk_bf16_f32 v52, v48, s0
	v_add_u32_e32 v48, v65, v113
	v_mov_b32_e32 v49, v140
	v_lshl_add_u64 v[50:51], v[48:49], 1, s[26:27]
	v_mul_f32_e32 v49, 0xbfb8aa3b, v57
	v_exp_f32_e32 v49, v49
	global_store_short v[50:51], v52, off
	v_add_f32_e32 v49, 1.0, v49
	v_div_scale_f32 v50, s[22:23], v49, v49, 1.0
	v_rcp_f32_e32 v51, v50
	s_nop 0
	v_fma_f32 v52, -v50, v51, 1.0
	v_fmac_f32_e32 v51, v52, v51
	v_div_scale_f32 v52, vcc, 1.0, v49, 1.0
	v_mul_f32_e32 v53, v52, v51
	v_fma_f32 v54, -v50, v53, v52
	v_fmac_f32_e32 v53, v54, v51
	v_fma_f32 v50, -v50, v53, v52
	v_div_fmas_f32 v50, v50, v51, v53
	v_div_fixup_f32 v49, v50, v49, 1.0
	v_add_u32_e32 v50, 0x100, v48
	v_mov_b32_e32 v51, v140
	v_cvt_pk_bf16_f32 v49, v49, s0
	v_lshl_add_u64 v[50:51], v[50:51], 1, s[26:27]
	global_store_short v[50:51], v49, off
	v_mul_f32_e32 v49, 0xbfb8aa3b, v58
	v_exp_f32_e32 v49, v49
	s_nop 0
	v_add_f32_e32 v49, 1.0, v49
	v_div_scale_f32 v50, s[22:23], v49, v49, 1.0
	v_rcp_f32_e32 v51, v50
	s_nop 0
	v_fma_f32 v52, -v50, v51, 1.0
	v_fmac_f32_e32 v51, v52, v51
	v_div_scale_f32 v52, vcc, 1.0, v49, 1.0
	v_mul_f32_e32 v53, v52, v51
	v_fma_f32 v54, -v50, v53, v52
	v_fmac_f32_e32 v53, v54, v51
	v_fma_f32 v50, -v50, v53, v52
	v_div_fmas_f32 v50, v50, v51, v53
	v_div_fixup_f32 v49, v50, v49, 1.0
	v_add_u32_e32 v50, 0x200, v48
	v_mov_b32_e32 v51, v140
	v_cvt_pk_bf16_f32 v49, v49, s0
	v_lshl_add_u64 v[50:51], v[50:51], 1, s[26:27]
	global_store_short v[50:51], v49, off
	v_mul_f32_e32 v49, 0xbfb8aa3b, v59
	v_exp_f32_e32 v49, v49
	v_add_u32_e32 v48, 0x300, v48
	v_add_f32_e32 v49, 1.0, v49
	v_div_scale_f32 v50, s[22:23], v49, v49, 1.0
	v_rcp_f32_e32 v51, v50
	s_nop 0
	v_fma_f32 v52, -v50, v51, 1.0
	v_fmac_f32_e32 v51, v52, v51
	v_div_scale_f32 v52, vcc, 1.0, v49, 1.0
	v_mul_f32_e32 v53, v52, v51
	v_fma_f32 v54, -v50, v53, v52
	v_fmac_f32_e32 v53, v54, v51
	v_fma_f32 v50, -v50, v53, v52
	v_div_fmas_f32 v50, v50, v51, v53
	v_div_fixup_f32 v49, v50, v49, 1.0
	v_cvt_pk_bf16_f32 v50, v49, s0
	v_mov_b32_e32 v49, v140
	v_lshl_add_u64 v[48:49], v[48:49], 1, s[26:27]
	global_store_short v[48:49], v50, off
	v_mul_f32_e32 v48, 0xbfb8aa3b, v60
	v_exp_f32_e32 v48, v48
	v_mul_f32_e32 v49, 0xbfb8aa3b, v61
	v_exp_f32_e32 v49, v49
	v_add_f32_e32 v48, 1.0, v48
	v_div_scale_f32 v50, s[22:23], v48, v48, 1.0
	v_rcp_f32_e32 v51, v50
	v_div_scale_f32 v52, vcc, 1.0, v48, 1.0
	v_fma_f32 v53, -v50, v51, 1.0
	v_fmac_f32_e32 v51, v53, v51
	v_mul_f32_e32 v53, v52, v51
	v_fma_f32 v54, -v50, v53, v52
	v_fmac_f32_e32 v53, v54, v51
	v_fma_f32 v50, -v50, v53, v52
	v_div_fmas_f32 v50, v50, v51, v53
	v_add_f32_e32 v53, 1.0, v49
	v_div_scale_f32 v54, s[22:23], v53, v53, 1.0
	v_rcp_f32_e32 v55, v54
	v_div_fixup_f32 v48, v50, v48, 1.0
	v_cvt_pk_bf16_f32 v52, v48, s0
	v_add_u32_e32 v48, v65, v114
	v_mov_b32_e32 v49, v140
	v_lshl_add_u64 v[50:51], v[48:49], 1, s[26:27]
	v_fma_f32 v49, -v54, v55, 1.0
	v_fmac_f32_e32 v55, v49, v55
	v_div_scale_f32 v49, vcc, 1.0, v53, 1.0
	global_store_short v[50:51], v52, off
	v_mul_f32_e32 v50, v49, v55
	v_fma_f32 v51, -v54, v50, v49
	v_fmac_f32_e32 v50, v51, v55
	v_fma_f32 v49, -v54, v50, v49
	v_div_fmas_f32 v49, v49, v55, v50
	v_mul_f32_e32 v50, 0xbfb8aa3b, v62
	v_exp_f32_e32 v51, v50
	v_div_fixup_f32 v49, v49, v53, 1.0
	v_add_u32_e32 v50, 0x100, v48
	v_cvt_pk_bf16_f32 v49, v49, s0
	v_add_f32_e32 v52, 1.0, v51
	v_div_scale_f32 v53, s[22:23], v52, v52, 1.0
	v_rcp_f32_e32 v54, v53
	v_mov_b32_e32 v51, v140
	v_lshl_add_u64 v[50:51], v[50:51], 1, s[26:27]
	global_store_short v[50:51], v49, off
	v_fma_f32 v49, -v53, v54, 1.0
	v_fmac_f32_e32 v54, v49, v54
	v_div_scale_f32 v49, vcc, 1.0, v52, 1.0
	v_mul_f32_e32 v50, v49, v54
	v_fma_f32 v51, -v53, v50, v49
	v_fmac_f32_e32 v50, v51, v54
	v_fma_f32 v49, -v53, v50, v49
	v_div_fmas_f32 v49, v49, v54, v50
	v_mul_f32_e32 v50, 0xbfb8aa3b, v63
	v_exp_f32_e32 v51, v50
	v_div_fixup_f32 v49, v49, v52, 1.0
	v_add_u32_e32 v50, 0x200, v48
	v_cvt_pk_bf16_f32 v49, v49, s0
	v_add_f32_e32 v52, 1.0, v51
	v_div_scale_f32 v53, s[22:23], v52, v52, 1.0
	v_rcp_f32_e32 v54, v53
	v_mov_b32_e32 v51, v140
	v_lshl_add_u64 v[50:51], v[50:51], 1, s[26:27]
	global_store_short v[50:51], v49, off
	v_fma_f32 v49, -v53, v54, 1.0
	v_fmac_f32_e32 v54, v49, v54
	v_div_scale_f32 v49, vcc, 1.0, v52, 1.0
	v_mul_f32_e32 v50, v49, v54
	v_fma_f32 v51, -v53, v50, v49
	v_fmac_f32_e32 v50, v51, v54
	v_fma_f32 v49, -v53, v50, v49
	v_div_fmas_f32 v49, v49, v54, v50
	v_div_fixup_f32 v49, v49, v52, 1.0
	v_cvt_pk_bf16_f32 v50, v49, s0
	v_add_u32_e32 v48, 0x300, v48
	v_mov_b32_e32 v49, v140
	v_lshl_add_u64 v[48:49], v[48:49], 1, s[26:27]
	global_store_short v[48:49], v50, off

.LBB0_969:
	s_mul_hi_i32 s4, s40, 0x38e38e39
	s_lshr_b32 s8, s4, 31
	s_ashr_i32 s4, s4, 4
	s_add_i32 s4, s4, s8
	s_mul_i32 s8, s4, 0x48
	s_sub_i32 s8, s40, s8
	s_lshl_b32 s8, s8, 7
	v_add_u32_e32 v0, s8, v123
	v_ashrrev_i32_e32 v1, 31, v0
	v_lshlrev_b64 v[32:33], 14, v[0:1]
	v_lshl_add_u64 v[34:35], v[98:99], 0, v[32:33]
	v_add_co_u32_e32 v40, vcc, s41, v34
	s_lshl_b32 s9, s4, 7
	s_nop 0
	v_addc_co_u32_e32 v41, vcc, 0, v35, vcc
	v_add_co_u32_e32 v42, vcc, s42, v34
	v_add_u32_e32 v0, s9, v123
	s_nop 0
	v_addc_co_u32_e32 v43, vcc, 0, v35, vcc
	v_ashrrev_i32_e32 v1, 31, v0
	v_add_co_u32_e32 v44, vcc, s19, v34
	v_lshlrev_b64 v[36:37], 14, v[0:1]
	s_nop 0
	v_addc_co_u32_e32 v45, vcc, 0, v35, vcc
	v_lshl_add_u64 v[38:39], v[100:101], 0, v[36:37]
	v_readfirstlane_b32 s100, v114
	s_nop 3
	s_add_u32 m0, s100, 0x0
	s_nop 0
	global_load_lds_dwordx4 v[34:35], off
	s_add_u32 m0, s100, 0x1000
	s_nop 0
	global_load_lds_dwordx4 v[40:41], off
	s_add_u32 m0, s100, 0x2000
	s_nop 0
	global_load_lds_dwordx4 v[42:43], off
	s_add_u32 m0, s100, 0x3000
	s_nop 0
	global_load_lds_dwordx4 v[44:45], off
	s_add_u32 m0, s100, 0x4000
	s_nop 0
	global_load_lds_dwordx4 v[38:39], off
	v_add_co_u32_e32 v46, vcc, s41, v38
	v_lshl_add_u64 v[106:107], v[102:103], 0, v[36:37]
	s_nop 0
	v_addc_co_u32_e32 v47, vcc, 0, v39, vcc
	s_waitcnt vmcnt(16)
	v_add_co_u32_e32 v48, vcc, s42, v38
	s_add_u32 m0, s100, 0x5000
	s_nop 0
	global_load_lds_dwordx4 v[46:47], off
	s_nop 0
	v_addc_co_u32_e32 v49, vcc, 0, v39, vcc
	v_add_co_u32_e32 v50, vcc, s19, v38
	s_add_u32 m0, s100, 0x6000
	s_nop 0
	global_load_lds_dwordx4 v[48:49], off
	s_nop 0
	v_addc_co_u32_e32 v51, vcc, 0, v39, vcc
	s_add_u32 m0, s100, 0x7000
	s_nop 0
	global_load_lds_dwordx4 v[50:51], off
	v_lshl_add_u64 v[108:109], v[104:105], 0, v[32:33]
	s_mov_b64 s[36:37], 0
	v_mov_b32_e32 v0, 0
	v_mov_b32_e32 v1, v0
	v_mov_b32_e32 v2, v0
	v_mov_b32_e32 v3, v0
	v_mov_b32_e32 v4, v0
	v_mov_b32_e32 v5, v0
	v_mov_b32_e32 v6, v0
	v_mov_b32_e32 v7, v0
	v_mov_b32_e32 v8, v0
	v_mov_b32_e32 v9, v0
	v_mov_b32_e32 v10, v0
	v_mov_b32_e32 v11, v0
	v_mov_b32_e32 v12, v0
	v_mov_b32_e32 v13, v0
	v_mov_b32_e32 v14, v0
	v_mov_b32_e32 v15, v0
	v_mov_b32_e32 v16, v0
	v_mov_b32_e32 v17, v0
	v_mov_b32_e32 v18, v0
	v_mov_b32_e32 v19, v0
	v_mov_b32_e32 v20, v0
	v_mov_b32_e32 v21, v0
	v_mov_b32_e32 v22, v0
	v_mov_b32_e32 v23, v0
	v_mov_b32_e32 v24, v0
	v_mov_b32_e32 v25, v0
	v_mov_b32_e32 v26, v0
	v_mov_b32_e32 v27, v0
	v_mov_b32_e32 v28, v0
	v_mov_b32_e32 v29, v0
	v_mov_b32_e32 v30, v0
	v_mov_b32_e32 v31, v0
	v_mov_b32_e32 v32, v0
	v_mov_b32_e32 v33, v0
	v_mov_b32_e32 v34, v0
	v_mov_b32_e32 v35, v0
	v_mov_b32_e32 v36, v0
	v_mov_b32_e32 v37, v0
	v_mov_b32_e32 v38, v0
	v_mov_b32_e32 v39, v0
	v_mov_b32_e32 v40, v0
	v_mov_b32_e32 v41, v0
	v_mov_b32_e32 v42, v0
	v_mov_b32_e32 v43, v0
	v_mov_b32_e32 v44, v0
	v_mov_b32_e32 v45, v0
	v_mov_b32_e32 v46, v0
	v_mov_b32_e32 v47, v0
	v_mov_b32_e32 v48, v0
	v_mov_b32_e32 v49, v0
	v_mov_b32_e32 v50, v0
	v_mov_b32_e32 v51, v0
	v_mov_b32_e32 v52, v0
	v_mov_b32_e32 v53, v0
	v_mov_b32_e32 v54, v0
	v_mov_b32_e32 v55, v0
	v_mov_b32_e32 v56, v0
	v_mov_b32_e32 v57, v0
	v_mov_b32_e32 v58, v0
	v_mov_b32_e32 v59, v0
	v_mov_b32_e32 v60, v0
	v_mov_b32_e32 v61, v0
	v_mov_b32_e32 v62, v0
	v_mov_b32_e32 v63, v0
	v_and_b32_e32 v132, 15, v143
	v_lshrrev_b32_e32 v133, 1, v132
	v_bfe_u32 v126, v143, 4, 2
	v_xor_b32_e32 v133, v133, v126
	v_lshlrev_b32_e32 v133, 4, v133
	v_lshl_add_u32 v133, v132, 7, v133
	v_lshrrev_b32_e32 v132, 6, v143
	v_lshrrev_b32_e32 v124, 1, v132
	v_and_b32_e32 v132, 1, v132
	v_lshl_add_u32 v124, v124, 13, v133
	v_lshl_add_u32 v125, v132, 13, v133
	v_add_u32_e32 v125, 0x4000, v125
	v_xor_b32_e32 v126, 64, v124
	v_xor_b32_e32 v127, 64, v125
	s_waitcnt vmcnt(0) lgkmcnt(0)
	s_barrier
.LBB0_970:
	v_lshl_add_u64 v[72:73], v[108:109], 0, s[36:37]
	v_add_co_u32_e32 v152, vcc, s6, v72
	v_lshl_add_u64 v[88:89], v[106:107], 0, s[36:37]
	s_nop 0
	v_addc_co_u32_e32 v153, vcc, 0, v73, vcc
	v_add_co_u32_e32 v154, vcc, s78, v72
	s_nop 1
	v_addc_co_u32_e32 v155, vcc, 0, v73, vcc
	v_add_co_u32_e32 v156, vcc, s63, v72
	v_addc_co_u32_e32 v157, vcc, 0, v73, vcc
	v_add_co_u32_e32 v178, vcc, s7, v72
	s_nop 1
	v_addc_co_u32_e32 v179, vcc, 0, v73, vcc
	v_add_co_u32_e32 v180, vcc, s79, v88
	v_addc_co_u32_e32 v181, vcc, 0, v89, vcc
	v_add_co_u32_e32 v182, vcc, s82, v88
	s_nop 1
	v_addc_co_u32_e32 v183, vcc, 0, v89, vcc
	v_add_co_u32_e32 v184, vcc, s2, v88
	v_addc_co_u32_e32 v185, vcc, 0, v89, vcc
	v_add_co_u32_e32 v186, vcc, s17, v88
	s_nop 1
	v_addc_co_u32_e32 v187, vcc, 0, v89, vcc
	v_lshl_add_u64 v[152:153], 8, 4, v[152:153]
	v_lshl_add_u64 v[154:155], 8, 4, v[154:155]
	v_lshl_add_u64 v[156:157], 8, 4, v[156:157]
	v_lshl_add_u64 v[178:179], 8, 4, v[178:179]
	v_lshl_add_u64 v[180:181], 8, 4, v[180:181]
	v_lshl_add_u64 v[182:183], 8, 4, v[182:183]
	v_lshl_add_u64 v[184:185], 8, 4, v[184:185]
	v_lshl_add_u64 v[186:187], 8, 4, v[186:187]
	s_add_u32 m0, s100, 0x8000
	s_nop 0
	global_load_lds_dwordx4 v[152:153], off
	s_add_u32 m0, s100, 0x9000
	s_nop 0
	global_load_lds_dwordx4 v[154:155], off
	s_add_u32 m0, s100, 0xa000
	s_nop 0
	global_load_lds_dwordx4 v[156:157], off
	s_add_u32 m0, s100, 0xb000
	s_nop 0
	global_load_lds_dwordx4 v[178:179], off
	s_add_u32 m0, s100, 0xc000
	s_nop 0
	global_load_lds_dwordx4 v[180:181], off
	s_add_u32 m0, s100, 0xd000
	s_nop 0
	global_load_lds_dwordx4 v[182:183], off
	s_add_u32 m0, s100, 0xe000
	s_nop 0
	global_load_lds_dwordx4 v[184:185], off
	s_add_u32 m0, s100, 0xf000
	s_nop 0
	global_load_lds_dwordx4 v[186:187], off
	ds_read_b128 a[0:3], v124
	ds_read_b128 v[80:83], v125
	ds_read_b128 a[4:7], v124 offset:2048
	ds_read_b128 a[8:11], v124 offset:4096
	ds_read_b128 a[12:15], v124 offset:6144
	ds_read_b128 v[92:95], v125 offset:2048
	ds_read_b128 v[88:91], v125 offset:4096
	ds_read_b128 v[84:87], v125 offset:6144
	ds_read_b128 a[16:19], v126
	ds_read_b128 a[20:23], v126 offset:2048
	ds_read_b128 a[24:27], v126 offset:4096
	ds_read_b128 a[28:31], v126 offset:6144
	s_setprio 1
	s_waitcnt lgkmcnt(10)
	v_mfma_f32_16x16x32_bf16 v[0:3], a[0:3], v[80:83], v[0:3]
	s_waitcnt lgkmcnt(9)
	v_mfma_f32_16x16x32_bf16 v[16:19], a[4:7], v[80:83], v[16:19]
	s_waitcnt lgkmcnt(8)
	v_mfma_f32_16x16x32_bf16 v[32:35], a[8:11], v[80:83], v[32:35]
	s_waitcnt lgkmcnt(7)
	v_mfma_f32_16x16x32_bf16 v[48:51], a[12:15], v[80:83], v[48:51]
	ds_read_b128 v[80:83], v127
	s_waitcnt lgkmcnt(7)
	v_mfma_f32_16x16x32_bf16 v[4:7], a[0:3], v[92:95], v[4:7]
	v_mfma_f32_16x16x32_bf16 v[20:23], a[4:7], v[92:95], v[20:23]
	v_mfma_f32_16x16x32_bf16 v[36:39], a[8:11], v[92:95], v[36:39]
	v_mfma_f32_16x16x32_bf16 v[52:55], a[12:15], v[92:95], v[52:55]
	ds_read_b128 v[92:95], v127 offset:2048
	s_waitcnt lgkmcnt(7)
	v_mfma_f32_16x16x32_bf16 v[8:11], a[0:3], v[88:91], v[8:11]
	v_mfma_f32_16x16x32_bf16 v[24:27], a[4:7], v[88:91], v[24:27]
	v_mfma_f32_16x16x32_bf16 v[40:43], a[8:11], v[88:91], v[40:43]
	v_mfma_f32_16x16x32_bf16 v[56:59], a[12:15], v[88:91], v[56:59]
	ds_read_b128 v[88:91], v127 offset:4096
	s_waitcnt lgkmcnt(7)
	v_mfma_f32_16x16x32_bf16 v[12:15], a[0:3], v[84:87], v[12:15]
	v_mfma_f32_16x16x32_bf16 v[28:31], a[4:7], v[84:87], v[28:31]
	v_mfma_f32_16x16x32_bf16 v[44:47], a[8:11], v[84:87], v[44:47]
	v_mfma_f32_16x16x32_bf16 v[60:63], a[12:15], v[84:87], v[60:63]
	ds_read_b128 v[84:87], v127 offset:6144
	s_waitcnt lgkmcnt(3)
	v_mfma_f32_16x16x32_bf16 v[0:3], a[16:19], v[80:83], v[0:3]
	v_mfma_f32_16x16x32_bf16 v[16:19], a[20:23], v[80:83], v[16:19]
	v_mfma_f32_16x16x32_bf16 v[32:35], a[24:27], v[80:83], v[32:35]
	v_mfma_f32_16x16x32_bf16 v[48:51], a[28:31], v[80:83], v[48:51]
	s_waitcnt lgkmcnt(2)
	v_mfma_f32_16x16x32_bf16 v[4:7], a[16:19], v[92:95], v[4:7]
	v_mfma_f32_16x16x32_bf16 v[20:23], a[20:23], v[92:95], v[20:23]
	v_mfma_f32_16x16x32_bf16 v[36:39], a[24:27], v[92:95], v[36:39]
	v_mfma_f32_16x16x32_bf16 v[52:55], a[28:31], v[92:95], v[52:55]
	s_waitcnt lgkmcnt(1)
	v_mfma_f32_16x16x32_bf16 v[8:11], a[16:19], v[88:91], v[8:11]
	v_mfma_f32_16x16x32_bf16 v[24:27], a[20:23], v[88:91], v[24:27]
	v_mfma_f32_16x16x32_bf16 v[40:43], a[24:27], v[88:91], v[40:43]
	v_mfma_f32_16x16x32_bf16 v[56:59], a[28:31], v[88:91], v[56:59]
	s_waitcnt lgkmcnt(0)
	v_mfma_f32_16x16x32_bf16 v[12:15], a[16:19], v[84:87], v[12:15]
	v_mfma_f32_16x16x32_bf16 v[28:31], a[20:23], v[84:87], v[28:31]
	v_mfma_f32_16x16x32_bf16 v[44:47], a[24:27], v[84:87], v[44:47]
	v_mfma_f32_16x16x32_bf16 v[60:63], a[28:31], v[84:87], v[60:63]
	s_setprio 0
	s_waitcnt vmcnt(0) lgkmcnt(0)
	s_barrier
	v_lshl_add_u64 v[64:65], 8, 4, v[152:153]
	v_lshl_add_u64 v[66:67], 8, 4, v[154:155]
	v_lshl_add_u64 v[68:69], 8, 4, v[156:157]
	v_lshl_add_u64 v[70:71], 8, 4, v[178:179]
	v_lshl_add_u64 v[76:77], 8, 4, v[180:181]
	v_lshl_add_u64 v[78:79], 8, 4, v[182:183]
	v_lshl_add_u64 v[72:73], 8, 4, v[184:185]
	v_lshl_add_u64 v[74:75], 8, 4, v[186:187]
	s_add_u32 m0, s100, 0x0
	s_nop 0
	global_load_lds_dwordx4 v[64:65], off
	s_add_u32 m0, s100, 0x1000
	s_nop 0
	global_load_lds_dwordx4 v[66:67], off
	s_add_u32 m0, s100, 0x2000
	s_nop 0
	global_load_lds_dwordx4 v[68:69], off
	s_add_u32 m0, s100, 0x3000
	s_nop 0
	global_load_lds_dwordx4 v[70:71], off
	s_add_u32 m0, s100, 0x4000
	s_nop 0
	global_load_lds_dwordx4 v[76:77], off
	s_add_u32 m0, s100, 0x5000
	s_nop 0
	global_load_lds_dwordx4 v[78:79], off
	s_add_u32 m0, s100, 0x6000
	s_nop 0
	global_load_lds_dwordx4 v[72:73], off
	s_add_u32 m0, s100, 0x7000
	s_nop 0
	global_load_lds_dwordx4 v[74:75], off
	ds_read_b128 a[0:3], v124 offset:32768
	ds_read_b128 v[80:83], v125 offset:32768
	ds_read_b128 a[4:7], v124 offset:34816
	ds_read_b128 a[8:11], v124 offset:36864
	ds_read_b128 a[12:15], v124 offset:38912
	ds_read_b128 v[92:95], v125 offset:34816
	ds_read_b128 v[88:91], v125 offset:36864
	ds_read_b128 v[84:87], v125 offset:38912
	ds_read_b128 a[16:19], v126 offset:32768
	ds_read_b128 a[20:23], v126 offset:34816
	ds_read_b128 a[24:27], v126 offset:36864
	ds_read_b128 a[28:31], v126 offset:38912
	s_setprio 1
	s_waitcnt lgkmcnt(10)
	v_mfma_f32_16x16x32_bf16 v[0:3], a[0:3], v[80:83], v[0:3]
	s_waitcnt lgkmcnt(9)
	v_mfma_f32_16x16x32_bf16 v[16:19], a[4:7], v[80:83], v[16:19]
	s_waitcnt lgkmcnt(8)
	v_mfma_f32_16x16x32_bf16 v[32:35], a[8:11], v[80:83], v[32:35]
	s_waitcnt lgkmcnt(7)
	v_mfma_f32_16x16x32_bf16 v[48:51], a[12:15], v[80:83], v[48:51]
	ds_read_b128 v[80:83], v127 offset:32768
	s_waitcnt lgkmcnt(7)
	v_mfma_f32_16x16x32_bf16 v[4:7], a[0:3], v[92:95], v[4:7]
	v_mfma_f32_16x16x32_bf16 v[20:23], a[4:7], v[92:95], v[20:23]
	v_mfma_f32_16x16x32_bf16 v[36:39], a[8:11], v[92:95], v[36:39]
	v_mfma_f32_16x16x32_bf16 v[52:55], a[12:15], v[92:95], v[52:55]
	ds_read_b128 v[92:95], v127 offset:34816
	s_waitcnt lgkmcnt(7)
	v_mfma_f32_16x16x32_bf16 v[8:11], a[0:3], v[88:91], v[8:11]
	v_mfma_f32_16x16x32_bf16 v[24:27], a[4:7], v[88:91], v[24:27]
	v_mfma_f32_16x16x32_bf16 v[40:43], a[8:11], v[88:91], v[40:43]
	v_mfma_f32_16x16x32_bf16 v[56:59], a[12:15], v[88:91], v[56:59]
	ds_read_b128 v[88:91], v127 offset:36864
	s_waitcnt lgkmcnt(7)
	v_mfma_f32_16x16x32_bf16 v[12:15], a[0:3], v[84:87], v[12:15]
	v_mfma_f32_16x16x32_bf16 v[28:31], a[4:7], v[84:87], v[28:31]
	v_mfma_f32_16x16x32_bf16 v[44:47], a[8:11], v[84:87], v[44:47]
	v_mfma_f32_16x16x32_bf16 v[60:63], a[12:15], v[84:87], v[60:63]
	ds_read_b128 v[84:87], v127 offset:38912
	s_waitcnt lgkmcnt(3)
	v_mfma_f32_16x16x32_bf16 v[0:3], a[16:19], v[80:83], v[0:3]
	v_mfma_f32_16x16x32_bf16 v[16:19], a[20:23], v[80:83], v[16:19]
	v_mfma_f32_16x16x32_bf16 v[32:35], a[24:27], v[80:83], v[32:35]
	v_mfma_f32_16x16x32_bf16 v[48:51], a[28:31], v[80:83], v[48:51]
	s_waitcnt lgkmcnt(2)
	v_mfma_f32_16x16x32_bf16 v[4:7], a[16:19], v[92:95], v[4:7]
	v_mfma_f32_16x16x32_bf16 v[20:23], a[20:23], v[92:95], v[20:23]
	v_mfma_f32_16x16x32_bf16 v[36:39], a[24:27], v[92:95], v[36:39]
	v_mfma_f32_16x16x32_bf16 v[52:55], a[28:31], v[92:95], v[52:55]
	s_waitcnt lgkmcnt(1)
	v_mfma_f32_16x16x32_bf16 v[8:11], a[16:19], v[88:91], v[8:11]
	v_mfma_f32_16x16x32_bf16 v[24:27], a[20:23], v[88:91], v[24:27]
	v_mfma_f32_16x16x32_bf16 v[40:43], a[24:27], v[88:91], v[40:43]
	v_mfma_f32_16x16x32_bf16 v[56:59], a[28:31], v[88:91], v[56:59]
	s_waitcnt lgkmcnt(0)
	v_mfma_f32_16x16x32_bf16 v[12:15], a[16:19], v[84:87], v[12:15]
	v_mfma_f32_16x16x32_bf16 v[28:31], a[20:23], v[84:87], v[28:31]
	v_mfma_f32_16x16x32_bf16 v[44:47], a[24:27], v[84:87], v[44:47]
	v_mfma_f32_16x16x32_bf16 v[60:63], a[28:31], v[84:87], v[60:63]
	s_setprio 0
	s_waitcnt vmcnt(0) lgkmcnt(0)
	s_barrier
	s_add_u32 s36, s36, 0x100
	s_addc_u32 s37, s37, 0
	s_cmpk_eq_i32 s36, 0x3f00
	s_cbranch_scc0 .LBB0_970
	v_lshl_add_u64 v[64:65], 8, 4, v[64:65]
	v_lshl_add_u64 v[66:67], 8, 4, v[66:67]
	v_lshl_add_u64 v[68:69], 8, 4, v[68:69]
	v_lshl_add_u64 v[70:71], 8, 4, v[70:71]
	v_lshl_add_u64 v[76:77], 8, 4, v[76:77]
	v_lshl_add_u64 v[78:79], 8, 4, v[78:79]
	v_lshl_add_u64 v[72:73], 8, 4, v[72:73]
	v_lshl_add_u64 v[74:75], 8, 4, v[74:75]
	s_add_u32 m0, s100, 0x8000
	s_nop 0
	global_load_lds_dwordx4 v[64:65], off
	s_add_u32 m0, s100, 0x9000
	s_nop 0
	global_load_lds_dwordx4 v[66:67], off
	s_add_u32 m0, s100, 0xa000
	s_nop 0
	global_load_lds_dwordx4 v[68:69], off
	s_add_u32 m0, s100, 0xb000
	s_nop 0
	global_load_lds_dwordx4 v[70:71], off
	s_add_u32 m0, s100, 0xc000
	s_nop 0
	global_load_lds_dwordx4 v[76:77], off
	s_add_u32 m0, s100, 0xd000
	s_nop 0
	global_load_lds_dwordx4 v[78:79], off
	s_add_u32 m0, s100, 0xe000
	s_nop 0
	global_load_lds_dwordx4 v[72:73], off
	s_add_u32 m0, s100, 0xf000
	s_nop 0
	global_load_lds_dwordx4 v[74:75], off
	ds_read_b128 a[0:3], v124
	ds_read_b128 v[80:83], v125
	ds_read_b128 a[4:7], v124 offset:2048
	ds_read_b128 a[8:11], v124 offset:4096
	ds_read_b128 a[12:15], v124 offset:6144
	ds_read_b128 v[92:95], v125 offset:2048
	ds_read_b128 v[88:91], v125 offset:4096
	ds_read_b128 v[84:87], v125 offset:6144
	ds_read_b128 a[16:19], v126
	ds_read_b128 a[20:23], v126 offset:2048
	ds_read_b128 a[24:27], v126 offset:4096
	ds_read_b128 a[28:31], v126 offset:6144
	s_setprio 1
	s_waitcnt lgkmcnt(10)
	v_mfma_f32_16x16x32_bf16 v[0:3], a[0:3], v[80:83], v[0:3]
	s_waitcnt lgkmcnt(9)
	v_mfma_f32_16x16x32_bf16 v[16:19], a[4:7], v[80:83], v[16:19]
	s_waitcnt lgkmcnt(8)
	v_mfma_f32_16x16x32_bf16 v[32:35], a[8:11], v[80:83], v[32:35]
	s_waitcnt lgkmcnt(7)
	v_mfma_f32_16x16x32_bf16 v[48:51], a[12:15], v[80:83], v[48:51]
	ds_read_b128 v[80:83], v127
	s_waitcnt lgkmcnt(7)
	v_mfma_f32_16x16x32_bf16 v[4:7], a[0:3], v[92:95], v[4:7]
	v_mfma_f32_16x16x32_bf16 v[20:23], a[4:7], v[92:95], v[20:23]
	v_mfma_f32_16x16x32_bf16 v[36:39], a[8:11], v[92:95], v[36:39]
	v_mfma_f32_16x16x32_bf16 v[52:55], a[12:15], v[92:95], v[52:55]
	ds_read_b128 v[92:95], v127 offset:2048
	s_waitcnt lgkmcnt(7)
	v_mfma_f32_16x16x32_bf16 v[8:11], a[0:3], v[88:91], v[8:11]
	v_mfma_f32_16x16x32_bf16 v[24:27], a[4:7], v[88:91], v[24:27]
	v_mfma_f32_16x16x32_bf16 v[40:43], a[8:11], v[88:91], v[40:43]
	v_mfma_f32_16x16x32_bf16 v[56:59], a[12:15], v[88:91], v[56:59]
	ds_read_b128 v[88:91], v127 offset:4096
	s_waitcnt lgkmcnt(7)
	v_mfma_f32_16x16x32_bf16 v[12:15], a[0:3], v[84:87], v[12:15]
	v_mfma_f32_16x16x32_bf16 v[28:31], a[4:7], v[84:87], v[28:31]
	v_mfma_f32_16x16x32_bf16 v[44:47], a[8:11], v[84:87], v[44:47]
	v_mfma_f32_16x16x32_bf16 v[60:63], a[12:15], v[84:87], v[60:63]
	ds_read_b128 v[84:87], v127 offset:6144
	s_waitcnt lgkmcnt(3)
	v_mfma_f32_16x16x32_bf16 v[0:3], a[16:19], v[80:83], v[0:3]
	v_mfma_f32_16x16x32_bf16 v[16:19], a[20:23], v[80:83], v[16:19]
	v_mfma_f32_16x16x32_bf16 v[32:35], a[24:27], v[80:83], v[32:35]
	v_mfma_f32_16x16x32_bf16 v[48:51], a[28:31], v[80:83], v[48:51]
	s_waitcnt lgkmcnt(2)
	v_mfma_f32_16x16x32_bf16 v[4:7], a[16:19], v[92:95], v[4:7]
	v_mfma_f32_16x16x32_bf16 v[20:23], a[20:23], v[92:95], v[20:23]
	v_mfma_f32_16x16x32_bf16 v[36:39], a[24:27], v[92:95], v[36:39]
	v_mfma_f32_16x16x32_bf16 v[52:55], a[28:31], v[92:95], v[52:55]
	s_waitcnt lgkmcnt(1)
	v_mfma_f32_16x16x32_bf16 v[8:11], a[16:19], v[88:91], v[8:11]
	v_mfma_f32_16x16x32_bf16 v[24:27], a[20:23], v[88:91], v[24:27]
	v_mfma_f32_16x16x32_bf16 v[40:43], a[24:27], v[88:91], v[40:43]
	v_mfma_f32_16x16x32_bf16 v[56:59], a[28:31], v[88:91], v[56:59]
	s_waitcnt lgkmcnt(0)
	v_mfma_f32_16x16x32_bf16 v[12:15], a[16:19], v[84:87], v[12:15]
	v_mfma_f32_16x16x32_bf16 v[28:31], a[20:23], v[84:87], v[28:31]
	v_mfma_f32_16x16x32_bf16 v[44:47], a[24:27], v[84:87], v[44:47]
	v_mfma_f32_16x16x32_bf16 v[60:63], a[28:31], v[84:87], v[60:63]
	s_setprio 0
	s_waitcnt vmcnt(0) lgkmcnt(0)
	s_barrier
	ds_read_b128 a[0:3], v124 offset:32768
	ds_read_b128 v[80:83], v125 offset:32768
	ds_read_b128 a[4:7], v124 offset:34816
	ds_read_b128 a[8:11], v124 offset:36864
	ds_read_b128 a[12:15], v124 offset:38912
	ds_read_b128 v[92:95], v125 offset:34816
	ds_read_b128 v[88:91], v125 offset:36864
	ds_read_b128 v[84:87], v125 offset:38912
	ds_read_b128 a[16:19], v126 offset:32768
	ds_read_b128 a[20:23], v126 offset:34816
	ds_read_b128 a[24:27], v126 offset:36864
	ds_read_b128 a[28:31], v126 offset:38912
	s_setprio 1
	s_waitcnt lgkmcnt(10)
	v_mfma_f32_16x16x32_bf16 v[0:3], a[0:3], v[80:83], v[0:3]
	s_waitcnt lgkmcnt(9)
	v_mfma_f32_16x16x32_bf16 v[16:19], a[4:7], v[80:83], v[16:19]
	s_waitcnt lgkmcnt(8)
	v_mfma_f32_16x16x32_bf16 v[32:35], a[8:11], v[80:83], v[32:35]
	s_waitcnt lgkmcnt(7)
	v_mfma_f32_16x16x32_bf16 v[48:51], a[12:15], v[80:83], v[48:51]
	ds_read_b128 v[80:83], v127 offset:32768
	s_waitcnt lgkmcnt(7)
	v_mfma_f32_16x16x32_bf16 v[4:7], a[0:3], v[92:95], v[4:7]
	v_mfma_f32_16x16x32_bf16 v[20:23], a[4:7], v[92:95], v[20:23]
	v_mfma_f32_16x16x32_bf16 v[36:39], a[8:11], v[92:95], v[36:39]
	v_mfma_f32_16x16x32_bf16 v[52:55], a[12:15], v[92:95], v[52:55]
	ds_read_b128 v[92:95], v127 offset:34816
	s_waitcnt lgkmcnt(7)
	v_mfma_f32_16x16x32_bf16 v[8:11], a[0:3], v[88:91], v[8:11]
	v_mfma_f32_16x16x32_bf16 v[24:27], a[4:7], v[88:91], v[24:27]
	v_mfma_f32_16x16x32_bf16 v[40:43], a[8:11], v[88:91], v[40:43]
	v_mfma_f32_16x16x32_bf16 v[56:59], a[12:15], v[88:91], v[56:59]
	ds_read_b128 v[88:91], v127 offset:36864
	s_waitcnt lgkmcnt(7)
	v_mfma_f32_16x16x32_bf16 v[12:15], a[0:3], v[84:87], v[12:15]
	v_mfma_f32_16x16x32_bf16 v[28:31], a[4:7], v[84:87], v[28:31]
	v_mfma_f32_16x16x32_bf16 v[44:47], a[8:11], v[84:87], v[44:47]
	v_mfma_f32_16x16x32_bf16 v[60:63], a[12:15], v[84:87], v[60:63]
	ds_read_b128 v[84:87], v127 offset:38912
	s_waitcnt lgkmcnt(3)
	v_mfma_f32_16x16x32_bf16 v[0:3], a[16:19], v[80:83], v[0:3]
	v_mfma_f32_16x16x32_bf16 v[16:19], a[20:23], v[80:83], v[16:19]
	v_mfma_f32_16x16x32_bf16 v[32:35], a[24:27], v[80:83], v[32:35]
	v_mfma_f32_16x16x32_bf16 v[48:51], a[28:31], v[80:83], v[48:51]
	s_waitcnt lgkmcnt(2)
	v_mfma_f32_16x16x32_bf16 v[4:7], a[16:19], v[92:95], v[4:7]
	v_mfma_f32_16x16x32_bf16 v[20:23], a[20:23], v[92:95], v[20:23]
	v_mfma_f32_16x16x32_bf16 v[36:39], a[24:27], v[92:95], v[36:39]
	v_mfma_f32_16x16x32_bf16 v[52:55], a[28:31], v[92:95], v[52:55]
	s_waitcnt lgkmcnt(1)
	v_mfma_f32_16x16x32_bf16 v[8:11], a[16:19], v[88:91], v[8:11]
	v_mfma_f32_16x16x32_bf16 v[24:27], a[20:23], v[88:91], v[24:27]
	v_mfma_f32_16x16x32_bf16 v[40:43], a[24:27], v[88:91], v[40:43]
	v_mfma_f32_16x16x32_bf16 v[56:59], a[28:31], v[88:91], v[56:59]
	s_waitcnt lgkmcnt(0)
	v_mfma_f32_16x16x32_bf16 v[12:15], a[16:19], v[84:87], v[12:15]
	v_mfma_f32_16x16x32_bf16 v[28:31], a[20:23], v[84:87], v[28:31]
	v_mfma_f32_16x16x32_bf16 v[44:47], a[24:27], v[84:87], v[44:47]
	v_mfma_f32_16x16x32_bf16 v[60:63], a[28:31], v[84:87], v[60:63]
	s_setprio 0
	v_readfirstlane_b32 s15, v113
	v_readfirstlane_b32 s4, v112
	s_lshl_b32 s15, s15, 6
	s_waitcnt lgkmcnt(0)
	s_barrier
	s_add_i32 s15, s15, s9
	s_lshl_b32 s23, s4, 6
	s_add_i32 s23, s23, s8
	v_or_b32_e32 v67, s15, v111
	s_movk_i32 s4, 0x800
	s_ashr_i32 s22, s23, 11
	v_cmp_gt_i32_e32 vcc, s4, v67
	v_add_u32_e32 v65, 0x2800, v67
	v_add_u32_e32 v64, v67, v97
	v_lshl_or_b32 v66, s23, 11, v97
	s_barrier
	v_and_b32_e32 v132, 15, v143
	v_bfe_u32 v133, v143, 4, 2
	v_xor_b32_e32 v133, v133, v132
	v_lshlrev_b32_e32 v133, 4, v133
	v_lshl_add_u32 v133, v132, 8, v133
	v_lshrrev_b32_e32 v132, 6, v143
	v_lshl_add_u32 v133, v132, 14, v133
	ds_write_b128 v133, v[0:3]
	ds_write_b128 v133, v[4:7] offset:4096
	ds_write_b128 v133, v[8:11] offset:8192
	ds_write_b128 v133, v[12:15] offset:12288
	v_xor_b32_e32 v127, 64, v133
	ds_write_b128 v127, v[16:19]
	ds_write_b128 v127, v[20:23] offset:4096
	ds_write_b128 v127, v[24:27] offset:8192
	ds_write_b128 v127, v[28:31] offset:12288
	v_xor_b32_e32 v127, 128, v133
	ds_write_b128 v127, v[32:35]
	ds_write_b128 v127, v[36:39] offset:4096
	ds_write_b128 v127, v[40:43] offset:8192
	ds_write_b128 v127, v[44:47] offset:12288
	v_xor_b32_e32 v127, 192, v133
	ds_write_b128 v127, v[48:51]
	ds_write_b128 v127, v[52:55] offset:4096
	ds_write_b128 v127, v[56:59] offset:8192
	ds_write_b128 v127, v[60:63] offset:12288
	v_and_b32_e32 v124, 31, v143
	v_bfe_u32 v126, v143, 5, 1
	v_and_b32_e32 v133, 15, v124
	v_xor_b32_e32 v126, v126, v133
	v_lshlrev_b32_e32 v126, 4, v126
	v_lshl_add_u32 v126, v124, 8, v126
	v_lshl_add_u32 v126, v132, 14, v126
	ds_read_b128 v[48:51], v126
	ds_read_b128 v[32:35], v126 offset:8192
	v_xor_b32_e32 v125, 32, v126
	ds_read_b128 v[52:55], v125
	ds_read_b128 v[36:39], v125 offset:8192
	v_xor_b32_e32 v125, 64, v126
	ds_read_b128 v[56:59], v125
	ds_read_b128 v[40:43], v125 offset:8192
	v_xor_b32_e32 v125, 96, v126
	ds_read_b128 v[60:63], v125
	ds_read_b128 v[44:47], v125 offset:8192
	v_xor_b32_e32 v125, 128, v126
	ds_read_b128 v[16:19], v125
	ds_read_b128 v[0:3], v125 offset:8192
	v_xor_b32_e32 v125, 160, v126
	ds_read_b128 v[20:23], v125
	ds_read_b128 v[4:7], v125 offset:8192
	v_xor_b32_e32 v125, 192, v126
	ds_read_b128 v[24:27], v125
	ds_read_b128 v[8:11], v125 offset:8192
	v_xor_b32_e32 v125, 224, v126
	ds_read_b128 v[28:31], v125
	ds_read_b128 v[12:15], v125 offset:8192
	s_waitcnt lgkmcnt(0)
	s_barrier
	s_and_saveexec_b64 s[8:9], vcc
	s_cbranch_execz .LBB0_973
	s_add_i32 s4, s23, 0xffffe000
	s_lshr_b32 s4, s4, 3
	s_or_b32 s4, s4, 4
	s_cmpk_lt_i32 s23, 0x2000
	s_cselect_b32 s4, s22, s4
	s_mulk_i32 s4, 0x3000
	v_add_u32_e32 v68, s4, v65
	v_mov_b32_e32 v69, v140
	v_lshl_add_u64 v[68:69], v[68:69], 2, s[26:27]
	global_load_dword v72, v[68:69], off
	v_add_u32_e32 v68, v66, v67
	v_mov_b32_e32 v69, v140
	v_lshl_add_u64 v[70:71], v[68:69], 2, s[0:1]
	global_load_dword v69, v[70:71], off
	s_waitcnt vmcnt(0)
	v_fmac_f32_e32 v69, v48, v72
	global_store_dword v[70:71], v69, off
	v_add_u32_e32 v70, 0x800, v68
	v_mov_b32_e32 v71, v140
	v_lshl_add_u64 v[70:71], v[70:71], 2, s[0:1]
	global_load_dword v48, v[70:71], off
	s_waitcnt vmcnt(0)
	v_fmac_f32_e32 v48, v49, v72
	global_store_dword v[70:71], v48, off
	v_add_u32_e32 v48, 0x1000, v68
	v_mov_b32_e32 v49, v140
	v_lshl_add_u64 v[48:49], v[48:49], 2, s[0:1]
	global_load_dword v69, v[48:49], off
	s_waitcnt vmcnt(0)
	v_fmac_f32_e32 v69, v50, v72
	global_store_dword v[48:49], v69, off
	v_add_u32_e32 v48, 0x1800, v68
	v_mov_b32_e32 v49, v140
	v_lshl_add_u64 v[48:49], v[48:49], 2, s[0:1]
	global_load_dword v50, v[48:49], off
	s_waitcnt vmcnt(0)
	v_fmac_f32_e32 v50, v51, v72
	global_store_dword v[48:49], v50, off
	s_add_i32 s15, s23, 0xffffe008
	s_lshr_b32 s15, s15, 3
	s_or_b32 s4, s23, 8
	s_or_b32 s15, s15, 4
	s_cmpk_lt_i32 s4, 0x2000
	s_cselect_b32 s15, s22, s15
	s_mulk_i32 s15, 0x3000
	v_add_u32_e32 v48, s15, v65
	v_mov_b32_e32 v49, v140
	v_lshl_add_u64 v[48:49], v[48:49], 2, s[26:27]
	global_load_dword v68, v[48:49], off
	v_lshl_add_u32 v48, s4, 11, v64
	v_mov_b32_e32 v49, v140
	v_lshl_add_u64 v[50:51], v[48:49], 2, s[0:1]
	global_load_dword v49, v[50:51], off
	s_waitcnt vmcnt(0)
	v_fmac_f32_e32 v49, v52, v68
	global_store_dword v[50:51], v49, off
	v_add_u32_e32 v50, 0x800, v48
	v_mov_b32_e32 v51, v140
	v_lshl_add_u64 v[50:51], v[50:51], 2, s[0:1]
	global_load_dword v49, v[50:51], off
	s_waitcnt vmcnt(0)
	v_fmac_f32_e32 v49, v53, v68
	global_store_dword v[50:51], v49, off
	v_add_u32_e32 v50, 0x1000, v48
	v_mov_b32_e32 v51, v140
	v_lshl_add_u64 v[50:51], v[50:51], 2, s[0:1]
	global_load_dword v49, v[50:51], off
	v_add_u32_e32 v48, 0x1800, v48
	s_waitcnt vmcnt(0)
	v_fmac_f32_e32 v49, v54, v68
	global_store_dword v[50:51], v49, off
	v_mov_b32_e32 v49, v140
	v_lshl_add_u64 v[48:49], v[48:49], 2, s[0:1]
	global_load_dword v50, v[48:49], off
	s_waitcnt vmcnt(0)
	v_fmac_f32_e32 v50, v55, v68
	global_store_dword v[48:49], v50, off
	s_add_i32 s15, s23, 0xffffe010
	s_lshr_b32 s15, s15, 3
	s_or_b32 s4, s23, 16
	s_or_b32 s15, s15, 4
	s_cmpk_lt_i32 s4, 0x2000
	s_cselect_b32 s15, s22, s15
	s_mulk_i32 s15, 0x3000
	v_add_u32_e32 v48, s15, v65
	v_mov_b32_e32 v49, v140
	v_lshl_add_u64 v[48:49], v[48:49], 2, s[26:27]
	global_load_dword v52, v[48:49], off
	v_lshl_add_u32 v48, s4, 11, v64
	v_mov_b32_e32 v49, v140
	v_lshl_add_u64 v[50:51], v[48:49], 2, s[0:1]
	global_load_dword v49, v[50:51], off
	s_waitcnt vmcnt(0)
	v_fmac_f32_e32 v49, v56, v52
	global_store_dword v[50:51], v49, off
	v_add_u32_e32 v50, 0x800, v48
	v_mov_b32_e32 v51, v140
	v_lshl_add_u64 v[50:51], v[50:51], 2, s[0:1]
	global_load_dword v49, v[50:51], off
	s_waitcnt vmcnt(0)
	v_fmac_f32_e32 v49, v57, v52
	global_store_dword v[50:51], v49, off
	v_add_u32_e32 v50, 0x1000, v48
	v_mov_b32_e32 v51, v140
	v_lshl_add_u64 v[50:51], v[50:51], 2, s[0:1]
	global_load_dword v49, v[50:51], off
	v_add_u32_e32 v48, 0x1800, v48
	s_waitcnt vmcnt(0)
	v_fmac_f32_e32 v49, v58, v52
	global_store_dword v[50:51], v49, off
	v_mov_b32_e32 v49, v140
	v_lshl_add_u64 v[48:49], v[48:49], 2, s[0:1]
	global_load_dword v50, v[48:49], off
	s_waitcnt vmcnt(0)
	v_fmac_f32_e32 v50, v59, v52
	global_store_dword v[48:49], v50, off
	s_add_i32 s15, s23, 0xffffe018
	s_lshr_b32 s15, s15, 3
	s_or_b32 s4, s23, 24
	s_or_b32 s15, s15, 4
	s_cmpk_lt_i32 s4, 0x2000
	s_cselect_b32 s15, s22, s15
	s_mulk_i32 s15, 0x3000
	v_add_u32_e32 v48, s15, v65
	v_mov_b32_e32 v49, v140
	v_lshl_add_u64 v[48:49], v[48:49], 2, s[26:27]
	global_load_dword v52, v[48:49], off
	v_lshl_add_u32 v48, s4, 11, v64
	v_mov_b32_e32 v49, v140
	v_lshl_add_u64 v[50:51], v[48:49], 2, s[0:1]
	global_load_dword v49, v[50:51], off
	s_waitcnt vmcnt(0)
	v_fmac_f32_e32 v49, v60, v52
	global_store_dword v[50:51], v49, off
	v_add_u32_e32 v50, 0x800, v48
	v_mov_b32_e32 v51, v140
	v_lshl_add_u64 v[50:51], v[50:51], 2, s[0:1]
	global_load_dword v49, v[50:51], off
	s_waitcnt vmcnt(0)
	v_fmac_f32_e32 v49, v61, v52
	global_store_dword v[50:51], v49, off
	v_add_u32_e32 v50, 0x1000, v48
	v_mov_b32_e32 v51, v140
	v_lshl_add_u64 v[50:51], v[50:51], 2, s[0:1]
	global_load_dword v49, v[50:51], off
	v_add_u32_e32 v48, 0x1800, v48
	s_waitcnt vmcnt(0)
	v_fmac_f32_e32 v49, v62, v52
	global_store_dword v[50:51], v49, off
	v_mov_b32_e32 v49, v140
	v_lshl_add_u64 v[48:49], v[48:49], 2, s[0:1]
	global_load_dword v50, v[48:49], off
	s_waitcnt vmcnt(0)
	v_fmac_f32_e32 v50, v63, v52
	global_store_dword v[48:49], v50, off

.LBB0_979:
	v_readlane_b32 s8, v219, 0
	v_readlane_b32 s9, v219, 1
	s_and_b64 vcc, exec, s[8:9]
	s_cbranch_vccz .LBB0_991
	v_readlane_b32 s4, v219, 2
	v_mov_b32_e32 v97, v140
	v_readlane_b32 s8, v219, 26
	v_add_u32_e32 v0, s4, v123
	v_ashrrev_i32_e32 v1, 31, v0
	v_lshlrev_b64 v[34:35], 14, v[0:1]
	v_lshl_add_u64 v[0:1], s[30:31], 0, v[34:35]
	v_lshl_add_u64 v[0:1], v[0:1], 0, v[96:97]
	v_readlane_b32 s9, v219, 27
	v_readlane_b32 s4, v219, 3
	v_lshlrev_b32_e32 v54, 4, v120
	v_lshl_add_u64 v[36:37], v[0:1], 0, s[8:9]
	v_add_u32_e32 v0, s4, v123
	v_add_co_u32_e32 v42, vcc, s41, v36
	v_ashrrev_i32_e32 v1, 31, v0
	s_nop 0
	v_addc_co_u32_e32 v43, vcc, 0, v37, vcc
	v_lshlrev_b64 v[38:39], 14, v[0:1]
	v_add_co_u32_e32 v44, vcc, s42, v36
	v_lshl_add_u64 v[0:1], s[34:35], 0, v[38:39]
	s_nop 0
	v_addc_co_u32_e32 v45, vcc, 0, v37, vcc
	v_lshl_add_u64 v[0:1], v[0:1], 0, v[96:97]
	v_add_co_u32_e32 v46, vcc, s19, v36
	v_lshl_add_u64 v[40:41], v[0:1], 0, s[8:9]
	s_nop 0
	v_addc_co_u32_e32 v47, vcc, 0, v37, vcc
	s_waitcnt vmcnt(11)
	v_add_co_u32_e32 v48, vcc, s41, v40
	v_readfirstlane_b32 s100, v114
	s_nop 3
	s_add_u32 m0, s100, 0x0
	s_nop 0
	global_load_lds_dwordx4 v[36:37], off
	s_add_u32 m0, s100, 0x1000
	s_nop 0
	global_load_lds_dwordx4 v[42:43], off
	v_addc_co_u32_e32 v49, vcc, 0, v41, vcc
	v_add_co_u32_e32 v50, vcc, s42, v40
	s_add_u32 m0, s100, 0x2000
	s_nop 0
	global_load_lds_dwordx4 v[44:45], off
	s_nop 0
	v_addc_co_u32_e32 v51, vcc, 0, v41, vcc
	v_add_co_u32_e32 v52, vcc, s19, v40
	s_add_u32 m0, s100, 0x3000
	s_nop 0
	global_load_lds_dwordx4 v[46:47], off
	s_add_u32 m0, s100, 0x4000
	s_nop 0
	global_load_lds_dwordx4 v[40:41], off
	v_addc_co_u32_e32 v53, vcc, 0, v41, vcc
	s_add_u32 m0, s100, 0x5000
	s_nop 0
	global_load_lds_dwordx4 v[48:49], off
	s_add_u32 m0, s100, 0x6000
	s_nop 0
	global_load_lds_dwordx4 v[50:51], off
	s_add_u32 m0, s100, 0x7000
	s_nop 0
	global_load_lds_dwordx4 v[52:53], off
	v_lshlrev_b32_e32 v58, 4, v118
	v_lshlrev_b32_e32 v1, 4, v119
	v_lshlrev_b32_e32 v56, 4, v121
	v_lshlrev_b32_e32 v57, 4, v122
	s_add_u32 s8, s28, s8
	v_mov_b32_e32 v55, v140
	v_or_b32_e32 v60, v54, v116
	v_or_b32_e32 v61, v54, v117
	v_and_b32_e32 v54, 0x70, v58
	v_lshl_add_u64 v[38:39], s[94:95], 0, v[38:39]
	v_mov_b32_e32 v0, 0
	v_or_b32_e32 v59, v1, v116
	v_or_b32_e32 v1, v1, v117
	v_or_b32_e32 v62, v56, v116
	v_or_b32_e32 v56, v56, v117
	v_or_b32_e32 v63, v57, v116
	v_or_b32_e32 v57, v57, v117
	s_addc_u32 s9, s29, s9
	v_or_b32_e32 v34, v34, v54
	v_lshl_add_u64 v[38:39], v[38:39], 0, v[54:55]
	s_mov_b64 s[30:31], 0
	v_lshl_add_u64 v[96:97], s[8:9], 0, v[34:35]
	v_lshl_add_u64 v[98:99], s[8:9], 0, v[38:39]
	v_add_u32_e32 v104, v59, v115
	v_add_u32_e32 v107, v1, v115
	v_add_u32_e32 v105, v60, v115
	v_add_u32_e32 v106, v61, v115
	v_add_u32_e32 v102, v62, v115
	v_add_u32_e32 v103, v56, v115
	v_add_u32_e32 v100, v63, v115
	v_add_u32_e32 v101, v57, v115
	v_mov_b32_e32 v1, v0
	v_mov_b32_e32 v34, v0
	v_mov_b32_e32 v35, v0
	v_mov_b32_e32 v36, v0
	v_mov_b32_e32 v37, v0
	v_mov_b32_e32 v38, v0
	v_mov_b32_e32 v39, v0
	v_mov_b32_e32 v40, v0
	v_mov_b32_e32 v41, v0
	v_mov_b32_e32 v42, v0
	v_mov_b32_e32 v43, v0
	v_mov_b32_e32 v44, v0
	v_mov_b32_e32 v2, v0
	v_mov_b32_e32 v3, v0
	v_mov_b32_e32 v4, v0
	v_mov_b32_e32 v5, v0
	v_mov_b32_e32 v6, v0
	v_mov_b32_e32 v7, v0
	v_mov_b32_e32 v8, v0
	v_mov_b32_e32 v9, v0
	v_mov_b32_e32 v10, v0
	v_mov_b32_e32 v11, v0
	v_mov_b32_e32 v12, v0
	v_mov_b32_e32 v13, v0
	v_mov_b32_e32 v14, v0
	v_mov_b32_e32 v15, v0
	v_mov_b32_e32 v16, v0
	v_mov_b32_e32 v17, v0
	v_mov_b32_e32 v18, v0
	v_mov_b32_e32 v19, v0
	v_mov_b32_e32 v20, v0
	v_mov_b32_e32 v21, v0
	v_mov_b32_e32 v22, v0
	v_mov_b32_e32 v23, v0
	v_mov_b32_e32 v24, v0
	v_mov_b32_e32 v25, v0
	v_mov_b32_e32 v26, v0
	v_mov_b32_e32 v27, v0
	v_mov_b32_e32 v28, v0
	v_mov_b32_e32 v29, v0
	v_mov_b32_e32 v30, v0
	v_mov_b32_e32 v31, v0
	v_mov_b32_e32 v32, v0
	v_mov_b32_e32 v33, v0
	v_mov_b32_e32 v45, v0
	v_mov_b32_e32 v46, v0
	v_mov_b32_e32 v47, v0
	v_mov_b32_e32 v48, v0
	v_mov_b32_e32 v49, v0
	v_mov_b32_e32 v50, v0
	v_mov_b32_e32 v51, v0
	v_mov_b32_e32 v52, v0
	v_mov_b32_e32 v53, v0
	v_mov_b32_e32 v54, v0
	v_mov_b32_e32 v55, v0
	v_mov_b32_e32 v56, v0
	v_mov_b32_e32 v57, v0
	v_mov_b32_e32 v58, v0
	v_mov_b32_e32 v59, v0
	v_mov_b32_e32 v60, v0
	v_mov_b32_e32 v61, v0
	v_mov_b32_e32 v62, v0
	v_mov_b32_e32 v63, v0
	v_and_b32_e32 v116, 15, v143
	v_lshrrev_b32_e32 v117, 1, v116
	v_bfe_u32 v105, v143, 4, 2
	v_xor_b32_e32 v117, v117, v105
	v_lshlrev_b32_e32 v117, 4, v117
	v_lshl_add_u32 v117, v116, 7, v117
	v_lshrrev_b32_e32 v116, 6, v143
	v_lshrrev_b32_e32 v104, 1, v116
	v_and_b32_e32 v116, 1, v116
	v_lshl_add_u32 v104, v104, 13, v117
	v_lshl_add_u32 v107, v116, 13, v117
	v_add_u32_e32 v107, 0x4000, v107
	v_xor_b32_e32 v105, 64, v104
	v_xor_b32_e32 v106, 64, v107
	s_waitcnt vmcnt(0) lgkmcnt(0)
	s_barrier
.LBB0_981:
	v_lshl_add_u64 v[72:73], v[96:97], 0, s[30:31]
	v_add_co_u32_e32 v108, vcc, s6, v72
	v_lshl_add_u64 v[88:89], v[98:99], 0, s[30:31]
	s_nop 0
	v_addc_co_u32_e32 v109, vcc, 0, v73, vcc
	v_add_co_u32_e32 v128, vcc, s78, v72
	s_nop 1
	v_addc_co_u32_e32 v129, vcc, 0, v73, vcc
	v_add_co_u32_e32 v130, vcc, s63, v72
	v_addc_co_u32_e32 v131, vcc, 0, v73, vcc
	v_add_co_u32_e32 v132, vcc, s7, v72
	s_nop 1
	v_addc_co_u32_e32 v133, vcc, 0, v73, vcc
	v_add_co_u32_e32 v134, vcc, s79, v88
	v_addc_co_u32_e32 v135, vcc, 0, v89, vcc
	v_add_co_u32_e32 v144, vcc, s82, v88
	s_nop 1
	v_addc_co_u32_e32 v145, vcc, 0, v89, vcc
	v_add_co_u32_e32 v146, vcc, s2, v88
	v_addc_co_u32_e32 v147, vcc, 0, v89, vcc
	v_add_co_u32_e32 v148, vcc, s17, v88
	s_nop 1
	v_addc_co_u32_e32 v149, vcc, 0, v89, vcc
	v_lshl_add_u64 v[108:109], 8, 4, v[108:109]
	v_lshl_add_u64 v[128:129], 8, 4, v[128:129]
	v_lshl_add_u64 v[130:131], 8, 4, v[130:131]
	v_lshl_add_u64 v[132:133], 8, 4, v[132:133]
	v_lshl_add_u64 v[134:135], 8, 4, v[134:135]
	v_lshl_add_u64 v[144:145], 8, 4, v[144:145]
	v_lshl_add_u64 v[146:147], 8, 4, v[146:147]
	v_lshl_add_u64 v[148:149], 8, 4, v[148:149]
	s_add_u32 m0, s100, 0x8000
	s_nop 0
	global_load_lds_dwordx4 v[108:109], off
	s_add_u32 m0, s100, 0x9000
	s_nop 0
	global_load_lds_dwordx4 v[128:129], off
	s_add_u32 m0, s100, 0xa000
	s_nop 0
	global_load_lds_dwordx4 v[130:131], off
	s_add_u32 m0, s100, 0xb000
	s_nop 0
	global_load_lds_dwordx4 v[132:133], off
	s_add_u32 m0, s100, 0xc000
	s_nop 0
	global_load_lds_dwordx4 v[134:135], off
	s_add_u32 m0, s100, 0xd000
	s_nop 0
	global_load_lds_dwordx4 v[144:145], off
	s_add_u32 m0, s100, 0xe000
	s_nop 0
	global_load_lds_dwordx4 v[146:147], off
	s_add_u32 m0, s100, 0xf000
	s_nop 0
	global_load_lds_dwordx4 v[148:149], off
	ds_read_b128 a[0:3], v104
	ds_read_b128 v[64:67], v107
	ds_read_b128 a[4:7], v104 offset:2048
	ds_read_b128 a[8:11], v104 offset:4096
	ds_read_b128 a[12:15], v104 offset:6144
	ds_read_b128 v[80:83], v107 offset:2048
	ds_read_b128 v[76:79], v107 offset:4096
	ds_read_b128 v[72:75], v107 offset:6144
	ds_read_b128 a[16:19], v105
	ds_read_b128 a[20:23], v105 offset:2048
	ds_read_b128 a[24:27], v105 offset:4096
	ds_read_b128 a[28:31], v105 offset:6144
	s_setprio 1
	s_waitcnt lgkmcnt(10)
	v_mfma_f32_16x16x32_bf16 v[0:3], a[0:3], v[64:67], v[0:3]
	s_waitcnt lgkmcnt(9)
	v_mfma_f32_16x16x32_bf16 v[16:19], a[4:7], v[64:67], v[16:19]
	s_waitcnt lgkmcnt(8)
	v_mfma_f32_16x16x32_bf16 v[32:35], a[8:11], v[64:67], v[32:35]
	s_waitcnt lgkmcnt(7)
	v_mfma_f32_16x16x32_bf16 v[48:51], a[12:15], v[64:67], v[48:51]
	ds_read_b128 v[64:67], v106
	s_waitcnt lgkmcnt(7)
	v_mfma_f32_16x16x32_bf16 v[4:7], a[0:3], v[80:83], v[4:7]
	v_mfma_f32_16x16x32_bf16 v[20:23], a[4:7], v[80:83], v[20:23]
	v_mfma_f32_16x16x32_bf16 v[36:39], a[8:11], v[80:83], v[36:39]
	v_mfma_f32_16x16x32_bf16 v[52:55], a[12:15], v[80:83], v[52:55]
	ds_read_b128 v[80:83], v106 offset:2048
	s_waitcnt lgkmcnt(7)
	v_mfma_f32_16x16x32_bf16 v[8:11], a[0:3], v[76:79], v[8:11]
	v_mfma_f32_16x16x32_bf16 v[24:27], a[4:7], v[76:79], v[24:27]
	v_mfma_f32_16x16x32_bf16 v[40:43], a[8:11], v[76:79], v[40:43]
	v_mfma_f32_16x16x32_bf16 v[56:59], a[12:15], v[76:79], v[56:59]
	ds_read_b128 v[76:79], v106 offset:4096
	s_waitcnt lgkmcnt(7)
	v_mfma_f32_16x16x32_bf16 v[12:15], a[0:3], v[72:75], v[12:15]
	v_mfma_f32_16x16x32_bf16 v[28:31], a[4:7], v[72:75], v[28:31]
	v_mfma_f32_16x16x32_bf16 v[44:47], a[8:11], v[72:75], v[44:47]
	v_mfma_f32_16x16x32_bf16 v[60:63], a[12:15], v[72:75], v[60:63]
	ds_read_b128 v[72:75], v106 offset:6144
	s_waitcnt lgkmcnt(3)
	v_mfma_f32_16x16x32_bf16 v[0:3], a[16:19], v[64:67], v[0:3]
	v_mfma_f32_16x16x32_bf16 v[16:19], a[20:23], v[64:67], v[16:19]
	v_mfma_f32_16x16x32_bf16 v[32:35], a[24:27], v[64:67], v[32:35]
	v_mfma_f32_16x16x32_bf16 v[48:51], a[28:31], v[64:67], v[48:51]
	s_waitcnt lgkmcnt(2)
	v_mfma_f32_16x16x32_bf16 v[4:7], a[16:19], v[80:83], v[4:7]
	v_mfma_f32_16x16x32_bf16 v[20:23], a[20:23], v[80:83], v[20:23]
	v_mfma_f32_16x16x32_bf16 v[36:39], a[24:27], v[80:83], v[36:39]
	v_mfma_f32_16x16x32_bf16 v[52:55], a[28:31], v[80:83], v[52:55]
	s_waitcnt lgkmcnt(1)
	v_mfma_f32_16x16x32_bf16 v[8:11], a[16:19], v[76:79], v[8:11]
	v_mfma_f32_16x16x32_bf16 v[24:27], a[20:23], v[76:79], v[24:27]
	v_mfma_f32_16x16x32_bf16 v[40:43], a[24:27], v[76:79], v[40:43]
	v_mfma_f32_16x16x32_bf16 v[56:59], a[28:31], v[76:79], v[56:59]
	s_waitcnt lgkmcnt(0)
	v_mfma_f32_16x16x32_bf16 v[12:15], a[16:19], v[72:75], v[12:15]
	v_mfma_f32_16x16x32_bf16 v[28:31], a[20:23], v[72:75], v[28:31]
	v_mfma_f32_16x16x32_bf16 v[44:47], a[24:27], v[72:75], v[44:47]
	v_mfma_f32_16x16x32_bf16 v[60:63], a[28:31], v[72:75], v[60:63]
	s_setprio 0
	s_waitcnt vmcnt(0) lgkmcnt(0)
	s_barrier
	v_lshl_add_u64 v[68:69], 8, 4, v[108:109]
	v_lshl_add_u64 v[70:71], 8, 4, v[128:129]
	v_lshl_add_u64 v[84:85], 8, 4, v[130:131]
	v_lshl_add_u64 v[86:87], 8, 4, v[132:133]
	v_lshl_add_u64 v[92:93], 8, 4, v[134:135]
	v_lshl_add_u64 v[94:95], 8, 4, v[144:145]
	v_lshl_add_u64 v[88:89], 8, 4, v[146:147]
	v_lshl_add_u64 v[90:91], 8, 4, v[148:149]
	s_add_u32 m0, s100, 0x0
	s_nop 0
	global_load_lds_dwordx4 v[68:69], off
	s_add_u32 m0, s100, 0x1000
	s_nop 0
	global_load_lds_dwordx4 v[70:71], off
	s_add_u32 m0, s100, 0x2000
	s_nop 0
	global_load_lds_dwordx4 v[84:85], off
	s_add_u32 m0, s100, 0x3000
	s_nop 0
	global_load_lds_dwordx4 v[86:87], off
	s_add_u32 m0, s100, 0x4000
	s_nop 0
	global_load_lds_dwordx4 v[92:93], off
	s_add_u32 m0, s100, 0x5000
	s_nop 0
	global_load_lds_dwordx4 v[94:95], off
	s_add_u32 m0, s100, 0x6000
	s_nop 0
	global_load_lds_dwordx4 v[88:89], off
	s_add_u32 m0, s100, 0x7000
	s_nop 0
	global_load_lds_dwordx4 v[90:91], off
	ds_read_b128 a[0:3], v104 offset:32768
	ds_read_b128 v[64:67], v107 offset:32768
	ds_read_b128 a[4:7], v104 offset:34816
	ds_read_b128 a[8:11], v104 offset:36864
	ds_read_b128 a[12:15], v104 offset:38912
	ds_read_b128 v[80:83], v107 offset:34816
	ds_read_b128 v[76:79], v107 offset:36864
	ds_read_b128 v[72:75], v107 offset:38912
	ds_read_b128 a[16:19], v105 offset:32768
	ds_read_b128 a[20:23], v105 offset:34816
	ds_read_b128 a[24:27], v105 offset:36864
	ds_read_b128 a[28:31], v105 offset:38912
	s_setprio 1
	s_waitcnt lgkmcnt(10)
	v_mfma_f32_16x16x32_bf16 v[0:3], a[0:3], v[64:67], v[0:3]
	s_waitcnt lgkmcnt(9)
	v_mfma_f32_16x16x32_bf16 v[16:19], a[4:7], v[64:67], v[16:19]
	s_waitcnt lgkmcnt(8)
	v_mfma_f32_16x16x32_bf16 v[32:35], a[8:11], v[64:67], v[32:35]
	s_waitcnt lgkmcnt(7)
	v_mfma_f32_16x16x32_bf16 v[48:51], a[12:15], v[64:67], v[48:51]
	ds_read_b128 v[64:67], v106 offset:32768
	s_waitcnt lgkmcnt(7)
	v_mfma_f32_16x16x32_bf16 v[4:7], a[0:3], v[80:83], v[4:7]
	v_mfma_f32_16x16x32_bf16 v[20:23], a[4:7], v[80:83], v[20:23]
	v_mfma_f32_16x16x32_bf16 v[36:39], a[8:11], v[80:83], v[36:39]
	v_mfma_f32_16x16x32_bf16 v[52:55], a[12:15], v[80:83], v[52:55]
	ds_read_b128 v[80:83], v106 offset:34816
	s_waitcnt lgkmcnt(7)
	v_mfma_f32_16x16x32_bf16 v[8:11], a[0:3], v[76:79], v[8:11]
	v_mfma_f32_16x16x32_bf16 v[24:27], a[4:7], v[76:79], v[24:27]
	v_mfma_f32_16x16x32_bf16 v[40:43], a[8:11], v[76:79], v[40:43]
	v_mfma_f32_16x16x32_bf16 v[56:59], a[12:15], v[76:79], v[56:59]
	ds_read_b128 v[76:79], v106 offset:36864
	s_waitcnt lgkmcnt(7)
	v_mfma_f32_16x16x32_bf16 v[12:15], a[0:3], v[72:75], v[12:15]
	v_mfma_f32_16x16x32_bf16 v[28:31], a[4:7], v[72:75], v[28:31]
	v_mfma_f32_16x16x32_bf16 v[44:47], a[8:11], v[72:75], v[44:47]
	v_mfma_f32_16x16x32_bf16 v[60:63], a[12:15], v[72:75], v[60:63]
	ds_read_b128 v[72:75], v106 offset:38912
	s_waitcnt lgkmcnt(3)
	v_mfma_f32_16x16x32_bf16 v[0:3], a[16:19], v[64:67], v[0:3]
	v_mfma_f32_16x16x32_bf16 v[16:19], a[20:23], v[64:67], v[16:19]
	v_mfma_f32_16x16x32_bf16 v[32:35], a[24:27], v[64:67], v[32:35]
	v_mfma_f32_16x16x32_bf16 v[48:51], a[28:31], v[64:67], v[48:51]
	s_waitcnt lgkmcnt(2)
	v_mfma_f32_16x16x32_bf16 v[4:7], a[16:19], v[80:83], v[4:7]
	v_mfma_f32_16x16x32_bf16 v[20:23], a[20:23], v[80:83], v[20:23]
	v_mfma_f32_16x16x32_bf16 v[36:39], a[24:27], v[80:83], v[36:39]
	v_mfma_f32_16x16x32_bf16 v[52:55], a[28:31], v[80:83], v[52:55]
	s_waitcnt lgkmcnt(1)
	v_mfma_f32_16x16x32_bf16 v[8:11], a[16:19], v[76:79], v[8:11]
	v_mfma_f32_16x16x32_bf16 v[24:27], a[20:23], v[76:79], v[24:27]
	v_mfma_f32_16x16x32_bf16 v[40:43], a[24:27], v[76:79], v[40:43]
	v_mfma_f32_16x16x32_bf16 v[56:59], a[28:31], v[76:79], v[56:59]
	s_waitcnt lgkmcnt(0)
	v_mfma_f32_16x16x32_bf16 v[12:15], a[16:19], v[72:75], v[12:15]
	v_mfma_f32_16x16x32_bf16 v[28:31], a[20:23], v[72:75], v[28:31]
	v_mfma_f32_16x16x32_bf16 v[44:47], a[24:27], v[72:75], v[44:47]
	v_mfma_f32_16x16x32_bf16 v[60:63], a[28:31], v[72:75], v[60:63]
	s_setprio 0
	s_waitcnt vmcnt(0) lgkmcnt(0)
	s_barrier
	s_add_u32 s30, s30, 0x100
	s_addc_u32 s31, s31, 0
	s_cmpk_eq_i32 s30, 0xf00
	s_cbranch_scc0 .LBB0_981
	v_lshl_add_u64 v[68:69], 8, 4, v[68:69]
	v_lshl_add_u64 v[70:71], 8, 4, v[70:71]
	v_lshl_add_u64 v[84:85], 8, 4, v[84:85]
	v_lshl_add_u64 v[86:87], 8, 4, v[86:87]
	v_lshl_add_u64 v[92:93], 8, 4, v[92:93]
	v_lshl_add_u64 v[94:95], 8, 4, v[94:95]
	v_lshl_add_u64 v[88:89], 8, 4, v[88:89]
	v_lshl_add_u64 v[90:91], 8, 4, v[90:91]
	s_add_u32 m0, s100, 0x8000
	s_nop 0
	global_load_lds_dwordx4 v[68:69], off
	s_add_u32 m0, s100, 0x9000
	s_nop 0
	global_load_lds_dwordx4 v[70:71], off
	s_add_u32 m0, s100, 0xa000
	s_nop 0
	global_load_lds_dwordx4 v[84:85], off
	s_add_u32 m0, s100, 0xb000
	s_nop 0
	global_load_lds_dwordx4 v[86:87], off
	s_add_u32 m0, s100, 0xc000
	s_nop 0
	global_load_lds_dwordx4 v[92:93], off
	s_add_u32 m0, s100, 0xd000
	s_nop 0
	global_load_lds_dwordx4 v[94:95], off
	s_add_u32 m0, s100, 0xe000
	s_nop 0
	global_load_lds_dwordx4 v[88:89], off
	s_add_u32 m0, s100, 0xf000
	s_nop 0
	global_load_lds_dwordx4 v[90:91], off
	ds_read_b128 a[0:3], v104
	ds_read_b128 v[64:67], v107
	ds_read_b128 a[4:7], v104 offset:2048
	ds_read_b128 a[8:11], v104 offset:4096
	ds_read_b128 a[12:15], v104 offset:6144
	ds_read_b128 v[80:83], v107 offset:2048
	ds_read_b128 v[76:79], v107 offset:4096
	ds_read_b128 v[72:75], v107 offset:6144
	ds_read_b128 a[16:19], v105
	ds_read_b128 a[20:23], v105 offset:2048
	ds_read_b128 a[24:27], v105 offset:4096
	ds_read_b128 a[28:31], v105 offset:6144
	s_setprio 1
	s_waitcnt lgkmcnt(10)
	v_mfma_f32_16x16x32_bf16 v[0:3], a[0:3], v[64:67], v[0:3]
	s_waitcnt lgkmcnt(9)
	v_mfma_f32_16x16x32_bf16 v[16:19], a[4:7], v[64:67], v[16:19]
	s_waitcnt lgkmcnt(8)
	v_mfma_f32_16x16x32_bf16 v[32:35], a[8:11], v[64:67], v[32:35]
	s_waitcnt lgkmcnt(7)
	v_mfma_f32_16x16x32_bf16 v[48:51], a[12:15], v[64:67], v[48:51]
	ds_read_b128 v[64:67], v106
	s_waitcnt lgkmcnt(7)
	v_mfma_f32_16x16x32_bf16 v[4:7], a[0:3], v[80:83], v[4:7]
	v_mfma_f32_16x16x32_bf16 v[20:23], a[4:7], v[80:83], v[20:23]
	v_mfma_f32_16x16x32_bf16 v[36:39], a[8:11], v[80:83], v[36:39]
	v_mfma_f32_16x16x32_bf16 v[52:55], a[12:15], v[80:83], v[52:55]
	ds_read_b128 v[80:83], v106 offset:2048
	s_waitcnt lgkmcnt(7)
	v_mfma_f32_16x16x32_bf16 v[8:11], a[0:3], v[76:79], v[8:11]
	v_mfma_f32_16x16x32_bf16 v[24:27], a[4:7], v[76:79], v[24:27]
	v_mfma_f32_16x16x32_bf16 v[40:43], a[8:11], v[76:79], v[40:43]
	v_mfma_f32_16x16x32_bf16 v[56:59], a[12:15], v[76:79], v[56:59]
	ds_read_b128 v[76:79], v106 offset:4096
	s_waitcnt lgkmcnt(7)
	v_mfma_f32_16x16x32_bf16 v[12:15], a[0:3], v[72:75], v[12:15]
	v_mfma_f32_16x16x32_bf16 v[28:31], a[4:7], v[72:75], v[28:31]
	v_mfma_f32_16x16x32_bf16 v[44:47], a[8:11], v[72:75], v[44:47]
	v_mfma_f32_16x16x32_bf16 v[60:63], a[12:15], v[72:75], v[60:63]
	ds_read_b128 v[72:75], v106 offset:6144
	s_waitcnt lgkmcnt(3)
	v_mfma_f32_16x16x32_bf16 v[0:3], a[16:19], v[64:67], v[0:3]
	v_mfma_f32_16x16x32_bf16 v[16:19], a[20:23], v[64:67], v[16:19]
	v_mfma_f32_16x16x32_bf16 v[32:35], a[24:27], v[64:67], v[32:35]
	v_mfma_f32_16x16x32_bf16 v[48:51], a[28:31], v[64:67], v[48:51]
	s_waitcnt lgkmcnt(2)
	v_mfma_f32_16x16x32_bf16 v[4:7], a[16:19], v[80:83], v[4:7]
	v_mfma_f32_16x16x32_bf16 v[20:23], a[20:23], v[80:83], v[20:23]
	v_mfma_f32_16x16x32_bf16 v[36:39], a[24:27], v[80:83], v[36:39]
	v_mfma_f32_16x16x32_bf16 v[52:55], a[28:31], v[80:83], v[52:55]
	s_waitcnt lgkmcnt(1)
	v_mfma_f32_16x16x32_bf16 v[8:11], a[16:19], v[76:79], v[8:11]
	v_mfma_f32_16x16x32_bf16 v[24:27], a[20:23], v[76:79], v[24:27]
	v_mfma_f32_16x16x32_bf16 v[40:43], a[24:27], v[76:79], v[40:43]
	v_mfma_f32_16x16x32_bf16 v[56:59], a[28:31], v[76:79], v[56:59]
	s_waitcnt lgkmcnt(0)
	v_mfma_f32_16x16x32_bf16 v[12:15], a[16:19], v[72:75], v[12:15]
	v_mfma_f32_16x16x32_bf16 v[28:31], a[20:23], v[72:75], v[28:31]
	v_mfma_f32_16x16x32_bf16 v[44:47], a[24:27], v[72:75], v[44:47]
	v_mfma_f32_16x16x32_bf16 v[60:63], a[28:31], v[72:75], v[60:63]
	s_setprio 0
	s_waitcnt vmcnt(0) lgkmcnt(0)
	s_barrier
	ds_read_b128 a[0:3], v104 offset:32768
	ds_read_b128 v[64:67], v107 offset:32768
	ds_read_b128 a[4:7], v104 offset:34816
	ds_read_b128 a[8:11], v104 offset:36864
	ds_read_b128 a[12:15], v104 offset:38912
	ds_read_b128 v[80:83], v107 offset:34816
	ds_read_b128 v[76:79], v107 offset:36864
	ds_read_b128 v[72:75], v107 offset:38912
	ds_read_b128 a[16:19], v105 offset:32768
	ds_read_b128 a[20:23], v105 offset:34816
	ds_read_b128 a[24:27], v105 offset:36864
	ds_read_b128 a[28:31], v105 offset:38912
	s_setprio 1
	s_waitcnt lgkmcnt(10)
	v_mfma_f32_16x16x32_bf16 v[0:3], a[0:3], v[64:67], v[0:3]
	s_waitcnt lgkmcnt(9)
	v_mfma_f32_16x16x32_bf16 v[16:19], a[4:7], v[64:67], v[16:19]
	s_waitcnt lgkmcnt(8)
	v_mfma_f32_16x16x32_bf16 v[32:35], a[8:11], v[64:67], v[32:35]
	s_waitcnt lgkmcnt(7)
	v_mfma_f32_16x16x32_bf16 v[48:51], a[12:15], v[64:67], v[48:51]
	ds_read_b128 v[64:67], v106 offset:32768
	s_waitcnt lgkmcnt(7)
	v_mfma_f32_16x16x32_bf16 v[4:7], a[0:3], v[80:83], v[4:7]
	v_mfma_f32_16x16x32_bf16 v[20:23], a[4:7], v[80:83], v[20:23]
	v_mfma_f32_16x16x32_bf16 v[36:39], a[8:11], v[80:83], v[36:39]
	v_mfma_f32_16x16x32_bf16 v[52:55], a[12:15], v[80:83], v[52:55]
	ds_read_b128 v[80:83], v106 offset:34816
	s_waitcnt lgkmcnt(7)
	v_mfma_f32_16x16x32_bf16 v[8:11], a[0:3], v[76:79], v[8:11]
	v_mfma_f32_16x16x32_bf16 v[24:27], a[4:7], v[76:79], v[24:27]
	v_mfma_f32_16x16x32_bf16 v[40:43], a[8:11], v[76:79], v[40:43]
	v_mfma_f32_16x16x32_bf16 v[56:59], a[12:15], v[76:79], v[56:59]
	ds_read_b128 v[76:79], v106 offset:36864
	s_waitcnt lgkmcnt(7)
	v_mfma_f32_16x16x32_bf16 v[12:15], a[0:3], v[72:75], v[12:15]
	v_mfma_f32_16x16x32_bf16 v[28:31], a[4:7], v[72:75], v[28:31]
	v_mfma_f32_16x16x32_bf16 v[44:47], a[8:11], v[72:75], v[44:47]
	v_mfma_f32_16x16x32_bf16 v[60:63], a[12:15], v[72:75], v[60:63]
	ds_read_b128 v[72:75], v106 offset:38912
	s_waitcnt lgkmcnt(3)
	v_mfma_f32_16x16x32_bf16 v[0:3], a[16:19], v[64:67], v[0:3]
	v_mfma_f32_16x16x32_bf16 v[16:19], a[20:23], v[64:67], v[16:19]
	v_mfma_f32_16x16x32_bf16 v[32:35], a[24:27], v[64:67], v[32:35]
	v_mfma_f32_16x16x32_bf16 v[48:51], a[28:31], v[64:67], v[48:51]
	s_waitcnt lgkmcnt(2)
	v_mfma_f32_16x16x32_bf16 v[4:7], a[16:19], v[80:83], v[4:7]
	v_mfma_f32_16x16x32_bf16 v[20:23], a[20:23], v[80:83], v[20:23]
	v_mfma_f32_16x16x32_bf16 v[36:39], a[24:27], v[80:83], v[36:39]
	v_mfma_f32_16x16x32_bf16 v[52:55], a[28:31], v[80:83], v[52:55]
	s_waitcnt lgkmcnt(1)
	v_mfma_f32_16x16x32_bf16 v[8:11], a[16:19], v[76:79], v[8:11]
	v_mfma_f32_16x16x32_bf16 v[24:27], a[20:23], v[76:79], v[24:27]
	v_mfma_f32_16x16x32_bf16 v[40:43], a[24:27], v[76:79], v[40:43]
	v_mfma_f32_16x16x32_bf16 v[56:59], a[28:31], v[76:79], v[56:59]
	s_waitcnt lgkmcnt(0)
	v_mfma_f32_16x16x32_bf16 v[12:15], a[16:19], v[72:75], v[12:15]
	v_mfma_f32_16x16x32_bf16 v[28:31], a[20:23], v[72:75], v[28:31]
	v_mfma_f32_16x16x32_bf16 v[44:47], a[24:27], v[72:75], v[44:47]
	v_mfma_f32_16x16x32_bf16 v[60:63], a[28:31], v[72:75], v[60:63]
	s_setprio 0
	v_readfirstlane_b32 s8, v113
	v_readfirstlane_b32 s4, v112
	s_lshl_b32 s8, s8, 6
	v_readlane_b32 s9, v219, 3
	s_waitcnt lgkmcnt(0)
	s_barrier
	s_add_i32 s8, s8, s9
	s_lshl_b32 s15, s4, 6
	v_readlane_b32 s4, v219, 2
	s_add_i32 s15, s15, s4
	v_or_b32_e32 v65, s8, v111
	s_movk_i32 s4, 0x800
	v_cmp_gt_i32_e64 s[38:39], s4, v65
	v_add_u32_e32 v64, 0x2800, v65
	v_lshl_or_b32 v66, v110, 2, s15
	s_barrier
	v_and_b32_e32 v116, 15, v143
	v_bfe_u32 v117, v143, 4, 2
	v_xor_b32_e32 v117, v117, v116
	v_lshlrev_b32_e32 v117, 4, v117
	v_lshl_add_u32 v117, v116, 8, v117
	v_lshrrev_b32_e32 v116, 6, v143
	v_lshl_add_u32 v117, v116, 14, v117
	ds_write_b128 v117, v[0:3]
	ds_write_b128 v117, v[4:7] offset:4096
	ds_write_b128 v117, v[8:11] offset:8192
	ds_write_b128 v117, v[12:15] offset:12288
	v_xor_b32_e32 v106, 64, v117
	ds_write_b128 v106, v[16:19]
	ds_write_b128 v106, v[20:23] offset:4096
	ds_write_b128 v106, v[24:27] offset:8192
	ds_write_b128 v106, v[28:31] offset:12288
	v_xor_b32_e32 v106, 128, v117
	ds_write_b128 v106, v[32:35]
	ds_write_b128 v106, v[36:39] offset:4096
	ds_write_b128 v106, v[40:43] offset:8192
	ds_write_b128 v106, v[44:47] offset:12288
	v_xor_b32_e32 v106, 192, v117
	ds_write_b128 v106, v[48:51]
	ds_write_b128 v106, v[52:55] offset:4096
	ds_write_b128 v106, v[56:59] offset:8192
	ds_write_b128 v106, v[60:63] offset:12288
	v_and_b32_e32 v104, 31, v143
	v_bfe_u32 v105, v143, 5, 1
	v_and_b32_e32 v117, 15, v104
	v_xor_b32_e32 v105, v105, v117
	v_lshlrev_b32_e32 v105, 4, v105
	v_lshl_add_u32 v105, v104, 8, v105
	v_lshl_add_u32 v105, v116, 14, v105
	ds_read_b128 v[48:51], v105
	ds_read_b128 v[32:35], v105 offset:8192
	v_xor_b32_e32 v107, 32, v105
	ds_read_b128 v[52:55], v107
	ds_read_b128 v[36:39], v107 offset:8192
	v_xor_b32_e32 v107, 64, v105
	ds_read_b128 v[56:59], v107
	ds_read_b128 v[40:43], v107 offset:8192
	v_xor_b32_e32 v107, 96, v105
	ds_read_b128 v[60:63], v107
	ds_read_b128 v[44:47], v107 offset:8192
	v_xor_b32_e32 v107, 128, v105
	ds_read_b128 v[16:19], v107
	ds_read_b128 v[0:3], v107 offset:8192
	v_xor_b32_e32 v107, 160, v105
	ds_read_b128 v[20:23], v107
	ds_read_b128 v[4:7], v107 offset:8192
	v_xor_b32_e32 v107, 192, v105
	ds_read_b128 v[24:27], v107
	ds_read_b128 v[8:11], v107 offset:8192
	v_xor_b32_e32 v107, 224, v105
	ds_read_b128 v[28:31], v107
	ds_read_b128 v[12:15], v107 offset:8192
	s_waitcnt lgkmcnt(0)
	s_barrier
	s_and_saveexec_b64 s[8:9], s[38:39]
	s_cbranch_execz .LBB0_984
	s_add_i32 s22, s15, 0xffffe000
	s_lshr_b32 s22, s22, 3
	s_ashr_i32 s4, s15, 11
	s_or_b32 s22, s22, 4
	v_mov_b32_e32 v67, s22
	v_mov_b32_e32 v78, s4
	v_cmp_gt_i32_e32 vcc, s51, v66
	v_mov_b32_e32 v71, v140
	v_mov_b32_e32 v73, v140
	v_cndmask_b32_e32 v67, v67, v78, vcc
	v_mad_u64_u32 v[68:69], s[22:23], v67, s69, v[64:65]
	v_mov_b32_e32 v69, v140
	v_lshl_add_u64 v[68:69], v[68:69], 2, s[26:27]
	global_load_dword v67, v[68:69], off
	v_lshl_add_u32 v68, v66, 11, v65
	v_mov_b32_e32 v69, v140
	v_lshl_add_u64 v[76:77], v[68:69], 2, s[0:1]
	v_add_u32_e32 v70, 0x800, v68
	v_add_u32_e32 v72, 0x1000, v68
	v_mov_b32_e32 v75, v140
	v_add_u32_e32 v74, 0x1800, v68
	v_lshl_add_u64 v[68:69], v[70:71], 2, s[0:1]
	v_lshl_add_u64 v[70:71], v[72:73], 2, s[0:1]
	v_lshl_add_u64 v[72:73], v[74:75], 2, s[0:1]
	s_waitcnt vmcnt(0)
	v_mul_f32_e32 v48, v48, v67
	v_mul_f32_e32 v49, v49, v67
	v_mul_f32_e32 v50, v50, v67
	global_atomic_add_f32 v[76:77], v48, off
	global_atomic_add_f32 v[68:69], v49, off
	global_atomic_add_f32 v[70:71], v50, off
	v_mul_f32_e32 v48, v51, v67
	global_atomic_add_f32 v[72:73], v48, off
	s_add_i32 s4, s15, 0xffffe008
	s_lshr_b32 s4, s4, 3
	v_or_b32_e32 v50, 8, v66
	s_or_b32 s4, s4, 4
	v_mov_b32_e32 v48, s4
	v_cmp_gt_i32_e32 vcc, s51, v50
	v_mov_b32_e32 v51, v140
	v_mov_b32_e32 v69, v140
	v_cndmask_b32_e32 v48, v48, v78, vcc
	v_mad_u64_u32 v[48:49], s[22:23], v48, s69, v[64:65]
	v_mov_b32_e32 v49, v140
	v_lshl_add_u64 v[48:49], v[48:49], 2, s[26:27]
	global_load_dword v67, v[48:49], off
	v_mov_b32_e32 v49, v140
	v_lshl_add_u32 v48, v50, 11, v65
	v_lshl_add_u64 v[72:73], v[48:49], 2, s[0:1]
	v_add_u32_e32 v50, 0x800, v48
	v_add_u32_e32 v68, 0x1000, v48
	v_mov_b32_e32 v71, v140
	v_add_u32_e32 v70, 0x1800, v48
	v_lshl_add_u64 v[48:49], v[50:51], 2, s[0:1]
	v_lshl_add_u64 v[50:51], v[68:69], 2, s[0:1]
	v_lshl_add_u64 v[68:69], v[70:71], 2, s[0:1]
	s_waitcnt vmcnt(0)
	v_mul_f32_e32 v52, v52, v67
	v_mul_f32_e32 v53, v53, v67
	v_mul_f32_e32 v54, v54, v67
	global_atomic_add_f32 v[72:73], v52, off
	global_atomic_add_f32 v[48:49], v53, off
	global_atomic_add_f32 v[50:51], v54, off
	v_mul_f32_e32 v48, v55, v67
	global_atomic_add_f32 v[68:69], v48, off
	s_add_i32 s4, s15, 0xffffe010
	s_lshr_b32 s4, s4, 3
	v_or_b32_e32 v50, 16, v66
	s_or_b32 s4, s4, 4
	v_cmp_gt_i32_e32 vcc, s51, v50
	v_mov_b32_e32 v48, s4
	s_nop 0
	v_cndmask_b32_e32 v48, v48, v78, vcc
	v_mad_u64_u32 v[48:49], s[22:23], v48, s69, v[64:65]
	v_mov_b32_e32 v49, v140
	v_lshl_add_u64 v[48:49], v[48:49], 2, s[26:27]
	global_load_dword v52, v[48:49], off
	v_lshl_add_u32 v48, v50, 11, v65
	v_mov_b32_e32 v49, v140
	v_lshl_add_u64 v[50:51], v[48:49], 2, s[0:1]
	s_waitcnt vmcnt(0)
	v_mul_f32_e32 v49, v56, v52
	global_atomic_add_f32 v[50:51], v49, off
	v_add_u32_e32 v50, 0x800, v48
	v_mov_b32_e32 v51, v140
	v_lshl_add_u64 v[50:51], v[50:51], 2, s[0:1]
	v_mul_f32_e32 v49, v57, v52
	global_atomic_add_f32 v[50:51], v49, off
	v_add_u32_e32 v50, 0x1000, v48
	v_mov_b32_e32 v51, v140
	v_lshl_add_u64 v[50:51], v[50:51], 2, s[0:1]
	v_mul_f32_e32 v49, v58, v52
	global_atomic_add_f32 v[50:51], v49, off
	v_add_u32_e32 v48, 0x1800, v48
	v_mov_b32_e32 v49, v140
	v_lshl_add_u64 v[48:49], v[48:49], 2, s[0:1]
	v_mul_f32_e32 v50, v59, v52
	global_atomic_add_f32 v[48:49], v50, off
	s_add_i32 s4, s15, 0xffffe018
	s_lshr_b32 s4, s4, 3
	v_or_b32_e32 v50, 24, v66
	s_or_b32 s4, s4, 4
	v_mov_b32_e32 v48, s4
	v_cmp_gt_i32_e32 vcc, s51, v50
	v_mov_b32_e32 v51, v140
	v_mov_b32_e32 v53, v140
	v_cndmask_b32_e32 v48, v48, v78, vcc
	v_mad_u64_u32 v[48:49], s[22:23], v48, s69, v[64:65]
	v_mov_b32_e32 v49, v140
	v_lshl_add_u64 v[48:49], v[48:49], 2, s[26:27]
	global_load_dword v58, v[48:49], off
	v_lshl_add_u32 v48, v50, 11, v65
	v_mov_b32_e32 v49, v140
	v_mov_b32_e32 v55, v140
	v_add_u32_e32 v50, 0x800, v48
	v_add_u32_e32 v52, 0x1000, v48
	v_add_u32_e32 v54, 0x1800, v48
	v_lshl_add_u64 v[56:57], v[48:49], 2, s[0:1]
	v_lshl_add_u64 v[48:49], v[50:51], 2, s[0:1]
	v_lshl_add_u64 v[50:51], v[52:53], 2, s[0:1]
	v_lshl_add_u64 v[52:53], v[54:55], 2, s[0:1]
	s_waitcnt vmcnt(0)
	v_mul_f32_e32 v54, v60, v58
	v_mul_f32_e32 v55, v61, v58
	v_mul_f32_e32 v59, v62, v58
	global_atomic_add_f32 v[56:57], v54, off
	global_atomic_add_f32 v[48:49], v55, off
	global_atomic_add_f32 v[50:51], v59, off
	v_mul_f32_e32 v48, v63, v58
	global_atomic_add_f32 v[52:53], v48, off

.LBB0_1005:
	s_mul_hi_i32 s4, s22, 0x38e38e39
	s_lshr_b32 s8, s4, 31
	s_ashr_i32 s4, s4, 4
	s_add_i32 s4, s4, s8
	s_mul_i32 s8, s4, 0x48
	s_sub_i32 s8, s22, s8
	v_lshl_add_u32 v0, s8, 7, v111
	v_ashrrev_i32_e32 v1, 31, v0
	v_lshlrev_b64 v[32:33], 12, v[0:1]
	v_lshl_add_u64 v[34:35], v[96:97], 0, v[32:33]
	v_add_co_u32_e32 v40, vcc, s87, v34
	s_lshl_b32 s9, s4, 7
	s_nop 0
	v_addc_co_u32_e32 v41, vcc, 0, v35, vcc
	v_add_co_u32_e32 v42, vcc, s66, v34
	v_add_u32_e32 v0, s9, v111
	s_nop 0
	v_addc_co_u32_e32 v43, vcc, 0, v35, vcc
	v_ashrrev_i32_e32 v1, 31, v0
	v_add_co_u32_e32 v44, vcc, s20, v34
	v_lshlrev_b64 v[36:37], 12, v[0:1]
	s_nop 0
	v_addc_co_u32_e32 v45, vcc, 0, v35, vcc
	v_lshl_add_u64 v[38:39], v[98:99], 0, v[36:37]
	v_readfirstlane_b32 s100, v112
	s_nop 3
	s_add_u32 m0, s100, 0x0
	s_nop 0
	global_load_lds_dwordx4 v[34:35], off
	s_add_u32 m0, s100, 0x1000
	s_nop 0
	global_load_lds_dwordx4 v[40:41], off
	s_add_u32 m0, s100, 0x2000
	s_nop 0
	global_load_lds_dwordx4 v[42:43], off
	s_add_u32 m0, s100, 0x3000
	s_nop 0
	global_load_lds_dwordx4 v[44:45], off
	s_add_u32 m0, s100, 0x4000
	s_nop 0
	global_load_lds_dwordx4 v[38:39], off
	v_add_co_u32_e32 v46, vcc, s87, v38
	v_lshl_add_u64 v[104:105], v[100:101], 0, v[36:37]
	s_nop 0
	v_addc_co_u32_e32 v47, vcc, 0, v39, vcc
	s_waitcnt vmcnt(16)
	v_add_co_u32_e32 v48, vcc, s66, v38
	s_add_u32 m0, s100, 0x5000
	s_nop 0
	global_load_lds_dwordx4 v[46:47], off
	s_nop 0
	v_addc_co_u32_e32 v49, vcc, 0, v39, vcc
	v_add_co_u32_e32 v50, vcc, s20, v38
	s_add_u32 m0, s100, 0x6000
	s_nop 0
	global_load_lds_dwordx4 v[48:49], off
	s_nop 0
	v_addc_co_u32_e32 v51, vcc, 0, v39, vcc
	s_add_u32 m0, s100, 0x7000
	s_nop 0
	global_load_lds_dwordx4 v[50:51], off
	v_lshl_add_u64 v[106:107], v[102:103], 0, v[32:33]
	s_mov_b64 s[30:31], 0
	v_mov_b32_e32 v0, 0
	v_mov_b32_e32 v1, v0
	v_mov_b32_e32 v2, v0
	v_mov_b32_e32 v3, v0
	v_mov_b32_e32 v4, v0
	v_mov_b32_e32 v5, v0
	v_mov_b32_e32 v6, v0
	v_mov_b32_e32 v7, v0
	v_mov_b32_e32 v8, v0
	v_mov_b32_e32 v9, v0
	v_mov_b32_e32 v10, v0
	v_mov_b32_e32 v11, v0
	v_mov_b32_e32 v12, v0
	v_mov_b32_e32 v13, v0
	v_mov_b32_e32 v14, v0
	v_mov_b32_e32 v15, v0
	v_mov_b32_e32 v16, v0
	v_mov_b32_e32 v17, v0
	v_mov_b32_e32 v18, v0
	v_mov_b32_e32 v19, v0
	v_mov_b32_e32 v20, v0
	v_mov_b32_e32 v21, v0
	v_mov_b32_e32 v22, v0
	v_mov_b32_e32 v23, v0
	v_mov_b32_e32 v24, v0
	v_mov_b32_e32 v25, v0
	v_mov_b32_e32 v26, v0
	v_mov_b32_e32 v27, v0
	v_mov_b32_e32 v28, v0
	v_mov_b32_e32 v29, v0
	v_mov_b32_e32 v30, v0
	v_mov_b32_e32 v31, v0
	v_mov_b32_e32 v32, v0
	v_mov_b32_e32 v33, v0
	v_mov_b32_e32 v34, v0
	v_mov_b32_e32 v35, v0
	v_mov_b32_e32 v36, v0
	v_mov_b32_e32 v37, v0
	v_mov_b32_e32 v38, v0
	v_mov_b32_e32 v39, v0
	v_mov_b32_e32 v40, v0
	v_mov_b32_e32 v41, v0
	v_mov_b32_e32 v42, v0
	v_mov_b32_e32 v43, v0
	v_mov_b32_e32 v44, v0
	v_mov_b32_e32 v45, v0
	v_mov_b32_e32 v46, v0
	v_mov_b32_e32 v47, v0
	v_mov_b32_e32 v48, v0
	v_mov_b32_e32 v49, v0
	v_mov_b32_e32 v50, v0
	v_mov_b32_e32 v51, v0
	v_mov_b32_e32 v52, v0
	v_mov_b32_e32 v53, v0
	v_mov_b32_e32 v54, v0
	v_mov_b32_e32 v55, v0
	v_mov_b32_e32 v56, v0
	v_mov_b32_e32 v57, v0
	v_mov_b32_e32 v58, v0
	v_mov_b32_e32 v59, v0
	v_mov_b32_e32 v60, v0
	v_mov_b32_e32 v61, v0
	v_mov_b32_e32 v62, v0
	v_mov_b32_e32 v63, v0
	v_and_b32_e32 v126, 15, v143
	v_lshrrev_b32_e32 v127, 1, v126
	v_bfe_u32 v120, v143, 4, 2
	v_xor_b32_e32 v127, v127, v120
	v_lshlrev_b32_e32 v127, 4, v127
	v_lshl_add_u32 v127, v126, 7, v127
	v_lshrrev_b32_e32 v126, 6, v143
	v_lshrrev_b32_e32 v118, 1, v126
	v_and_b32_e32 v126, 1, v126
	v_lshl_add_u32 v118, v118, 13, v127
	v_lshl_add_u32 v119, v126, 13, v127
	v_add_u32_e32 v119, 0x4000, v119
	v_xor_b32_e32 v120, 64, v118
	v_xor_b32_e32 v121, 64, v119
	s_waitcnt vmcnt(0) lgkmcnt(0)
	s_barrier
.LBB0_1006:
	v_lshl_add_u64 v[72:73], v[106:107], 0, s[30:31]
	v_add_co_u32_e32 v134, vcc, s21, v72
	v_lshl_add_u64 v[88:89], v[104:105], 0, s[30:31]
	s_nop 0
	v_addc_co_u32_e32 v135, vcc, 0, v73, vcc
	v_add_co_u32_e32 v148, vcc, s74, v72
	s_mov_b32 s4, 0x2eb80000
	s_nop 0
	v_addc_co_u32_e32 v149, vcc, 0, v73, vcc
	v_add_co_u32_e32 v150, vcc, s75, v72
	v_addc_co_u32_e32 v151, vcc, 0, v73, vcc
	v_add_co_u32_e32 v152, vcc, s14, v72
	s_nop 1
	v_addc_co_u32_e32 v153, vcc, 0, v73, vcc
	v_add_co_u32_e32 v154, vcc, s4, v88
	s_mov_b32 s4, 0x2eba0000
	s_nop 0
	v_addc_co_u32_e32 v155, vcc, 0, v89, vcc
	v_add_co_u32_e32 v156, vcc, s4, v88
	s_mov_b32 s4, 0x2ebc0000
	s_nop 0
	v_addc_co_u32_e32 v157, vcc, 0, v89, vcc
	v_add_co_u32_e32 v178, vcc, s4, v88
	s_mov_b32 s4, 0x2ebe0000
	s_nop 0
	v_addc_co_u32_e32 v179, vcc, 0, v89, vcc
	v_add_co_u32_e32 v180, vcc, s4, v88
	v_addc_co_u32_e32 v181, vcc, 0, v89, vcc
	v_lshl_add_u64 v[134:135], 8, 4, v[134:135]
	v_lshl_add_u64 v[148:149], 8, 4, v[148:149]
	v_lshl_add_u64 v[150:151], 8, 4, v[150:151]
	v_lshl_add_u64 v[152:153], 8, 4, v[152:153]
	v_lshl_add_u64 v[154:155], 8, 4, v[154:155]
	v_lshl_add_u64 v[156:157], 8, 4, v[156:157]
	v_lshl_add_u64 v[178:179], 8, 4, v[178:179]
	v_lshl_add_u64 v[180:181], 8, 4, v[180:181]
	s_add_u32 m0, s100, 0x8000
	s_nop 0
	global_load_lds_dwordx4 v[134:135], off
	s_add_u32 m0, s100, 0x9000
	s_nop 0
	global_load_lds_dwordx4 v[148:149], off
	s_add_u32 m0, s100, 0xa000
	s_nop 0
	global_load_lds_dwordx4 v[150:151], off
	s_add_u32 m0, s100, 0xb000
	s_nop 0
	global_load_lds_dwordx4 v[152:153], off
	s_add_u32 m0, s100, 0xc000
	s_nop 0
	global_load_lds_dwordx4 v[154:155], off
	s_add_u32 m0, s100, 0xd000
	s_nop 0
	global_load_lds_dwordx4 v[156:157], off
	s_add_u32 m0, s100, 0xe000
	s_nop 0
	global_load_lds_dwordx4 v[178:179], off
	s_add_u32 m0, s100, 0xf000
	s_nop 0
	global_load_lds_dwordx4 v[180:181], off
	ds_read_b128 a[0:3], v118
	ds_read_b128 v[80:83], v119
	ds_read_b128 a[4:7], v118 offset:2048
	ds_read_b128 a[8:11], v118 offset:4096
	ds_read_b128 a[12:15], v118 offset:6144
	ds_read_b128 v[92:95], v119 offset:2048
	ds_read_b128 v[88:91], v119 offset:4096
	ds_read_b128 v[84:87], v119 offset:6144
	ds_read_b128 a[16:19], v120
	ds_read_b128 a[20:23], v120 offset:2048
	ds_read_b128 a[24:27], v120 offset:4096
	ds_read_b128 a[28:31], v120 offset:6144
	s_setprio 1
	s_waitcnt lgkmcnt(10)
	v_mfma_f32_16x16x32_bf16 v[0:3], a[0:3], v[80:83], v[0:3]
	s_waitcnt lgkmcnt(9)
	v_mfma_f32_16x16x32_bf16 v[16:19], a[4:7], v[80:83], v[16:19]
	s_waitcnt lgkmcnt(8)
	v_mfma_f32_16x16x32_bf16 v[32:35], a[8:11], v[80:83], v[32:35]
	s_waitcnt lgkmcnt(7)
	v_mfma_f32_16x16x32_bf16 v[48:51], a[12:15], v[80:83], v[48:51]
	ds_read_b128 v[80:83], v121
	s_waitcnt lgkmcnt(7)
	v_mfma_f32_16x16x32_bf16 v[4:7], a[0:3], v[92:95], v[4:7]
	v_mfma_f32_16x16x32_bf16 v[20:23], a[4:7], v[92:95], v[20:23]
	v_mfma_f32_16x16x32_bf16 v[36:39], a[8:11], v[92:95], v[36:39]
	v_mfma_f32_16x16x32_bf16 v[52:55], a[12:15], v[92:95], v[52:55]
	ds_read_b128 v[92:95], v121 offset:2048
	s_waitcnt lgkmcnt(7)
	v_mfma_f32_16x16x32_bf16 v[8:11], a[0:3], v[88:91], v[8:11]
	v_mfma_f32_16x16x32_bf16 v[24:27], a[4:7], v[88:91], v[24:27]
	v_mfma_f32_16x16x32_bf16 v[40:43], a[8:11], v[88:91], v[40:43]
	v_mfma_f32_16x16x32_bf16 v[56:59], a[12:15], v[88:91], v[56:59]
	ds_read_b128 v[88:91], v121 offset:4096
	s_waitcnt lgkmcnt(7)
	v_mfma_f32_16x16x32_bf16 v[12:15], a[0:3], v[84:87], v[12:15]
	v_mfma_f32_16x16x32_bf16 v[28:31], a[4:7], v[84:87], v[28:31]
	v_mfma_f32_16x16x32_bf16 v[44:47], a[8:11], v[84:87], v[44:47]
	v_mfma_f32_16x16x32_bf16 v[60:63], a[12:15], v[84:87], v[60:63]
	ds_read_b128 v[84:87], v121 offset:6144
	s_waitcnt lgkmcnt(3)
	v_mfma_f32_16x16x32_bf16 v[0:3], a[16:19], v[80:83], v[0:3]
	v_mfma_f32_16x16x32_bf16 v[16:19], a[20:23], v[80:83], v[16:19]
	v_mfma_f32_16x16x32_bf16 v[32:35], a[24:27], v[80:83], v[32:35]
	v_mfma_f32_16x16x32_bf16 v[48:51], a[28:31], v[80:83], v[48:51]
	s_waitcnt lgkmcnt(2)
	v_mfma_f32_16x16x32_bf16 v[4:7], a[16:19], v[92:95], v[4:7]
	v_mfma_f32_16x16x32_bf16 v[20:23], a[20:23], v[92:95], v[20:23]
	v_mfma_f32_16x16x32_bf16 v[36:39], a[24:27], v[92:95], v[36:39]
	v_mfma_f32_16x16x32_bf16 v[52:55], a[28:31], v[92:95], v[52:55]
	s_waitcnt lgkmcnt(1)
	v_mfma_f32_16x16x32_bf16 v[8:11], a[16:19], v[88:91], v[8:11]
	v_mfma_f32_16x16x32_bf16 v[24:27], a[20:23], v[88:91], v[24:27]
	v_mfma_f32_16x16x32_bf16 v[40:43], a[24:27], v[88:91], v[40:43]
	v_mfma_f32_16x16x32_bf16 v[56:59], a[28:31], v[88:91], v[56:59]
	s_waitcnt lgkmcnt(0)
	v_mfma_f32_16x16x32_bf16 v[12:15], a[16:19], v[84:87], v[12:15]
	v_mfma_f32_16x16x32_bf16 v[28:31], a[20:23], v[84:87], v[28:31]
	v_mfma_f32_16x16x32_bf16 v[44:47], a[24:27], v[84:87], v[44:47]
	v_mfma_f32_16x16x32_bf16 v[60:63], a[28:31], v[84:87], v[60:63]
	s_setprio 0
	s_waitcnt vmcnt(0) lgkmcnt(0)
	s_barrier
	v_lshl_add_u64 v[64:65], 8, 4, v[134:135]
	v_lshl_add_u64 v[66:67], 8, 4, v[148:149]
	v_lshl_add_u64 v[68:69], 8, 4, v[150:151]
	v_lshl_add_u64 v[70:71], 8, 4, v[152:153]
	v_lshl_add_u64 v[76:77], 8, 4, v[154:155]
	v_lshl_add_u64 v[78:79], 8, 4, v[156:157]
	v_lshl_add_u64 v[72:73], 8, 4, v[178:179]
	v_lshl_add_u64 v[74:75], 8, 4, v[180:181]
	s_add_u32 m0, s100, 0x0
	s_nop 0
	global_load_lds_dwordx4 v[64:65], off
	s_add_u32 m0, s100, 0x1000
	s_nop 0
	global_load_lds_dwordx4 v[66:67], off
	s_add_u32 m0, s100, 0x2000
	s_nop 0
	global_load_lds_dwordx4 v[68:69], off
	s_add_u32 m0, s100, 0x3000
	s_nop 0
	global_load_lds_dwordx4 v[70:71], off
	s_add_u32 m0, s100, 0x4000
	s_nop 0
	global_load_lds_dwordx4 v[76:77], off
	s_add_u32 m0, s100, 0x5000
	s_nop 0
	global_load_lds_dwordx4 v[78:79], off
	s_add_u32 m0, s100, 0x6000
	s_nop 0
	global_load_lds_dwordx4 v[72:73], off
	s_add_u32 m0, s100, 0x7000
	s_nop 0
	global_load_lds_dwordx4 v[74:75], off
	ds_read_b128 a[0:3], v118 offset:32768
	ds_read_b128 v[80:83], v119 offset:32768
	ds_read_b128 a[4:7], v118 offset:34816
	ds_read_b128 a[8:11], v118 offset:36864
	ds_read_b128 a[12:15], v118 offset:38912
	ds_read_b128 v[92:95], v119 offset:34816
	ds_read_b128 v[88:91], v119 offset:36864
	ds_read_b128 v[84:87], v119 offset:38912
	ds_read_b128 a[16:19], v120 offset:32768
	ds_read_b128 a[20:23], v120 offset:34816
	ds_read_b128 a[24:27], v120 offset:36864
	ds_read_b128 a[28:31], v120 offset:38912
	s_setprio 1
	s_waitcnt lgkmcnt(10)
	v_mfma_f32_16x16x32_bf16 v[0:3], a[0:3], v[80:83], v[0:3]
	s_waitcnt lgkmcnt(9)
	v_mfma_f32_16x16x32_bf16 v[16:19], a[4:7], v[80:83], v[16:19]
	s_waitcnt lgkmcnt(8)
	v_mfma_f32_16x16x32_bf16 v[32:35], a[8:11], v[80:83], v[32:35]
	s_waitcnt lgkmcnt(7)
	v_mfma_f32_16x16x32_bf16 v[48:51], a[12:15], v[80:83], v[48:51]
	ds_read_b128 v[80:83], v121 offset:32768
	s_waitcnt lgkmcnt(7)
	v_mfma_f32_16x16x32_bf16 v[4:7], a[0:3], v[92:95], v[4:7]
	v_mfma_f32_16x16x32_bf16 v[20:23], a[4:7], v[92:95], v[20:23]
	v_mfma_f32_16x16x32_bf16 v[36:39], a[8:11], v[92:95], v[36:39]
	v_mfma_f32_16x16x32_bf16 v[52:55], a[12:15], v[92:95], v[52:55]
	ds_read_b128 v[92:95], v121 offset:34816
	s_waitcnt lgkmcnt(7)
	v_mfma_f32_16x16x32_bf16 v[8:11], a[0:3], v[88:91], v[8:11]
	v_mfma_f32_16x16x32_bf16 v[24:27], a[4:7], v[88:91], v[24:27]
	v_mfma_f32_16x16x32_bf16 v[40:43], a[8:11], v[88:91], v[40:43]
	v_mfma_f32_16x16x32_bf16 v[56:59], a[12:15], v[88:91], v[56:59]
	ds_read_b128 v[88:91], v121 offset:36864
	s_waitcnt lgkmcnt(7)
	v_mfma_f32_16x16x32_bf16 v[12:15], a[0:3], v[84:87], v[12:15]
	v_mfma_f32_16x16x32_bf16 v[28:31], a[4:7], v[84:87], v[28:31]
	v_mfma_f32_16x16x32_bf16 v[44:47], a[8:11], v[84:87], v[44:47]
	v_mfma_f32_16x16x32_bf16 v[60:63], a[12:15], v[84:87], v[60:63]
	ds_read_b128 v[84:87], v121 offset:38912
	s_waitcnt lgkmcnt(3)
	v_mfma_f32_16x16x32_bf16 v[0:3], a[16:19], v[80:83], v[0:3]
	v_mfma_f32_16x16x32_bf16 v[16:19], a[20:23], v[80:83], v[16:19]
	v_mfma_f32_16x16x32_bf16 v[32:35], a[24:27], v[80:83], v[32:35]
	v_mfma_f32_16x16x32_bf16 v[48:51], a[28:31], v[80:83], v[48:51]
	s_waitcnt lgkmcnt(2)
	v_mfma_f32_16x16x32_bf16 v[4:7], a[16:19], v[92:95], v[4:7]
	v_mfma_f32_16x16x32_bf16 v[20:23], a[20:23], v[92:95], v[20:23]
	v_mfma_f32_16x16x32_bf16 v[36:39], a[24:27], v[92:95], v[36:39]
	v_mfma_f32_16x16x32_bf16 v[52:55], a[28:31], v[92:95], v[52:55]
	s_waitcnt lgkmcnt(1)
	v_mfma_f32_16x16x32_bf16 v[8:11], a[16:19], v[88:91], v[8:11]
	v_mfma_f32_16x16x32_bf16 v[24:27], a[20:23], v[88:91], v[24:27]
	v_mfma_f32_16x16x32_bf16 v[40:43], a[24:27], v[88:91], v[40:43]
	v_mfma_f32_16x16x32_bf16 v[56:59], a[28:31], v[88:91], v[56:59]
	s_waitcnt lgkmcnt(0)
	v_mfma_f32_16x16x32_bf16 v[12:15], a[16:19], v[84:87], v[12:15]
	v_mfma_f32_16x16x32_bf16 v[28:31], a[20:23], v[84:87], v[28:31]
	v_mfma_f32_16x16x32_bf16 v[44:47], a[24:27], v[84:87], v[44:47]
	v_mfma_f32_16x16x32_bf16 v[60:63], a[28:31], v[84:87], v[60:63]
	s_setprio 0
	s_waitcnt vmcnt(0) lgkmcnt(0)
	s_barrier
	s_add_u32 s30, s30, 0x100
	s_addc_u32 s31, s31, 0
	s_cmpk_eq_i32 s30, 0xf00
	s_cbranch_scc0 .LBB0_1006
	v_lshl_add_u64 v[64:65], 8, 4, v[64:65]
	v_lshl_add_u64 v[66:67], 8, 4, v[66:67]
	v_lshl_add_u64 v[68:69], 8, 4, v[68:69]
	v_lshl_add_u64 v[70:71], 8, 4, v[70:71]
	v_lshl_add_u64 v[76:77], 8, 4, v[76:77]
	v_lshl_add_u64 v[78:79], 8, 4, v[78:79]
	v_lshl_add_u64 v[72:73], 8, 4, v[72:73]
	v_lshl_add_u64 v[74:75], 8, 4, v[74:75]
	s_add_u32 m0, s100, 0x8000
	s_nop 0
	global_load_lds_dwordx4 v[64:65], off
	s_add_u32 m0, s100, 0x9000
	s_nop 0
	global_load_lds_dwordx4 v[66:67], off
	s_add_u32 m0, s100, 0xa000
	s_nop 0
	global_load_lds_dwordx4 v[68:69], off
	s_add_u32 m0, s100, 0xb000
	s_nop 0
	global_load_lds_dwordx4 v[70:71], off
	s_add_u32 m0, s100, 0xc000
	s_nop 0
	global_load_lds_dwordx4 v[76:77], off
	s_add_u32 m0, s100, 0xd000
	s_nop 0
	global_load_lds_dwordx4 v[78:79], off
	s_add_u32 m0, s100, 0xe000
	s_nop 0
	global_load_lds_dwordx4 v[72:73], off
	s_add_u32 m0, s100, 0xf000
	s_nop 0
	global_load_lds_dwordx4 v[74:75], off
	ds_read_b128 a[0:3], v118
	ds_read_b128 v[80:83], v119
	ds_read_b128 a[4:7], v118 offset:2048
	ds_read_b128 a[8:11], v118 offset:4096
	ds_read_b128 a[12:15], v118 offset:6144
	ds_read_b128 v[92:95], v119 offset:2048
	ds_read_b128 v[88:91], v119 offset:4096
	ds_read_b128 v[84:87], v119 offset:6144
	ds_read_b128 a[16:19], v120
	ds_read_b128 a[20:23], v120 offset:2048
	ds_read_b128 a[24:27], v120 offset:4096
	ds_read_b128 a[28:31], v120 offset:6144
	s_setprio 1
	s_waitcnt lgkmcnt(10)
	v_mfma_f32_16x16x32_bf16 v[0:3], a[0:3], v[80:83], v[0:3]
	s_waitcnt lgkmcnt(9)
	v_mfma_f32_16x16x32_bf16 v[16:19], a[4:7], v[80:83], v[16:19]
	s_waitcnt lgkmcnt(8)
	v_mfma_f32_16x16x32_bf16 v[32:35], a[8:11], v[80:83], v[32:35]
	s_waitcnt lgkmcnt(7)
	v_mfma_f32_16x16x32_bf16 v[48:51], a[12:15], v[80:83], v[48:51]
	ds_read_b128 v[80:83], v121
	s_waitcnt lgkmcnt(7)
	v_mfma_f32_16x16x32_bf16 v[4:7], a[0:3], v[92:95], v[4:7]
	v_mfma_f32_16x16x32_bf16 v[20:23], a[4:7], v[92:95], v[20:23]
	v_mfma_f32_16x16x32_bf16 v[36:39], a[8:11], v[92:95], v[36:39]
	v_mfma_f32_16x16x32_bf16 v[52:55], a[12:15], v[92:95], v[52:55]
	ds_read_b128 v[92:95], v121 offset:2048
	s_waitcnt lgkmcnt(7)
	v_mfma_f32_16x16x32_bf16 v[8:11], a[0:3], v[88:91], v[8:11]
	v_mfma_f32_16x16x32_bf16 v[24:27], a[4:7], v[88:91], v[24:27]
	v_mfma_f32_16x16x32_bf16 v[40:43], a[8:11], v[88:91], v[40:43]
	v_mfma_f32_16x16x32_bf16 v[56:59], a[12:15], v[88:91], v[56:59]
	ds_read_b128 v[88:91], v121 offset:4096
	s_waitcnt lgkmcnt(7)
	v_mfma_f32_16x16x32_bf16 v[12:15], a[0:3], v[84:87], v[12:15]
	v_mfma_f32_16x16x32_bf16 v[28:31], a[4:7], v[84:87], v[28:31]
	v_mfma_f32_16x16x32_bf16 v[44:47], a[8:11], v[84:87], v[44:47]
	v_mfma_f32_16x16x32_bf16 v[60:63], a[12:15], v[84:87], v[60:63]
	ds_read_b128 v[84:87], v121 offset:6144
	s_waitcnt lgkmcnt(3)
	v_mfma_f32_16x16x32_bf16 v[0:3], a[16:19], v[80:83], v[0:3]
	v_mfma_f32_16x16x32_bf16 v[16:19], a[20:23], v[80:83], v[16:19]
	v_mfma_f32_16x16x32_bf16 v[32:35], a[24:27], v[80:83], v[32:35]
	v_mfma_f32_16x16x32_bf16 v[48:51], a[28:31], v[80:83], v[48:51]
	s_waitcnt lgkmcnt(2)
	v_mfma_f32_16x16x32_bf16 v[4:7], a[16:19], v[92:95], v[4:7]
	v_mfma_f32_16x16x32_bf16 v[20:23], a[20:23], v[92:95], v[20:23]
	v_mfma_f32_16x16x32_bf16 v[36:39], a[24:27], v[92:95], v[36:39]
	v_mfma_f32_16x16x32_bf16 v[52:55], a[28:31], v[92:95], v[52:55]
	s_waitcnt lgkmcnt(1)
	v_mfma_f32_16x16x32_bf16 v[8:11], a[16:19], v[88:91], v[8:11]
	v_mfma_f32_16x16x32_bf16 v[24:27], a[20:23], v[88:91], v[24:27]
	v_mfma_f32_16x16x32_bf16 v[40:43], a[24:27], v[88:91], v[40:43]
	v_mfma_f32_16x16x32_bf16 v[56:59], a[28:31], v[88:91], v[56:59]
	s_waitcnt lgkmcnt(0)
	v_mfma_f32_16x16x32_bf16 v[12:15], a[16:19], v[84:87], v[12:15]
	v_mfma_f32_16x16x32_bf16 v[28:31], a[20:23], v[84:87], v[28:31]
	v_mfma_f32_16x16x32_bf16 v[44:47], a[24:27], v[84:87], v[44:47]
	v_mfma_f32_16x16x32_bf16 v[60:63], a[28:31], v[84:87], v[60:63]
	s_setprio 0
	s_waitcnt vmcnt(0) lgkmcnt(0)
	s_barrier
	ds_read_b128 a[0:3], v118 offset:32768
	ds_read_b128 v[80:83], v119 offset:32768
	ds_read_b128 a[4:7], v118 offset:34816
	ds_read_b128 a[8:11], v118 offset:36864
	ds_read_b128 a[12:15], v118 offset:38912
	ds_read_b128 v[92:95], v119 offset:34816
	ds_read_b128 v[88:91], v119 offset:36864
	ds_read_b128 v[84:87], v119 offset:38912
	ds_read_b128 a[16:19], v120 offset:32768
	ds_read_b128 a[20:23], v120 offset:34816
	ds_read_b128 a[24:27], v120 offset:36864
	ds_read_b128 a[28:31], v120 offset:38912
	s_setprio 1
	s_waitcnt lgkmcnt(10)
	v_mfma_f32_16x16x32_bf16 v[0:3], a[0:3], v[80:83], v[0:3]
	s_waitcnt lgkmcnt(9)
	v_mfma_f32_16x16x32_bf16 v[16:19], a[4:7], v[80:83], v[16:19]
	s_waitcnt lgkmcnt(8)
	v_mfma_f32_16x16x32_bf16 v[32:35], a[8:11], v[80:83], v[32:35]
	s_waitcnt lgkmcnt(7)
	v_mfma_f32_16x16x32_bf16 v[48:51], a[12:15], v[80:83], v[48:51]
	ds_read_b128 v[80:83], v121 offset:32768
	s_waitcnt lgkmcnt(7)
	v_mfma_f32_16x16x32_bf16 v[4:7], a[0:3], v[92:95], v[4:7]
	v_mfma_f32_16x16x32_bf16 v[20:23], a[4:7], v[92:95], v[20:23]
	v_mfma_f32_16x16x32_bf16 v[36:39], a[8:11], v[92:95], v[36:39]
	v_mfma_f32_16x16x32_bf16 v[52:55], a[12:15], v[92:95], v[52:55]
	ds_read_b128 v[92:95], v121 offset:34816
	s_waitcnt lgkmcnt(7)
	v_mfma_f32_16x16x32_bf16 v[8:11], a[0:3], v[88:91], v[8:11]
	v_mfma_f32_16x16x32_bf16 v[24:27], a[4:7], v[88:91], v[24:27]
	v_mfma_f32_16x16x32_bf16 v[40:43], a[8:11], v[88:91], v[40:43]
	v_mfma_f32_16x16x32_bf16 v[56:59], a[12:15], v[88:91], v[56:59]
	ds_read_b128 v[88:91], v121 offset:36864
	s_waitcnt lgkmcnt(7)
	v_mfma_f32_16x16x32_bf16 v[12:15], a[0:3], v[84:87], v[12:15]
	v_mfma_f32_16x16x32_bf16 v[28:31], a[4:7], v[84:87], v[28:31]
	v_mfma_f32_16x16x32_bf16 v[44:47], a[8:11], v[84:87], v[44:47]
	v_mfma_f32_16x16x32_bf16 v[60:63], a[12:15], v[84:87], v[60:63]
	ds_read_b128 v[84:87], v121 offset:38912
	s_waitcnt lgkmcnt(3)
	v_mfma_f32_16x16x32_bf16 v[0:3], a[16:19], v[80:83], v[0:3]
	v_mfma_f32_16x16x32_bf16 v[16:19], a[20:23], v[80:83], v[16:19]
	v_mfma_f32_16x16x32_bf16 v[32:35], a[24:27], v[80:83], v[32:35]
	v_mfma_f32_16x16x32_bf16 v[48:51], a[28:31], v[80:83], v[48:51]
	s_waitcnt lgkmcnt(2)
	v_mfma_f32_16x16x32_bf16 v[4:7], a[16:19], v[92:95], v[4:7]
	v_mfma_f32_16x16x32_bf16 v[20:23], a[20:23], v[92:95], v[20:23]
	v_mfma_f32_16x16x32_bf16 v[36:39], a[24:27], v[92:95], v[36:39]
	v_mfma_f32_16x16x32_bf16 v[52:55], a[28:31], v[92:95], v[52:55]
	s_waitcnt lgkmcnt(1)
	v_mfma_f32_16x16x32_bf16 v[8:11], a[16:19], v[88:91], v[8:11]
	v_mfma_f32_16x16x32_bf16 v[24:27], a[20:23], v[88:91], v[24:27]
	v_mfma_f32_16x16x32_bf16 v[40:43], a[24:27], v[88:91], v[40:43]
	v_mfma_f32_16x16x32_bf16 v[56:59], a[28:31], v[88:91], v[56:59]
	s_waitcnt lgkmcnt(0)
	v_mfma_f32_16x16x32_bf16 v[12:15], a[16:19], v[84:87], v[12:15]
	v_mfma_f32_16x16x32_bf16 v[28:31], a[20:23], v[84:87], v[28:31]
	v_mfma_f32_16x16x32_bf16 v[44:47], a[24:27], v[84:87], v[44:47]
	v_mfma_f32_16x16x32_bf16 v[60:63], a[28:31], v[84:87], v[60:63]
	s_setprio 0
	v_readfirstlane_b32 s15, v109
	v_readfirstlane_b32 s4, v108
	s_lshl_b32 s15, s15, 6
	s_waitcnt lgkmcnt(0)
	s_barrier
	s_add_i32 s9, s15, s9
	s_lshl_b32 s15, s4, 19
	s_lshl_b32 s4, s8, 20
	s_add_i32 s15, s15, s4
	v_or_b32_e32 v66, s9, v110
	v_cmp_gt_i32_e64 s[40:41], s51, v66
	v_and_b32_e32 v64, 0xffffffde, v66
	v_or_b32_e32 v65, s15, v113
	s_barrier
	v_and_b32_e32 v126, 15, v143
	v_bfe_u32 v127, v143, 4, 2
	v_xor_b32_e32 v127, v127, v126
	v_lshlrev_b32_e32 v127, 4, v127
	v_lshl_add_u32 v127, v126, 8, v127
	v_lshrrev_b32_e32 v126, 6, v143
	v_lshl_add_u32 v127, v126, 14, v127
	ds_write_b128 v127, v[0:3]
	ds_write_b128 v127, v[4:7] offset:4096
	ds_write_b128 v127, v[8:11] offset:8192
	ds_write_b128 v127, v[12:15] offset:12288
	v_xor_b32_e32 v121, 64, v127
	ds_write_b128 v121, v[16:19]
	ds_write_b128 v121, v[20:23] offset:4096
	ds_write_b128 v121, v[24:27] offset:8192
	ds_write_b128 v121, v[28:31] offset:12288
	v_xor_b32_e32 v121, 128, v127
	ds_write_b128 v121, v[32:35]
	ds_write_b128 v121, v[36:39] offset:4096
	ds_write_b128 v121, v[40:43] offset:8192
	ds_write_b128 v121, v[44:47] offset:12288
	v_xor_b32_e32 v121, 192, v127
	ds_write_b128 v121, v[48:51]
	ds_write_b128 v121, v[52:55] offset:4096
	ds_write_b128 v121, v[56:59] offset:8192
	ds_write_b128 v121, v[60:63] offset:12288
	v_and_b32_e32 v118, 31, v143
	v_bfe_u32 v120, v143, 5, 1
	v_and_b32_e32 v127, 15, v118
	v_xor_b32_e32 v120, v120, v127
	v_lshlrev_b32_e32 v120, 4, v120
	v_lshl_add_u32 v120, v118, 8, v120
	v_lshl_add_u32 v120, v126, 14, v120
	ds_read_b128 v[48:51], v120
	ds_read_b128 v[32:35], v120 offset:8192
	v_xor_b32_e32 v119, 32, v120
	ds_read_b128 v[52:55], v119
	ds_read_b128 v[36:39], v119 offset:8192
	v_xor_b32_e32 v119, 64, v120
	ds_read_b128 v[56:59], v119
	ds_read_b128 v[40:43], v119 offset:8192
	v_xor_b32_e32 v119, 96, v120
	ds_read_b128 v[60:63], v119
	ds_read_b128 v[44:47], v119 offset:8192
	v_xor_b32_e32 v119, 128, v120
	ds_read_b128 v[16:19], v119
	ds_read_b128 v[0:3], v119 offset:8192
	v_xor_b32_e32 v119, 160, v120
	ds_read_b128 v[20:23], v119
	ds_read_b128 v[4:7], v119 offset:8192
	v_xor_b32_e32 v119, 192, v120
	ds_read_b128 v[24:27], v119
	ds_read_b128 v[8:11], v119 offset:8192
	v_xor_b32_e32 v119, 224, v120
	ds_read_b128 v[28:31], v119
	ds_read_b128 v[12:15], v119 offset:8192
	s_waitcnt lgkmcnt(0)
	s_barrier
	s_and_saveexec_b64 s[8:9], s[40:41]
	s_cbranch_execz .LBB0_1009
	v_max_f32_e32 v48, v48, v48
	v_max_f32_e32 v49, v49, v49
	v_max_f32_e32 v50, v50, v50
	v_max_f32_e32 v51, v51, v51
	v_max_f32_e32 v48, 0, v48
	v_max_f32_e32 v49, 0, v49
	v_max_f32_e32 v50, 0, v50
	v_max_f32_e32 v51, 0, v51
	v_mul_f32_e32 v48, v48, v48
	v_mul_f32_e32 v49, v49, v49
	v_mul_f32_e32 v50, v50, v50
	v_mul_f32_e32 v51, v51, v51
	v_mov_b32_e32 v68, v140
	v_mov_b32_e32 v69, v140
	v_mov_b32_e32 v70, v140
	v_mov_b32_e32 v71, v140
	v_mov_b32_dpp v68, v48 quad_perm:[1,0,3,2] row_mask:0xf bank_mask:0xf
	v_mov_b32_dpp v69, v49 quad_perm:[1,0,3,2] row_mask:0xf bank_mask:0xf
	v_mov_b32_dpp v70, v50 quad_perm:[1,0,3,2] row_mask:0xf bank_mask:0xf
	v_mov_b32_dpp v71, v51 quad_perm:[1,0,3,2] row_mask:0xf bank_mask:0xf
	v_add_u32_e32 v67, v64, v65
	v_cndmask_b32_e64 v50, v50, v68, s[38:39]
	v_cndmask_b32_e64 v48, v70, v48, s[38:39]
	v_cndmask_b32_e64 v51, v51, v69, s[38:39]
	v_cndmask_b32_e64 v49, v71, v49, s[38:39]
	v_cvt_pk_bf16_f32 v51, v49, v51
	v_cvt_pk_bf16_f32 v50, v48, v50
	v_add_u32_e32 v48, v67, v114
	v_mov_b32_e32 v49, v140
	v_lshl_add_u64 v[48:49], v[48:49], 1, s[28:29]
	global_store_dword v[48:49], v50, off
	v_add_co_u32_e32 v48, vcc, s80, v48
	s_nop 1
	v_addc_co_u32_e32 v49, vcc, 0, v49, vcc
	global_store_dword v[48:49], v51, off
	v_max_f32_e32 v48, v52, v52
	v_max_f32_e32 v49, v53, v53
	v_max_f32_e32 v50, v54, v54
	v_max_f32_e32 v51, v55, v55
	v_max_f32_e32 v48, 0, v48
	v_max_f32_e32 v49, 0, v49
	v_max_f32_e32 v50, 0, v50
	v_max_f32_e32 v51, 0, v51
	v_mul_f32_e32 v48, v48, v48
	v_mul_f32_e32 v49, v49, v49
	v_mul_f32_e32 v50, v50, v50
	v_mul_f32_e32 v51, v51, v51
	v_mov_b32_e32 v52, v140
	v_mov_b32_e32 v53, v140
	v_mov_b32_e32 v54, v140
	v_mov_b32_e32 v55, v140
	v_mov_b32_dpp v52, v48 quad_perm:[1,0,3,2] row_mask:0xf bank_mask:0xf
	v_mov_b32_dpp v53, v49 quad_perm:[1,0,3,2] row_mask:0xf bank_mask:0xf
	v_mov_b32_dpp v54, v50 quad_perm:[1,0,3,2] row_mask:0xf bank_mask:0xf
	v_mov_b32_dpp v55, v51 quad_perm:[1,0,3,2] row_mask:0xf bank_mask:0xf
	v_cndmask_b32_e64 v50, v50, v52, s[38:39]
	v_cndmask_b32_e64 v48, v54, v48, s[38:39]
	v_cndmask_b32_e64 v51, v51, v53, s[38:39]
	v_cndmask_b32_e64 v49, v55, v49, s[38:39]
	v_cvt_pk_bf16_f32 v51, v49, v51
	v_cvt_pk_bf16_f32 v50, v48, v50
	v_add_u32_e32 v48, v67, v115
	v_mov_b32_e32 v49, v140
	v_lshl_add_u64 v[48:49], v[48:49], 1, s[28:29]
	global_store_dword v[48:49], v50, off
	v_add_co_u32_e32 v48, vcc, s80, v48
	s_nop 1
	v_addc_co_u32_e32 v49, vcc, 0, v49, vcc
	global_store_dword v[48:49], v51, off
	v_max_f32_e32 v48, v56, v56
	v_max_f32_e32 v49, v57, v57
	v_max_f32_e32 v50, v58, v58
	v_max_f32_e32 v51, v59, v59
	v_max_f32_e32 v48, 0, v48
	v_max_f32_e32 v49, 0, v49
	v_max_f32_e32 v50, 0, v50
	v_max_f32_e32 v51, 0, v51
	v_mul_f32_e32 v48, v48, v48
	v_mul_f32_e32 v49, v49, v49
	v_mul_f32_e32 v50, v50, v50
	v_mul_f32_e32 v51, v51, v51
	v_mov_b32_e32 v52, v140
	v_mov_b32_e32 v53, v140
	v_mov_b32_e32 v54, v140
	v_mov_b32_e32 v55, v140
	v_mov_b32_dpp v52, v48 quad_perm:[1,0,3,2] row_mask:0xf bank_mask:0xf
	v_mov_b32_dpp v53, v49 quad_perm:[1,0,3,2] row_mask:0xf bank_mask:0xf
	v_mov_b32_dpp v54, v50 quad_perm:[1,0,3,2] row_mask:0xf bank_mask:0xf
	v_mov_b32_dpp v55, v51 quad_perm:[1,0,3,2] row_mask:0xf bank_mask:0xf
	v_cndmask_b32_e64 v50, v50, v52, s[38:39]
	v_cndmask_b32_e64 v48, v54, v48, s[38:39]
	v_cndmask_b32_e64 v51, v51, v53, s[38:39]
	v_cndmask_b32_e64 v49, v55, v49, s[38:39]
	v_cvt_pk_bf16_f32 v51, v49, v51
	v_cvt_pk_bf16_f32 v50, v48, v50
	v_add_u32_e32 v48, v67, v116
	v_mov_b32_e32 v49, v140
	v_lshl_add_u64 v[48:49], v[48:49], 1, s[28:29]
	global_store_dword v[48:49], v50, off
	v_add_co_u32_e32 v48, vcc, s80, v48
	s_nop 1
	v_addc_co_u32_e32 v49, vcc, 0, v49, vcc
	global_store_dword v[48:49], v51, off
	v_max_f32_e32 v48, v60, v60
	v_max_f32_e32 v49, v61, v61
	v_max_f32_e32 v50, v62, v62
	v_max_f32_e32 v51, v63, v63
	v_max_f32_e32 v48, 0, v48
	v_max_f32_e32 v49, 0, v49
	v_max_f32_e32 v50, 0, v50
	v_max_f32_e32 v51, 0, v51
	v_mul_f32_e32 v48, v48, v48
	v_mul_f32_e32 v49, v49, v49
	v_mul_f32_e32 v50, v50, v50
	v_mul_f32_e32 v51, v51, v51
	v_mov_b32_e32 v52, v140
	v_mov_b32_e32 v53, v140
	v_mov_b32_e32 v54, v140
	v_mov_b32_e32 v55, v140
	v_mov_b32_dpp v52, v48 quad_perm:[1,0,3,2] row_mask:0xf bank_mask:0xf
	v_mov_b32_dpp v53, v49 quad_perm:[1,0,3,2] row_mask:0xf bank_mask:0xf
	v_mov_b32_dpp v54, v50 quad_perm:[1,0,3,2] row_mask:0xf bank_mask:0xf
	v_mov_b32_dpp v55, v51 quad_perm:[1,0,3,2] row_mask:0xf bank_mask:0xf
	v_cndmask_b32_e64 v50, v50, v52, s[38:39]
	v_cndmask_b32_e64 v48, v54, v48, s[38:39]
	v_cndmask_b32_e64 v51, v51, v53, s[38:39]
	v_cndmask_b32_e64 v49, v55, v49, s[38:39]
	v_cvt_pk_bf16_f32 v51, v49, v51
	v_cvt_pk_bf16_f32 v50, v48, v50
	v_add_u32_e32 v48, v67, v117
	v_mov_b32_e32 v49, v140
	v_lshl_add_u64 v[48:49], v[48:49], 1, s[28:29]
	global_store_dword v[48:49], v50, off
	v_add_co_u32_e32 v48, vcc, 0x4000, v48
	s_nop 1
	v_addc_co_u32_e32 v49, vcc, 0, v49, vcc
	global_store_dword v[48:49], v51, off

.LBB0_1026:
	s_mul_hi_i32 s4, s42, 0x38e38e39
	s_lshr_b32 s8, s4, 31
	s_ashr_i32 s4, s4, 4
	s_add_i32 s4, s4, s8
	s_mul_i32 s8, s4, 0x48
	s_sub_i32 s8, s42, s8
	s_lshl_b32 s8, s8, 7
	v_add_u32_e32 v0, s8, v109
	v_ashrrev_i32_e32 v1, 31, v0
	v_lshlrev_b64 v[32:33], 12, v[0:1]
	v_lshl_add_u64 v[34:35], v[96:97], 0, v[32:33]
	v_add_co_u32_e32 v40, vcc, s87, v34
	s_lshl_b32 s9, s4, 7
	s_nop 0
	v_addc_co_u32_e32 v41, vcc, 0, v35, vcc
	v_add_co_u32_e32 v42, vcc, s66, v34
	v_add_u32_e32 v0, s9, v109
	s_nop 0
	v_addc_co_u32_e32 v43, vcc, 0, v35, vcc
	v_ashrrev_i32_e32 v1, 31, v0
	v_add_co_u32_e32 v44, vcc, s20, v34
	v_lshlrev_b64 v[36:37], 12, v[0:1]
	s_nop 0
	v_addc_co_u32_e32 v45, vcc, 0, v35, vcc
	v_lshl_add_u64 v[38:39], v[98:99], 0, v[36:37]
	v_readfirstlane_b32 s100, v110
	s_nop 3
	s_add_u32 m0, s100, 0x0
	s_nop 0
	global_load_lds_dwordx4 v[34:35], off
	s_add_u32 m0, s100, 0x1000
	s_nop 0
	global_load_lds_dwordx4 v[40:41], off
	s_add_u32 m0, s100, 0x2000
	s_nop 0
	global_load_lds_dwordx4 v[42:43], off
	s_add_u32 m0, s100, 0x3000
	s_nop 0
	global_load_lds_dwordx4 v[44:45], off
	s_add_u32 m0, s100, 0x4000
	s_nop 0
	global_load_lds_dwordx4 v[38:39], off
	v_add_co_u32_e32 v46, vcc, s87, v38
	v_lshl_add_u64 v[102:103], v[100:101], 0, v[36:37]
	s_nop 0
	v_addc_co_u32_e32 v47, vcc, 0, v39, vcc
	s_waitcnt vmcnt(16)
	v_add_co_u32_e32 v48, vcc, s66, v38
	s_add_u32 m0, s100, 0x5000
	s_nop 0
	global_load_lds_dwordx4 v[46:47], off
	s_nop 0
	v_addc_co_u32_e32 v49, vcc, 0, v39, vcc
	v_add_co_u32_e32 v50, vcc, s20, v38
	s_add_u32 m0, s100, 0x6000
	s_nop 0
	global_load_lds_dwordx4 v[48:49], off
	s_nop 0
	v_addc_co_u32_e32 v51, vcc, 0, v39, vcc
	s_add_u32 m0, s100, 0x7000
	s_nop 0
	global_load_lds_dwordx4 v[50:51], off
	v_lshl_add_u64 v[104:105], v[100:101], 0, v[32:33]
	s_mov_b64 s[34:35], 0
	v_mov_b32_e32 v0, 0
	v_mov_b32_e32 v1, v0
	v_mov_b32_e32 v2, v0
	v_mov_b32_e32 v3, v0
	v_mov_b32_e32 v4, v0
	v_mov_b32_e32 v5, v0
	v_mov_b32_e32 v6, v0
	v_mov_b32_e32 v7, v0
	v_mov_b32_e32 v8, v0
	v_mov_b32_e32 v9, v0
	v_mov_b32_e32 v10, v0
	v_mov_b32_e32 v11, v0
	v_mov_b32_e32 v12, v0
	v_mov_b32_e32 v13, v0
	v_mov_b32_e32 v14, v0
	v_mov_b32_e32 v15, v0
	v_mov_b32_e32 v16, v0
	v_mov_b32_e32 v17, v0
	v_mov_b32_e32 v18, v0
	v_mov_b32_e32 v19, v0
	v_mov_b32_e32 v20, v0
	v_mov_b32_e32 v21, v0
	v_mov_b32_e32 v22, v0
	v_mov_b32_e32 v23, v0
	v_mov_b32_e32 v24, v0
	v_mov_b32_e32 v25, v0
	v_mov_b32_e32 v26, v0
	v_mov_b32_e32 v27, v0
	v_mov_b32_e32 v28, v0
	v_mov_b32_e32 v29, v0
	v_mov_b32_e32 v30, v0
	v_mov_b32_e32 v31, v0
	v_mov_b32_e32 v32, v0
	v_mov_b32_e32 v33, v0
	v_mov_b32_e32 v34, v0
	v_mov_b32_e32 v35, v0
	v_mov_b32_e32 v36, v0
	v_mov_b32_e32 v37, v0
	v_mov_b32_e32 v38, v0
	v_mov_b32_e32 v39, v0
	v_mov_b32_e32 v40, v0
	v_mov_b32_e32 v41, v0
	v_mov_b32_e32 v42, v0
	v_mov_b32_e32 v43, v0
	v_mov_b32_e32 v44, v0
	v_mov_b32_e32 v45, v0
	v_mov_b32_e32 v46, v0
	v_mov_b32_e32 v47, v0
	v_mov_b32_e32 v48, v0
	v_mov_b32_e32 v49, v0
	v_mov_b32_e32 v50, v0
	v_mov_b32_e32 v51, v0
	v_mov_b32_e32 v52, v0
	v_mov_b32_e32 v53, v0
	v_mov_b32_e32 v54, v0
	v_mov_b32_e32 v55, v0
	v_mov_b32_e32 v56, v0
	v_mov_b32_e32 v57, v0
	v_mov_b32_e32 v58, v0
	v_mov_b32_e32 v59, v0
	v_mov_b32_e32 v60, v0
	v_mov_b32_e32 v61, v0
	v_mov_b32_e32 v62, v0
	v_mov_b32_e32 v63, v0
	v_and_b32_e32 v120, 15, v143
	v_lshrrev_b32_e32 v121, 1, v120
	v_bfe_u32 v114, v143, 4, 2
	v_xor_b32_e32 v121, v121, v114
	v_lshlrev_b32_e32 v121, 4, v121
	v_lshl_add_u32 v121, v120, 7, v121
	v_lshrrev_b32_e32 v120, 6, v143
	v_lshrrev_b32_e32 v112, 1, v120
	v_and_b32_e32 v120, 1, v120
	v_lshl_add_u32 v112, v112, 13, v121
	v_lshl_add_u32 v113, v120, 13, v121
	v_add_u32_e32 v113, 0x4000, v113
	v_xor_b32_e32 v114, 64, v112
	v_xor_b32_e32 v115, 64, v113
	s_waitcnt vmcnt(0) lgkmcnt(0)
	s_barrier
.LBB0_1027:
	v_lshl_add_u64 v[72:73], v[104:105], 0, s[34:35]
	v_add_co_u32_e32 v132, vcc, s21, v72
	v_lshl_add_u64 v[88:89], v[102:103], 0, s[34:35]
	s_nop 0
	v_addc_co_u32_e32 v133, vcc, 0, v73, vcc
	v_add_co_u32_e32 v134, vcc, s74, v72
	s_mov_b32 s4, 0x2e380000
	s_nop 0
	v_addc_co_u32_e32 v135, vcc, 0, v73, vcc
	v_add_co_u32_e32 v144, vcc, s75, v72
	v_addc_co_u32_e32 v145, vcc, 0, v73, vcc
	v_add_co_u32_e32 v146, vcc, s14, v72
	s_nop 1
	v_addc_co_u32_e32 v147, vcc, 0, v73, vcc
	v_add_co_u32_e32 v148, vcc, s4, v88
	s_mov_b32 s4, 0x2e3a0000
	s_nop 0
	v_addc_co_u32_e32 v149, vcc, 0, v89, vcc
	v_add_co_u32_e32 v150, vcc, s4, v88
	s_mov_b32 s4, 0x2e3c0000
	s_nop 0
	v_addc_co_u32_e32 v151, vcc, 0, v89, vcc
	v_add_co_u32_e32 v152, vcc, s4, v88
	s_mov_b32 s4, 0x2e3e0000
	s_nop 0
	v_addc_co_u32_e32 v153, vcc, 0, v89, vcc
	v_add_co_u32_e32 v154, vcc, s4, v88
	v_addc_co_u32_e32 v155, vcc, 0, v89, vcc
	v_lshl_add_u64 v[132:133], 8, 4, v[132:133]
	v_lshl_add_u64 v[134:135], 8, 4, v[134:135]
	v_lshl_add_u64 v[144:145], 8, 4, v[144:145]
	v_lshl_add_u64 v[146:147], 8, 4, v[146:147]
	v_lshl_add_u64 v[148:149], 8, 4, v[148:149]
	v_lshl_add_u64 v[150:151], 8, 4, v[150:151]
	v_lshl_add_u64 v[152:153], 8, 4, v[152:153]
	v_lshl_add_u64 v[154:155], 8, 4, v[154:155]
	s_add_u32 m0, s100, 0x8000
	s_nop 0
	global_load_lds_dwordx4 v[132:133], off
	s_add_u32 m0, s100, 0x9000
	s_nop 0
	global_load_lds_dwordx4 v[134:135], off
	s_add_u32 m0, s100, 0xa000
	s_nop 0
	global_load_lds_dwordx4 v[144:145], off
	s_add_u32 m0, s100, 0xb000
	s_nop 0
	global_load_lds_dwordx4 v[146:147], off
	s_add_u32 m0, s100, 0xc000
	s_nop 0
	global_load_lds_dwordx4 v[148:149], off
	s_add_u32 m0, s100, 0xd000
	s_nop 0
	global_load_lds_dwordx4 v[150:151], off
	s_add_u32 m0, s100, 0xe000
	s_nop 0
	global_load_lds_dwordx4 v[152:153], off
	s_add_u32 m0, s100, 0xf000
	s_nop 0
	global_load_lds_dwordx4 v[154:155], off
	ds_read_b128 a[0:3], v112
	ds_read_b128 v[80:83], v113
	ds_read_b128 a[4:7], v112 offset:2048
	ds_read_b128 a[8:11], v112 offset:4096
	ds_read_b128 a[12:15], v112 offset:6144
	ds_read_b128 v[92:95], v113 offset:2048
	ds_read_b128 v[88:91], v113 offset:4096
	ds_read_b128 v[84:87], v113 offset:6144
	ds_read_b128 a[16:19], v114
	ds_read_b128 a[20:23], v114 offset:2048
	ds_read_b128 a[24:27], v114 offset:4096
	ds_read_b128 a[28:31], v114 offset:6144
	s_setprio 1
	s_waitcnt lgkmcnt(10)
	v_mfma_f32_16x16x32_bf16 v[0:3], a[0:3], v[80:83], v[0:3]
	s_waitcnt lgkmcnt(9)
	v_mfma_f32_16x16x32_bf16 v[16:19], a[4:7], v[80:83], v[16:19]
	s_waitcnt lgkmcnt(8)
	v_mfma_f32_16x16x32_bf16 v[32:35], a[8:11], v[80:83], v[32:35]
	s_waitcnt lgkmcnt(7)
	v_mfma_f32_16x16x32_bf16 v[48:51], a[12:15], v[80:83], v[48:51]
	ds_read_b128 v[80:83], v115
	s_waitcnt lgkmcnt(7)
	v_mfma_f32_16x16x32_bf16 v[4:7], a[0:3], v[92:95], v[4:7]
	v_mfma_f32_16x16x32_bf16 v[20:23], a[4:7], v[92:95], v[20:23]
	v_mfma_f32_16x16x32_bf16 v[36:39], a[8:11], v[92:95], v[36:39]
	v_mfma_f32_16x16x32_bf16 v[52:55], a[12:15], v[92:95], v[52:55]
	ds_read_b128 v[92:95], v115 offset:2048
	s_waitcnt lgkmcnt(7)
	v_mfma_f32_16x16x32_bf16 v[8:11], a[0:3], v[88:91], v[8:11]
	v_mfma_f32_16x16x32_bf16 v[24:27], a[4:7], v[88:91], v[24:27]
	v_mfma_f32_16x16x32_bf16 v[40:43], a[8:11], v[88:91], v[40:43]
	v_mfma_f32_16x16x32_bf16 v[56:59], a[12:15], v[88:91], v[56:59]
	ds_read_b128 v[88:91], v115 offset:4096
	s_waitcnt lgkmcnt(7)
	v_mfma_f32_16x16x32_bf16 v[12:15], a[0:3], v[84:87], v[12:15]
	v_mfma_f32_16x16x32_bf16 v[28:31], a[4:7], v[84:87], v[28:31]
	v_mfma_f32_16x16x32_bf16 v[44:47], a[8:11], v[84:87], v[44:47]
	v_mfma_f32_16x16x32_bf16 v[60:63], a[12:15], v[84:87], v[60:63]
	ds_read_b128 v[84:87], v115 offset:6144
	s_waitcnt lgkmcnt(3)
	v_mfma_f32_16x16x32_bf16 v[0:3], a[16:19], v[80:83], v[0:3]
	v_mfma_f32_16x16x32_bf16 v[16:19], a[20:23], v[80:83], v[16:19]
	v_mfma_f32_16x16x32_bf16 v[32:35], a[24:27], v[80:83], v[32:35]
	v_mfma_f32_16x16x32_bf16 v[48:51], a[28:31], v[80:83], v[48:51]
	s_waitcnt lgkmcnt(2)
	v_mfma_f32_16x16x32_bf16 v[4:7], a[16:19], v[92:95], v[4:7]
	v_mfma_f32_16x16x32_bf16 v[20:23], a[20:23], v[92:95], v[20:23]
	v_mfma_f32_16x16x32_bf16 v[36:39], a[24:27], v[92:95], v[36:39]
	v_mfma_f32_16x16x32_bf16 v[52:55], a[28:31], v[92:95], v[52:55]
	s_waitcnt lgkmcnt(1)
	v_mfma_f32_16x16x32_bf16 v[8:11], a[16:19], v[88:91], v[8:11]
	v_mfma_f32_16x16x32_bf16 v[24:27], a[20:23], v[88:91], v[24:27]
	v_mfma_f32_16x16x32_bf16 v[40:43], a[24:27], v[88:91], v[40:43]
	v_mfma_f32_16x16x32_bf16 v[56:59], a[28:31], v[88:91], v[56:59]
	s_waitcnt lgkmcnt(0)
	v_mfma_f32_16x16x32_bf16 v[12:15], a[16:19], v[84:87], v[12:15]
	v_mfma_f32_16x16x32_bf16 v[28:31], a[20:23], v[84:87], v[28:31]
	v_mfma_f32_16x16x32_bf16 v[44:47], a[24:27], v[84:87], v[44:47]
	v_mfma_f32_16x16x32_bf16 v[60:63], a[28:31], v[84:87], v[60:63]
	s_setprio 0
	s_waitcnt vmcnt(0) lgkmcnt(0)
	s_barrier
	v_lshl_add_u64 v[64:65], 8, 4, v[132:133]
	v_lshl_add_u64 v[66:67], 8, 4, v[134:135]
	v_lshl_add_u64 v[68:69], 8, 4, v[144:145]
	v_lshl_add_u64 v[70:71], 8, 4, v[146:147]
	v_lshl_add_u64 v[76:77], 8, 4, v[148:149]
	v_lshl_add_u64 v[78:79], 8, 4, v[150:151]
	v_lshl_add_u64 v[72:73], 8, 4, v[152:153]
	v_lshl_add_u64 v[74:75], 8, 4, v[154:155]
	s_add_u32 m0, s100, 0x0
	s_nop 0
	global_load_lds_dwordx4 v[64:65], off
	s_add_u32 m0, s100, 0x1000
	s_nop 0
	global_load_lds_dwordx4 v[66:67], off
	s_add_u32 m0, s100, 0x2000
	s_nop 0
	global_load_lds_dwordx4 v[68:69], off
	s_add_u32 m0, s100, 0x3000
	s_nop 0
	global_load_lds_dwordx4 v[70:71], off
	s_add_u32 m0, s100, 0x4000
	s_nop 0
	global_load_lds_dwordx4 v[76:77], off
	s_add_u32 m0, s100, 0x5000
	s_nop 0
	global_load_lds_dwordx4 v[78:79], off
	s_add_u32 m0, s100, 0x6000
	s_nop 0
	global_load_lds_dwordx4 v[72:73], off
	s_add_u32 m0, s100, 0x7000
	s_nop 0
	global_load_lds_dwordx4 v[74:75], off
	ds_read_b128 a[0:3], v112 offset:32768
	ds_read_b128 v[80:83], v113 offset:32768
	ds_read_b128 a[4:7], v112 offset:34816
	ds_read_b128 a[8:11], v112 offset:36864
	ds_read_b128 a[12:15], v112 offset:38912
	ds_read_b128 v[92:95], v113 offset:34816
	ds_read_b128 v[88:91], v113 offset:36864
	ds_read_b128 v[84:87], v113 offset:38912
	ds_read_b128 a[16:19], v114 offset:32768
	ds_read_b128 a[20:23], v114 offset:34816
	ds_read_b128 a[24:27], v114 offset:36864
	ds_read_b128 a[28:31], v114 offset:38912
	s_setprio 1
	s_waitcnt lgkmcnt(10)
	v_mfma_f32_16x16x32_bf16 v[0:3], a[0:3], v[80:83], v[0:3]
	s_waitcnt lgkmcnt(9)
	v_mfma_f32_16x16x32_bf16 v[16:19], a[4:7], v[80:83], v[16:19]
	s_waitcnt lgkmcnt(8)
	v_mfma_f32_16x16x32_bf16 v[32:35], a[8:11], v[80:83], v[32:35]
	s_waitcnt lgkmcnt(7)
	v_mfma_f32_16x16x32_bf16 v[48:51], a[12:15], v[80:83], v[48:51]
	ds_read_b128 v[80:83], v115 offset:32768
	s_waitcnt lgkmcnt(7)
	v_mfma_f32_16x16x32_bf16 v[4:7], a[0:3], v[92:95], v[4:7]
	v_mfma_f32_16x16x32_bf16 v[20:23], a[4:7], v[92:95], v[20:23]
	v_mfma_f32_16x16x32_bf16 v[36:39], a[8:11], v[92:95], v[36:39]
	v_mfma_f32_16x16x32_bf16 v[52:55], a[12:15], v[92:95], v[52:55]
	ds_read_b128 v[92:95], v115 offset:34816
	s_waitcnt lgkmcnt(7)
	v_mfma_f32_16x16x32_bf16 v[8:11], a[0:3], v[88:91], v[8:11]
	v_mfma_f32_16x16x32_bf16 v[24:27], a[4:7], v[88:91], v[24:27]
	v_mfma_f32_16x16x32_bf16 v[40:43], a[8:11], v[88:91], v[40:43]
	v_mfma_f32_16x16x32_bf16 v[56:59], a[12:15], v[88:91], v[56:59]
	ds_read_b128 v[88:91], v115 offset:36864
	s_waitcnt lgkmcnt(7)
	v_mfma_f32_16x16x32_bf16 v[12:15], a[0:3], v[84:87], v[12:15]
	v_mfma_f32_16x16x32_bf16 v[28:31], a[4:7], v[84:87], v[28:31]
	v_mfma_f32_16x16x32_bf16 v[44:47], a[8:11], v[84:87], v[44:47]
	v_mfma_f32_16x16x32_bf16 v[60:63], a[12:15], v[84:87], v[60:63]
	ds_read_b128 v[84:87], v115 offset:38912
	s_waitcnt lgkmcnt(3)
	v_mfma_f32_16x16x32_bf16 v[0:3], a[16:19], v[80:83], v[0:3]
	v_mfma_f32_16x16x32_bf16 v[16:19], a[20:23], v[80:83], v[16:19]
	v_mfma_f32_16x16x32_bf16 v[32:35], a[24:27], v[80:83], v[32:35]
	v_mfma_f32_16x16x32_bf16 v[48:51], a[28:31], v[80:83], v[48:51]
	s_waitcnt lgkmcnt(2)
	v_mfma_f32_16x16x32_bf16 v[4:7], a[16:19], v[92:95], v[4:7]
	v_mfma_f32_16x16x32_bf16 v[20:23], a[20:23], v[92:95], v[20:23]
	v_mfma_f32_16x16x32_bf16 v[36:39], a[24:27], v[92:95], v[36:39]
	v_mfma_f32_16x16x32_bf16 v[52:55], a[28:31], v[92:95], v[52:55]
	s_waitcnt lgkmcnt(1)
	v_mfma_f32_16x16x32_bf16 v[8:11], a[16:19], v[88:91], v[8:11]
	v_mfma_f32_16x16x32_bf16 v[24:27], a[20:23], v[88:91], v[24:27]
	v_mfma_f32_16x16x32_bf16 v[40:43], a[24:27], v[88:91], v[40:43]
	v_mfma_f32_16x16x32_bf16 v[56:59], a[28:31], v[88:91], v[56:59]
	s_waitcnt lgkmcnt(0)
	v_mfma_f32_16x16x32_bf16 v[12:15], a[16:19], v[84:87], v[12:15]
	v_mfma_f32_16x16x32_bf16 v[28:31], a[20:23], v[84:87], v[28:31]
	v_mfma_f32_16x16x32_bf16 v[44:47], a[24:27], v[84:87], v[44:47]
	v_mfma_f32_16x16x32_bf16 v[60:63], a[28:31], v[84:87], v[60:63]
	s_setprio 0
	s_waitcnt vmcnt(0) lgkmcnt(0)
	s_barrier
	s_add_u32 s34, s34, 0x100
	s_addc_u32 s35, s35, 0
	s_cmpk_eq_i32 s34, 0xf00
	s_cbranch_scc0 .LBB0_1027
	v_lshl_add_u64 v[64:65], 8, 4, v[64:65]
	v_lshl_add_u64 v[66:67], 8, 4, v[66:67]
	v_lshl_add_u64 v[68:69], 8, 4, v[68:69]
	v_lshl_add_u64 v[70:71], 8, 4, v[70:71]
	v_lshl_add_u64 v[76:77], 8, 4, v[76:77]
	v_lshl_add_u64 v[78:79], 8, 4, v[78:79]
	v_lshl_add_u64 v[72:73], 8, 4, v[72:73]
	v_lshl_add_u64 v[74:75], 8, 4, v[74:75]
	s_add_u32 m0, s100, 0x8000
	s_nop 0
	global_load_lds_dwordx4 v[64:65], off
	s_add_u32 m0, s100, 0x9000
	s_nop 0
	global_load_lds_dwordx4 v[66:67], off
	s_add_u32 m0, s100, 0xa000
	s_nop 0
	global_load_lds_dwordx4 v[68:69], off
	s_add_u32 m0, s100, 0xb000
	s_nop 0
	global_load_lds_dwordx4 v[70:71], off
	s_add_u32 m0, s100, 0xc000
	s_nop 0
	global_load_lds_dwordx4 v[76:77], off
	s_add_u32 m0, s100, 0xd000
	s_nop 0
	global_load_lds_dwordx4 v[78:79], off
	s_add_u32 m0, s100, 0xe000
	s_nop 0
	global_load_lds_dwordx4 v[72:73], off
	s_add_u32 m0, s100, 0xf000
	s_nop 0
	global_load_lds_dwordx4 v[74:75], off
	ds_read_b128 a[0:3], v112
	ds_read_b128 v[80:83], v113
	ds_read_b128 a[4:7], v112 offset:2048
	ds_read_b128 a[8:11], v112 offset:4096
	ds_read_b128 a[12:15], v112 offset:6144
	ds_read_b128 v[92:95], v113 offset:2048
	ds_read_b128 v[88:91], v113 offset:4096
	ds_read_b128 v[84:87], v113 offset:6144
	ds_read_b128 a[16:19], v114
	ds_read_b128 a[20:23], v114 offset:2048
	ds_read_b128 a[24:27], v114 offset:4096
	ds_read_b128 a[28:31], v114 offset:6144
	s_setprio 1
	s_waitcnt lgkmcnt(10)
	v_mfma_f32_16x16x32_bf16 v[0:3], a[0:3], v[80:83], v[0:3]
	s_waitcnt lgkmcnt(9)
	v_mfma_f32_16x16x32_bf16 v[16:19], a[4:7], v[80:83], v[16:19]
	s_waitcnt lgkmcnt(8)
	v_mfma_f32_16x16x32_bf16 v[32:35], a[8:11], v[80:83], v[32:35]
	s_waitcnt lgkmcnt(7)
	v_mfma_f32_16x16x32_bf16 v[48:51], a[12:15], v[80:83], v[48:51]
	ds_read_b128 v[80:83], v115
	s_waitcnt lgkmcnt(7)
	v_mfma_f32_16x16x32_bf16 v[4:7], a[0:3], v[92:95], v[4:7]
	v_mfma_f32_16x16x32_bf16 v[20:23], a[4:7], v[92:95], v[20:23]
	v_mfma_f32_16x16x32_bf16 v[36:39], a[8:11], v[92:95], v[36:39]
	v_mfma_f32_16x16x32_bf16 v[52:55], a[12:15], v[92:95], v[52:55]
	ds_read_b128 v[92:95], v115 offset:2048
	s_waitcnt lgkmcnt(7)
	v_mfma_f32_16x16x32_bf16 v[8:11], a[0:3], v[88:91], v[8:11]
	v_mfma_f32_16x16x32_bf16 v[24:27], a[4:7], v[88:91], v[24:27]
	v_mfma_f32_16x16x32_bf16 v[40:43], a[8:11], v[88:91], v[40:43]
	v_mfma_f32_16x16x32_bf16 v[56:59], a[12:15], v[88:91], v[56:59]
	ds_read_b128 v[88:91], v115 offset:4096
	s_waitcnt lgkmcnt(7)
	v_mfma_f32_16x16x32_bf16 v[12:15], a[0:3], v[84:87], v[12:15]
	v_mfma_f32_16x16x32_bf16 v[28:31], a[4:7], v[84:87], v[28:31]
	v_mfma_f32_16x16x32_bf16 v[44:47], a[8:11], v[84:87], v[44:47]
	v_mfma_f32_16x16x32_bf16 v[60:63], a[12:15], v[84:87], v[60:63]
	ds_read_b128 v[84:87], v115 offset:6144
	s_waitcnt lgkmcnt(3)
	v_mfma_f32_16x16x32_bf16 v[0:3], a[16:19], v[80:83], v[0:3]
	v_mfma_f32_16x16x32_bf16 v[16:19], a[20:23], v[80:83], v[16:19]
	v_mfma_f32_16x16x32_bf16 v[32:35], a[24:27], v[80:83], v[32:35]
	v_mfma_f32_16x16x32_bf16 v[48:51], a[28:31], v[80:83], v[48:51]
	s_waitcnt lgkmcnt(2)
	v_mfma_f32_16x16x32_bf16 v[4:7], a[16:19], v[92:95], v[4:7]
	v_mfma_f32_16x16x32_bf16 v[20:23], a[20:23], v[92:95], v[20:23]
	v_mfma_f32_16x16x32_bf16 v[36:39], a[24:27], v[92:95], v[36:39]
	v_mfma_f32_16x16x32_bf16 v[52:55], a[28:31], v[92:95], v[52:55]
	s_waitcnt lgkmcnt(1)
	v_mfma_f32_16x16x32_bf16 v[8:11], a[16:19], v[88:91], v[8:11]
	v_mfma_f32_16x16x32_bf16 v[24:27], a[20:23], v[88:91], v[24:27]
	v_mfma_f32_16x16x32_bf16 v[40:43], a[24:27], v[88:91], v[40:43]
	v_mfma_f32_16x16x32_bf16 v[56:59], a[28:31], v[88:91], v[56:59]
	s_waitcnt lgkmcnt(0)
	v_mfma_f32_16x16x32_bf16 v[12:15], a[16:19], v[84:87], v[12:15]
	v_mfma_f32_16x16x32_bf16 v[28:31], a[20:23], v[84:87], v[28:31]
	v_mfma_f32_16x16x32_bf16 v[44:47], a[24:27], v[84:87], v[44:47]
	v_mfma_f32_16x16x32_bf16 v[60:63], a[28:31], v[84:87], v[60:63]
	s_setprio 0
	s_waitcnt vmcnt(0) lgkmcnt(0)
	s_barrier
	ds_read_b128 a[0:3], v112 offset:32768
	ds_read_b128 v[80:83], v113 offset:32768
	ds_read_b128 a[4:7], v112 offset:34816
	ds_read_b128 a[8:11], v112 offset:36864
	ds_read_b128 a[12:15], v112 offset:38912
	ds_read_b128 v[92:95], v113 offset:34816
	ds_read_b128 v[88:91], v113 offset:36864
	ds_read_b128 v[84:87], v113 offset:38912
	ds_read_b128 a[16:19], v114 offset:32768
	ds_read_b128 a[20:23], v114 offset:34816
	ds_read_b128 a[24:27], v114 offset:36864
	ds_read_b128 a[28:31], v114 offset:38912
	s_setprio 1
	s_waitcnt lgkmcnt(10)
	v_mfma_f32_16x16x32_bf16 v[0:3], a[0:3], v[80:83], v[0:3]
	s_waitcnt lgkmcnt(9)
	v_mfma_f32_16x16x32_bf16 v[16:19], a[4:7], v[80:83], v[16:19]
	s_waitcnt lgkmcnt(8)
	v_mfma_f32_16x16x32_bf16 v[32:35], a[8:11], v[80:83], v[32:35]
	s_waitcnt lgkmcnt(7)
	v_mfma_f32_16x16x32_bf16 v[48:51], a[12:15], v[80:83], v[48:51]
	ds_read_b128 v[80:83], v115 offset:32768
	s_waitcnt lgkmcnt(7)
	v_mfma_f32_16x16x32_bf16 v[4:7], a[0:3], v[92:95], v[4:7]
	v_mfma_f32_16x16x32_bf16 v[20:23], a[4:7], v[92:95], v[20:23]
	v_mfma_f32_16x16x32_bf16 v[36:39], a[8:11], v[92:95], v[36:39]
	v_mfma_f32_16x16x32_bf16 v[52:55], a[12:15], v[92:95], v[52:55]
	ds_read_b128 v[92:95], v115 offset:34816
	s_waitcnt lgkmcnt(7)
	v_mfma_f32_16x16x32_bf16 v[8:11], a[0:3], v[88:91], v[8:11]
	v_mfma_f32_16x16x32_bf16 v[24:27], a[4:7], v[88:91], v[24:27]
	v_mfma_f32_16x16x32_bf16 v[40:43], a[8:11], v[88:91], v[40:43]
	v_mfma_f32_16x16x32_bf16 v[56:59], a[12:15], v[88:91], v[56:59]
	ds_read_b128 v[88:91], v115 offset:36864
	s_waitcnt lgkmcnt(7)
	v_mfma_f32_16x16x32_bf16 v[12:15], a[0:3], v[84:87], v[12:15]
	v_mfma_f32_16x16x32_bf16 v[28:31], a[4:7], v[84:87], v[28:31]
	v_mfma_f32_16x16x32_bf16 v[44:47], a[8:11], v[84:87], v[44:47]
	v_mfma_f32_16x16x32_bf16 v[60:63], a[12:15], v[84:87], v[60:63]
	ds_read_b128 v[84:87], v115 offset:38912
	s_waitcnt lgkmcnt(3)
	v_mfma_f32_16x16x32_bf16 v[0:3], a[16:19], v[80:83], v[0:3]
	v_mfma_f32_16x16x32_bf16 v[16:19], a[20:23], v[80:83], v[16:19]
	v_mfma_f32_16x16x32_bf16 v[32:35], a[24:27], v[80:83], v[32:35]
	v_mfma_f32_16x16x32_bf16 v[48:51], a[28:31], v[80:83], v[48:51]
	s_waitcnt lgkmcnt(2)
	v_mfma_f32_16x16x32_bf16 v[4:7], a[16:19], v[92:95], v[4:7]
	v_mfma_f32_16x16x32_bf16 v[20:23], a[20:23], v[92:95], v[20:23]
	v_mfma_f32_16x16x32_bf16 v[36:39], a[24:27], v[92:95], v[36:39]
	v_mfma_f32_16x16x32_bf16 v[52:55], a[28:31], v[92:95], v[52:55]
	s_waitcnt lgkmcnt(1)
	v_mfma_f32_16x16x32_bf16 v[8:11], a[16:19], v[88:91], v[8:11]
	v_mfma_f32_16x16x32_bf16 v[24:27], a[20:23], v[88:91], v[24:27]
	v_mfma_f32_16x16x32_bf16 v[40:43], a[24:27], v[88:91], v[40:43]
	v_mfma_f32_16x16x32_bf16 v[56:59], a[28:31], v[88:91], v[56:59]
	s_waitcnt lgkmcnt(0)
	v_mfma_f32_16x16x32_bf16 v[12:15], a[16:19], v[84:87], v[12:15]
	v_mfma_f32_16x16x32_bf16 v[28:31], a[20:23], v[84:87], v[28:31]
	v_mfma_f32_16x16x32_bf16 v[44:47], a[24:27], v[84:87], v[44:47]
	v_mfma_f32_16x16x32_bf16 v[60:63], a[28:31], v[84:87], v[60:63]
	s_setprio 0
	v_readfirstlane_b32 s15, v107
	v_readfirstlane_b32 s4, v106
	s_lshl_b32 s15, s15, 6
	s_waitcnt lgkmcnt(0)
	s_barrier
	s_add_i32 s15, s15, s9
	s_lshl_b32 s44, s4, 6
	s_add_i32 s44, s44, s8
	v_or_b32_e32 v65, s15, v108
	s_movk_i32 s4, 0x800
	s_ashr_i32 s43, s44, 11
	v_cmp_gt_i32_e64 s[40:41], s4, v65
	v_add_u32_e32 v64, 0x1000, v65
	s_barrier
	v_and_b32_e32 v120, 15, v143
	v_bfe_u32 v121, v143, 4, 2
	v_xor_b32_e32 v121, v121, v120
	v_lshlrev_b32_e32 v121, 4, v121
	v_lshl_add_u32 v121, v120, 8, v121
	v_lshrrev_b32_e32 v120, 6, v143
	v_lshl_add_u32 v121, v120, 14, v121
	ds_write_b128 v121, v[0:3]
	ds_write_b128 v121, v[4:7] offset:4096
	ds_write_b128 v121, v[8:11] offset:8192
	ds_write_b128 v121, v[12:15] offset:12288
	v_xor_b32_e32 v115, 64, v121
	ds_write_b128 v115, v[16:19]
	ds_write_b128 v115, v[20:23] offset:4096
	ds_write_b128 v115, v[24:27] offset:8192
	ds_write_b128 v115, v[28:31] offset:12288
	v_xor_b32_e32 v115, 128, v121
	ds_write_b128 v115, v[32:35]
	ds_write_b128 v115, v[36:39] offset:4096
	ds_write_b128 v115, v[40:43] offset:8192
	ds_write_b128 v115, v[44:47] offset:12288
	v_xor_b32_e32 v115, 192, v121
	ds_write_b128 v115, v[48:51]
	ds_write_b128 v115, v[52:55] offset:4096
	ds_write_b128 v115, v[56:59] offset:8192
	ds_write_b128 v115, v[60:63] offset:12288
	v_and_b32_e32 v112, 31, v143
	v_bfe_u32 v114, v143, 5, 1
	v_and_b32_e32 v121, 15, v112
	v_xor_b32_e32 v114, v114, v121
	v_lshlrev_b32_e32 v114, 4, v114
	v_lshl_add_u32 v114, v112, 8, v114
	v_lshl_add_u32 v114, v120, 14, v114
	ds_read_b128 v[48:51], v114
	ds_read_b128 v[32:35], v114 offset:8192
	v_xor_b32_e32 v113, 32, v114
	ds_read_b128 v[52:55], v113
	ds_read_b128 v[36:39], v113 offset:8192
	v_xor_b32_e32 v113, 64, v114
	ds_read_b128 v[56:59], v113
	ds_read_b128 v[40:43], v113 offset:8192
	v_xor_b32_e32 v113, 96, v114
	ds_read_b128 v[60:63], v113
	ds_read_b128 v[44:47], v113 offset:8192
	v_xor_b32_e32 v113, 128, v114
	ds_read_b128 v[16:19], v113
	ds_read_b128 v[0:3], v113 offset:8192
	v_xor_b32_e32 v113, 160, v114
	ds_read_b128 v[20:23], v113
	ds_read_b128 v[4:7], v113 offset:8192
	v_xor_b32_e32 v113, 192, v114
	ds_read_b128 v[24:27], v113
	ds_read_b128 v[8:11], v113 offset:8192
	v_xor_b32_e32 v113, 224, v114
	ds_read_b128 v[28:31], v113
	ds_read_b128 v[12:15], v113 offset:8192
	s_waitcnt lgkmcnt(0)
	s_barrier
	s_and_saveexec_b64 s[34:35], s[40:41]
	s_cbranch_execz .LBB0_1046
	s_add_i32 s4, s44, 0xffffe000
	s_lshr_b32 s4, s4, 3
	s_or_b32 s4, s4, 4
	s_cmpk_lt_i32 s44, 0x2000
	s_cselect_b32 s4, s43, s4
	s_mulk_i32 s4, 0x3000
	v_add_u32_e32 v66, s4, v64
	v_mov_b32_e32 v67, v140
	v_lshl_add_u64 v[66:67], v[66:67], 2, s[28:29]
	global_load_dword v66, v[66:67], off
	s_cmpk_gt_i32 s44, 0x1fff
	s_mov_b64 s[36:37], -1
	s_cbranch_scc0 .LBB0_1031
	s_load_dwordx2 s[8:9], s[26:27], 0x8
	s_mov_b64 s[36:37], 0
	s_waitcnt lgkmcnt(0)
	s_add_u32 s8, s8, 0xfc000000
	s_addc_u32 s9, s9, -1

.LBB0_1725:
	s_mul_hi_i32 s4, s26, 0x38e38e39
	s_lshr_b32 s8, s4, 31
	s_ashr_i32 s4, s4, 4
	s_add_i32 s4, s4, s8
	s_mul_i32 s8, s4, 0x48
	s_sub_i32 s8, s26, s8
	s_lshl_b32 s8, s8, 7
	v_add_u32_e32 v0, s8, v109
	v_ashrrev_i32_e32 v1, 31, v0
	v_lshlrev_b64 v[32:33], 12, v[0:1]
	v_lshl_add_u64 v[34:35], v[96:97], 0, v[32:33]
	v_add_co_u32_e32 v40, vcc, s87, v34
	s_lshl_b32 s9, s4, 7
	s_nop 0
	v_addc_co_u32_e32 v41, vcc, 0, v35, vcc
	v_add_co_u32_e32 v42, vcc, s66, v34
	v_add_u32_e32 v0, s9, v109
	s_nop 0
	v_addc_co_u32_e32 v43, vcc, 0, v35, vcc
	v_ashrrev_i32_e32 v1, 31, v0
	s_waitcnt vmcnt(13)
	v_add_co_u32_e32 v44, vcc, s20, v34
	v_lshlrev_b64 v[36:37], 12, v[0:1]
	s_nop 0
	v_addc_co_u32_e32 v45, vcc, 0, v35, vcc
	v_lshl_add_u64 v[38:39], v[98:99], 0, v[36:37]
	v_readfirstlane_b32 s100, v110
	s_nop 3
	s_add_u32 m0, s100, 0x0
	s_nop 0
	global_load_lds_dwordx4 v[34:35], off
	s_add_u32 m0, s100, 0x1000
	s_nop 0
	global_load_lds_dwordx4 v[40:41], off
	s_add_u32 m0, s100, 0x2000
	s_nop 0
	global_load_lds_dwordx4 v[42:43], off
	s_add_u32 m0, s100, 0x3000
	s_nop 0
	global_load_lds_dwordx4 v[44:45], off
	s_add_u32 m0, s100, 0x4000
	s_nop 0
	global_load_lds_dwordx4 v[38:39], off
	v_add_co_u32_e32 v46, vcc, s87, v38
	v_lshl_add_u64 v[102:103], v[100:101], 0, v[36:37]
	s_nop 0
	v_addc_co_u32_e32 v47, vcc, 0, v39, vcc
	s_waitcnt vmcnt(8)
	v_add_co_u32_e32 v48, vcc, s66, v38
	s_add_u32 m0, s100, 0x5000
	s_nop 0
	global_load_lds_dwordx4 v[46:47], off
	s_nop 0
	v_addc_co_u32_e32 v49, vcc, 0, v39, vcc
	v_add_co_u32_e32 v50, vcc, s20, v38
	s_add_u32 m0, s100, 0x6000
	s_nop 0
	global_load_lds_dwordx4 v[48:49], off
	s_nop 0
	v_addc_co_u32_e32 v51, vcc, 0, v39, vcc
	s_add_u32 m0, s100, 0x7000
	s_nop 0
	global_load_lds_dwordx4 v[50:51], off
	v_lshl_add_u64 v[104:105], v[100:101], 0, v[32:33]
	s_mov_b64 s[22:23], 0
	v_mov_b32_e32 v0, 0
	v_mov_b32_e32 v1, v0
	v_mov_b32_e32 v2, v0
	v_mov_b32_e32 v3, v0
	v_mov_b32_e32 v4, v0
	v_mov_b32_e32 v5, v0
	v_mov_b32_e32 v6, v0
	v_mov_b32_e32 v7, v0
	v_mov_b32_e32 v8, v0
	v_mov_b32_e32 v9, v0
	v_mov_b32_e32 v10, v0
	v_mov_b32_e32 v11, v0
	v_mov_b32_e32 v12, v0
	v_mov_b32_e32 v13, v0
	v_mov_b32_e32 v14, v0
	v_mov_b32_e32 v15, v0
	v_mov_b32_e32 v16, v0
	v_mov_b32_e32 v17, v0
	v_mov_b32_e32 v18, v0
	v_mov_b32_e32 v19, v0
	v_mov_b32_e32 v20, v0
	v_mov_b32_e32 v21, v0
	v_mov_b32_e32 v22, v0
	v_mov_b32_e32 v23, v0
	v_mov_b32_e32 v24, v0
	v_mov_b32_e32 v25, v0
	v_mov_b32_e32 v26, v0
	v_mov_b32_e32 v27, v0
	v_mov_b32_e32 v28, v0
	v_mov_b32_e32 v29, v0
	v_mov_b32_e32 v30, v0
	v_mov_b32_e32 v31, v0
	v_mov_b32_e32 v32, v0
	v_mov_b32_e32 v33, v0
	v_mov_b32_e32 v34, v0
	v_mov_b32_e32 v35, v0
	v_mov_b32_e32 v36, v0
	v_mov_b32_e32 v37, v0
	v_mov_b32_e32 v38, v0
	v_mov_b32_e32 v39, v0
	v_mov_b32_e32 v40, v0
	v_mov_b32_e32 v41, v0
	v_mov_b32_e32 v42, v0
	v_mov_b32_e32 v43, v0
	v_mov_b32_e32 v44, v0
	v_mov_b32_e32 v45, v0
	v_mov_b32_e32 v46, v0
	v_mov_b32_e32 v47, v0
	v_mov_b32_e32 v48, v0
	v_mov_b32_e32 v49, v0
	v_mov_b32_e32 v50, v0
	v_mov_b32_e32 v51, v0
	v_mov_b32_e32 v52, v0
	v_mov_b32_e32 v53, v0
	v_mov_b32_e32 v54, v0
	v_mov_b32_e32 v55, v0
	v_mov_b32_e32 v56, v0
	v_mov_b32_e32 v57, v0
	v_mov_b32_e32 v58, v0
	v_mov_b32_e32 v59, v0
	v_mov_b32_e32 v60, v0
	v_mov_b32_e32 v61, v0
	v_mov_b32_e32 v62, v0
	v_mov_b32_e32 v63, v0
	v_and_b32_e32 v120, 15, v143
	v_lshrrev_b32_e32 v121, 1, v120
	v_bfe_u32 v114, v143, 4, 2
	v_xor_b32_e32 v121, v121, v114
	v_lshlrev_b32_e32 v121, 4, v121
	v_lshl_add_u32 v121, v120, 7, v121
	v_lshrrev_b32_e32 v120, 6, v143
	v_lshrrev_b32_e32 v112, 1, v120
	v_and_b32_e32 v120, 1, v120
	v_lshl_add_u32 v112, v112, 13, v121
	v_lshl_add_u32 v113, v120, 13, v121
	v_add_u32_e32 v113, 0x4000, v113
	v_xor_b32_e32 v114, 64, v112
	v_xor_b32_e32 v115, 64, v113
	s_waitcnt vmcnt(0) lgkmcnt(0)
	s_barrier
.LBB0_1726:
	v_lshl_add_u64 v[72:73], v[104:105], 0, s[22:23]
	v_add_co_u32_e32 v132, vcc, s21, v72
	v_lshl_add_u64 v[88:89], v[102:103], 0, s[22:23]
	s_nop 0
	v_addc_co_u32_e32 v133, vcc, 0, v73, vcc
	v_add_co_u32_e32 v134, vcc, s74, v72
	s_mov_b32 s4, 0x2c300000
	s_nop 0
	v_addc_co_u32_e32 v135, vcc, 0, v73, vcc
	v_add_co_u32_e32 v144, vcc, s75, v72
	v_addc_co_u32_e32 v145, vcc, 0, v73, vcc
	v_add_co_u32_e32 v146, vcc, s14, v72
	s_nop 1
	v_addc_co_u32_e32 v147, vcc, 0, v73, vcc
	v_add_co_u32_e32 v148, vcc, s4, v88
	s_mov_b32 s4, 0x2c320000
	s_nop 0
	v_addc_co_u32_e32 v149, vcc, 0, v89, vcc
	v_add_co_u32_e32 v150, vcc, s4, v88
	s_mov_b32 s4, 0x2c340000
	s_nop 0
	v_addc_co_u32_e32 v151, vcc, 0, v89, vcc
	v_add_co_u32_e32 v152, vcc, s4, v88
	s_mov_b32 s4, 0x2c360000
	s_nop 0
	v_addc_co_u32_e32 v153, vcc, 0, v89, vcc
	v_add_co_u32_e32 v154, vcc, s4, v88
	v_addc_co_u32_e32 v155, vcc, 0, v89, vcc
	v_lshl_add_u64 v[132:133], 8, 4, v[132:133]
	v_lshl_add_u64 v[134:135], 8, 4, v[134:135]
	v_lshl_add_u64 v[144:145], 8, 4, v[144:145]
	v_lshl_add_u64 v[146:147], 8, 4, v[146:147]
	v_lshl_add_u64 v[148:149], 8, 4, v[148:149]
	v_lshl_add_u64 v[150:151], 8, 4, v[150:151]
	v_lshl_add_u64 v[152:153], 8, 4, v[152:153]
	v_lshl_add_u64 v[154:155], 8, 4, v[154:155]
	s_add_u32 m0, s100, 0x8000
	s_nop 0
	global_load_lds_dwordx4 v[132:133], off
	s_add_u32 m0, s100, 0x9000
	s_nop 0
	global_load_lds_dwordx4 v[134:135], off
	s_add_u32 m0, s100, 0xa000
	s_nop 0
	global_load_lds_dwordx4 v[144:145], off
	s_add_u32 m0, s100, 0xb000
	s_nop 0
	global_load_lds_dwordx4 v[146:147], off
	s_add_u32 m0, s100, 0xc000
	s_nop 0
	global_load_lds_dwordx4 v[148:149], off
	s_add_u32 m0, s100, 0xd000
	s_nop 0
	global_load_lds_dwordx4 v[150:151], off
	s_add_u32 m0, s100, 0xe000
	s_nop 0
	global_load_lds_dwordx4 v[152:153], off
	s_add_u32 m0, s100, 0xf000
	s_nop 0
	global_load_lds_dwordx4 v[154:155], off
	ds_read_b128 a[0:3], v112
	ds_read_b128 v[80:83], v113
	ds_read_b128 a[4:7], v112 offset:2048
	ds_read_b128 a[8:11], v112 offset:4096
	ds_read_b128 a[12:15], v112 offset:6144
	ds_read_b128 v[92:95], v113 offset:2048
	ds_read_b128 v[88:91], v113 offset:4096
	ds_read_b128 v[84:87], v113 offset:6144
	ds_read_b128 a[16:19], v114
	ds_read_b128 a[20:23], v114 offset:2048
	ds_read_b128 a[24:27], v114 offset:4096
	ds_read_b128 a[28:31], v114 offset:6144
	s_setprio 1
	s_waitcnt lgkmcnt(10)
	v_mfma_f32_16x16x32_bf16 v[0:3], a[0:3], v[80:83], v[0:3]
	s_waitcnt lgkmcnt(9)
	v_mfma_f32_16x16x32_bf16 v[16:19], a[4:7], v[80:83], v[16:19]
	s_waitcnt lgkmcnt(8)
	v_mfma_f32_16x16x32_bf16 v[32:35], a[8:11], v[80:83], v[32:35]
	s_waitcnt lgkmcnt(7)
	v_mfma_f32_16x16x32_bf16 v[48:51], a[12:15], v[80:83], v[48:51]
	ds_read_b128 v[80:83], v115
	s_waitcnt lgkmcnt(7)
	v_mfma_f32_16x16x32_bf16 v[4:7], a[0:3], v[92:95], v[4:7]
	v_mfma_f32_16x16x32_bf16 v[20:23], a[4:7], v[92:95], v[20:23]
	v_mfma_f32_16x16x32_bf16 v[36:39], a[8:11], v[92:95], v[36:39]
	v_mfma_f32_16x16x32_bf16 v[52:55], a[12:15], v[92:95], v[52:55]
	ds_read_b128 v[92:95], v115 offset:2048
	s_waitcnt lgkmcnt(7)
	v_mfma_f32_16x16x32_bf16 v[8:11], a[0:3], v[88:91], v[8:11]
	v_mfma_f32_16x16x32_bf16 v[24:27], a[4:7], v[88:91], v[24:27]
	v_mfma_f32_16x16x32_bf16 v[40:43], a[8:11], v[88:91], v[40:43]
	v_mfma_f32_16x16x32_bf16 v[56:59], a[12:15], v[88:91], v[56:59]
	ds_read_b128 v[88:91], v115 offset:4096
	s_waitcnt lgkmcnt(7)
	v_mfma_f32_16x16x32_bf16 v[12:15], a[0:3], v[84:87], v[12:15]
	v_mfma_f32_16x16x32_bf16 v[28:31], a[4:7], v[84:87], v[28:31]
	v_mfma_f32_16x16x32_bf16 v[44:47], a[8:11], v[84:87], v[44:47]
	v_mfma_f32_16x16x32_bf16 v[60:63], a[12:15], v[84:87], v[60:63]
	ds_read_b128 v[84:87], v115 offset:6144
	s_waitcnt lgkmcnt(3)
	v_mfma_f32_16x16x32_bf16 v[0:3], a[16:19], v[80:83], v[0:3]
	v_mfma_f32_16x16x32_bf16 v[16:19], a[20:23], v[80:83], v[16:19]
	v_mfma_f32_16x16x32_bf16 v[32:35], a[24:27], v[80:83], v[32:35]
	v_mfma_f32_16x16x32_bf16 v[48:51], a[28:31], v[80:83], v[48:51]
	s_waitcnt lgkmcnt(2)
	v_mfma_f32_16x16x32_bf16 v[4:7], a[16:19], v[92:95], v[4:7]
	v_mfma_f32_16x16x32_bf16 v[20:23], a[20:23], v[92:95], v[20:23]
	v_mfma_f32_16x16x32_bf16 v[36:39], a[24:27], v[92:95], v[36:39]
	v_mfma_f32_16x16x32_bf16 v[52:55], a[28:31], v[92:95], v[52:55]
	s_waitcnt lgkmcnt(1)
	v_mfma_f32_16x16x32_bf16 v[8:11], a[16:19], v[88:91], v[8:11]
	v_mfma_f32_16x16x32_bf16 v[24:27], a[20:23], v[88:91], v[24:27]
	v_mfma_f32_16x16x32_bf16 v[40:43], a[24:27], v[88:91], v[40:43]
	v_mfma_f32_16x16x32_bf16 v[56:59], a[28:31], v[88:91], v[56:59]
	s_waitcnt lgkmcnt(0)
	v_mfma_f32_16x16x32_bf16 v[12:15], a[16:19], v[84:87], v[12:15]
	v_mfma_f32_16x16x32_bf16 v[28:31], a[20:23], v[84:87], v[28:31]
	v_mfma_f32_16x16x32_bf16 v[44:47], a[24:27], v[84:87], v[44:47]
	v_mfma_f32_16x16x32_bf16 v[60:63], a[28:31], v[84:87], v[60:63]
	s_setprio 0
	s_waitcnt vmcnt(0) lgkmcnt(0)
	s_barrier
	v_lshl_add_u64 v[64:65], 8, 4, v[132:133]
	v_lshl_add_u64 v[66:67], 8, 4, v[134:135]
	v_lshl_add_u64 v[68:69], 8, 4, v[144:145]
	v_lshl_add_u64 v[70:71], 8, 4, v[146:147]
	v_lshl_add_u64 v[76:77], 8, 4, v[148:149]
	v_lshl_add_u64 v[78:79], 8, 4, v[150:151]
	v_lshl_add_u64 v[72:73], 8, 4, v[152:153]
	v_lshl_add_u64 v[74:75], 8, 4, v[154:155]
	s_add_u32 m0, s100, 0x0
	s_nop 0
	global_load_lds_dwordx4 v[64:65], off
	s_add_u32 m0, s100, 0x1000
	s_nop 0
	global_load_lds_dwordx4 v[66:67], off
	s_add_u32 m0, s100, 0x2000
	s_nop 0
	global_load_lds_dwordx4 v[68:69], off
	s_add_u32 m0, s100, 0x3000
	s_nop 0
	global_load_lds_dwordx4 v[70:71], off
	s_add_u32 m0, s100, 0x4000
	s_nop 0
	global_load_lds_dwordx4 v[76:77], off
	s_add_u32 m0, s100, 0x5000
	s_nop 0
	global_load_lds_dwordx4 v[78:79], off
	s_add_u32 m0, s100, 0x6000
	s_nop 0
	global_load_lds_dwordx4 v[72:73], off
	s_add_u32 m0, s100, 0x7000
	s_nop 0
	global_load_lds_dwordx4 v[74:75], off
	ds_read_b128 a[0:3], v112 offset:32768
	ds_read_b128 v[80:83], v113 offset:32768
	ds_read_b128 a[4:7], v112 offset:34816
	ds_read_b128 a[8:11], v112 offset:36864
	ds_read_b128 a[12:15], v112 offset:38912
	ds_read_b128 v[92:95], v113 offset:34816
	ds_read_b128 v[88:91], v113 offset:36864
	ds_read_b128 v[84:87], v113 offset:38912
	ds_read_b128 a[16:19], v114 offset:32768
	ds_read_b128 a[20:23], v114 offset:34816
	ds_read_b128 a[24:27], v114 offset:36864
	ds_read_b128 a[28:31], v114 offset:38912
	s_setprio 1
	s_waitcnt lgkmcnt(10)
	v_mfma_f32_16x16x32_bf16 v[0:3], a[0:3], v[80:83], v[0:3]
	s_waitcnt lgkmcnt(9)
	v_mfma_f32_16x16x32_bf16 v[16:19], a[4:7], v[80:83], v[16:19]
	s_waitcnt lgkmcnt(8)
	v_mfma_f32_16x16x32_bf16 v[32:35], a[8:11], v[80:83], v[32:35]
	s_waitcnt lgkmcnt(7)
	v_mfma_f32_16x16x32_bf16 v[48:51], a[12:15], v[80:83], v[48:51]
	ds_read_b128 v[80:83], v115 offset:32768
	s_waitcnt lgkmcnt(7)
	v_mfma_f32_16x16x32_bf16 v[4:7], a[0:3], v[92:95], v[4:7]
	v_mfma_f32_16x16x32_bf16 v[20:23], a[4:7], v[92:95], v[20:23]
	v_mfma_f32_16x16x32_bf16 v[36:39], a[8:11], v[92:95], v[36:39]
	v_mfma_f32_16x16x32_bf16 v[52:55], a[12:15], v[92:95], v[52:55]
	ds_read_b128 v[92:95], v115 offset:34816
	s_waitcnt lgkmcnt(7)
	v_mfma_f32_16x16x32_bf16 v[8:11], a[0:3], v[88:91], v[8:11]
	v_mfma_f32_16x16x32_bf16 v[24:27], a[4:7], v[88:91], v[24:27]
	v_mfma_f32_16x16x32_bf16 v[40:43], a[8:11], v[88:91], v[40:43]
	v_mfma_f32_16x16x32_bf16 v[56:59], a[12:15], v[88:91], v[56:59]
	ds_read_b128 v[88:91], v115 offset:36864
	s_waitcnt lgkmcnt(7)
	v_mfma_f32_16x16x32_bf16 v[12:15], a[0:3], v[84:87], v[12:15]
	v_mfma_f32_16x16x32_bf16 v[28:31], a[4:7], v[84:87], v[28:31]
	v_mfma_f32_16x16x32_bf16 v[44:47], a[8:11], v[84:87], v[44:47]
	v_mfma_f32_16x16x32_bf16 v[60:63], a[12:15], v[84:87], v[60:63]
	ds_read_b128 v[84:87], v115 offset:38912
	s_waitcnt lgkmcnt(3)
	v_mfma_f32_16x16x32_bf16 v[0:3], a[16:19], v[80:83], v[0:3]
	v_mfma_f32_16x16x32_bf16 v[16:19], a[20:23], v[80:83], v[16:19]
	v_mfma_f32_16x16x32_bf16 v[32:35], a[24:27], v[80:83], v[32:35]
	v_mfma_f32_16x16x32_bf16 v[48:51], a[28:31], v[80:83], v[48:51]
	s_waitcnt lgkmcnt(2)
	v_mfma_f32_16x16x32_bf16 v[4:7], a[16:19], v[92:95], v[4:7]
	v_mfma_f32_16x16x32_bf16 v[20:23], a[20:23], v[92:95], v[20:23]
	v_mfma_f32_16x16x32_bf16 v[36:39], a[24:27], v[92:95], v[36:39]
	v_mfma_f32_16x16x32_bf16 v[52:55], a[28:31], v[92:95], v[52:55]
	s_waitcnt lgkmcnt(1)
	v_mfma_f32_16x16x32_bf16 v[8:11], a[16:19], v[88:91], v[8:11]
	v_mfma_f32_16x16x32_bf16 v[24:27], a[20:23], v[88:91], v[24:27]
	v_mfma_f32_16x16x32_bf16 v[40:43], a[24:27], v[88:91], v[40:43]
	v_mfma_f32_16x16x32_bf16 v[56:59], a[28:31], v[88:91], v[56:59]
	s_waitcnt lgkmcnt(0)
	v_mfma_f32_16x16x32_bf16 v[12:15], a[16:19], v[84:87], v[12:15]
	v_mfma_f32_16x16x32_bf16 v[28:31], a[20:23], v[84:87], v[28:31]
	v_mfma_f32_16x16x32_bf16 v[44:47], a[24:27], v[84:87], v[44:47]
	v_mfma_f32_16x16x32_bf16 v[60:63], a[28:31], v[84:87], v[60:63]
	s_setprio 0
	s_waitcnt vmcnt(0) lgkmcnt(0)
	s_barrier
	s_add_u32 s22, s22, 0x100
	s_addc_u32 s23, s23, 0
	s_cmpk_eq_i32 s22, 0xf00
	s_cbranch_scc0 .LBB0_1726
	v_lshl_add_u64 v[64:65], 8, 4, v[64:65]
	v_lshl_add_u64 v[66:67], 8, 4, v[66:67]
	v_lshl_add_u64 v[68:69], 8, 4, v[68:69]
	v_lshl_add_u64 v[70:71], 8, 4, v[70:71]
	v_lshl_add_u64 v[76:77], 8, 4, v[76:77]
	v_lshl_add_u64 v[78:79], 8, 4, v[78:79]
	v_lshl_add_u64 v[72:73], 8, 4, v[72:73]
	v_lshl_add_u64 v[74:75], 8, 4, v[74:75]
	s_add_u32 m0, s100, 0x8000
	s_nop 0
	global_load_lds_dwordx4 v[64:65], off
	s_add_u32 m0, s100, 0x9000
	s_nop 0
	global_load_lds_dwordx4 v[66:67], off
	s_add_u32 m0, s100, 0xa000
	s_nop 0
	global_load_lds_dwordx4 v[68:69], off
	s_add_u32 m0, s100, 0xb000
	s_nop 0
	global_load_lds_dwordx4 v[70:71], off
	s_add_u32 m0, s100, 0xc000
	s_nop 0
	global_load_lds_dwordx4 v[76:77], off
	s_add_u32 m0, s100, 0xd000
	s_nop 0
	global_load_lds_dwordx4 v[78:79], off
	s_add_u32 m0, s100, 0xe000
	s_nop 0
	global_load_lds_dwordx4 v[72:73], off
	s_add_u32 m0, s100, 0xf000
	s_nop 0
	global_load_lds_dwordx4 v[74:75], off
	ds_read_b128 a[0:3], v112
	ds_read_b128 v[80:83], v113
	ds_read_b128 a[4:7], v112 offset:2048
	ds_read_b128 a[8:11], v112 offset:4096
	ds_read_b128 a[12:15], v112 offset:6144
	ds_read_b128 v[92:95], v113 offset:2048
	ds_read_b128 v[88:91], v113 offset:4096
	ds_read_b128 v[84:87], v113 offset:6144
	ds_read_b128 a[16:19], v114
	ds_read_b128 a[20:23], v114 offset:2048
	ds_read_b128 a[24:27], v114 offset:4096
	ds_read_b128 a[28:31], v114 offset:6144
	s_setprio 1
	s_waitcnt lgkmcnt(10)
	v_mfma_f32_16x16x32_bf16 v[0:3], a[0:3], v[80:83], v[0:3]
	s_waitcnt lgkmcnt(9)
	v_mfma_f32_16x16x32_bf16 v[16:19], a[4:7], v[80:83], v[16:19]
	s_waitcnt lgkmcnt(8)
	v_mfma_f32_16x16x32_bf16 v[32:35], a[8:11], v[80:83], v[32:35]
	s_waitcnt lgkmcnt(7)
	v_mfma_f32_16x16x32_bf16 v[48:51], a[12:15], v[80:83], v[48:51]
	ds_read_b128 v[80:83], v115
	s_waitcnt lgkmcnt(7)
	v_mfma_f32_16x16x32_bf16 v[4:7], a[0:3], v[92:95], v[4:7]
	v_mfma_f32_16x16x32_bf16 v[20:23], a[4:7], v[92:95], v[20:23]
	v_mfma_f32_16x16x32_bf16 v[36:39], a[8:11], v[92:95], v[36:39]
	v_mfma_f32_16x16x32_bf16 v[52:55], a[12:15], v[92:95], v[52:55]
	ds_read_b128 v[92:95], v115 offset:2048
	s_waitcnt lgkmcnt(7)
	v_mfma_f32_16x16x32_bf16 v[8:11], a[0:3], v[88:91], v[8:11]
	v_mfma_f32_16x16x32_bf16 v[24:27], a[4:7], v[88:91], v[24:27]
	v_mfma_f32_16x16x32_bf16 v[40:43], a[8:11], v[88:91], v[40:43]
	v_mfma_f32_16x16x32_bf16 v[56:59], a[12:15], v[88:91], v[56:59]
	ds_read_b128 v[88:91], v115 offset:4096
	s_waitcnt lgkmcnt(7)
	v_mfma_f32_16x16x32_bf16 v[12:15], a[0:3], v[84:87], v[12:15]
	v_mfma_f32_16x16x32_bf16 v[28:31], a[4:7], v[84:87], v[28:31]
	v_mfma_f32_16x16x32_bf16 v[44:47], a[8:11], v[84:87], v[44:47]
	v_mfma_f32_16x16x32_bf16 v[60:63], a[12:15], v[84:87], v[60:63]
	ds_read_b128 v[84:87], v115 offset:6144
	s_waitcnt lgkmcnt(3)
	v_mfma_f32_16x16x32_bf16 v[0:3], a[16:19], v[80:83], v[0:3]
	v_mfma_f32_16x16x32_bf16 v[16:19], a[20:23], v[80:83], v[16:19]
	v_mfma_f32_16x16x32_bf16 v[32:35], a[24:27], v[80:83], v[32:35]
	v_mfma_f32_16x16x32_bf16 v[48:51], a[28:31], v[80:83], v[48:51]
	s_waitcnt lgkmcnt(2)
	v_mfma_f32_16x16x32_bf16 v[4:7], a[16:19], v[92:95], v[4:7]
	v_mfma_f32_16x16x32_bf16 v[20:23], a[20:23], v[92:95], v[20:23]
	v_mfma_f32_16x16x32_bf16 v[36:39], a[24:27], v[92:95], v[36:39]
	v_mfma_f32_16x16x32_bf16 v[52:55], a[28:31], v[92:95], v[52:55]
	s_waitcnt lgkmcnt(1)
	v_mfma_f32_16x16x32_bf16 v[8:11], a[16:19], v[88:91], v[8:11]
	v_mfma_f32_16x16x32_bf16 v[24:27], a[20:23], v[88:91], v[24:27]
	v_mfma_f32_16x16x32_bf16 v[40:43], a[24:27], v[88:91], v[40:43]
	v_mfma_f32_16x16x32_bf16 v[56:59], a[28:31], v[88:91], v[56:59]
	s_waitcnt lgkmcnt(0)
	v_mfma_f32_16x16x32_bf16 v[12:15], a[16:19], v[84:87], v[12:15]
	v_mfma_f32_16x16x32_bf16 v[28:31], a[20:23], v[84:87], v[28:31]
	v_mfma_f32_16x16x32_bf16 v[44:47], a[24:27], v[84:87], v[44:47]
	v_mfma_f32_16x16x32_bf16 v[60:63], a[28:31], v[84:87], v[60:63]
	s_setprio 0
	s_waitcnt vmcnt(0) lgkmcnt(0)
	s_barrier
	ds_read_b128 a[0:3], v112 offset:32768
	ds_read_b128 v[80:83], v113 offset:32768
	ds_read_b128 a[4:7], v112 offset:34816
	ds_read_b128 a[8:11], v112 offset:36864
	ds_read_b128 a[12:15], v112 offset:38912
	ds_read_b128 v[92:95], v113 offset:34816
	ds_read_b128 v[88:91], v113 offset:36864
	ds_read_b128 v[84:87], v113 offset:38912
	ds_read_b128 a[16:19], v114 offset:32768
	ds_read_b128 a[20:23], v114 offset:34816
	ds_read_b128 a[24:27], v114 offset:36864
	ds_read_b128 a[28:31], v114 offset:38912
	s_setprio 1
	s_waitcnt lgkmcnt(10)
	v_mfma_f32_16x16x32_bf16 v[0:3], a[0:3], v[80:83], v[0:3]
	s_waitcnt lgkmcnt(9)
	v_mfma_f32_16x16x32_bf16 v[16:19], a[4:7], v[80:83], v[16:19]
	s_waitcnt lgkmcnt(8)
	v_mfma_f32_16x16x32_bf16 v[32:35], a[8:11], v[80:83], v[32:35]
	s_waitcnt lgkmcnt(7)
	v_mfma_f32_16x16x32_bf16 v[48:51], a[12:15], v[80:83], v[48:51]
	ds_read_b128 v[80:83], v115 offset:32768
	s_waitcnt lgkmcnt(7)
	v_mfma_f32_16x16x32_bf16 v[4:7], a[0:3], v[92:95], v[4:7]
	v_mfma_f32_16x16x32_bf16 v[20:23], a[4:7], v[92:95], v[20:23]
	v_mfma_f32_16x16x32_bf16 v[36:39], a[8:11], v[92:95], v[36:39]
	v_mfma_f32_16x16x32_bf16 v[52:55], a[12:15], v[92:95], v[52:55]
	ds_read_b128 v[92:95], v115 offset:34816
	s_waitcnt lgkmcnt(7)
	v_mfma_f32_16x16x32_bf16 v[8:11], a[0:3], v[88:91], v[8:11]
	v_mfma_f32_16x16x32_bf16 v[24:27], a[4:7], v[88:91], v[24:27]
	v_mfma_f32_16x16x32_bf16 v[40:43], a[8:11], v[88:91], v[40:43]
	v_mfma_f32_16x16x32_bf16 v[56:59], a[12:15], v[88:91], v[56:59]
	ds_read_b128 v[88:91], v115 offset:36864
	s_waitcnt lgkmcnt(7)
	v_mfma_f32_16x16x32_bf16 v[12:15], a[0:3], v[84:87], v[12:15]
	v_mfma_f32_16x16x32_bf16 v[28:31], a[4:7], v[84:87], v[28:31]
	v_mfma_f32_16x16x32_bf16 v[44:47], a[8:11], v[84:87], v[44:47]
	v_mfma_f32_16x16x32_bf16 v[60:63], a[12:15], v[84:87], v[60:63]
	ds_read_b128 v[84:87], v115 offset:38912
	s_waitcnt lgkmcnt(3)
	v_mfma_f32_16x16x32_bf16 v[0:3], a[16:19], v[80:83], v[0:3]
	v_mfma_f32_16x16x32_bf16 v[16:19], a[20:23], v[80:83], v[16:19]
	v_mfma_f32_16x16x32_bf16 v[32:35], a[24:27], v[80:83], v[32:35]
	v_mfma_f32_16x16x32_bf16 v[48:51], a[28:31], v[80:83], v[48:51]
	s_waitcnt lgkmcnt(2)
	v_mfma_f32_16x16x32_bf16 v[4:7], a[16:19], v[92:95], v[4:7]
	v_mfma_f32_16x16x32_bf16 v[20:23], a[20:23], v[92:95], v[20:23]
	v_mfma_f32_16x16x32_bf16 v[36:39], a[24:27], v[92:95], v[36:39]
	v_mfma_f32_16x16x32_bf16 v[52:55], a[28:31], v[92:95], v[52:55]
	s_waitcnt lgkmcnt(1)
	v_mfma_f32_16x16x32_bf16 v[8:11], a[16:19], v[88:91], v[8:11]
	v_mfma_f32_16x16x32_bf16 v[24:27], a[20:23], v[88:91], v[24:27]
	v_mfma_f32_16x16x32_bf16 v[40:43], a[24:27], v[88:91], v[40:43]
	v_mfma_f32_16x16x32_bf16 v[56:59], a[28:31], v[88:91], v[56:59]
	s_waitcnt lgkmcnt(0)
	v_mfma_f32_16x16x32_bf16 v[12:15], a[16:19], v[84:87], v[12:15]
	v_mfma_f32_16x16x32_bf16 v[28:31], a[20:23], v[84:87], v[28:31]
	v_mfma_f32_16x16x32_bf16 v[44:47], a[24:27], v[84:87], v[44:47]
	v_mfma_f32_16x16x32_bf16 v[60:63], a[28:31], v[84:87], v[60:63]
	s_setprio 0
	v_readfirstlane_b32 s15, v107
	v_readfirstlane_b32 s4, v106
	s_lshl_b32 s15, s15, 6
	s_waitcnt lgkmcnt(0)
	s_barrier
	s_add_i32 s9, s15, s9
	s_lshl_b32 s15, s4, 6
	s_add_i32 s15, s15, s8
	v_or_b32_e32 v64, s9, v108
	v_cmp_gt_i32_e32 vcc, s27, v64
	v_or_b32_e32 v65, s15, v111
	s_barrier
	v_and_b32_e32 v120, 15, v143
	v_bfe_u32 v121, v143, 4, 2
	v_xor_b32_e32 v121, v121, v120
	v_lshlrev_b32_e32 v121, 4, v121
	v_lshl_add_u32 v121, v120, 8, v121
	v_lshrrev_b32_e32 v120, 6, v143
	v_lshl_add_u32 v121, v120, 14, v121
	ds_write_b128 v121, v[0:3]
	ds_write_b128 v121, v[4:7] offset:4096
	ds_write_b128 v121, v[8:11] offset:8192
	ds_write_b128 v121, v[12:15] offset:12288
	v_xor_b32_e32 v115, 64, v121
	ds_write_b128 v115, v[16:19]
	ds_write_b128 v115, v[20:23] offset:4096
	ds_write_b128 v115, v[24:27] offset:8192
	ds_write_b128 v115, v[28:31] offset:12288
	v_xor_b32_e32 v115, 128, v121
	ds_write_b128 v115, v[32:35]
	ds_write_b128 v115, v[36:39] offset:4096
	ds_write_b128 v115, v[40:43] offset:8192
	ds_write_b128 v115, v[44:47] offset:12288
	v_xor_b32_e32 v115, 192, v121
	ds_write_b128 v115, v[48:51]
	ds_write_b128 v115, v[52:55] offset:4096
	ds_write_b128 v115, v[56:59] offset:8192
	ds_write_b128 v115, v[60:63] offset:12288
	v_and_b32_e32 v112, 31, v143
	v_bfe_u32 v114, v143, 5, 1
	v_and_b32_e32 v121, 15, v112
	v_xor_b32_e32 v114, v114, v121
	v_lshlrev_b32_e32 v114, 4, v114
	v_lshl_add_u32 v114, v112, 8, v114
	v_lshl_add_u32 v114, v120, 14, v114
	ds_read_b128 v[48:51], v114
	ds_read_b128 v[32:35], v114 offset:8192
	v_xor_b32_e32 v113, 32, v114
	ds_read_b128 v[52:55], v113
	ds_read_b128 v[36:39], v113 offset:8192
	v_xor_b32_e32 v113, 64, v114
	ds_read_b128 v[56:59], v113
	ds_read_b128 v[40:43], v113 offset:8192
	v_xor_b32_e32 v113, 96, v114
	ds_read_b128 v[60:63], v113
	ds_read_b128 v[44:47], v113 offset:8192
	v_xor_b32_e32 v113, 128, v114
	ds_read_b128 v[16:19], v113
	ds_read_b128 v[0:3], v113 offset:8192
	v_xor_b32_e32 v113, 160, v114
	ds_read_b128 v[20:23], v113
	ds_read_b128 v[4:7], v113 offset:8192
	v_xor_b32_e32 v113, 192, v114
	ds_read_b128 v[24:27], v113
	ds_read_b128 v[8:11], v113 offset:8192
	v_xor_b32_e32 v113, 224, v114
	ds_read_b128 v[28:31], v113
	ds_read_b128 v[12:15], v113 offset:8192
	s_waitcnt lgkmcnt(0)
	s_barrier
	s_and_saveexec_b64 s[8:9], vcc
	s_cbranch_execz .LBB0_1729
	v_mad_u64_u32 v[66:67], s[22:23], v65, s27, v[64:65]
	v_mov_b32_e32 v67, v140
	v_lshl_add_u64 v[68:69], v[66:67], 2, s[0:1]
	global_store_dword v[68:69], v48, off
	v_add_u32_e32 v68, 0x2008, v66
	v_mov_b32_e32 v69, v140
	v_lshl_add_u64 v[68:69], v[68:69], 2, s[0:1]
	global_store_dword v[68:69], v49, off
	v_add_u32_e32 v48, 0x4010, v66
	v_mov_b32_e32 v49, v140
	v_lshl_add_u64 v[48:49], v[48:49], 2, s[0:1]
	global_store_dword v[48:49], v50, off
	v_add_u32_e32 v48, 0x6018, v66
	v_mov_b32_e32 v49, v140
	v_lshl_add_u64 v[48:49], v[48:49], 2, s[0:1]
	global_store_dword v[48:49], v51, off
	v_add_u32_e32 v48, 0x10040, v66
	v_mov_b32_e32 v49, v140
	v_lshl_add_u64 v[48:49], v[48:49], 2, s[0:1]
	global_store_dword v[48:49], v52, off
	v_add_u32_e32 v48, 0x12048, v66
	v_mov_b32_e32 v49, v140
	v_lshl_add_u64 v[48:49], v[48:49], 2, s[0:1]
	global_store_dword v[48:49], v53, off
	v_add_u32_e32 v48, 0x14050, v66
	v_mov_b32_e32 v49, v140
	v_lshl_add_u64 v[48:49], v[48:49], 2, s[0:1]
	global_store_dword v[48:49], v54, off
	v_add_u32_e32 v48, 0x16058, v66
	v_mov_b32_e32 v49, v140
	v_lshl_add_u64 v[48:49], v[48:49], 2, s[0:1]
	global_store_dword v[48:49], v55, off
	v_add_u32_e32 v48, 0x20080, v66
	v_mov_b32_e32 v49, v140
	v_lshl_add_u64 v[48:49], v[48:49], 2, s[0:1]
	global_store_dword v[48:49], v56, off
	v_add_u32_e32 v48, 0x22088, v66
	v_mov_b32_e32 v49, v140
	v_lshl_add_u64 v[48:49], v[48:49], 2, s[0:1]
	global_store_dword v[48:49], v57, off
	v_add_u32_e32 v48, 0x24090, v66
	v_mov_b32_e32 v49, v140
	v_lshl_add_u64 v[48:49], v[48:49], 2, s[0:1]
	global_store_dword v[48:49], v58, off
	v_add_u32_e32 v48, 0x26098, v66
	v_mov_b32_e32 v49, v140
	v_lshl_add_u64 v[48:49], v[48:49], 2, s[0:1]
	global_store_dword v[48:49], v59, off
	v_add_u32_e32 v48, 0x300c0, v66
	v_mov_b32_e32 v49, v140
	v_lshl_add_u64 v[48:49], v[48:49], 2, s[0:1]
	global_store_dword v[48:49], v60, off
	v_add_u32_e32 v48, 0x320c8, v66
	v_mov_b32_e32 v49, v140
	v_lshl_add_u64 v[48:49], v[48:49], 2, s[0:1]
	global_store_dword v[48:49], v61, off
	v_add_u32_e32 v48, 0x340d0, v66
	v_mov_b32_e32 v49, v140
	v_lshl_add_u64 v[48:49], v[48:49], 2, s[0:1]
	global_store_dword v[48:49], v62, off
	v_add_u32_e32 v48, 0x360d8, v66
	v_mov_b32_e32 v49, v140
	v_lshl_add_u64 v[48:49], v[48:49], 2, s[0:1]
	global_store_dword v[48:49], v63, off

	.amdhsa_kernel _Z14fwd_megakernel6Params
		.amdhsa_group_segment_fixed_size 65600
		.amdhsa_private_segment_fixed_size 0
		.amdhsa_kernarg_size 616
		.amdhsa_user_sgpr_count 2
		.amdhsa_user_sgpr_dispatch_ptr 0
		.amdhsa_user_sgpr_queue_ptr 0
		.amdhsa_user_sgpr_kernarg_segment_ptr 1
		.amdhsa_user_sgpr_dispatch_id 0
		.amdhsa_user_sgpr_kernarg_preload_length 0
		.amdhsa_user_sgpr_kernarg_preload_offset 0
		.amdhsa_user_sgpr_private_segment_size 0
		.amdhsa_uses_dynamic_stack 0
		.amdhsa_enable_private_segment 0
		.amdhsa_system_sgpr_workgroup_id_x 1
		.amdhsa_system_sgpr_workgroup_id_y 0
		.amdhsa_system_sgpr_workgroup_id_z 0
		.amdhsa_system_sgpr_workgroup_info 0
		.amdhsa_system_vgpr_workitem_id 2
		.amdhsa_next_free_vgpr 256
		.amdhsa_next_free_sgpr 102
		.amdhsa_accum_offset 224
		.amdhsa_reserve_vcc 1
		.amdhsa_float_round_mode_32 0
		.amdhsa_float_round_mode_16_64 0
		.amdhsa_float_denorm_mode_32 3
		.amdhsa_float_denorm_mode_16_64 3
		.amdhsa_dx10_clamp 1
		.amdhsa_ieee_mode 1
		.amdhsa_fp16_overflow 0
		.amdhsa_tg_split 0
		.amdhsa_exception_fp_ieee_invalid_op 0
		.amdhsa_exception_fp_denorm_src 0
		.amdhsa_exception_fp_ieee_div_zero 0
		.amdhsa_exception_fp_ieee_overflow 0
		.amdhsa_exception_fp_ieee_underflow 0
		.amdhsa_exception_fp_ieee_inexact 0
		.amdhsa_exception_int_div_zero 0
	.end_amdhsa_kernel

amdhsa.kernels:
  - .agpr_count:     32
    .args:
      - .offset:         0
        .size:           360
        .value_kind:     by_value
      - .offset:         360
        .size:           4
        .value_kind:     hidden_block_count_x
      - .offset:         364
        .size:           4
        .value_kind:     hidden_block_count_y
      - .offset:         368
        .size:           4
        .value_kind:     hidden_block_count_z
      - .offset:         372
        .size:           2
        .value_kind:     hidden_group_size_x
      - .offset:         374
        .size:           2
        .value_kind:     hidden_group_size_y
      - .offset:         376
        .size:           2
        .value_kind:     hidden_group_size_z
      - .offset:         378
        .size:           2
        .value_kind:     hidden_remainder_x
      - .offset:         380
        .size:           2
        .value_kind:     hidden_remainder_y
      - .offset:         382
        .size:           2
        .value_kind:     hidden_remainder_z
      - .offset:         400
        .size:           8
        .value_kind:     hidden_global_offset_x
      - .offset:         408
        .size:           8
        .value_kind:     hidden_global_offset_y
      - .offset:         416
        .size:           8
        .value_kind:     hidden_global_offset_z
      - .offset:         424
        .size:           2
        .value_kind:     hidden_grid_dims
      - .offset:         448
        .size:           8
        .value_kind:     hidden_multigrid_sync_arg
    .group_segment_fixed_size: 65600
    .kernarg_segment_align: 8
    .kernarg_segment_size: 616
    .language:       OpenCL C
    .language_version:
      - 2
      - 0
    .max_flat_workgroup_size: 256
    .name:           _Z14fwd_megakernel6Params
    .private_segment_fixed_size: 0
    .sgpr_count:     108
    .sgpr_spill_count: 148
    .symbol:         _Z14fwd_megakernel6Params.kd
    .uniform_work_group_size: 1
    .uses_dynamic_stack: false
    .vgpr_count:     221
    .vgpr_spill_count: 0
    .wavefront_size: 64
